# layer-1 V expert table f32->fp4 conversion moved out of PRO into the attention phase (two 4-KB chunks per unit per wave, loads at the unit head behind the query prefetch, conversion at the unit tail)
# speedup vs baseline: 1.1450x; 1.0133x over previous
.LBB0_83:
	s_or_b64 exec, exec, s[6:7]
	v_writelane_b32 v248, s64, 16
	v_writelane_b32 v248, s65, 17
	v_writelane_b32 v248, s62, 12
	v_writelane_b32 v248, s63, 13
	v_writelane_b32 v248, s40, 14
	v_writelane_b32 v248, s41, 15
	s_ashr_i32 s1, s33, 1
	s_cmpk_lt_i32 s1, 0x4000
	s_mov_b64 s[26:27], 0
	s_lshl_b32 s1, s1, 11
	s_and_b32 s16, s1, 0x1fff800
	v_readlane_b32 s1, v248, 3
	s_lshl_b32 s1, s1, 10
	s_and_b32 s17, s1, 0x400
	s_add_i32 s1, s33, s90
	s_cmp_lt_i32 s1, 0x10000
	s_cselect_b32 s1, s1, s33
	s_ashr_i32 s4, s1, 1
	s_cmpk_lt_i32 s4, 0x4000
	s_mov_b64 s[30:31], 0
	s_lshl_b32 s4, s4, 11
	s_lshl_b32 s1, s1, 10
	s_and_b32 s28, s4, 0x1fff800
	s_and_b32 s38, s1, 0x400
	s_cmp_lt_i32 s33, 0x10000
	v_readlane_b32 s34, v248, 0
	s_cselect_b64 s[14:15], -1, 0
	v_lshlrev_b32_e32 v68, 1, v80
	s_waitcnt vmcnt(31)
	v_and_b32_e32 v2, 7, v80
	v_lshrrev_b32_e32 v1, 1, v80
	s_bfe_u32 s70, s34, 0x10006
	s_lshl_b32 s1, s58, 4
	v_ashrrev_i32_e32 v73, 31, v72
	v_and_b32_e32 v74, 0xffffffe0, v68
	v_lshlrev_b32_e32 v76, 3, v2
	v_mov_b32_e32 v77, 0
	v_and_b32_e32 v78, 4, v1
	v_lshlrev_b32_e32 v1, 2, v2
	v_cmp_gt_u32_e64 s[6:7], 4, v2
	v_cmp_eq_u32_e64 s[8:9], 3, v2
	v_cmp_eq_u32_e64 s[10:11], 2, v2
	v_cmp_eq_u32_e64 s[12:13], 1, v2
	s_lshl_b32 s39, s70, 10
	s_mul_i32 s34, s58, 24
	v_cndmask_b32_e64 v2, 0, 1, s[14:15]
	s_mov_b32 s29, 0
	v_cmp_eq_u32_e64 s[4:5], 0, v80
	v_ashrrev_i32_e32 v75, 31, v74
	v_mov_b32_e32 v79, v77
	v_ashrrev_i32_e32 v69, 31, v68
	s_lshl_b32 s71, s70, 23
	s_add_i32 s76, s0, s34
	s_add_i32 s77, s0, s90
	s_add_i32 s78, s0, s1
	s_mov_b64 s[34:35], -1
	v_cmp_ne_u32_e64 s[14:15], 1, v2
	v_lshlrev_b64 v[72:73], 2, v[72:73]
	s_lshl_b32 s79, s28, 2
	s_lshl_b32 s80, s38, 2
	s_lshl_b32 s81, s16, 2
	s_lshl_b32 s82, s17, 2
	s_lshl_b32 s38, s39, 2
	s_mov_b32 s83, 0xda24260
	s_mov_b32 s16, 0
	s_branch .LBB0_85
.LBB0_84:
	s_xor_b64 s[42:43], s[34:35], -1
	s_mov_b32 s16, 1
	s_mov_b64 s[34:35], 0
	s_and_b64 vcc, exec, s[42:43]
	s_branch .LBB0_133

.LBB0_485:
	s_cmp_lt_i32 s56, 7
	s_cselect_b64 s[0:1], -1, 0
	s_and_b64 s[44:45], s[0:1], s[4:5]
	s_andn2_b64 vcc, exec, s[44:45]
	s_cbranch_vccnz .LBB0_540
	v_mbcnt_lo_u32_b32 v246, -1, 0
	v_mbcnt_hi_u32_b32 v246, -1, v246
	v_readlane_b32 s21, v248, 0
	s_andn2_b32 s26, s21, 63
	v_add_u32_e32 v242, s26, v246
	s_lshr_b32 s21, s21, 6
	s_mov_b32 s4, 0
	s_mov_b32 s5, -1
	s_mov_b32 s6, 0xffffff80
	s_mov_b32 s7, 0xffffffc0
	v_lshrrev_b32_e32 v245, 5, v246
	v_and_b32_e32 v247, 31, v246
	v_lshlrev_b32_e32 v239, 12, v247
	v_lshl_or_b32 v239, v245, 4, v239
	v_lshlrev_b32_e32 v241, 9, v247
	v_lshl_or_b32 v241, v245, 5, v241
	v_lshlrev_b32_e32 v240, 4, v247
	s_lshl_b32 s26, s21, 11
	s_add_i32 s26, s26, 0x10000
	v_add_u32_e32 v240, s26, v240
	v_and_b32_e32 v215, 15, v246
	v_xor_b32_e32 v215, v215, v245
	v_lshlrev_b32_e32 v215, 4, v215
	v_lshl_or_b32 v215, v247, 8, v215
	v_xor_b32_e32 v232, 32, v215
	v_xor_b32_e32 v233, 64, v215
	v_xor_b32_e32 v234, 0x60, v215
	v_xor_b32_e32 v235, 0x80, v215
	v_xor_b32_e32 v236, 0xa0, v215
	v_xor_b32_e32 v237, 0xc0, v215
	v_xor_b32_e32 v238, 0xe0, v215
	v_lshlrev_b32_e32 v247, 2, v245
	v_xor_b32_e32 v211, 4, v247
	v_lshrrev_b32_e32 v243, 4, v242
	v_xor_b32_e32 v247, v243, v242
	v_lshlrev_b32_e32 v242, 4, v242
	v_and_b32_e32 v247, 15, v247
	v_lshlrev_b32_e32 v247, 4, v247
	v_lshl_or_b32 v243, v243, 8, v247
	v_mov_b32_e32 v244, 0xff800000
	v_mov_b32_e32 v247, 0x14000
	v_mov_b32_e32 v128, 0x20021001
	ds_write_b32 v247, v128 offset:0
	v_mov_b32_e32 v128, 0x40043003
	ds_write_b32 v247, v128 offset:4
	v_mov_b32_e32 v128, 0x60065005
	ds_write_b32 v247, v128 offset:8
	v_mov_b32_e32 v128, 0x80087007
	ds_write_b32 v247, v128 offset:12
	v_mov_b32_e32 v128, 0xa00a9009
	ds_write_b32 v247, v128 offset:16
	v_mov_b32_e32 v128, 0xc00cb00b
	ds_write_b32 v247, v128 offset:20
	v_mov_b32_e32 v128, 0xe00ed00d
	ds_write_b32 v247, v128 offset:24
	v_mov_b32_e32 v128, 0x2112f00f
	ds_write_b32 v247, v128 offset:28
	v_mov_b32_e32 v128, 0x41143113
	ds_write_b32 v247, v128 offset:32
	v_mov_b32_e32 v128, 0x61165115
	ds_write_b32 v247, v128 offset:36
	v_mov_b32_e32 v128, 0x32237117
	ds_write_b32 v247, v128 offset:40
	v_mov_b32_e32 v128, 0x4224
	ds_write_b32 v247, v128 offset:44
	v_mov_b32_e32 v128, 0x22221111
	ds_write_b32 v247, v128 offset:48
	v_mov_b32_e32 v128, 0x3333
	ds_write_b32 v247, v128 offset:52
	v_mov_b32_e32 v128, 0
	ds_write_b32 v247, v128 offset:56
	v_mov_b32_e32 v128, 0
	ds_write_b32 v247, v128 offset:60
	s_and_b32 s25, s2, 7
	s_lshl_b32 s25, s25, 3
	s_bfe_u32 s26, s2, 0x30003
	s_add_i32 s25, s25, s26
	s_lshl_b32 s23, s25, 8
	s_lshl_b32 s26, s21, 5
	s_add_i32 s23, s23, s26
	v_lshlrev_b32_e32 v212, 4, v246
	v_lshlrev_b32_e32 v213, 1, v246
	v_mov_b32_e32 v214, 0
	s_lshl_b32 s14, s2, 3
	s_add_i32 s14, s14, s21
	s_and_b32 s15, s14, 1
	s_lshr_b32 s14, s14, 1
	v_readlane_b32 s8, v248, 12
	v_readlane_b32 s9, v248, 13
	s_lshl_b32 s26, s14, 13
	s_lshl_b32 s25, s15, 12
	s_add_i32 s26, s26, s25
	s_add_u32 s8, s8, s26
	s_addc_u32 s9, s9, 0
	v_readlane_b32 s12, v248, 14
	v_readlane_b32 s13, v248, 15
	s_add_u32 s12, s12, s25
	s_addc_u32 s13, s13, 0
	global_load_dwordx4 v[176:179], v212, s[12:13] offset:0
	global_load_dwordx4 v[180:183], v212, s[12:13] offset:1024
	global_load_dwordx4 v[184:187], v212, s[12:13] offset:2048
	global_load_dwordx4 v[188:191], v212, s[12:13] offset:3072
	s_lshl_b32 s26, s15, 23
	s_lshl_b32 s25, s14, 7
	s_add_i32 s26, s26, s25
	s_add_i32 s26, s26, 0x8000000
	s_add_u32 s10, s54, s26
	s_addc_u32 s11, s55, 0
	s_lshl_b32 s26, s14, 3
	s_lshl_b32 s25, s15, 2
	s_add_i32 s26, s26, s25
	s_add_i32 s26, s26, 0x80000
	s_add_u32 s12, s54, s26
	s_addc_u32 s13, s55, 0
	global_load_dwordx4 v[160:163], v212, s[8:9] offset:0 nt
	global_load_dwordx4 v[164:167], v212, s[8:9] offset:1024 nt
	global_load_dwordx4 v[168:171], v212, s[8:9] offset:2048 nt
	global_load_dwordx4 v[172:175], v212, s[8:9] offset:3072 nt
	s_add_u32 s8, s8, 0x800000
	s_addc_u32 s9, s9, 0
	v_mov_b32_e32 v246, 0x14000
	s_lshr_b32 s24, s2, 6
	s_mov_b32 s22, 0
.Ltk0_unit:
	s_lshl_b32 s26, s24, 9
	s_lshl_b32 s20, s23, 12
	s_add_i32 s26, s26, s20
	s_add_i32 s26, s26, 0x1c000000
	s_add_u32 s16, s54, s26
	s_addc_u32 s17, s55, 0
	s_lshl_b32 s26, s24, 16
	s_add_i32 s26, s26, 0x300000
	s_add_u32 s18, s54, s26
	s_addc_u32 s19, s55, 0
	s_lshl_b32 s20, s23, 9
	s_lshl_b32 s26, s24, 6
	s_add_i32 s20, s20, s26
	s_add_i32 s26, s20, 0x28000000
	s_add_u32 s28, s54, s26
	s_addc_u32 s29, s55, 0
	s_add_i32 s26, s20, 0x28800000
	s_add_u32 s30, s54, s26
	s_addc_u32 s31, s55, 0
	s_barrier
	global_load_dwordx4 v[0:3], v242, s[18:19]
	v_add_u32_e32 v247, 0x2000, v242
	global_load_dwordx4 v[4:7], v247, s[18:19]
	v_add_u32_e32 v247, 0x4000, v242
	global_load_dwordx4 v[8:11], v247, s[18:19]
	v_add_u32_e32 v247, 0x6000, v242
	global_load_dwordx4 v[12:15], v247, s[18:19]
	v_add_u32_e32 v247, 0x8000, v242
	global_load_dwordx4 v[16:19], v247, s[18:19]
	v_add_u32_e32 v247, 0xa000, v242
	global_load_dwordx4 v[20:23], v247, s[18:19]
	v_add_u32_e32 v247, 0xc000, v242
	global_load_dwordx4 v[24:27], v247, s[18:19]
	v_add_u32_e32 v247, 0xe000, v242
	global_load_dwordx4 v[28:31], v247, s[18:19]
	global_load_dwordx4 v[64:67], v239, s[16:17] offset:0
	global_load_dwordx4 v[68:71], v239, s[16:17] offset:32
	global_load_dwordx4 v[72:75], v239, s[16:17] offset:64
	global_load_dwordx4 v[76:79], v239, s[16:17] offset:96
	global_load_dwordx4 v[80:83], v239, s[16:17] offset:128
	global_load_dwordx4 v[84:87], v239, s[16:17] offset:160
	global_load_dwordx4 v[88:91], v239, s[16:17] offset:192
	global_load_dwordx4 v[92:95], v239, s[16:17] offset:224
	s_waitcnt vmcnt(15)
	ds_write_b128 v243, v[0:3] offset:0
	s_waitcnt vmcnt(14)
	ds_write_b128 v243, v[4:7] offset:8192
	s_waitcnt vmcnt(13)
	ds_write_b128 v243, v[8:11] offset:16384
	s_waitcnt vmcnt(12)
	ds_write_b128 v243, v[12:15] offset:24576
	s_waitcnt vmcnt(11)
	ds_write_b128 v243, v[16:19] offset:32768
	s_waitcnt vmcnt(10)
	ds_write_b128 v243, v[20:23] offset:40960
	s_waitcnt vmcnt(9)
	ds_write_b128 v243, v[24:27] offset:49152
	s_waitcnt vmcnt(8)
	ds_write_b128 v243, v[28:31] offset:57344
	s_waitcnt lgkmcnt(0)
	s_barrier
	ds_read_b128 v[96:99], v215 offset:0
	ds_read_b128 v[100:103], v232 offset:0
	ds_read_b128 v[104:107], v233 offset:0
	ds_read_b128 v[108:111], v234 offset:0
	ds_read_b128 v[112:115], v235 offset:0
	ds_read_b128 v[116:119], v236 offset:0
	ds_read_b128 v[120:123], v237 offset:0
	ds_read_b128 v[124:127], v238 offset:0
	s_waitcnt vmcnt(0)
	s_waitcnt lgkmcnt(4)
	v_mfma_f32_32x32x16_bf16 v[0:15], v[96:99], v[64:67], 0
	v_mfma_f32_32x32x16_bf16 v[0:15], v[100:103], v[68:71], v[0:15]
	v_mfma_f32_32x32x16_bf16 v[0:15], v[104:107], v[72:75], v[0:15]
	v_mfma_f32_32x32x16_bf16 v[0:15], v[108:111], v[76:79], v[0:15]
	ds_read_b128 v[96:99], v215 offset:8192
	ds_read_b128 v[100:103], v232 offset:8192
	ds_read_b128 v[104:107], v233 offset:8192
	ds_read_b128 v[108:111], v234 offset:8192
	s_waitcnt lgkmcnt(4)
	v_mfma_f32_32x32x16_bf16 v[0:15], v[112:115], v[80:83], v[0:15]
	v_mfma_f32_32x32x16_bf16 v[0:15], v[116:119], v[84:87], v[0:15]
	v_mfma_f32_32x32x16_bf16 v[0:15], v[120:123], v[88:91], v[0:15]
	v_mfma_f32_32x32x16_bf16 v[0:15], v[124:127], v[92:95], v[0:15]
	ds_read_b128 v[112:115], v235 offset:8192
	ds_read_b128 v[116:119], v236 offset:8192
	ds_read_b128 v[120:123], v237 offset:8192
	ds_read_b128 v[124:127], v238 offset:8192
	s_waitcnt lgkmcnt(4)
	v_mfma_f32_32x32x16_bf16 v[16:31], v[96:99], v[64:67], 0
	v_mfma_f32_32x32x16_bf16 v[16:31], v[100:103], v[68:71], v[16:31]
	v_mfma_f32_32x32x16_bf16 v[16:31], v[104:107], v[72:75], v[16:31]
	v_mfma_f32_32x32x16_bf16 v[16:31], v[108:111], v[76:79], v[16:31]
	ds_read_b128 v[96:99], v215 offset:16384
	ds_read_b128 v[100:103], v232 offset:16384
	ds_read_b128 v[104:107], v233 offset:16384
	ds_read_b128 v[108:111], v234 offset:16384
	s_waitcnt lgkmcnt(4)
	v_mfma_f32_32x32x16_bf16 v[16:31], v[112:115], v[80:83], v[16:31]
	v_mfma_f32_32x32x16_bf16 v[16:31], v[116:119], v[84:87], v[16:31]
	v_mfma_f32_32x32x16_bf16 v[16:31], v[120:123], v[88:91], v[16:31]
	v_mfma_f32_32x32x16_bf16 v[16:31], v[124:127], v[92:95], v[16:31]
	ds_read_b128 v[112:115], v235 offset:16384
	ds_read_b128 v[116:119], v236 offset:16384
	ds_read_b128 v[120:123], v237 offset:16384
	ds_read_b128 v[124:127], v238 offset:16384
	s_waitcnt lgkmcnt(4)
	v_mfma_f32_32x32x16_bf16 v[32:47], v[96:99], v[64:67], 0
	v_mfma_f32_32x32x16_bf16 v[32:47], v[100:103], v[68:71], v[32:47]
	v_mfma_f32_32x32x16_bf16 v[32:47], v[104:107], v[72:75], v[32:47]
	v_mfma_f32_32x32x16_bf16 v[32:47], v[108:111], v[76:79], v[32:47]
	ds_read_b128 v[96:99], v215 offset:24576
	ds_read_b128 v[100:103], v232 offset:24576
	ds_read_b128 v[104:107], v233 offset:24576
	ds_read_b128 v[108:111], v234 offset:24576
	s_waitcnt lgkmcnt(4)
	v_mfma_f32_32x32x16_bf16 v[32:47], v[112:115], v[80:83], v[32:47]
	v_mfma_f32_32x32x16_bf16 v[32:47], v[116:119], v[84:87], v[32:47]
	v_mfma_f32_32x32x16_bf16 v[32:47], v[120:123], v[88:91], v[32:47]
	v_mfma_f32_32x32x16_bf16 v[32:47], v[124:127], v[92:95], v[32:47]
	ds_read_b128 v[112:115], v235 offset:24576
	ds_read_b128 v[116:119], v236 offset:24576
	ds_read_b128 v[120:123], v237 offset:24576
	ds_read_b128 v[124:127], v238 offset:24576
	s_waitcnt lgkmcnt(4)
	v_mfma_f32_32x32x16_bf16 v[48:63], v[96:99], v[64:67], 0
	v_mfma_f32_32x32x16_bf16 v[48:63], v[100:103], v[68:71], v[48:63]
	v_mfma_f32_32x32x16_bf16 v[48:63], v[104:107], v[72:75], v[48:63]
	v_mfma_f32_32x32x16_bf16 v[48:63], v[108:111], v[76:79], v[48:63]
	s_waitcnt lgkmcnt(0)
	v_mfma_f32_32x32x16_bf16 v[48:63], v[112:115], v[80:83], v[48:63]
	v_mfma_f32_32x32x16_bf16 v[48:63], v[116:119], v[84:87], v[48:63]
	v_mfma_f32_32x32x16_bf16 v[48:63], v[120:123], v[88:91], v[48:63]
	v_mfma_f32_32x32x16_bf16 v[48:63], v[124:127], v[92:95], v[48:63]
	global_load_dwordx4 v[64:67], v239, s[16:17] offset:256
	global_load_dwordx4 v[68:71], v239, s[16:17] offset:288
	global_load_dwordx4 v[72:75], v239, s[16:17] offset:320
	global_load_dwordx4 v[76:79], v239, s[16:17] offset:352
	global_load_dwordx4 v[80:83], v239, s[16:17] offset:384
	global_load_dwordx4 v[84:87], v239, s[16:17] offset:416
	global_load_dwordx4 v[88:91], v239, s[16:17] offset:448
	global_load_dwordx4 v[92:95], v239, s[16:17] offset:480
	s_nop 11
	v_and_or_b32 v0, v0, s6, v211
	v_or_b32_e32 v0, 0x7b, v0
	v_and_or_b32 v1, v1, s6, v211
	v_or_b32_e32 v1, 0x7a, v1
	v_and_or_b32 v2, v2, s6, v211
	v_or_b32_e32 v2, 0x79, v2
	v_and_or_b32 v3, v3, s6, v211
	v_or_b32_e32 v3, 0x78, v3
	v_and_or_b32 v4, v4, s6, v211
	v_or_b32_e32 v4, 0x73, v4
	v_and_or_b32 v5, v5, s6, v211
	v_or_b32_e32 v5, 0x72, v5
	v_and_or_b32 v6, v6, s6, v211
	v_or_b32_e32 v6, 0x71, v6
	v_and_or_b32 v7, v7, s6, v211
	v_or_b32_e32 v7, 0x70, v7
	v_and_or_b32 v8, v8, s6, v211
	v_or_b32_e32 v8, 0x6b, v8
	v_and_or_b32 v9, v9, s6, v211
	v_or_b32_e32 v9, 0x6a, v9
	v_and_or_b32 v10, v10, s6, v211
	v_or_b32_e32 v10, 0x69, v10
	v_and_or_b32 v11, v11, s6, v211
	v_or_b32_e32 v11, 0x68, v11
	v_and_or_b32 v12, v12, s6, v211
	v_or_b32_e32 v12, 0x63, v12
	v_and_or_b32 v13, v13, s6, v211
	v_or_b32_e32 v13, 0x62, v13
	v_and_or_b32 v14, v14, s6, v211
	v_or_b32_e32 v14, 0x61, v14
	v_and_or_b32 v15, v15, s6, v211
	v_or_b32_e32 v15, 0x60, v15
	v_and_or_b32 v16, v16, s6, v211
	v_or_b32_e32 v16, 0x5b, v16
	v_and_or_b32 v17, v17, s6, v211
	v_or_b32_e32 v17, 0x5a, v17
	v_and_or_b32 v18, v18, s6, v211
	v_or_b32_e32 v18, 0x59, v18
	v_and_or_b32 v19, v19, s6, v211
	v_or_b32_e32 v19, 0x58, v19
	v_and_or_b32 v20, v20, s6, v211
	v_or_b32_e32 v20, 0x53, v20
	v_and_or_b32 v21, v21, s6, v211
	v_or_b32_e32 v21, 0x52, v21
	v_and_or_b32 v22, v22, s6, v211
	v_or_b32_e32 v22, 0x51, v22
	v_and_or_b32 v23, v23, s6, v211
	v_or_b32_e32 v23, 0x50, v23
	v_and_or_b32 v24, v24, s6, v211
	v_or_b32_e32 v24, 0x4b, v24
	v_and_or_b32 v25, v25, s6, v211
	v_or_b32_e32 v25, 0x4a, v25
	v_and_or_b32 v26, v26, s6, v211
	v_or_b32_e32 v26, 0x49, v26
	v_and_or_b32 v27, v27, s6, v211
	v_or_b32_e32 v27, 0x48, v27
	v_and_or_b32 v28, v28, s6, v211
	v_or_b32_e32 v28, 0x43, v28
	v_and_or_b32 v29, v29, s6, v211
	v_or_b32_e32 v29, 0x42, v29
	v_and_or_b32 v30, v30, s6, v211
	v_or_b32_e32 v30, 0x41, v30
	v_and_or_b32 v31, v31, s6, v211
	v_or_b32_e32 v31, 64, v31
	v_and_or_b32 v32, v32, s6, v211
	v_or_b32_e32 v32, 59, v32
	v_and_or_b32 v33, v33, s6, v211
	v_or_b32_e32 v33, 58, v33
	v_and_or_b32 v34, v34, s6, v211
	v_or_b32_e32 v34, 57, v34
	v_and_or_b32 v35, v35, s6, v211
	v_or_b32_e32 v35, 56, v35
	v_and_or_b32 v36, v36, s6, v211
	v_or_b32_e32 v36, 51, v36
	v_and_or_b32 v37, v37, s6, v211
	v_or_b32_e32 v37, 50, v37
	v_and_or_b32 v38, v38, s6, v211
	v_or_b32_e32 v38, 49, v38
	v_and_or_b32 v39, v39, s6, v211
	v_or_b32_e32 v39, 48, v39
	v_and_or_b32 v40, v40, s6, v211
	v_or_b32_e32 v40, 43, v40
	v_and_or_b32 v41, v41, s6, v211
	v_or_b32_e32 v41, 42, v41
	v_and_or_b32 v42, v42, s6, v211
	v_or_b32_e32 v42, 41, v42
	v_and_or_b32 v43, v43, s6, v211
	v_or_b32_e32 v43, 40, v43
	v_and_or_b32 v44, v44, s6, v211
	v_or_b32_e32 v44, 35, v44
	v_and_or_b32 v45, v45, s6, v211
	v_or_b32_e32 v45, 34, v45
	v_and_or_b32 v46, v46, s6, v211
	v_or_b32_e32 v46, 33, v46
	v_and_or_b32 v47, v47, s6, v211
	v_or_b32_e32 v47, 32, v47
	v_and_or_b32 v48, v48, s6, v211
	v_or_b32_e32 v48, 27, v48
	v_and_or_b32 v49, v49, s6, v211
	v_or_b32_e32 v49, 26, v49
	v_and_or_b32 v50, v50, s6, v211
	v_or_b32_e32 v50, 25, v50
	v_and_or_b32 v51, v51, s6, v211
	v_or_b32_e32 v51, 24, v51
	v_and_or_b32 v52, v52, s6, v211
	v_or_b32_e32 v52, 19, v52
	v_and_or_b32 v53, v53, s6, v211
	v_or_b32_e32 v53, 18, v53
	v_and_or_b32 v54, v54, s6, v211
	v_or_b32_e32 v54, 17, v54
	v_and_or_b32 v55, v55, s6, v211
	v_or_b32_e32 v55, 16, v55
	v_and_or_b32 v56, v56, s6, v211
	v_or_b32_e32 v56, 11, v56
	v_and_or_b32 v57, v57, s6, v211
	v_or_b32_e32 v57, 10, v57
	v_and_or_b32 v58, v58, s6, v211
	v_or_b32_e32 v58, 9, v58
	v_and_or_b32 v59, v59, s6, v211
	v_or_b32_e32 v59, 8, v59
	v_and_or_b32 v60, v60, s6, v211
	v_or_b32_e32 v60, 3, v60
	v_and_or_b32 v61, v61, s6, v211
	v_or_b32_e32 v61, 2, v61
	v_and_or_b32 v62, v62, s6, v211
	v_or_b32_e32 v62, 1, v62
	v_and_or_b32 v63, v63, s6, v211
	v_or_b32_e32 v63, 0, v63
	v_max_f32_e32 v144, v0, v13
	v_min_f32_e32 v13, v0, v13
	v_max_f32_e32 v145, v1, v12
	v_min_f32_e32 v12, v1, v12
	v_max_f32_e32 v146, v2, v15
	v_min_f32_e32 v15, v2, v15
	v_max_f32_e32 v147, v3, v14
	v_min_f32_e32 v14, v3, v14
	v_max_f32_e32 v148, v4, v8
	v_min_f32_e32 v8, v4, v8
	v_max_f32_e32 v149, v5, v6
	v_min_f32_e32 v6, v5, v6
	v_max_f32_e32 v150, v7, v11
	v_min_f32_e32 v11, v7, v11
	v_max_f32_e32 v151, v9, v10
	v_min_f32_e32 v10, v9, v10
	v_max_f32_e32 v249, v144, v149
	v_min_f32_e32 v149, v144, v149
	v_max_f32_e32 v250, v145, v150
	v_min_f32_e32 v150, v145, v150
	v_max_f32_e32 v251, v146, v151
	v_min_f32_e32 v151, v146, v151
	v_max_f32_e32 v252, v147, v148
	v_min_f32_e32 v148, v147, v148
	v_max_f32_e32 v253, v6, v13
	v_min_f32_e32 v13, v6, v13
	v_max_f32_e32 v254, v8, v14
	v_min_f32_e32 v14, v8, v14
	v_max_f32_e32 v255, v10, v15
	v_min_f32_e32 v15, v10, v15
	v_max_f32_e32 v96, v11, v12
	v_min_f32_e32 v12, v11, v12
	v_max_f32_e32 v97, v249, v250
	v_min_f32_e32 v250, v249, v250
	v_max_f32_e32 v98, v251, v252
	v_min_f32_e32 v252, v251, v252
	v_max_f32_e32 v99, v148, v149
	v_min_f32_e32 v149, v148, v149
	v_max_f32_e32 v100, v253, v254
	v_min_f32_e32 v254, v253, v254
	v_max_f32_e32 v101, v150, v151
	v_min_f32_e32 v151, v150, v151
	v_max_f32_e32 v102, v255, v96
	v_min_f32_e32 v96, v255, v96
	v_max_f32_e32 v103, v12, v13
	v_min_f32_e32 v13, v12, v13
	v_max_f32_e32 v104, v14, v15
	v_min_f32_e32 v15, v14, v15
	v_max_f32_e32 v105, v97, v98
	v_min_f32_e32 v98, v97, v98
	v_max_f32_e32 v106, v250, v252
	v_min_f32_e32 v252, v250, v252
	v_max_f32_e32 v107, v99, v102
	v_min_f32_e32 v102, v99, v102
	v_max_f32_e32 v108, v149, v96
	v_min_f32_e32 v96, v149, v96
	v_max_f32_e32 v109, v100, v101
	v_min_f32_e32 v101, v100, v101
	v_max_f32_e32 v110, v254, v151
	v_min_f32_e32 v151, v254, v151
	v_max_f32_e32 v111, v103, v104
	v_min_f32_e32 v104, v103, v104
	v_max_f32_e32 v112, v13, v15
	v_min_f32_e32 v15, v13, v15
	v_max_f32_e32 v113, v106, v98
	v_min_f32_e32 v98, v106, v98
	v_max_f32_e32 v114, v252, v111
	v_min_f32_e32 v111, v252, v111
	v_max_f32_e32 v115, v107, v109
	v_min_f32_e32 v109, v107, v109
	v_max_f32_e32 v116, v108, v101
	v_min_f32_e32 v101, v108, v101
	v_max_f32_e32 v117, v110, v102
	v_min_f32_e32 v102, v110, v102
	v_max_f32_e32 v118, v151, v96
	v_min_f32_e32 v96, v151, v96
	v_max_f32_e32 v119, v112, v104
	v_min_f32_e32 v104, v112, v104
	v_max_f32_e32 v120, v113, v115
	v_min_f32_e32 v115, v113, v115
	v_max_f32_e32 v121, v98, v109
	v_min_f32_e32 v109, v98, v109
	v_max_f32_e32 v122, v116, v117
	v_min_f32_e32 v117, v116, v117
	v_max_f32_e32 v123, v101, v102
	v_min_f32_e32 v102, v101, v102
	v_max_f32_e32 v124, v118, v119
	v_min_f32_e32 v119, v118, v119
	v_max_f32_e32 v125, v96, v104
	v_min_f32_e32 v104, v96, v104
	v_max_f32_e32 v126, v121, v115
	v_min_f32_e32 v115, v121, v115
	v_max_f32_e32 v127, v114, v109
	v_min_f32_e32 v109, v114, v109
	v_max_f32_e32 v0, v124, v111
	v_min_f32_e32 v111, v124, v111
	v_max_f32_e32 v1, v125, v119
	v_min_f32_e32 v119, v125, v119
	v_max_f32_e32 v2, v127, v122
	v_min_f32_e32 v122, v127, v122
	v_max_f32_e32 v3, v109, v117
	v_min_f32_e32 v117, v109, v117
	v_max_f32_e32 v4, v123, v0
	v_min_f32_e32 v0, v123, v0
	v_max_f32_e32 v5, v102, v111
	v_min_f32_e32 v111, v102, v111
	v_max_f32_e32 v7, v2, v115
	v_min_f32_e32 v115, v2, v115
	v_max_f32_e32 v9, v122, v3
	v_min_f32_e32 v3, v122, v3
	v_max_f32_e32 v144, v4, v117
	v_min_f32_e32 v117, v4, v117
	v_max_f32_e32 v145, v0, v5
	v_min_f32_e32 v5, v0, v5
	v_max_f32_e32 v146, v1, v111
	v_min_f32_e32 v111, v1, v111
	v_max_f32_e32 v147, v3, v144
	v_min_f32_e32 v144, v3, v144
	v_max_f32_e32 v6, v117, v145
	v_min_f32_e32 v145, v117, v145
	v_max_f32_e32 v8, v16, v29
	v_min_f32_e32 v29, v16, v29
	v_max_f32_e32 v10, v17, v28
	v_min_f32_e32 v28, v17, v28
	v_max_f32_e32 v11, v18, v31
	v_min_f32_e32 v31, v18, v31
	v_max_f32_e32 v249, v19, v30
	v_min_f32_e32 v30, v19, v30
	v_max_f32_e32 v251, v20, v24
	v_min_f32_e32 v24, v20, v24
	v_max_f32_e32 v148, v21, v22
	v_min_f32_e32 v22, v21, v22
	v_max_f32_e32 v253, v23, v27
	v_min_f32_e32 v27, v23, v27
	v_max_f32_e32 v150, v25, v26
	v_min_f32_e32 v26, v25, v26
	v_max_f32_e32 v255, v8, v148
	v_min_f32_e32 v148, v8, v148
	v_max_f32_e32 v12, v10, v253
	v_min_f32_e32 v253, v10, v253
	v_max_f32_e32 v14, v11, v150
	v_min_f32_e32 v150, v11, v150
	v_max_f32_e32 v97, v249, v251
	v_min_f32_e32 v251, v249, v251
	v_max_f32_e32 v250, v22, v29
	v_min_f32_e32 v29, v22, v29
	v_max_f32_e32 v99, v24, v30
	v_min_f32_e32 v30, v24, v30
	v_max_f32_e32 v149, v26, v31
	v_min_f32_e32 v31, v26, v31
	v_max_f32_e32 v100, v27, v28
	v_min_f32_e32 v28, v27, v28
	v_max_f32_e32 v254, v255, v12
	v_min_f32_e32 v12, v255, v12
	v_max_f32_e32 v103, v14, v97
	v_min_f32_e32 v97, v14, v97
	v_max_f32_e32 v13, v251, v148
	v_min_f32_e32 v148, v251, v148
	v_max_f32_e32 v106, v250, v99
	v_min_f32_e32 v99, v250, v99
	v_max_f32_e32 v252, v253, v150
	v_min_f32_e32 v150, v253, v150
	v_max_f32_e32 v107, v149, v100
	v_min_f32_e32 v100, v149, v100
	v_max_f32_e32 v108, v28, v29
	v_min_f32_e32 v29, v28, v29
	v_max_f32_e32 v110, v30, v31
	v_min_f32_e32 v31, v30, v31
	v_max_f32_e32 v151, v254, v103
	v_min_f32_e32 v103, v254, v103
	v_max_f32_e32 v112, v12, v97
	v_min_f32_e32 v97, v12, v97
	v_max_f32_e32 v113, v13, v107
	v_min_f32_e32 v107, v13, v107
	v_max_f32_e32 v98, v148, v100
	v_min_f32_e32 v100, v148, v100
	v_max_f32_e32 v116, v106, v252
	v_min_f32_e32 v252, v106, v252
	v_max_f32_e32 v101, v99, v150
	v_min_f32_e32 v150, v99, v150
	v_max_f32_e32 v118, v108, v110
	v_min_f32_e32 v110, v108, v110
	v_max_f32_e32 v96, v29, v31
	v_min_f32_e32 v31, v29, v31
	v_max_f32_e32 v121, v112, v103
	v_min_f32_e32 v103, v112, v103
	v_max_f32_e32 v114, v97, v118
	v_min_f32_e32 v118, v97, v118
	v_max_f32_e32 v124, v113, v116
	v_min_f32_e32 v116, v113, v116
	v_max_f32_e32 v125, v98, v252
	v_min_f32_e32 v252, v98, v252
	v_max_f32_e32 v127, v101, v107
	v_min_f32_e32 v107, v101, v107
	v_max_f32_e32 v109, v150, v100
	v_min_f32_e32 v100, v150, v100
	v_max_f32_e32 v123, v96, v110
	v_min_f32_e32 v110, v96, v110
	v_max_f32_e32 v102, v121, v124
	v_min_f32_e32 v124, v121, v124
	v_max_f32_e32 v2, v103, v116
	v_min_f32_e32 v116, v103, v116
	v_max_f32_e32 v122, v125, v127
	v_min_f32_e32 v127, v125, v127
	v_max_f32_e32 v4, v252, v107
	v_min_f32_e32 v107, v252, v107
	v_max_f32_e32 v0, v109, v123
	v_min_f32_e32 v123, v109, v123
	v_max_f32_e32 v1, v100, v110
	v_min_f32_e32 v110, v100, v110
	v_max_f32_e32 v3, v2, v124
	v_min_f32_e32 v124, v2, v124
	v_max_f32_e32 v117, v114, v116
	v_min_f32_e32 v116, v114, v116
	v_max_f32_e32 v16, v0, v118
	v_min_f32_e32 v118, v0, v118
	v_max_f32_e32 v17, v1, v123
	v_min_f32_e32 v123, v1, v123
	v_max_f32_e32 v18, v117, v122
	v_min_f32_e32 v122, v117, v122
	v_max_f32_e32 v19, v116, v127
	v_min_f32_e32 v127, v116, v127
	v_max_f32_e32 v20, v4, v16
	v_min_f32_e32 v16, v4, v16
	v_max_f32_e32 v21, v107, v118
	v_min_f32_e32 v118, v107, v118
	v_max_f32_e32 v23, v18, v124
	v_min_f32_e32 v124, v18, v124
	v_max_f32_e32 v25, v122, v19
	v_min_f32_e32 v19, v122, v19
	v_max_f32_e32 v8, v20, v127
	v_min_f32_e32 v127, v20, v127
	v_max_f32_e32 v10, v16, v21
	v_min_f32_e32 v21, v16, v21
	v_max_f32_e32 v11, v17, v118
	v_min_f32_e32 v118, v17, v118
	v_max_f32_e32 v249, v19, v8
	v_min_f32_e32 v8, v19, v8
	v_max_f32_e32 v22, v127, v10
	v_min_f32_e32 v10, v127, v10
	s_waitcnt vmcnt(24)
	v_pk_mul_f32 v[160:161], v[160:161], v[176:177]
	v_pk_mul_f32 v[162:163], v[162:163], v[178:179]
	v_pk_mul_f32 v[164:165], v[164:165], v[180:181]
	v_pk_mul_f32 v[166:167], v[166:167], v[182:183]
	v_pk_mul_f32 v[168:169], v[168:169], v[184:185]
	v_pk_mul_f32 v[170:171], v[170:171], v[186:187]
	v_pk_mul_f32 v[172:173], v[172:173], v[188:189]
	v_pk_mul_f32 v[174:175], v[174:175], v[190:191]
	v_max3_f32 v192, |v160|, |v161|, |v162|
	v_max3_f32 v192, |v163|, |v164|, v192
	v_max3_f32 v192, |v165|, |v166|, v192
	v_max3_f32 v192, |v167|, |v168|, v192
	v_max3_f32 v192, |v169|, |v170|, v192
	v_max3_f32 v192, |v171|, |v172|, v192
	v_max3_f32 v192, |v173|, |v174|, v192
	v_max_f32_e64 v192, |v175|, v192
	s_nop 1
	v_mov_b32_dpp v193, v192 quad_perm:[1,0,3,2] row_mask:0xf bank_mask:0xf bound_ctrl:1
	v_max_f32_e32 v192, v192, v193
	s_nop 1
	v_mov_b32_dpp v193, v192 quad_perm:[2,3,0,1] row_mask:0xf bank_mask:0xf bound_ctrl:1
	v_max_f32_e32 v192, v192, v193
	s_nop 1
	v_mov_b32_dpp v193, v192 row_half_mirror row_mask:0xf bank_mask:0xf bound_ctrl:1
	v_max_f32_e32 v192, v192, v193
	s_nop 1
	v_mov_b32_dpp v193, v192 row_mirror row_mask:0xf bank_mask:0xf bound_ctrl:1
	v_max_f32_e32 v192, v192, v193
	v_mov_b32_e32 v193, v192
	s_nop 1
	v_permlane16_swap_b32_e32 v192, v193
	s_nop 1
	v_max_f32_e32 v192, v192, v193
	v_mov_b32_e32 v193, v192
	s_nop 1
	v_permlane32_swap_b32_e32 v192, v193
	s_nop 1
	v_max_f32_e32 v192, v192, v193
	v_max_f32_e32 v192, 0xda24260, v192
	v_mul_f32_e32 v194, 0x3e2aaaab, v192
	global_store_dword v214, v194, s[12:13]
	v_div_scale_f32 v195, s[26:27], v194, v194, 1.0
	v_rcp_f32_e32 v196, v195
	v_div_scale_f32 v204, vcc, 1.0, v194, 1.0
	v_fma_f32 v205, -v195, v196, 1.0
	v_fmac_f32_e32 v196, v205, v196
	v_mul_f32_e32 v205, v204, v196
	v_fma_f32 v206, -v195, v205, v204
	v_fmac_f32_e32 v205, v206, v196
	v_fma_f32 v195, -v195, v205, v204
	s_nop 0
	v_div_fmas_f32 v195, v195, v196, v205
	v_div_fixup_f32 v207, v195, v194, 1.0
	v_mul_f32_e32 v160, v207, v160
	v_mul_f32_e32 v161, v207, v161
	v_mul_f32_e32 v162, v207, v162
	v_mul_f32_e32 v163, v207, v163
	v_mul_f32_e32 v164, v207, v164
	v_mul_f32_e32 v165, v207, v165
	v_mul_f32_e32 v166, v207, v166
	v_mul_f32_e32 v167, v207, v167
	v_mul_f32_e32 v168, v207, v168
	v_mul_f32_e32 v169, v207, v169
	v_mul_f32_e32 v170, v207, v170
	v_mul_f32_e32 v171, v207, v171
	v_mul_f32_e32 v172, v207, v172
	v_mul_f32_e32 v173, v207, v173
	v_mul_f32_e32 v174, v207, v174
	v_mul_f32_e32 v175, v207, v175
	v_mov_b32_e32 v208, 0
	v_mov_b32_e32 v209, 0
	v_mov_b32_e32 v210, 0
	v_mov_b32_e32 v193, 0
	v_cvt_scalef32_pk_fp4_f32 v208, v160, v161, 1.0
	v_cvt_scalef32_pk_fp4_f32 v209, v164, v165, 1.0
	v_cvt_scalef32_pk_fp4_f32 v210, v168, v169, 1.0
	v_cvt_scalef32_pk_fp4_f32 v193, v172, v173, 1.0
	v_cvt_scalef32_pk_fp4_f32 v208, v162, v163, 1.0 op_sel:[0,0,1,0]
	v_cvt_scalef32_pk_fp4_f32 v209, v166, v167, 1.0 op_sel:[0,0,1,0]
	v_cvt_scalef32_pk_fp4_f32 v210, v170, v171, 1.0 op_sel:[0,0,1,0]
	v_cvt_scalef32_pk_fp4_f32 v193, v174, v175, 1.0 op_sel:[0,0,1,0]
	global_store_short v213, v208, s[10:11] nt
	s_add_u32 s14, s10, 0x200000
	s_addc_u32 s15, s11, 0
	global_store_short v213, v209, s[14:15] nt
	s_add_u32 s14, s10, 0x400000
	s_addc_u32 s15, s11, 0
	global_store_short v213, v210, s[14:15] nt
	s_add_u32 s14, s10, 0x600000
	s_addc_u32 s15, s11, 0
	global_store_short v213, v193, s[14:15] nt
	s_add_u32 s10, s10, 0x20000
	s_addc_u32 s11, s11, 0
	s_add_u32 s12, s12, 0x2000
	s_addc_u32 s13, s13, 0
	global_load_dwordx4 v[160:163], v212, s[8:9] offset:0 nt
	global_load_dwordx4 v[164:167], v212, s[8:9] offset:1024 nt
	global_load_dwordx4 v[168:171], v212, s[8:9] offset:2048 nt
	global_load_dwordx4 v[172:175], v212, s[8:9] offset:3072 nt
	s_add_u32 s8, s8, 0x800000
	s_addc_u32 s9, s9, 0
	v_max_f32_e32 v24, v32, v45
	v_min_f32_e32 v45, v32, v45
	v_max_f32_e32 v26, v33, v44
	v_min_f32_e32 v44, v33, v44
	v_max_f32_e32 v27, v34, v47
	v_min_f32_e32 v47, v34, v47
	v_max_f32_e32 v255, v35, v46
	v_min_f32_e32 v46, v35, v46
	v_max_f32_e32 v14, v36, v40
	v_min_f32_e32 v40, v36, v40
	v_max_f32_e32 v251, v37, v38
	v_min_f32_e32 v38, v37, v38
	v_max_f32_e32 v250, v39, v43
	v_min_f32_e32 v43, v39, v43
	v_max_f32_e32 v253, v41, v42
	v_min_f32_e32 v42, v41, v42
	v_max_f32_e32 v149, v24, v251
	v_min_f32_e32 v251, v24, v251
	v_max_f32_e32 v28, v26, v250
	v_min_f32_e32 v250, v26, v250
	v_max_f32_e32 v30, v27, v253
	v_min_f32_e32 v253, v27, v253
	v_max_f32_e32 v254, v255, v14
	v_min_f32_e32 v14, v255, v14
	v_max_f32_e32 v12, v38, v45
	v_min_f32_e32 v45, v38, v45
	v_max_f32_e32 v13, v40, v46
	v_min_f32_e32 v46, v40, v46
	v_max_f32_e32 v148, v42, v47
	v_min_f32_e32 v47, v42, v47
	v_max_f32_e32 v106, v43, v44
	v_min_f32_e32 v44, v43, v44
	v_max_f32_e32 v99, v149, v28
	v_min_f32_e32 v28, v149, v28
	v_max_f32_e32 v108, v30, v254
	v_min_f32_e32 v254, v30, v254
	v_max_f32_e32 v29, v14, v251
	v_min_f32_e32 v251, v14, v251
	v_max_f32_e32 v112, v12, v13
	v_min_f32_e32 v13, v12, v13
	v_max_f32_e32 v97, v250, v253
	v_min_f32_e32 v253, v250, v253
	v_max_f32_e32 v113, v148, v106
	v_min_f32_e32 v106, v148, v106
	v_max_f32_e32 v98, v44, v45
	v_min_f32_e32 v45, v44, v45
	v_max_f32_e32 v101, v46, v47
	v_min_f32_e32 v47, v46, v47
	v_max_f32_e32 v150, v99, v108
	v_min_f32_e32 v108, v99, v108
	v_max_f32_e32 v96, v28, v254
	v_min_f32_e32 v254, v28, v254
	v_max_f32_e32 v121, v29, v113
	v_min_f32_e32 v113, v29, v113
	v_max_f32_e32 v103, v251, v106
	v_min_f32_e32 v106, v251, v106
	v_max_f32_e32 v125, v112, v97
	v_min_f32_e32 v97, v112, v97
	v_max_f32_e32 v252, v13, v253
	v_min_f32_e32 v253, v13, v253
	v_max_f32_e32 v109, v98, v101
	v_min_f32_e32 v101, v98, v101
	v_max_f32_e32 v100, v45, v47
	v_min_f32_e32 v47, v45, v47
	v_max_f32_e32 v2, v96, v108
	v_min_f32_e32 v108, v96, v108
	v_max_f32_e32 v114, v254, v109
	v_min_f32_e32 v109, v254, v109
	v_max_f32_e32 v0, v121, v125
	v_min_f32_e32 v125, v121, v125
	v_max_f32_e32 v1, v103, v97
	v_min_f32_e32 v97, v103, v97
	v_max_f32_e32 v117, v252, v113
	v_min_f32_e32 v113, v252, v113
	v_max_f32_e32 v116, v253, v106
	v_min_f32_e32 v106, v253, v106
	v_max_f32_e32 v4, v100, v101
	v_min_f32_e32 v101, v100, v101
	v_max_f32_e32 v107, v2, v0
	v_min_f32_e32 v0, v2, v0
	v_max_f32_e32 v18, v108, v125
	v_min_f32_e32 v125, v108, v125
	v_max_f32_e32 v122, v1, v117
	v_min_f32_e32 v117, v1, v117
	v_max_f32_e32 v20, v97, v113
	v_min_f32_e32 v113, v97, v113
	v_max_f32_e32 v16, v116, v4
	v_min_f32_e32 v4, v116, v4
	v_max_f32_e32 v17, v106, v101
	v_min_f32_e32 v101, v106, v101
	v_max_f32_e32 v19, v18, v0
	v_min_f32_e32 v0, v18, v0
	v_max_f32_e32 v127, v114, v125
	v_min_f32_e32 v125, v114, v125
	v_max_f32_e32 v32, v16, v109
	v_min_f32_e32 v109, v16, v109
	v_max_f32_e32 v33, v17, v4
	v_min_f32_e32 v4, v17, v4
	v_max_f32_e32 v34, v127, v122
	v_min_f32_e32 v122, v127, v122
	v_max_f32_e32 v35, v125, v117
	v_min_f32_e32 v117, v125, v117
	v_max_f32_e32 v36, v20, v32
	v_min_f32_e32 v32, v20, v32
	v_max_f32_e32 v37, v113, v109
	v_min_f32_e32 v109, v113, v109
	v_max_f32_e32 v39, v34, v0
	v_min_f32_e32 v0, v34, v0
	v_max_f32_e32 v41, v122, v35
	v_min_f32_e32 v35, v122, v35
	v_max_f32_e32 v24, v36, v117
	v_min_f32_e32 v117, v36, v117
	v_max_f32_e32 v26, v32, v37
	v_min_f32_e32 v37, v32, v37
	v_max_f32_e32 v27, v33, v109
	v_min_f32_e32 v109, v33, v109
	v_max_f32_e32 v255, v35, v24
	v_min_f32_e32 v24, v35, v24
	v_max_f32_e32 v38, v117, v26
	v_min_f32_e32 v26, v117, v26
	v_max_f32_e32 v40, v48, v61
	v_min_f32_e32 v61, v48, v61
	v_max_f32_e32 v42, v49, v60
	v_min_f32_e32 v60, v49, v60
	v_max_f32_e32 v43, v50, v63
	v_min_f32_e32 v63, v50, v63
	v_max_f32_e32 v149, v51, v62
	v_min_f32_e32 v62, v51, v62
	v_max_f32_e32 v30, v52, v56
	v_min_f32_e32 v56, v52, v56
	v_max_f32_e32 v14, v53, v54
	v_min_f32_e32 v54, v53, v54
	v_max_f32_e32 v12, v55, v59
	v_min_f32_e32 v59, v55, v59
	v_max_f32_e32 v250, v57, v58
	v_min_f32_e32 v58, v57, v58
	v_max_f32_e32 v148, v40, v14
	v_min_f32_e32 v14, v40, v14
	v_max_f32_e32 v44, v42, v12
	v_min_f32_e32 v12, v42, v12
	v_max_f32_e32 v46, v43, v250
	v_min_f32_e32 v250, v43, v250
	v_max_f32_e32 v99, v149, v30
	v_min_f32_e32 v30, v149, v30
	v_max_f32_e32 v28, v54, v61
	v_min_f32_e32 v61, v54, v61
	v_max_f32_e32 v29, v56, v62
	v_min_f32_e32 v62, v56, v62
	v_max_f32_e32 v251, v58, v63
	v_min_f32_e32 v63, v58, v63
	v_max_f32_e32 v112, v59, v60
	v_min_f32_e32 v60, v59, v60
	v_max_f32_e32 v13, v148, v44
	v_min_f32_e32 v44, v148, v44
	v_max_f32_e32 v98, v46, v99
	v_min_f32_e32 v99, v46, v99
	v_max_f32_e32 v45, v30, v14
	v_min_f32_e32 v14, v30, v14
	v_max_f32_e32 v96, v28, v29
	v_min_f32_e32 v29, v28, v29
	v_max_f32_e32 v254, v12, v250
	v_min_f32_e32 v250, v12, v250
	v_max_f32_e32 v121, v251, v112
	v_min_f32_e32 v112, v251, v112
	v_max_f32_e32 v103, v60, v61
	v_min_f32_e32 v61, v60, v61
	v_max_f32_e32 v252, v62, v63
	v_min_f32_e32 v63, v62, v63
	v_max_f32_e32 v253, v13, v98
	v_min_f32_e32 v98, v13, v98
	v_max_f32_e32 v100, v44, v99
	v_min_f32_e32 v99, v44, v99
	v_max_f32_e32 v2, v45, v121
	v_min_f32_e32 v121, v45, v121
	v_max_f32_e32 v108, v14, v112
	v_min_f32_e32 v112, v14, v112
	v_max_f32_e32 v1, v96, v254
	v_min_f32_e32 v254, v96, v254
	v_max_f32_e32 v97, v29, v250
	v_min_f32_e32 v250, v29, v250
	v_max_f32_e32 v116, v103, v252
	v_min_f32_e32 v252, v103, v252
	v_max_f32_e32 v106, v61, v63
	v_min_f32_e32 v63, v61, v63
	v_max_f32_e32 v18, v100, v98
	v_min_f32_e32 v98, v100, v98
	v_max_f32_e32 v114, v99, v116
	v_min_f32_e32 v116, v99, v116
	v_max_f32_e32 v16, v2, v1
	v_min_f32_e32 v1, v2, v1
	v_max_f32_e32 v17, v108, v254
	v_min_f32_e32 v254, v108, v254
	v_max_f32_e32 v127, v97, v121
	v_min_f32_e32 v121, v97, v121
	v_max_f32_e32 v125, v250, v112
	v_min_f32_e32 v112, v250, v112
	v_max_f32_e32 v20, v106, v252
	v_min_f32_e32 v252, v106, v252
	v_max_f32_e32 v113, v18, v16
	v_min_f32_e32 v16, v18, v16
	v_max_f32_e32 v34, v98, v1
	v_min_f32_e32 v1, v98, v1
	v_max_f32_e32 v122, v17, v127
	v_min_f32_e32 v127, v17, v127
	v_max_f32_e32 v36, v254, v121
	v_min_f32_e32 v121, v254, v121
	v_max_f32_e32 v32, v125, v20
	v_min_f32_e32 v20, v125, v20
	v_max_f32_e32 v33, v112, v252
	v_min_f32_e32 v252, v112, v252
	v_max_f32_e32 v35, v34, v16
	v_min_f32_e32 v16, v34, v16
	v_max_f32_e32 v117, v114, v1
	v_min_f32_e32 v1, v114, v1
	v_max_f32_e32 v48, v32, v116
	v_min_f32_e32 v116, v32, v116
	v_max_f32_e32 v49, v33, v20
	v_min_f32_e32 v20, v33, v20
	v_max_f32_e32 v50, v117, v122
	v_min_f32_e32 v122, v117, v122
	v_max_f32_e32 v51, v1, v127
	v_min_f32_e32 v127, v1, v127
	v_max_f32_e32 v52, v36, v48
	v_min_f32_e32 v48, v36, v48
	v_max_f32_e32 v53, v121, v116
	v_min_f32_e32 v116, v121, v116
	v_max_f32_e32 v55, v50, v16
	v_min_f32_e32 v16, v50, v16
	v_max_f32_e32 v57, v122, v51
	v_min_f32_e32 v51, v122, v51
	v_max_f32_e32 v40, v52, v127
	v_min_f32_e32 v127, v52, v127
	v_max_f32_e32 v42, v48, v53
	v_min_f32_e32 v53, v48, v53
	v_max_f32_e32 v43, v49, v116
	v_min_f32_e32 v116, v49, v116
	v_max_f32_e32 v149, v51, v40
	v_min_f32_e32 v40, v51, v40
	v_max_f32_e32 v54, v127, v42
	v_min_f32_e32 v42, v127, v42
	s_waitcnt vmcnt(0)
	v_pk_mul_f32 v[160:161], v[160:161], v[176:177]
	v_pk_mul_f32 v[162:163], v[162:163], v[178:179]
	v_pk_mul_f32 v[164:165], v[164:165], v[180:181]
	v_pk_mul_f32 v[166:167], v[166:167], v[182:183]
	v_pk_mul_f32 v[168:169], v[168:169], v[184:185]
	v_pk_mul_f32 v[170:171], v[170:171], v[186:187]
	v_pk_mul_f32 v[172:173], v[172:173], v[188:189]
	v_pk_mul_f32 v[174:175], v[174:175], v[190:191]
	v_max3_f32 v192, |v160|, |v161|, |v162|
	v_max3_f32 v192, |v163|, |v164|, v192
	v_max3_f32 v192, |v165|, |v166|, v192
	v_max3_f32 v192, |v167|, |v168|, v192
	v_max3_f32 v192, |v169|, |v170|, v192
	v_max3_f32 v192, |v171|, |v172|, v192
	v_max3_f32 v192, |v173|, |v174|, v192
	v_max_f32_e64 v192, |v175|, v192
	s_nop 1
	v_mov_b32_dpp v193, v192 quad_perm:[1,0,3,2] row_mask:0xf bank_mask:0xf bound_ctrl:1
	v_max_f32_e32 v192, v192, v193
	s_nop 1
	v_mov_b32_dpp v193, v192 quad_perm:[2,3,0,1] row_mask:0xf bank_mask:0xf bound_ctrl:1
	v_max_f32_e32 v192, v192, v193
	s_nop 1
	v_mov_b32_dpp v193, v192 row_half_mirror row_mask:0xf bank_mask:0xf bound_ctrl:1
	v_max_f32_e32 v192, v192, v193
	s_nop 1
	v_mov_b32_dpp v193, v192 row_mirror row_mask:0xf bank_mask:0xf bound_ctrl:1
	v_max_f32_e32 v192, v192, v193
	v_mov_b32_e32 v193, v192
	s_nop 1
	v_permlane16_swap_b32_e32 v192, v193
	s_nop 1
	v_max_f32_e32 v192, v192, v193
	v_mov_b32_e32 v193, v192
	s_nop 1
	v_permlane32_swap_b32_e32 v192, v193
	s_nop 1
	v_max_f32_e32 v192, v192, v193
	v_max_f32_e32 v192, 0xda24260, v192
	v_mul_f32_e32 v194, 0x3e2aaaab, v192
	global_store_dword v214, v194, s[12:13]
	v_div_scale_f32 v195, s[26:27], v194, v194, 1.0
	v_rcp_f32_e32 v196, v195
	v_div_scale_f32 v204, vcc, 1.0, v194, 1.0
	v_fma_f32 v205, -v195, v196, 1.0
	v_fmac_f32_e32 v196, v205, v196
	v_mul_f32_e32 v205, v204, v196
	v_fma_f32 v206, -v195, v205, v204
	v_fmac_f32_e32 v205, v206, v196
	v_fma_f32 v195, -v195, v205, v204
	s_nop 0
	v_div_fmas_f32 v195, v195, v196, v205
	v_div_fixup_f32 v207, v195, v194, 1.0
	v_mul_f32_e32 v160, v207, v160
	v_mul_f32_e32 v161, v207, v161
	v_mul_f32_e32 v162, v207, v162
	v_mul_f32_e32 v163, v207, v163
	v_mul_f32_e32 v164, v207, v164
	v_mul_f32_e32 v165, v207, v165
	v_mul_f32_e32 v166, v207, v166
	v_mul_f32_e32 v167, v207, v167
	v_mul_f32_e32 v168, v207, v168
	v_mul_f32_e32 v169, v207, v169
	v_mul_f32_e32 v170, v207, v170
	v_mul_f32_e32 v171, v207, v171
	v_mul_f32_e32 v172, v207, v172
	v_mul_f32_e32 v173, v207, v173
	v_mul_f32_e32 v174, v207, v174
	v_mul_f32_e32 v175, v207, v175
	v_mov_b32_e32 v208, 0
	v_mov_b32_e32 v209, 0
	v_mov_b32_e32 v210, 0
	v_mov_b32_e32 v193, 0
	v_cvt_scalef32_pk_fp4_f32 v208, v160, v161, 1.0
	v_cvt_scalef32_pk_fp4_f32 v209, v164, v165, 1.0
	v_cvt_scalef32_pk_fp4_f32 v210, v168, v169, 1.0
	v_cvt_scalef32_pk_fp4_f32 v193, v172, v173, 1.0
	v_cvt_scalef32_pk_fp4_f32 v208, v162, v163, 1.0 op_sel:[0,0,1,0]
	v_cvt_scalef32_pk_fp4_f32 v209, v166, v167, 1.0 op_sel:[0,0,1,0]
	v_cvt_scalef32_pk_fp4_f32 v210, v170, v171, 1.0 op_sel:[0,0,1,0]
	v_cvt_scalef32_pk_fp4_f32 v193, v174, v175, 1.0 op_sel:[0,0,1,0]
	global_store_short v213, v208, s[10:11] nt
	s_add_u32 s14, s10, 0x200000
	s_addc_u32 s15, s11, 0
	global_store_short v213, v209, s[14:15] nt
	s_add_u32 s14, s10, 0x400000
	s_addc_u32 s15, s11, 0
	global_store_short v213, v210, s[14:15] nt
	s_add_u32 s14, s10, 0x600000
	s_addc_u32 s15, s11, 0
	global_store_short v213, v193, s[14:15] nt
	s_add_u32 s10, s10, 0x20000
	s_addc_u32 s11, s11, 0
	s_add_u32 s12, s12, 0x2000
	s_addc_u32 s13, s13, 0
	global_load_dwordx4 v[160:163], v212, s[8:9] offset:0 nt
	global_load_dwordx4 v[164:167], v212, s[8:9] offset:1024 nt
	global_load_dwordx4 v[168:171], v212, s[8:9] offset:2048 nt
	global_load_dwordx4 v[172:175], v212, s[8:9] offset:3072 nt
	s_add_u32 s8, s8, 0x800000
	s_addc_u32 s9, s9, 0
	v_max_f32_e32 v105, v105, v31
	v_max_f32_e32 v120, v120, v110
	v_max_f32_e32 v126, v126, v123
	v_max_f32_e32 v7, v7, v118
	v_max_f32_e32 v115, v115, v11
	v_max_f32_e32 v9, v9, v21
	v_max_f32_e32 v147, v147, v10
	v_max_f32_e32 v144, v144, v22
	v_max_f32_e32 v6, v6, v8
	v_max_f32_e32 v145, v145, v249
	v_max_f32_e32 v5, v5, v25
	v_max_f32_e32 v146, v146, v124
	v_max_f32_e32 v111, v111, v23
	v_max_f32_e32 v119, v119, v3
	v_max_f32_e32 v104, v104, v102
	v_max_f32_e32 v15, v15, v151
	v_max_f32_e32 v56, v105, v6
	v_min_f32_e32 v6, v105, v6
	v_max_f32_e32 v58, v120, v145
	v_min_f32_e32 v145, v120, v145
	v_max_f32_e32 v59, v126, v5
	v_min_f32_e32 v5, v126, v5
	v_max_f32_e32 v148, v7, v146
	v_min_f32_e32 v146, v7, v146
	v_max_f32_e32 v46, v115, v111
	v_min_f32_e32 v111, v115, v111
	v_max_f32_e32 v30, v9, v119
	v_min_f32_e32 v119, v9, v119
	v_max_f32_e32 v28, v147, v104
	v_min_f32_e32 v104, v147, v104
	v_max_f32_e32 v12, v144, v15
	v_min_f32_e32 v15, v144, v15
	v_max_f32_e32 v251, v56, v46
	v_min_f32_e32 v46, v56, v46
	v_max_f32_e32 v60, v58, v30
	v_min_f32_e32 v30, v58, v30
	v_max_f32_e32 v62, v59, v28
	v_min_f32_e32 v28, v59, v28
	v_max_f32_e32 v13, v148, v12
	v_min_f32_e32 v12, v148, v12
	v_max_f32_e32 v44, v6, v111
	v_min_f32_e32 v111, v6, v111
	v_max_f32_e32 v45, v145, v119
	v_min_f32_e32 v119, v145, v119
	v_max_f32_e32 v14, v5, v104
	v_min_f32_e32 v104, v5, v104
	v_max_f32_e32 v96, v146, v15
	v_min_f32_e32 v15, v146, v15
	v_max_f32_e32 v29, v251, v62
	v_min_f32_e32 v62, v251, v62
	v_max_f32_e32 v103, v60, v13
	v_min_f32_e32 v13, v60, v13
	v_max_f32_e32 v61, v46, v28
	v_min_f32_e32 v28, v46, v28
	v_max_f32_e32 v100, v30, v12
	v_min_f32_e32 v12, v30, v12
	v_max_f32_e32 v99, v44, v14
	v_min_f32_e32 v14, v44, v14
	v_max_f32_e32 v2, v45, v96
	v_min_f32_e32 v96, v45, v96
	v_max_f32_e32 v108, v111, v104
	v_min_f32_e32 v104, v111, v104
	v_max_f32_e32 v97, v119, v15
	v_min_f32_e32 v15, v119, v15
	v_max_f32_e32 v250, v29, v103
	v_min_f32_e32 v103, v29, v103
	v_max_f32_e32 v106, v62, v13
	v_min_f32_e32 v13, v62, v13
	v_max_f32_e32 v18, v61, v100
	v_min_f32_e32 v100, v61, v100
	v_max_f32_e32 v98, v28, v12
	v_min_f32_e32 v12, v28, v12
	v_max_f32_e32 v17, v99, v2
	v_min_f32_e32 v2, v99, v2
	v_max_f32_e32 v254, v14, v96
	v_min_f32_e32 v96, v14, v96
	v_max_f32_e32 v125, v108, v97
	v_min_f32_e32 v97, v108, v97
	v_max_f32_e32 v112, v104, v15
	v_min_f32_e32 v15, v104, v15
	v_max_f32_e32 v150, v150, v63
	v_max_f32_e32 v107, v107, v252
	v_max_f32_e32 v19, v19, v20
	v_max_f32_e32 v39, v39, v116
	v_max_f32_e32 v0, v0, v43
	v_max_f32_e32 v41, v41, v53
	v_max_f32_e32 v255, v255, v42
	v_max_f32_e32 v24, v24, v54
	v_max_f32_e32 v38, v38, v40
	v_max_f32_e32 v26, v26, v149
	v_max_f32_e32 v37, v37, v57
	v_max_f32_e32 v27, v27, v16
	v_max_f32_e32 v109, v109, v55
	v_max_f32_e32 v4, v4, v35
	v_max_f32_e32 v101, v101, v113
	v_max_f32_e32 v47, v47, v253
	v_max_f32_e32 v34, v150, v38
	v_min_f32_e32 v38, v150, v38
	v_max_f32_e32 v114, v107, v26
	v_min_f32_e32 v26, v107, v26
	v_max_f32_e32 v32, v19, v37
	v_min_f32_e32 v37, v19, v37
	v_max_f32_e32 v33, v39, v27
	v_min_f32_e32 v27, v39, v27
	v_max_f32_e32 v117, v0, v109
	v_min_f32_e32 v109, v0, v109
	v_max_f32_e32 v1, v41, v4
	v_min_f32_e32 v4, v41, v4
	v_max_f32_e32 v36, v255, v101
	v_min_f32_e32 v101, v255, v101
	v_max_f32_e32 v121, v24, v47
	v_min_f32_e32 v47, v24, v47
	v_max_f32_e32 v50, v34, v117
	v_min_f32_e32 v117, v34, v117
	v_max_f32_e32 v122, v114, v1
	v_min_f32_e32 v1, v114, v1
	v_max_f32_e32 v52, v32, v36
	v_min_f32_e32 v36, v32, v36
	v_max_f32_e32 v48, v33, v121
	v_min_f32_e32 v121, v33, v121
	v_max_f32_e32 v49, v38, v109
	v_min_f32_e32 v109, v38, v109
	v_max_f32_e32 v51, v26, v4
	v_min_f32_e32 v4, v26, v4
	v_max_f32_e32 v127, v37, v101
	v_min_f32_e32 v101, v37, v101
	v_max_f32_e32 v151, v27, v47
	v_min_f32_e32 v47, v27, v47
	v_max_f32_e32 v102, v50, v52
	v_min_f32_e32 v52, v50, v52
	v_max_f32_e32 v3, v122, v48
	v_min_f32_e32 v48, v122, v48
	v_max_f32_e32 v23, v117, v36
	v_min_f32_e32 v36, v117, v36
	v_max_f32_e32 v124, v1, v121
	v_min_f32_e32 v121, v1, v121
	v_max_f32_e32 v25, v49, v127
	v_min_f32_e32 v127, v49, v127
	v_max_f32_e32 v249, v51, v151
	v_min_f32_e32 v151, v51, v151
	v_max_f32_e32 v8, v109, v101
	v_min_f32_e32 v101, v109, v101
	v_max_f32_e32 v22, v4, v47
	v_min_f32_e32 v47, v4, v47
	v_max_f32_e32 v10, v102, v3
	v_min_f32_e32 v3, v102, v3
	v_max_f32_e32 v21, v52, v48
	v_min_f32_e32 v48, v52, v48
	v_max_f32_e32 v11, v23, v124
	v_min_f32_e32 v124, v23, v124
	v_max_f32_e32 v118, v36, v121
	v_min_f32_e32 v121, v36, v121
	v_max_f32_e32 v123, v25, v249
	v_min_f32_e32 v249, v25, v249
	v_max_f32_e32 v110, v127, v151
	v_min_f32_e32 v151, v127, v151
	v_max_f32_e32 v31, v8, v22
	v_min_f32_e32 v22, v8, v22
	v_max_f32_e32 v105, v101, v47
	v_min_f32_e32 v47, v101, v47
	v_max_f32_e32 v250, v250, v47
	v_max_f32_e32 v103, v103, v105
	v_max_f32_e32 v106, v106, v22
	v_max_f32_e32 v13, v13, v31
	v_max_f32_e32 v18, v18, v151
	v_max_f32_e32 v100, v100, v110
	v_max_f32_e32 v98, v98, v249
	v_max_f32_e32 v12, v12, v123
	v_max_f32_e32 v17, v17, v121
	v_max_f32_e32 v2, v2, v118
	v_max_f32_e32 v254, v254, v124
	v_max_f32_e32 v96, v96, v11
	v_max_f32_e32 v125, v125, v48
	v_max_f32_e32 v97, v97, v21
	v_max_f32_e32 v112, v112, v3
	v_max_f32_e32 v15, v15, v10
	v_max_f32_e32 v120, v250, v17
	v_min_f32_e32 v17, v250, v17
	v_max_f32_e32 v126, v103, v2
	v_min_f32_e32 v2, v103, v2
	v_max_f32_e32 v7, v106, v254
	v_min_f32_e32 v254, v106, v254
	v_max_f32_e32 v115, v13, v96
	v_min_f32_e32 v96, v13, v96
	v_max_f32_e32 v9, v18, v125
	v_min_f32_e32 v125, v18, v125
	v_max_f32_e32 v147, v100, v97
	v_min_f32_e32 v97, v100, v97
	v_max_f32_e32 v144, v98, v112
	v_min_f32_e32 v112, v98, v112
	v_max_f32_e32 v56, v12, v15
	v_min_f32_e32 v15, v12, v15
	v_max_f32_e32 v58, v120, v9
	v_min_f32_e32 v9, v120, v9
	v_max_f32_e32 v59, v126, v147
	v_min_f32_e32 v147, v126, v147
	v_max_f32_e32 v148, v7, v144
	v_min_f32_e32 v144, v7, v144
	v_max_f32_e32 v6, v115, v56
	v_min_f32_e32 v56, v115, v56
	v_max_f32_e32 v145, v17, v125
	v_min_f32_e32 v125, v17, v125
	v_max_f32_e32 v5, v2, v97
	v_min_f32_e32 v97, v2, v97
	v_max_f32_e32 v146, v254, v112
	v_min_f32_e32 v112, v254, v112
	v_max_f32_e32 v251, v96, v15
	v_min_f32_e32 v15, v96, v15
	v_max_f32_e32 v60, v58, v148
	v_min_f32_e32 v148, v58, v148
	v_max_f32_e32 v46, v59, v6
	v_min_f32_e32 v6, v59, v6
	v_max_f32_e32 v30, v9, v144
	v_min_f32_e32 v144, v9, v144
	v_max_f32_e32 v44, v147, v56
	v_min_f32_e32 v56, v147, v56
	v_max_f32_e32 v45, v145, v146
	v_min_f32_e32 v146, v145, v146
	v_max_f32_e32 v111, v5, v251
	v_min_f32_e32 v251, v5, v251
	v_max_f32_e32 v119, v125, v112
	v_min_f32_e32 v112, v125, v112
	v_max_f32_e32 v29, v97, v15
	v_min_f32_e32 v15, v97, v15
	v_max_f32_e32 v62, v60, v46
	v_min_f32_e32 v46, v60, v46
	v_max_f32_e32 v61, v148, v6
	v_min_f32_e32 v6, v148, v6
	v_max_f32_e32 v28, v30, v44
	v_min_f32_e32 v44, v30, v44
	v_max_f32_e32 v99, v144, v56
	v_min_f32_e32 v56, v144, v56
	v_max_f32_e32 v14, v45, v111
	v_min_f32_e32 v111, v45, v111
	v_max_f32_e32 v108, v146, v251
	v_min_f32_e32 v251, v146, v251
	v_max_f32_e32 v104, v119, v29
	v_min_f32_e32 v29, v119, v29
	v_max_f32_e32 v253, v112, v15
	v_min_f32_e32 v15, v112, v15
	v_mov_b32_e32 v113, v62
	v_mov_b32_e32 v35, v46
	v_mov_b32_e32 v55, v61
	v_mov_b32_e32 v16, v6
	v_mov_b32_e32 v57, v28
	v_mov_b32_e32 v149, v44
	v_mov_b32_e32 v40, v99
	v_mov_b32_e32 v54, v56
	v_mov_b32_e32 v42, v14
	v_mov_b32_e32 v53, v111
	v_mov_b32_e32 v43, v108
	v_mov_b32_e32 v116, v251
	v_mov_b32_e32 v20, v104
	v_mov_b32_e32 v252, v29
	v_mov_b32_e32 v63, v253
	v_mov_b32_e32 v150, v15
	s_nop 1
	v_permlane32_swap_b32_e32 v62, v113
	v_permlane32_swap_b32_e32 v46, v35
	v_permlane32_swap_b32_e32 v61, v55
	v_permlane32_swap_b32_e32 v6, v16
	v_permlane32_swap_b32_e32 v28, v57
	v_permlane32_swap_b32_e32 v44, v149
	v_permlane32_swap_b32_e32 v99, v40
	v_permlane32_swap_b32_e32 v56, v54
	v_permlane32_swap_b32_e32 v14, v42
	v_permlane32_swap_b32_e32 v111, v53
	v_permlane32_swap_b32_e32 v108, v43
	v_permlane32_swap_b32_e32 v251, v116
	v_permlane32_swap_b32_e32 v104, v20
	v_permlane32_swap_b32_e32 v29, v252
	v_permlane32_swap_b32_e32 v253, v63
	v_permlane32_swap_b32_e32 v15, v150
	s_nop 1
	v_max_f32_e32 v62, v62, v150
	v_max_f32_e32 v46, v46, v63
	v_max_f32_e32 v61, v61, v252
	v_max_f32_e32 v6, v6, v20
	v_max_f32_e32 v28, v28, v116
	v_max_f32_e32 v44, v44, v43
	v_max_f32_e32 v99, v99, v53
	v_max_f32_e32 v56, v56, v42
	v_max_f32_e32 v14, v14, v54
	v_max_f32_e32 v111, v111, v40
	v_max_f32_e32 v108, v108, v149
	v_max_f32_e32 v251, v251, v57
	v_max_f32_e32 v104, v104, v16
	v_max_f32_e32 v29, v29, v55
	v_max_f32_e32 v253, v253, v35
	v_max_f32_e32 v15, v15, v113
	v_max_f32_e32 v107, v62, v14
	v_min_f32_e32 v14, v62, v14
	v_max_f32_e32 v19, v46, v111
	v_min_f32_e32 v111, v46, v111
	v_max_f32_e32 v39, v61, v108
	v_min_f32_e32 v108, v61, v108
	v_max_f32_e32 v0, v6, v251
	v_min_f32_e32 v251, v6, v251
	v_max_f32_e32 v41, v28, v104
	v_min_f32_e32 v104, v28, v104
	v_max_f32_e32 v255, v44, v29
	v_min_f32_e32 v29, v44, v29
	v_max_f32_e32 v24, v99, v253
	v_min_f32_e32 v253, v99, v253
	v_max_f32_e32 v34, v56, v15
	v_min_f32_e32 v15, v56, v15
	v_max_f32_e32 v114, v107, v41
	v_min_f32_e32 v41, v107, v41
	v_max_f32_e32 v32, v19, v255
	v_min_f32_e32 v255, v19, v255
	v_max_f32_e32 v33, v39, v24
	v_min_f32_e32 v24, v39, v24
	v_max_f32_e32 v38, v0, v34
	v_min_f32_e32 v34, v0, v34
	v_max_f32_e32 v26, v14, v104
	v_min_f32_e32 v104, v14, v104
	v_max_f32_e32 v37, v111, v29
	v_min_f32_e32 v29, v111, v29
	v_max_f32_e32 v27, v108, v253
	v_min_f32_e32 v253, v108, v253
	v_max_f32_e32 v50, v251, v15
	v_min_f32_e32 v15, v251, v15
	v_max_f32_e32 v122, v114, v33
	v_min_f32_e32 v33, v114, v33
	v_max_f32_e32 v117, v32, v38
	v_min_f32_e32 v38, v32, v38
	v_max_f32_e32 v1, v41, v24
	v_min_f32_e32 v24, v41, v24
	v_max_f32_e32 v49, v255, v34
	v_min_f32_e32 v34, v255, v34
	v_max_f32_e32 v51, v26, v27
	v_min_f32_e32 v27, v26, v27
	v_max_f32_e32 v109, v37, v50
	v_min_f32_e32 v50, v37, v50
	v_max_f32_e32 v4, v104, v253
	v_min_f32_e32 v253, v104, v253
	v_max_f32_e32 v102, v29, v15
	v_min_f32_e32 v15, v29, v15
	v_max_f32_e32 v128, v122, v117
	v_min_f32_e32 v129, v122, v117
	v_max_f32_e32 v130, v33, v38
	v_min_f32_e32 v131, v33, v38
	v_max_f32_e32 v132, v1, v49
	v_min_f32_e32 v133, v1, v49
	v_max_f32_e32 v134, v24, v34
	v_min_f32_e32 v135, v24, v34
	v_max_f32_e32 v136, v51, v109
	v_min_f32_e32 v137, v51, v109
	v_max_f32_e32 v138, v27, v50
	v_min_f32_e32 v139, v27, v50
	v_max_f32_e32 v140, v4, v102
	v_min_f32_e32 v141, v4, v102
	v_max_f32_e32 v142, v253, v15
	v_min_f32_e32 v143, v253, v15
	s_waitcnt vmcnt(0)
	v_pk_mul_f32 v[160:161], v[160:161], v[176:177]
	v_pk_mul_f32 v[162:163], v[162:163], v[178:179]
	v_pk_mul_f32 v[164:165], v[164:165], v[180:181]
	v_pk_mul_f32 v[166:167], v[166:167], v[182:183]
	v_pk_mul_f32 v[168:169], v[168:169], v[184:185]
	v_pk_mul_f32 v[170:171], v[170:171], v[186:187]
	v_pk_mul_f32 v[172:173], v[172:173], v[188:189]
	v_pk_mul_f32 v[174:175], v[174:175], v[190:191]
	v_max3_f32 v192, |v160|, |v161|, |v162|
	v_max3_f32 v192, |v163|, |v164|, v192
	v_max3_f32 v192, |v165|, |v166|, v192
	v_max3_f32 v192, |v167|, |v168|, v192
	v_max3_f32 v192, |v169|, |v170|, v192
	v_max3_f32 v192, |v171|, |v172|, v192
	v_max3_f32 v192, |v173|, |v174|, v192
	v_max_f32_e64 v192, |v175|, v192
	s_nop 1
	v_mov_b32_dpp v193, v192 quad_perm:[1,0,3,2] row_mask:0xf bank_mask:0xf bound_ctrl:1
	v_max_f32_e32 v192, v192, v193
	s_nop 1
	v_mov_b32_dpp v193, v192 quad_perm:[2,3,0,1] row_mask:0xf bank_mask:0xf bound_ctrl:1
	v_max_f32_e32 v192, v192, v193
	s_nop 1
	v_mov_b32_dpp v193, v192 row_half_mirror row_mask:0xf bank_mask:0xf bound_ctrl:1
	v_max_f32_e32 v192, v192, v193
	s_nop 1
	v_mov_b32_dpp v193, v192 row_mirror row_mask:0xf bank_mask:0xf bound_ctrl:1
	v_max_f32_e32 v192, v192, v193
	v_mov_b32_e32 v193, v192
	s_nop 1
	v_permlane16_swap_b32_e32 v192, v193
	s_nop 1
	v_max_f32_e32 v192, v192, v193
	v_mov_b32_e32 v193, v192
	s_nop 1
	v_permlane32_swap_b32_e32 v192, v193
	s_nop 1
	v_max_f32_e32 v192, v192, v193
	v_max_f32_e32 v192, 0xda24260, v192
	v_mul_f32_e32 v194, 0x3e2aaaab, v192
	global_store_dword v214, v194, s[12:13]
	v_div_scale_f32 v195, s[26:27], v194, v194, 1.0
	v_rcp_f32_e32 v196, v195
	v_div_scale_f32 v204, vcc, 1.0, v194, 1.0
	v_fma_f32 v205, -v195, v196, 1.0
	v_fmac_f32_e32 v196, v205, v196
	v_mul_f32_e32 v205, v204, v196
	v_fma_f32 v206, -v195, v205, v204
	v_fmac_f32_e32 v205, v206, v196
	v_fma_f32 v195, -v195, v205, v204
	s_nop 0
	v_div_fmas_f32 v195, v195, v196, v205
	v_div_fixup_f32 v207, v195, v194, 1.0
	v_mul_f32_e32 v160, v207, v160
	v_mul_f32_e32 v161, v207, v161
	v_mul_f32_e32 v162, v207, v162
	v_mul_f32_e32 v163, v207, v163
	v_mul_f32_e32 v164, v207, v164
	v_mul_f32_e32 v165, v207, v165
	v_mul_f32_e32 v166, v207, v166
	v_mul_f32_e32 v167, v207, v167
	v_mul_f32_e32 v168, v207, v168
	v_mul_f32_e32 v169, v207, v169
	v_mul_f32_e32 v170, v207, v170
	v_mul_f32_e32 v171, v207, v171
	v_mul_f32_e32 v172, v207, v172
	v_mul_f32_e32 v173, v207, v173
	v_mul_f32_e32 v174, v207, v174
	v_mul_f32_e32 v175, v207, v175
	v_mov_b32_e32 v208, 0
	v_mov_b32_e32 v209, 0
	v_mov_b32_e32 v210, 0
	v_mov_b32_e32 v193, 0
	v_cvt_scalef32_pk_fp4_f32 v208, v160, v161, 1.0
	v_cvt_scalef32_pk_fp4_f32 v209, v164, v165, 1.0
	v_cvt_scalef32_pk_fp4_f32 v210, v168, v169, 1.0
	v_cvt_scalef32_pk_fp4_f32 v193, v172, v173, 1.0
	v_cvt_scalef32_pk_fp4_f32 v208, v162, v163, 1.0 op_sel:[0,0,1,0]
	v_cvt_scalef32_pk_fp4_f32 v209, v166, v167, 1.0 op_sel:[0,0,1,0]
	v_cvt_scalef32_pk_fp4_f32 v210, v170, v171, 1.0 op_sel:[0,0,1,0]
	v_cvt_scalef32_pk_fp4_f32 v193, v174, v175, 1.0 op_sel:[0,0,1,0]
	global_store_short v213, v208, s[10:11] nt
	s_add_u32 s14, s10, 0x200000
	s_addc_u32 s15, s11, 0
	global_store_short v213, v209, s[14:15] nt
	s_add_u32 s14, s10, 0x400000
	s_addc_u32 s15, s11, 0
	global_store_short v213, v210, s[14:15] nt
	s_add_u32 s14, s10, 0x600000
	s_addc_u32 s15, s11, 0
	global_store_short v213, v193, s[14:15] nt
	s_add_u32 s10, s10, 0x20000
	s_addc_u32 s11, s11, 0
	s_add_u32 s12, s12, 0x2000
	s_addc_u32 s13, s13, 0
	global_load_dwordx4 v[160:163], v212, s[8:9] offset:0 nt
	global_load_dwordx4 v[164:167], v212, s[8:9] offset:1024 nt
	global_load_dwordx4 v[168:171], v212, s[8:9] offset:2048 nt
	global_load_dwordx4 v[172:175], v212, s[8:9] offset:3072 nt
	s_add_u32 s8, s8, 0x800000
	s_addc_u32 s9, s9, 0
	ds_write_b8 v240, v128 offset:0
	ds_write_b8 v240, v129 offset:1
	ds_write_b8 v240, v130 offset:2
	ds_write_b8 v240, v131 offset:3
	ds_write_b8 v240, v132 offset:4
	ds_write_b8 v240, v133 offset:5
	ds_write_b8 v240, v134 offset:6
	ds_write_b8 v240, v135 offset:7
	ds_write_b8 v240, v136 offset:8
	ds_write_b8 v240, v137 offset:9
	ds_write_b8 v240, v138 offset:10
	ds_write_b8 v240, v139 offset:11
	ds_write_b8 v240, v140 offset:12
	ds_write_b8 v240, v141 offset:13
	ds_write_b8 v240, v142 offset:14
	ds_write_b8 v240, v143 offset:15
	ds_read_b128 v[96:99], v215 offset:32768
	ds_read_b128 v[100:103], v232 offset:32768
	ds_read_b128 v[104:107], v233 offset:32768
	ds_read_b128 v[108:111], v234 offset:32768
	ds_read_b128 v[112:115], v235 offset:32768
	ds_read_b128 v[116:119], v236 offset:32768
	ds_read_b128 v[120:123], v237 offset:32768
	ds_read_b128 v[124:127], v238 offset:32768
	s_waitcnt vmcnt(27)
	s_waitcnt lgkmcnt(4)
	v_mfma_f32_32x32x16_bf16 v[0:15], v[96:99], v[64:67], 0
	v_mfma_f32_32x32x16_bf16 v[0:15], v[100:103], v[68:71], v[0:15]
	v_mfma_f32_32x32x16_bf16 v[0:15], v[104:107], v[72:75], v[0:15]
	v_mfma_f32_32x32x16_bf16 v[0:15], v[108:111], v[76:79], v[0:15]
	ds_read_b128 v[96:99], v215 offset:40960
	ds_read_b128 v[100:103], v232 offset:40960
	ds_read_b128 v[104:107], v233 offset:40960
	ds_read_b128 v[108:111], v234 offset:40960
	s_waitcnt lgkmcnt(4)
	v_mfma_f32_32x32x16_bf16 v[0:15], v[112:115], v[80:83], v[0:15]
	v_mfma_f32_32x32x16_bf16 v[0:15], v[116:119], v[84:87], v[0:15]
	v_mfma_f32_32x32x16_bf16 v[0:15], v[120:123], v[88:91], v[0:15]
	v_mfma_f32_32x32x16_bf16 v[0:15], v[124:127], v[92:95], v[0:15]
	ds_read_b128 v[112:115], v235 offset:40960
	ds_read_b128 v[116:119], v236 offset:40960
	ds_read_b128 v[120:123], v237 offset:40960
	ds_read_b128 v[124:127], v238 offset:40960
	s_waitcnt lgkmcnt(4)
	v_mfma_f32_32x32x16_bf16 v[16:31], v[96:99], v[64:67], 0
	v_mfma_f32_32x32x16_bf16 v[16:31], v[100:103], v[68:71], v[16:31]
	v_mfma_f32_32x32x16_bf16 v[16:31], v[104:107], v[72:75], v[16:31]
	v_mfma_f32_32x32x16_bf16 v[16:31], v[108:111], v[76:79], v[16:31]
	ds_read_b128 v[96:99], v215 offset:49152
	ds_read_b128 v[100:103], v232 offset:49152
	ds_read_b128 v[104:107], v233 offset:49152
	ds_read_b128 v[108:111], v234 offset:49152
	s_waitcnt lgkmcnt(4)
	v_mfma_f32_32x32x16_bf16 v[16:31], v[112:115], v[80:83], v[16:31]
	v_mfma_f32_32x32x16_bf16 v[16:31], v[116:119], v[84:87], v[16:31]
	v_mfma_f32_32x32x16_bf16 v[16:31], v[120:123], v[88:91], v[16:31]
	v_mfma_f32_32x32x16_bf16 v[16:31], v[124:127], v[92:95], v[16:31]
	ds_read_b128 v[112:115], v235 offset:49152
	ds_read_b128 v[116:119], v236 offset:49152
	ds_read_b128 v[120:123], v237 offset:49152
	ds_read_b128 v[124:127], v238 offset:49152
	s_waitcnt lgkmcnt(4)
	v_mfma_f32_32x32x16_bf16 v[32:47], v[96:99], v[64:67], 0
	v_mfma_f32_32x32x16_bf16 v[32:47], v[100:103], v[68:71], v[32:47]
	v_mfma_f32_32x32x16_bf16 v[32:47], v[104:107], v[72:75], v[32:47]
	v_mfma_f32_32x32x16_bf16 v[32:47], v[108:111], v[76:79], v[32:47]
	ds_read_b128 v[96:99], v215 offset:57344
	ds_read_b128 v[100:103], v232 offset:57344
	ds_read_b128 v[104:107], v233 offset:57344
	ds_read_b128 v[108:111], v234 offset:57344
	s_waitcnt lgkmcnt(4)
	v_mfma_f32_32x32x16_bf16 v[32:47], v[112:115], v[80:83], v[32:47]
	v_mfma_f32_32x32x16_bf16 v[32:47], v[116:119], v[84:87], v[32:47]
	v_mfma_f32_32x32x16_bf16 v[32:47], v[120:123], v[88:91], v[32:47]
	v_mfma_f32_32x32x16_bf16 v[32:47], v[124:127], v[92:95], v[32:47]
	ds_read_b128 v[112:115], v235 offset:57344
	ds_read_b128 v[116:119], v236 offset:57344
	ds_read_b128 v[120:123], v237 offset:57344
	ds_read_b128 v[124:127], v238 offset:57344
	s_waitcnt lgkmcnt(4)
	v_mfma_f32_32x32x16_bf16 v[48:63], v[96:99], v[64:67], 0
	v_mfma_f32_32x32x16_bf16 v[48:63], v[100:103], v[68:71], v[48:63]
	v_mfma_f32_32x32x16_bf16 v[48:63], v[104:107], v[72:75], v[48:63]
	v_mfma_f32_32x32x16_bf16 v[48:63], v[108:111], v[76:79], v[48:63]
	s_waitcnt lgkmcnt(0)
	v_mfma_f32_32x32x16_bf16 v[48:63], v[112:115], v[80:83], v[48:63]
	v_mfma_f32_32x32x16_bf16 v[48:63], v[116:119], v[84:87], v[48:63]
	v_mfma_f32_32x32x16_bf16 v[48:63], v[120:123], v[88:91], v[48:63]
	v_mfma_f32_32x32x16_bf16 v[48:63], v[124:127], v[92:95], v[48:63]
	s_nop 11
	v_and_or_b32 v0, v0, s6, v211
	v_or_b32_e32 v0, 0x7b, v0
	v_and_or_b32 v1, v1, s6, v211
	v_or_b32_e32 v1, 0x7a, v1
	v_and_or_b32 v2, v2, s6, v211
	v_or_b32_e32 v2, 0x79, v2
	v_and_or_b32 v3, v3, s6, v211
	v_or_b32_e32 v3, 0x78, v3
	v_and_or_b32 v4, v4, s6, v211
	v_or_b32_e32 v4, 0x73, v4
	v_and_or_b32 v5, v5, s6, v211
	v_or_b32_e32 v5, 0x72, v5
	v_and_or_b32 v6, v6, s6, v211
	v_or_b32_e32 v6, 0x71, v6
	v_and_or_b32 v7, v7, s6, v211
	v_or_b32_e32 v7, 0x70, v7
	v_and_or_b32 v8, v8, s6, v211
	v_or_b32_e32 v8, 0x6b, v8
	v_and_or_b32 v9, v9, s6, v211
	v_or_b32_e32 v9, 0x6a, v9
	v_and_or_b32 v10, v10, s6, v211
	v_or_b32_e32 v10, 0x69, v10
	v_and_or_b32 v11, v11, s6, v211
	v_or_b32_e32 v11, 0x68, v11
	v_and_or_b32 v12, v12, s6, v211
	v_or_b32_e32 v12, 0x63, v12
	v_and_or_b32 v13, v13, s6, v211
	v_or_b32_e32 v13, 0x62, v13
	v_and_or_b32 v14, v14, s6, v211
	v_or_b32_e32 v14, 0x61, v14
	v_and_or_b32 v15, v15, s6, v211
	v_or_b32_e32 v15, 0x60, v15
	v_and_or_b32 v16, v16, s6, v211
	v_or_b32_e32 v16, 0x5b, v16
	v_and_or_b32 v17, v17, s6, v211
	v_or_b32_e32 v17, 0x5a, v17
	v_and_or_b32 v18, v18, s6, v211
	v_or_b32_e32 v18, 0x59, v18
	v_and_or_b32 v19, v19, s6, v211
	v_or_b32_e32 v19, 0x58, v19
	v_and_or_b32 v20, v20, s6, v211
	v_or_b32_e32 v20, 0x53, v20
	v_and_or_b32 v21, v21, s6, v211
	v_or_b32_e32 v21, 0x52, v21
	v_and_or_b32 v22, v22, s6, v211
	v_or_b32_e32 v22, 0x51, v22
	v_and_or_b32 v23, v23, s6, v211
	v_or_b32_e32 v23, 0x50, v23
	v_and_or_b32 v24, v24, s6, v211
	v_or_b32_e32 v24, 0x4b, v24
	v_and_or_b32 v25, v25, s6, v211
	v_or_b32_e32 v25, 0x4a, v25
	v_and_or_b32 v26, v26, s6, v211
	v_or_b32_e32 v26, 0x49, v26
	v_and_or_b32 v27, v27, s6, v211
	v_or_b32_e32 v27, 0x48, v27
	v_and_or_b32 v28, v28, s6, v211
	v_or_b32_e32 v28, 0x43, v28
	v_and_or_b32 v29, v29, s6, v211
	v_or_b32_e32 v29, 0x42, v29
	v_and_or_b32 v30, v30, s6, v211
	v_or_b32_e32 v30, 0x41, v30
	v_and_or_b32 v31, v31, s6, v211
	v_or_b32_e32 v31, 64, v31
	v_and_or_b32 v32, v32, s6, v211
	v_or_b32_e32 v32, 59, v32
	v_and_or_b32 v33, v33, s6, v211
	v_or_b32_e32 v33, 58, v33
	v_and_or_b32 v34, v34, s6, v211
	v_or_b32_e32 v34, 57, v34
	v_and_or_b32 v35, v35, s6, v211
	v_or_b32_e32 v35, 56, v35
	v_and_or_b32 v36, v36, s6, v211
	v_or_b32_e32 v36, 51, v36
	v_and_or_b32 v37, v37, s6, v211
	v_or_b32_e32 v37, 50, v37
	v_and_or_b32 v38, v38, s6, v211
	v_or_b32_e32 v38, 49, v38
	v_and_or_b32 v39, v39, s6, v211
	v_or_b32_e32 v39, 48, v39
	v_and_or_b32 v40, v40, s6, v211
	v_or_b32_e32 v40, 43, v40
	v_and_or_b32 v41, v41, s6, v211
	v_or_b32_e32 v41, 42, v41
	v_and_or_b32 v42, v42, s6, v211
	v_or_b32_e32 v42, 41, v42
	v_and_or_b32 v43, v43, s6, v211
	v_or_b32_e32 v43, 40, v43
	v_and_or_b32 v44, v44, s6, v211
	v_or_b32_e32 v44, 35, v44
	v_and_or_b32 v45, v45, s6, v211
	v_or_b32_e32 v45, 34, v45
	v_and_or_b32 v46, v46, s6, v211
	v_or_b32_e32 v46, 33, v46
	v_and_or_b32 v47, v47, s6, v211
	v_or_b32_e32 v47, 32, v47
	v_and_or_b32 v48, v48, s6, v211
	v_or_b32_e32 v48, 27, v48
	v_and_or_b32 v49, v49, s6, v211
	v_or_b32_e32 v49, 26, v49
	v_and_or_b32 v50, v50, s6, v211
	v_or_b32_e32 v50, 25, v50
	v_and_or_b32 v51, v51, s6, v211
	v_or_b32_e32 v51, 24, v51
	v_and_or_b32 v52, v52, s6, v211
	v_or_b32_e32 v52, 19, v52
	v_and_or_b32 v53, v53, s6, v211
	v_or_b32_e32 v53, 18, v53
	v_and_or_b32 v54, v54, s6, v211
	v_or_b32_e32 v54, 17, v54
	v_and_or_b32 v55, v55, s6, v211
	v_or_b32_e32 v55, 16, v55
	v_and_or_b32 v56, v56, s6, v211
	v_or_b32_e32 v56, 11, v56
	v_and_or_b32 v57, v57, s6, v211
	v_or_b32_e32 v57, 10, v57
	v_and_or_b32 v58, v58, s6, v211
	v_or_b32_e32 v58, 9, v58
	v_and_or_b32 v59, v59, s6, v211
	v_or_b32_e32 v59, 8, v59
	v_and_or_b32 v60, v60, s6, v211
	v_or_b32_e32 v60, 3, v60
	v_and_or_b32 v61, v61, s6, v211
	v_or_b32_e32 v61, 2, v61
	v_and_or_b32 v62, v62, s6, v211
	v_or_b32_e32 v62, 1, v62
	v_and_or_b32 v63, v63, s6, v211
	v_or_b32_e32 v63, 0, v63
	v_max_f32_e32 v144, v0, v13
	v_min_f32_e32 v13, v0, v13
	v_max_f32_e32 v145, v1, v12
	v_min_f32_e32 v12, v1, v12
	v_max_f32_e32 v146, v2, v15
	v_min_f32_e32 v15, v2, v15
	v_max_f32_e32 v147, v3, v14
	v_min_f32_e32 v14, v3, v14
	v_max_f32_e32 v148, v4, v8
	v_min_f32_e32 v8, v4, v8
	v_max_f32_e32 v149, v5, v6
	v_min_f32_e32 v6, v5, v6
	v_max_f32_e32 v150, v7, v11
	v_min_f32_e32 v11, v7, v11
	v_max_f32_e32 v151, v9, v10
	v_min_f32_e32 v10, v9, v10
	v_max_f32_e32 v249, v144, v149
	v_min_f32_e32 v149, v144, v149
	v_max_f32_e32 v250, v145, v150
	v_min_f32_e32 v150, v145, v150
	v_max_f32_e32 v251, v146, v151
	v_min_f32_e32 v151, v146, v151
	v_max_f32_e32 v252, v147, v148
	v_min_f32_e32 v148, v147, v148
	v_max_f32_e32 v253, v6, v13
	v_min_f32_e32 v13, v6, v13
	v_max_f32_e32 v254, v8, v14
	v_min_f32_e32 v14, v8, v14
	v_max_f32_e32 v255, v10, v15
	v_min_f32_e32 v15, v10, v15
	v_max_f32_e32 v96, v11, v12
	v_min_f32_e32 v12, v11, v12
	v_max_f32_e32 v97, v249, v250
	v_min_f32_e32 v250, v249, v250
	v_max_f32_e32 v98, v251, v252
	v_min_f32_e32 v252, v251, v252
	v_max_f32_e32 v99, v148, v149
	v_min_f32_e32 v149, v148, v149
	v_max_f32_e32 v100, v253, v254
	v_min_f32_e32 v254, v253, v254
	v_max_f32_e32 v101, v150, v151
	v_min_f32_e32 v151, v150, v151
	v_max_f32_e32 v102, v255, v96
	v_min_f32_e32 v96, v255, v96
	v_max_f32_e32 v103, v12, v13
	v_min_f32_e32 v13, v12, v13
	v_max_f32_e32 v104, v14, v15
	v_min_f32_e32 v15, v14, v15
	v_max_f32_e32 v105, v97, v98
	v_min_f32_e32 v98, v97, v98
	v_max_f32_e32 v106, v250, v252
	v_min_f32_e32 v252, v250, v252
	v_max_f32_e32 v107, v99, v102
	v_min_f32_e32 v102, v99, v102
	v_max_f32_e32 v108, v149, v96
	v_min_f32_e32 v96, v149, v96
	v_max_f32_e32 v109, v100, v101
	v_min_f32_e32 v101, v100, v101
	v_max_f32_e32 v110, v254, v151
	v_min_f32_e32 v151, v254, v151
	v_max_f32_e32 v111, v103, v104
	v_min_f32_e32 v104, v103, v104
	v_max_f32_e32 v112, v13, v15
	v_min_f32_e32 v15, v13, v15
	v_max_f32_e32 v113, v106, v98
	v_min_f32_e32 v98, v106, v98
	v_max_f32_e32 v114, v252, v111
	v_min_f32_e32 v111, v252, v111
	v_max_f32_e32 v115, v107, v109
	v_min_f32_e32 v109, v107, v109
	v_max_f32_e32 v116, v108, v101
	v_min_f32_e32 v101, v108, v101
	v_max_f32_e32 v117, v110, v102
	v_min_f32_e32 v102, v110, v102
	v_max_f32_e32 v118, v151, v96
	v_min_f32_e32 v96, v151, v96
	v_max_f32_e32 v119, v112, v104
	v_min_f32_e32 v104, v112, v104
	v_max_f32_e32 v120, v113, v115
	v_min_f32_e32 v115, v113, v115
	v_max_f32_e32 v121, v98, v109
	v_min_f32_e32 v109, v98, v109
	v_max_f32_e32 v122, v116, v117
	v_min_f32_e32 v117, v116, v117
	v_max_f32_e32 v123, v101, v102
	v_min_f32_e32 v102, v101, v102
	v_max_f32_e32 v124, v118, v119
	v_min_f32_e32 v119, v118, v119
	v_max_f32_e32 v125, v96, v104
	v_min_f32_e32 v104, v96, v104
	v_max_f32_e32 v126, v121, v115
	v_min_f32_e32 v115, v121, v115
	v_max_f32_e32 v127, v114, v109
	v_min_f32_e32 v109, v114, v109
	v_max_f32_e32 v64, v124, v111
	v_min_f32_e32 v111, v124, v111
	v_max_f32_e32 v65, v125, v119
	v_min_f32_e32 v119, v125, v119
	v_max_f32_e32 v66, v127, v122
	v_min_f32_e32 v122, v127, v122
	v_max_f32_e32 v67, v109, v117
	v_min_f32_e32 v117, v109, v117
	v_max_f32_e32 v68, v123, v64
	v_min_f32_e32 v64, v123, v64
	v_max_f32_e32 v69, v102, v111
	v_min_f32_e32 v111, v102, v111
	v_max_f32_e32 v70, v66, v115
	v_min_f32_e32 v115, v66, v115
	v_max_f32_e32 v71, v122, v67
	v_min_f32_e32 v67, v122, v67
	v_max_f32_e32 v72, v68, v117
	v_min_f32_e32 v117, v68, v117
	v_max_f32_e32 v73, v64, v69
	v_min_f32_e32 v69, v64, v69
	v_max_f32_e32 v74, v65, v111
	v_min_f32_e32 v111, v65, v111
	v_max_f32_e32 v75, v67, v72
	v_min_f32_e32 v72, v67, v72
	v_max_f32_e32 v76, v117, v73
	v_min_f32_e32 v73, v117, v73
	v_max_f32_e32 v77, v16, v29
	v_min_f32_e32 v29, v16, v29
	v_max_f32_e32 v78, v17, v28
	v_min_f32_e32 v28, v17, v28
	v_max_f32_e32 v79, v18, v31
	v_min_f32_e32 v31, v18, v31
	v_max_f32_e32 v80, v19, v30
	v_min_f32_e32 v30, v19, v30
	v_max_f32_e32 v81, v20, v24
	v_min_f32_e32 v24, v20, v24
	v_max_f32_e32 v82, v21, v22
	v_min_f32_e32 v22, v21, v22
	v_max_f32_e32 v83, v23, v27
	v_min_f32_e32 v27, v23, v27
	v_max_f32_e32 v84, v25, v26
	v_min_f32_e32 v26, v25, v26
	v_max_f32_e32 v85, v77, v82
	v_min_f32_e32 v82, v77, v82
	v_max_f32_e32 v86, v78, v83
	v_min_f32_e32 v83, v78, v83
	v_max_f32_e32 v87, v79, v84
	v_min_f32_e32 v84, v79, v84
	v_max_f32_e32 v88, v80, v81
	v_min_f32_e32 v81, v80, v81
	v_max_f32_e32 v89, v22, v29
	v_min_f32_e32 v29, v22, v29
	v_max_f32_e32 v90, v24, v30
	v_min_f32_e32 v30, v24, v30
	v_max_f32_e32 v91, v26, v31
	v_min_f32_e32 v31, v26, v31
	v_max_f32_e32 v92, v27, v28
	v_min_f32_e32 v28, v27, v28
	v_max_f32_e32 v93, v85, v86
	v_min_f32_e32 v86, v85, v86
	v_max_f32_e32 v94, v87, v88
	v_min_f32_e32 v88, v87, v88
	v_max_f32_e32 v95, v81, v82
	v_min_f32_e32 v82, v81, v82
	v_max_f32_e32 v0, v89, v90
	v_min_f32_e32 v90, v89, v90
	v_max_f32_e32 v1, v83, v84
	v_min_f32_e32 v84, v83, v84
	v_max_f32_e32 v2, v91, v92
	v_min_f32_e32 v92, v91, v92
	v_max_f32_e32 v3, v28, v29
	v_min_f32_e32 v29, v28, v29
	v_max_f32_e32 v4, v30, v31
	v_min_f32_e32 v31, v30, v31
	v_max_f32_e32 v5, v93, v94
	v_min_f32_e32 v94, v93, v94
	v_max_f32_e32 v7, v86, v88
	v_min_f32_e32 v88, v86, v88
	v_max_f32_e32 v9, v95, v2
	v_min_f32_e32 v2, v95, v2
	v_max_f32_e32 v144, v82, v92
	v_min_f32_e32 v92, v82, v92
	v_max_f32_e32 v145, v0, v1
	v_min_f32_e32 v1, v0, v1
	v_max_f32_e32 v146, v90, v84
	v_min_f32_e32 v84, v90, v84
	v_max_f32_e32 v147, v3, v4
	v_min_f32_e32 v4, v3, v4
	v_max_f32_e32 v6, v29, v31
	v_min_f32_e32 v31, v29, v31
	v_max_f32_e32 v8, v7, v94
	v_min_f32_e32 v94, v7, v94
	v_max_f32_e32 v10, v88, v147
	v_min_f32_e32 v147, v88, v147
	v_max_f32_e32 v11, v9, v145
	v_min_f32_e32 v145, v9, v145
	v_max_f32_e32 v249, v144, v1
	v_min_f32_e32 v1, v144, v1
	v_max_f32_e32 v251, v146, v2
	v_min_f32_e32 v2, v146, v2
	v_max_f32_e32 v148, v84, v92
	v_min_f32_e32 v92, v84, v92
	v_max_f32_e32 v253, v6, v4
	v_min_f32_e32 v4, v6, v4
	v_max_f32_e32 v150, v8, v11
	v_min_f32_e32 v11, v8, v11
	v_max_f32_e32 v255, v94, v145
	v_min_f32_e32 v145, v94, v145
	v_max_f32_e32 v12, v249, v251
	v_min_f32_e32 v251, v249, v251
	v_max_f32_e32 v14, v1, v2
	v_min_f32_e32 v2, v1, v2
	v_max_f32_e32 v97, v148, v253
	v_min_f32_e32 v253, v148, v253
	v_max_f32_e32 v250, v92, v4
	v_min_f32_e32 v4, v92, v4
	v_max_f32_e32 v99, v255, v11
	v_min_f32_e32 v11, v255, v11
	v_max_f32_e32 v149, v10, v145
	v_min_f32_e32 v145, v10, v145
	v_max_f32_e32 v100, v97, v147
	v_min_f32_e32 v147, v97, v147
	v_max_f32_e32 v254, v250, v253
	v_min_f32_e32 v253, v250, v253
	v_max_f32_e32 v103, v149, v12
	v_min_f32_e32 v12, v149, v12
	v_max_f32_e32 v13, v145, v251
	v_min_f32_e32 v251, v145, v251
	v_max_f32_e32 v106, v14, v100
	v_min_f32_e32 v100, v14, v100
	v_max_f32_e32 v252, v2, v147
	v_min_f32_e32 v147, v2, v147
	v_max_f32_e32 v107, v103, v11
	v_min_f32_e32 v11, v103, v11
	v_max_f32_e32 v108, v12, v13
	v_min_f32_e32 v13, v12, v13
	v_max_f32_e32 v110, v106, v251
	v_min_f32_e32 v251, v106, v251
	v_max_f32_e32 v151, v100, v252
	v_min_f32_e32 v252, v100, v252
	v_max_f32_e32 v112, v254, v147
	v_min_f32_e32 v147, v254, v147
	v_max_f32_e32 v113, v13, v110
	v_min_f32_e32 v110, v13, v110
	v_max_f32_e32 v98, v251, v151
	v_min_f32_e32 v151, v251, v151
	s_waitcnt vmcnt(0)
	v_pk_mul_f32 v[160:161], v[160:161], v[176:177]
	v_pk_mul_f32 v[162:163], v[162:163], v[178:179]
	v_pk_mul_f32 v[164:165], v[164:165], v[180:181]
	v_pk_mul_f32 v[166:167], v[166:167], v[182:183]
	v_pk_mul_f32 v[168:169], v[168:169], v[184:185]
	v_pk_mul_f32 v[170:171], v[170:171], v[186:187]
	v_pk_mul_f32 v[172:173], v[172:173], v[188:189]
	v_pk_mul_f32 v[174:175], v[174:175], v[190:191]
	v_max3_f32 v192, |v160|, |v161|, |v162|
	v_max3_f32 v192, |v163|, |v164|, v192
	v_max3_f32 v192, |v165|, |v166|, v192
	v_max3_f32 v192, |v167|, |v168|, v192
	v_max3_f32 v192, |v169|, |v170|, v192
	v_max3_f32 v192, |v171|, |v172|, v192
	v_max3_f32 v192, |v173|, |v174|, v192
	v_max_f32_e64 v192, |v175|, v192
	s_nop 1
	v_mov_b32_dpp v193, v192 quad_perm:[1,0,3,2] row_mask:0xf bank_mask:0xf bound_ctrl:1
	v_max_f32_e32 v192, v192, v193
	s_nop 1
	v_mov_b32_dpp v193, v192 quad_perm:[2,3,0,1] row_mask:0xf bank_mask:0xf bound_ctrl:1
	v_max_f32_e32 v192, v192, v193
	s_nop 1
	v_mov_b32_dpp v193, v192 row_half_mirror row_mask:0xf bank_mask:0xf bound_ctrl:1
	v_max_f32_e32 v192, v192, v193
	s_nop 1
	v_mov_b32_dpp v193, v192 row_mirror row_mask:0xf bank_mask:0xf bound_ctrl:1
	v_max_f32_e32 v192, v192, v193
	v_mov_b32_e32 v193, v192
	s_nop 1
	v_permlane16_swap_b32_e32 v192, v193
	s_nop 1
	v_max_f32_e32 v192, v192, v193
	v_mov_b32_e32 v193, v192
	s_nop 1
	v_permlane32_swap_b32_e32 v192, v193
	s_nop 1
	v_max_f32_e32 v192, v192, v193
	v_max_f32_e32 v192, 0xda24260, v192
	v_mul_f32_e32 v194, 0x3e2aaaab, v192
	global_store_dword v214, v194, s[12:13]
	v_div_scale_f32 v195, s[26:27], v194, v194, 1.0
	v_rcp_f32_e32 v196, v195
	v_div_scale_f32 v204, vcc, 1.0, v194, 1.0
	v_fma_f32 v205, -v195, v196, 1.0
	v_fmac_f32_e32 v196, v205, v196
	v_mul_f32_e32 v205, v204, v196
	v_fma_f32 v206, -v195, v205, v204
	v_fmac_f32_e32 v205, v206, v196
	v_fma_f32 v195, -v195, v205, v204
	s_nop 0
	v_div_fmas_f32 v195, v195, v196, v205
	v_div_fixup_f32 v207, v195, v194, 1.0
	v_mul_f32_e32 v160, v207, v160
	v_mul_f32_e32 v161, v207, v161
	v_mul_f32_e32 v162, v207, v162
	v_mul_f32_e32 v163, v207, v163
	v_mul_f32_e32 v164, v207, v164
	v_mul_f32_e32 v165, v207, v165
	v_mul_f32_e32 v166, v207, v166
	v_mul_f32_e32 v167, v207, v167
	v_mul_f32_e32 v168, v207, v168
	v_mul_f32_e32 v169, v207, v169
	v_mul_f32_e32 v170, v207, v170
	v_mul_f32_e32 v171, v207, v171
	v_mul_f32_e32 v172, v207, v172
	v_mul_f32_e32 v173, v207, v173
	v_mul_f32_e32 v174, v207, v174
	v_mul_f32_e32 v175, v207, v175
	v_mov_b32_e32 v208, 0
	v_mov_b32_e32 v209, 0
	v_mov_b32_e32 v210, 0
	v_mov_b32_e32 v193, 0
	v_cvt_scalef32_pk_fp4_f32 v208, v160, v161, 1.0
	v_cvt_scalef32_pk_fp4_f32 v209, v164, v165, 1.0
	v_cvt_scalef32_pk_fp4_f32 v210, v168, v169, 1.0
	v_cvt_scalef32_pk_fp4_f32 v193, v172, v173, 1.0
	v_cvt_scalef32_pk_fp4_f32 v208, v162, v163, 1.0 op_sel:[0,0,1,0]
	v_cvt_scalef32_pk_fp4_f32 v209, v166, v167, 1.0 op_sel:[0,0,1,0]
	v_cvt_scalef32_pk_fp4_f32 v210, v170, v171, 1.0 op_sel:[0,0,1,0]
	v_cvt_scalef32_pk_fp4_f32 v193, v174, v175, 1.0 op_sel:[0,0,1,0]
	global_store_short v213, v208, s[10:11] nt
	s_add_u32 s14, s10, 0x200000
	s_addc_u32 s15, s11, 0
	global_store_short v213, v209, s[14:15] nt
	s_add_u32 s14, s10, 0x400000
	s_addc_u32 s15, s11, 0
	global_store_short v213, v210, s[14:15] nt
	s_add_u32 s14, s10, 0x600000
	s_addc_u32 s15, s11, 0
	global_store_short v213, v193, s[14:15] nt
	s_add_u32 s10, s10, 0x20000
	s_addc_u32 s11, s11, 0
	s_add_u32 s12, s12, 0x2000
	s_addc_u32 s13, s13, 0
	global_load_dwordx4 v[160:163], v212, s[8:9] offset:0 nt
	global_load_dwordx4 v[164:167], v212, s[8:9] offset:1024 nt
	global_load_dwordx4 v[168:171], v212, s[8:9] offset:2048 nt
	global_load_dwordx4 v[172:175], v212, s[8:9] offset:3072 nt
	s_add_u32 s8, s8, 0x800000
	s_addc_u32 s9, s9, 0
	v_max_f32_e32 v116, v32, v45
	v_min_f32_e32 v45, v32, v45
	v_max_f32_e32 v101, v33, v44
	v_min_f32_e32 v44, v33, v44
	v_max_f32_e32 v118, v34, v47
	v_min_f32_e32 v47, v34, v47
	v_max_f32_e32 v96, v35, v46
	v_min_f32_e32 v46, v35, v46
	v_max_f32_e32 v121, v36, v40
	v_min_f32_e32 v40, v36, v40
	v_max_f32_e32 v114, v37, v38
	v_min_f32_e32 v38, v37, v38
	v_max_f32_e32 v124, v39, v43
	v_min_f32_e32 v43, v39, v43
	v_max_f32_e32 v125, v41, v42
	v_min_f32_e32 v42, v41, v42
	v_max_f32_e32 v127, v116, v114
	v_min_f32_e32 v114, v116, v114
	v_max_f32_e32 v109, v101, v124
	v_min_f32_e32 v124, v101, v124
	v_max_f32_e32 v123, v118, v125
	v_min_f32_e32 v125, v118, v125
	v_max_f32_e32 v102, v96, v121
	v_min_f32_e32 v121, v96, v121
	v_max_f32_e32 v66, v38, v45
	v_min_f32_e32 v45, v38, v45
	v_max_f32_e32 v122, v40, v46
	v_min_f32_e32 v46, v40, v46
	v_max_f32_e32 v68, v42, v47
	v_min_f32_e32 v47, v42, v47
	v_max_f32_e32 v64, v43, v44
	v_min_f32_e32 v44, v43, v44
	v_max_f32_e32 v65, v127, v109
	v_min_f32_e32 v109, v127, v109
	v_max_f32_e32 v67, v123, v102
	v_min_f32_e32 v102, v123, v102
	v_max_f32_e32 v117, v121, v114
	v_min_f32_e32 v114, v121, v114
	v_max_f32_e32 v16, v66, v122
	v_min_f32_e32 v122, v66, v122
	v_max_f32_e32 v17, v124, v125
	v_min_f32_e32 v125, v124, v125
	v_max_f32_e32 v18, v68, v64
	v_min_f32_e32 v64, v68, v64
	v_max_f32_e32 v19, v44, v45
	v_min_f32_e32 v45, v44, v45
	v_max_f32_e32 v20, v46, v47
	v_min_f32_e32 v47, v46, v47
	v_max_f32_e32 v21, v65, v67
	v_min_f32_e32 v67, v65, v67
	v_max_f32_e32 v23, v109, v102
	v_min_f32_e32 v102, v109, v102
	v_max_f32_e32 v25, v117, v18
	v_min_f32_e32 v18, v117, v18
	v_max_f32_e32 v77, v114, v64
	v_min_f32_e32 v64, v114, v64
	v_max_f32_e32 v78, v16, v17
	v_min_f32_e32 v17, v16, v17
	v_max_f32_e32 v79, v122, v125
	v_min_f32_e32 v125, v122, v125
	v_max_f32_e32 v80, v19, v20
	v_min_f32_e32 v20, v19, v20
	v_max_f32_e32 v22, v45, v47
	v_min_f32_e32 v47, v45, v47
	v_max_f32_e32 v24, v23, v67
	v_min_f32_e32 v67, v23, v67
	v_max_f32_e32 v26, v102, v80
	v_min_f32_e32 v80, v102, v80
	v_max_f32_e32 v27, v25, v78
	v_min_f32_e32 v78, v25, v78
	v_max_f32_e32 v85, v77, v17
	v_min_f32_e32 v17, v77, v17
	v_max_f32_e32 v87, v79, v18
	v_min_f32_e32 v18, v79, v18
	v_max_f32_e32 v81, v125, v64
	v_min_f32_e32 v64, v125, v64
	v_max_f32_e32 v89, v22, v20
	v_min_f32_e32 v20, v22, v20
	v_max_f32_e32 v83, v24, v27
	v_min_f32_e32 v27, v24, v27
	v_max_f32_e32 v91, v67, v78
	v_min_f32_e32 v78, v67, v78
	v_max_f32_e32 v28, v85, v87
	v_min_f32_e32 v87, v85, v87
	v_max_f32_e32 v30, v17, v18
	v_min_f32_e32 v18, v17, v18
	v_max_f32_e32 v93, v81, v89
	v_min_f32_e32 v89, v81, v89
	v_max_f32_e32 v86, v64, v20
	v_min_f32_e32 v20, v64, v20
	v_max_f32_e32 v95, v91, v27
	v_min_f32_e32 v27, v91, v27
	v_max_f32_e32 v82, v26, v78
	v_min_f32_e32 v78, v26, v78
	v_max_f32_e32 v0, v93, v80
	v_min_f32_e32 v80, v93, v80
	v_max_f32_e32 v90, v86, v89
	v_min_f32_e32 v89, v86, v89
	v_max_f32_e32 v3, v82, v28
	v_min_f32_e32 v28, v82, v28
	v_max_f32_e32 v29, v78, v87
	v_min_f32_e32 v87, v78, v87
	v_max_f32_e32 v7, v30, v0
	v_min_f32_e32 v0, v30, v0
	v_max_f32_e32 v88, v18, v80
	v_min_f32_e32 v80, v18, v80
	v_max_f32_e32 v9, v3, v27
	v_min_f32_e32 v27, v3, v27
	v_max_f32_e32 v144, v28, v29
	v_min_f32_e32 v29, v28, v29
	v_max_f32_e32 v146, v7, v87
	v_min_f32_e32 v87, v7, v87
	v_max_f32_e32 v84, v0, v88
	v_min_f32_e32 v88, v0, v88
	v_max_f32_e32 v6, v90, v80
	v_min_f32_e32 v80, v90, v80
	v_max_f32_e32 v8, v29, v146
	v_min_f32_e32 v146, v29, v146
	v_max_f32_e32 v94, v87, v84
	v_min_f32_e32 v84, v87, v84
	v_max_f32_e32 v249, v48, v61
	v_min_f32_e32 v61, v48, v61
	v_max_f32_e32 v1, v49, v60
	v_min_f32_e32 v60, v49, v60
	v_max_f32_e32 v148, v50, v63
	v_min_f32_e32 v63, v50, v63
	v_max_f32_e32 v92, v51, v62
	v_min_f32_e32 v62, v51, v62
	v_max_f32_e32 v255, v52, v56
	v_min_f32_e32 v56, v52, v56
	v_max_f32_e32 v10, v53, v54
	v_min_f32_e32 v54, v53, v54
	v_max_f32_e32 v97, v55, v59
	v_min_f32_e32 v59, v55, v59
	v_max_f32_e32 v250, v57, v58
	v_min_f32_e32 v58, v57, v58
	v_max_f32_e32 v149, v249, v10
	v_min_f32_e32 v10, v249, v10
	v_max_f32_e32 v145, v1, v97
	v_min_f32_e32 v97, v1, v97
	v_max_f32_e32 v14, v148, v250
	v_min_f32_e32 v250, v148, v250
	v_max_f32_e32 v2, v92, v255
	v_min_f32_e32 v255, v92, v255
	v_max_f32_e32 v103, v54, v61
	v_min_f32_e32 v61, v54, v61
	v_max_f32_e32 v12, v56, v62
	v_min_f32_e32 v62, v56, v62
	v_max_f32_e32 v106, v58, v63
	v_min_f32_e32 v63, v58, v63
	v_max_f32_e32 v100, v59, v60
	v_min_f32_e32 v60, v59, v60
	v_max_f32_e32 v254, v149, v145
	v_min_f32_e32 v145, v149, v145
	v_max_f32_e32 v13, v14, v2
	v_min_f32_e32 v2, v14, v2
	v_max_f32_e32 v251, v255, v10
	v_min_f32_e32 v10, v255, v10
	v_max_f32_e32 v32, v103, v12
	v_min_f32_e32 v12, v103, v12
	v_max_f32_e32 v33, v97, v250
	v_min_f32_e32 v250, v97, v250
	v_max_f32_e32 v34, v106, v100
	v_min_f32_e32 v100, v106, v100
	v_max_f32_e32 v35, v60, v61
	v_min_f32_e32 v61, v60, v61
	v_max_f32_e32 v36, v62, v63
	v_min_f32_e32 v63, v62, v63
	v_max_f32_e32 v37, v254, v13
	v_min_f32_e32 v13, v254, v13
	v_max_f32_e32 v39, v145, v2
	v_min_f32_e32 v2, v145, v2
	v_max_f32_e32 v41, v251, v34
	v_min_f32_e32 v34, v251, v34
	v_max_f32_e32 v116, v10, v100
	v_min_f32_e32 v100, v10, v100
	v_max_f32_e32 v101, v32, v33
	v_min_f32_e32 v33, v32, v33
	v_max_f32_e32 v118, v12, v250
	v_min_f32_e32 v250, v12, v250
	v_max_f32_e32 v96, v35, v36
	v_min_f32_e32 v36, v35, v36
	v_max_f32_e32 v38, v61, v63
	v_min_f32_e32 v63, v61, v63
	v_max_f32_e32 v40, v39, v13
	v_min_f32_e32 v13, v39, v13
	v_max_f32_e32 v42, v2, v96
	v_min_f32_e32 v96, v2, v96
	v_max_f32_e32 v43, v41, v101
	v_min_f32_e32 v101, v41, v101
	v_max_f32_e32 v127, v116, v33
	v_min_f32_e32 v33, v116, v33
	v_max_f32_e32 v123, v118, v34
	v_min_f32_e32 v34, v118, v34
	v_max_f32_e32 v121, v250, v100
	v_min_f32_e32 v100, v250, v100
	v_max_f32_e32 v66, v38, v36
	v_min_f32_e32 v36, v38, v36
	v_max_f32_e32 v124, v40, v43
	v_min_f32_e32 v43, v40, v43
	v_max_f32_e32 v68, v13, v101
	v_min_f32_e32 v101, v13, v101
	v_max_f32_e32 v44, v127, v123
	v_min_f32_e32 v123, v127, v123
	v_max_f32_e32 v46, v33, v34
	v_min_f32_e32 v34, v33, v34
	v_max_f32_e32 v65, v121, v66
	v_min_f32_e32 v66, v121, v66
	v_max_f32_e32 v109, v100, v36
	v_min_f32_e32 v36, v100, v36
	v_max_f32_e32 v117, v68, v43
	v_min_f32_e32 v43, v68, v43
	v_max_f32_e32 v114, v42, v101
	v_min_f32_e32 v101, v42, v101
	v_max_f32_e32 v16, v65, v96
	v_min_f32_e32 v96, v65, v96
	v_max_f32_e32 v122, v109, v66
	v_min_f32_e32 v66, v109, v66
	v_max_f32_e32 v19, v114, v44
	v_min_f32_e32 v44, v114, v44
	v_max_f32_e32 v45, v101, v123
	v_min_f32_e32 v123, v101, v123
	v_max_f32_e32 v23, v46, v16
	v_min_f32_e32 v16, v46, v16
	v_max_f32_e32 v102, v34, v96
	v_min_f32_e32 v96, v34, v96
	v_max_f32_e32 v25, v19, v43
	v_min_f32_e32 v43, v19, v43
	v_max_f32_e32 v77, v44, v45
	v_min_f32_e32 v45, v44, v45
	v_max_f32_e32 v79, v23, v123
	v_min_f32_e32 v123, v23, v123
	v_max_f32_e32 v125, v16, v102
	v_min_f32_e32 v102, v16, v102
	v_max_f32_e32 v22, v122, v96
	v_min_f32_e32 v96, v122, v96
	v_max_f32_e32 v24, v45, v79
	v_min_f32_e32 v79, v45, v79
	v_max_f32_e32 v67, v123, v125
	v_min_f32_e32 v125, v123, v125
	s_waitcnt vmcnt(0)
	v_pk_mul_f32 v[160:161], v[160:161], v[176:177]
	v_pk_mul_f32 v[162:163], v[162:163], v[178:179]
	v_pk_mul_f32 v[164:165], v[164:165], v[180:181]
	v_pk_mul_f32 v[166:167], v[166:167], v[182:183]
	v_pk_mul_f32 v[168:169], v[168:169], v[184:185]
	v_pk_mul_f32 v[170:171], v[170:171], v[186:187]
	v_pk_mul_f32 v[172:173], v[172:173], v[188:189]
	v_pk_mul_f32 v[174:175], v[174:175], v[190:191]
	v_max3_f32 v192, |v160|, |v161|, |v162|
	v_max3_f32 v192, |v163|, |v164|, v192
	v_max3_f32 v192, |v165|, |v166|, v192
	v_max3_f32 v192, |v167|, |v168|, v192
	v_max3_f32 v192, |v169|, |v170|, v192
	v_max3_f32 v192, |v171|, |v172|, v192
	v_max3_f32 v192, |v173|, |v174|, v192
	v_max_f32_e64 v192, |v175|, v192
	s_nop 1
	v_mov_b32_dpp v193, v192 quad_perm:[1,0,3,2] row_mask:0xf bank_mask:0xf bound_ctrl:1
	v_max_f32_e32 v192, v192, v193
	s_nop 1
	v_mov_b32_dpp v193, v192 quad_perm:[2,3,0,1] row_mask:0xf bank_mask:0xf bound_ctrl:1
	v_max_f32_e32 v192, v192, v193
	s_nop 1
	v_mov_b32_dpp v193, v192 row_half_mirror row_mask:0xf bank_mask:0xf bound_ctrl:1
	v_max_f32_e32 v192, v192, v193
	s_nop 1
	v_mov_b32_dpp v193, v192 row_mirror row_mask:0xf bank_mask:0xf bound_ctrl:1
	v_max_f32_e32 v192, v192, v193
	v_mov_b32_e32 v193, v192
	s_nop 1
	v_permlane16_swap_b32_e32 v192, v193
	s_nop 1
	v_max_f32_e32 v192, v192, v193
	v_mov_b32_e32 v193, v192
	s_nop 1
	v_permlane32_swap_b32_e32 v192, v193
	s_nop 1
	v_max_f32_e32 v192, v192, v193
	v_max_f32_e32 v192, 0xda24260, v192
	v_mul_f32_e32 v194, 0x3e2aaaab, v192
	global_store_dword v214, v194, s[12:13]
	v_div_scale_f32 v195, s[26:27], v194, v194, 1.0
	v_rcp_f32_e32 v196, v195
	v_div_scale_f32 v204, vcc, 1.0, v194, 1.0
	v_fma_f32 v205, -v195, v196, 1.0
	v_fmac_f32_e32 v196, v205, v196
	v_mul_f32_e32 v205, v204, v196
	v_fma_f32 v206, -v195, v205, v204
	v_fmac_f32_e32 v205, v206, v196
	v_fma_f32 v195, -v195, v205, v204
	s_nop 0
	v_div_fmas_f32 v195, v195, v196, v205
	v_div_fixup_f32 v207, v195, v194, 1.0
	v_mul_f32_e32 v160, v207, v160
	v_mul_f32_e32 v161, v207, v161
	v_mul_f32_e32 v162, v207, v162
	v_mul_f32_e32 v163, v207, v163
	v_mul_f32_e32 v164, v207, v164
	v_mul_f32_e32 v165, v207, v165
	v_mul_f32_e32 v166, v207, v166
	v_mul_f32_e32 v167, v207, v167
	v_mul_f32_e32 v168, v207, v168
	v_mul_f32_e32 v169, v207, v169
	v_mul_f32_e32 v170, v207, v170
	v_mul_f32_e32 v171, v207, v171
	v_mul_f32_e32 v172, v207, v172
	v_mul_f32_e32 v173, v207, v173
	v_mul_f32_e32 v174, v207, v174
	v_mul_f32_e32 v175, v207, v175
	v_mov_b32_e32 v208, 0
	v_mov_b32_e32 v209, 0
	v_mov_b32_e32 v210, 0
	v_mov_b32_e32 v193, 0
	v_cvt_scalef32_pk_fp4_f32 v208, v160, v161, 1.0
	v_cvt_scalef32_pk_fp4_f32 v209, v164, v165, 1.0
	v_cvt_scalef32_pk_fp4_f32 v210, v168, v169, 1.0
	v_cvt_scalef32_pk_fp4_f32 v193, v172, v173, 1.0
	v_cvt_scalef32_pk_fp4_f32 v208, v162, v163, 1.0 op_sel:[0,0,1,0]
	v_cvt_scalef32_pk_fp4_f32 v209, v166, v167, 1.0 op_sel:[0,0,1,0]
	v_cvt_scalef32_pk_fp4_f32 v210, v170, v171, 1.0 op_sel:[0,0,1,0]
	v_cvt_scalef32_pk_fp4_f32 v193, v174, v175, 1.0 op_sel:[0,0,1,0]
	global_store_short v213, v208, s[10:11] nt
	s_add_u32 s14, s10, 0x200000
	s_addc_u32 s15, s11, 0
	global_store_short v213, v209, s[14:15] nt
	s_add_u32 s14, s10, 0x400000
	s_addc_u32 s15, s11, 0
	global_store_short v213, v210, s[14:15] nt
	s_add_u32 s14, s10, 0x600000
	s_addc_u32 s15, s11, 0
	global_store_short v213, v193, s[14:15] nt
	s_add_u32 s10, s10, 0x20000
	s_addc_u32 s11, s11, 0
	s_add_u32 s12, s12, 0x2000
	s_addc_u32 s13, s13, 0
	global_load_dwordx4 v[160:163], v212, s[8:9] offset:0 nt
	global_load_dwordx4 v[164:167], v212, s[8:9] offset:1024 nt
	global_load_dwordx4 v[168:171], v212, s[8:9] offset:2048 nt
	global_load_dwordx4 v[172:175], v212, s[8:9] offset:3072 nt
	s_add_u32 s8, s8, 0x800000
	s_addc_u32 s9, s9, 0
	v_max_f32_e32 v105, v105, v31
	v_max_f32_e32 v120, v120, v4
	v_max_f32_e32 v126, v126, v253
	v_max_f32_e32 v70, v70, v147
	v_max_f32_e32 v115, v115, v112
	v_max_f32_e32 v71, v71, v252
	v_max_f32_e32 v75, v75, v151
	v_max_f32_e32 v72, v72, v98
	v_max_f32_e32 v76, v76, v110
	v_max_f32_e32 v73, v73, v113
	v_max_f32_e32 v69, v69, v108
	v_max_f32_e32 v74, v74, v11
	v_max_f32_e32 v111, v111, v107
	v_max_f32_e32 v119, v119, v99
	v_max_f32_e32 v104, v104, v150
	v_max_f32_e32 v15, v15, v5
	v_max_f32_e32 v85, v105, v76
	v_min_f32_e32 v76, v105, v76
	v_max_f32_e32 v17, v120, v73
	v_min_f32_e32 v73, v120, v73
	v_max_f32_e32 v81, v126, v69
	v_min_f32_e32 v69, v126, v69
	v_max_f32_e32 v64, v70, v74
	v_min_f32_e32 v74, v70, v74
	v_max_f32_e32 v91, v115, v111
	v_min_f32_e32 v111, v115, v111
	v_max_f32_e32 v26, v71, v119
	v_min_f32_e32 v119, v71, v119
	v_max_f32_e32 v93, v75, v104
	v_min_f32_e32 v104, v75, v104
	v_max_f32_e32 v86, v72, v15
	v_min_f32_e32 v15, v72, v15
	v_max_f32_e32 v82, v85, v91
	v_min_f32_e32 v91, v85, v91
	v_max_f32_e32 v78, v17, v26
	v_min_f32_e32 v26, v17, v26
	v_max_f32_e32 v30, v81, v93
	v_min_f32_e32 v93, v81, v93
	v_max_f32_e32 v18, v64, v86
	v_min_f32_e32 v86, v64, v86
	v_max_f32_e32 v3, v76, v111
	v_min_f32_e32 v111, v76, v111
	v_max_f32_e32 v28, v73, v119
	v_min_f32_e32 v119, v73, v119
	v_max_f32_e32 v7, v69, v104
	v_min_f32_e32 v104, v69, v104
	v_max_f32_e32 v0, v74, v15
	v_min_f32_e32 v15, v74, v15
	v_max_f32_e32 v90, v82, v30
	v_min_f32_e32 v30, v82, v30
	v_max_f32_e32 v29, v78, v18
	v_min_f32_e32 v18, v78, v18
	v_max_f32_e32 v87, v91, v93
	v_min_f32_e32 v93, v91, v93
	v_max_f32_e32 v48, v26, v86
	v_min_f32_e32 v86, v26, v86
	v_max_f32_e32 v49, v3, v7
	v_min_f32_e32 v7, v3, v7
	v_max_f32_e32 v50, v28, v0
	v_min_f32_e32 v0, v28, v0
	v_max_f32_e32 v51, v111, v104
	v_min_f32_e32 v104, v111, v104
	v_max_f32_e32 v52, v119, v15
	v_min_f32_e32 v15, v119, v15
	v_max_f32_e32 v53, v90, v29
	v_min_f32_e32 v29, v90, v29
	v_max_f32_e32 v55, v30, v18
	v_min_f32_e32 v18, v30, v18
	v_max_f32_e32 v57, v87, v48
	v_min_f32_e32 v48, v87, v48
	v_max_f32_e32 v249, v93, v86
	v_min_f32_e32 v86, v93, v86
	v_max_f32_e32 v1, v49, v50
	v_min_f32_e32 v50, v49, v50
	v_max_f32_e32 v148, v7, v0
	v_min_f32_e32 v0, v7, v0
	v_max_f32_e32 v92, v51, v52
	v_min_f32_e32 v52, v51, v52
	v_max_f32_e32 v54, v104, v15
	v_min_f32_e32 v15, v104, v15
	v_max_f32_e32 v21, v21, v63
	v_max_f32_e32 v83, v83, v36
	v_max_f32_e32 v95, v95, v66
	v_max_f32_e32 v9, v9, v96
	v_max_f32_e32 v27, v27, v22
	v_max_f32_e32 v144, v144, v102
	v_max_f32_e32 v8, v8, v125
	v_max_f32_e32 v146, v146, v67
	v_max_f32_e32 v94, v94, v79
	v_max_f32_e32 v84, v84, v24
	v_max_f32_e32 v88, v88, v77
	v_max_f32_e32 v6, v6, v43
	v_max_f32_e32 v80, v80, v25
	v_max_f32_e32 v89, v89, v117
	v_max_f32_e32 v20, v20, v124
	v_max_f32_e32 v47, v47, v37
	v_max_f32_e32 v56, v21, v94
	v_min_f32_e32 v94, v21, v94
	v_max_f32_e32 v58, v83, v84
	v_min_f32_e32 v84, v83, v84
	v_max_f32_e32 v59, v95, v88
	v_min_f32_e32 v88, v95, v88
	v_max_f32_e32 v149, v9, v6
	v_min_f32_e32 v6, v9, v6
	v_max_f32_e32 v14, v27, v80
	v_min_f32_e32 v80, v27, v80
	v_max_f32_e32 v255, v144, v89
	v_min_f32_e32 v89, v144, v89
	v_max_f32_e32 v103, v8, v20
	v_min_f32_e32 v20, v8, v20
	v_max_f32_e32 v97, v146, v47
	v_min_f32_e32 v47, v146, v47
	v_max_f32_e32 v106, v56, v14
	v_min_f32_e32 v14, v56, v14
	v_max_f32_e32 v60, v58, v255
	v_min_f32_e32 v255, v58, v255
	v_max_f32_e32 v62, v59, v103
	v_min_f32_e32 v103, v59, v103
	v_max_f32_e32 v254, v149, v97
	v_min_f32_e32 v97, v149, v97
	v_max_f32_e32 v145, v94, v80
	v_min_f32_e32 v80, v94, v80
	v_max_f32_e32 v251, v84, v89
	v_min_f32_e32 v89, v84, v89
	v_max_f32_e32 v10, v88, v20
	v_min_f32_e32 v20, v88, v20
	v_max_f32_e32 v32, v6, v47
	v_min_f32_e32 v47, v6, v47
	v_max_f32_e32 v12, v106, v62
	v_min_f32_e32 v62, v106, v62
	v_max_f32_e32 v35, v60, v254
	v_min_f32_e32 v254, v60, v254
	v_max_f32_e32 v61, v14, v103
	v_min_f32_e32 v103, v14, v103
	v_max_f32_e32 v39, v255, v97
	v_min_f32_e32 v97, v255, v97
	v_max_f32_e32 v2, v145, v10
	v_min_f32_e32 v10, v145, v10
	v_max_f32_e32 v41, v251, v32
	v_min_f32_e32 v32, v251, v32
	v_max_f32_e32 v116, v80, v20
	v_min_f32_e32 v20, v80, v20
	v_max_f32_e32 v118, v89, v47
	v_min_f32_e32 v47, v89, v47
	v_max_f32_e32 v250, v12, v35
	v_min_f32_e32 v35, v12, v35
	v_max_f32_e32 v38, v62, v254
	v_min_f32_e32 v254, v62, v254
	v_max_f32_e32 v40, v61, v39
	v_min_f32_e32 v39, v61, v39
	v_max_f32_e32 v13, v103, v97
	v_min_f32_e32 v97, v103, v97
	v_max_f32_e32 v127, v2, v41
	v_min_f32_e32 v41, v2, v41
	v_max_f32_e32 v33, v10, v32
	v_min_f32_e32 v32, v10, v32
	v_max_f32_e32 v121, v116, v118
	v_min_f32_e32 v118, v116, v118
	v_max_f32_e32 v100, v20, v47
	v_min_f32_e32 v47, v20, v47
	v_max_f32_e32 v53, v53, v47
	v_max_f32_e32 v29, v29, v100
	v_max_f32_e32 v55, v55, v118
	v_max_f32_e32 v18, v18, v121
	v_max_f32_e32 v57, v57, v32
	v_max_f32_e32 v48, v48, v33
	v_max_f32_e32 v249, v249, v41
	v_max_f32_e32 v86, v86, v127
	v_max_f32_e32 v1, v1, v97
	v_max_f32_e32 v50, v50, v13
	v_max_f32_e32 v148, v148, v39
	v_max_f32_e32 v0, v0, v40
	v_max_f32_e32 v92, v92, v254
	v_max_f32_e32 v52, v52, v38
	v_max_f32_e32 v54, v54, v35
	v_max_f32_e32 v15, v15, v250
	v_max_f32_e32 v68, v53, v1
	v_min_f32_e32 v1, v53, v1
	v_max_f32_e32 v42, v29, v50
	v_min_f32_e32 v50, v29, v50
	v_max_f32_e32 v65, v55, v148
	v_min_f32_e32 v148, v55, v148
	v_max_f32_e32 v109, v18, v0
	v_min_f32_e32 v0, v18, v0
	v_max_f32_e32 v114, v57, v92
	v_min_f32_e32 v92, v57, v92
	v_max_f32_e32 v101, v48, v52
	v_min_f32_e32 v52, v48, v52
	v_max_f32_e32 v46, v249, v54
	v_min_f32_e32 v54, v249, v54
	v_max_f32_e32 v34, v86, v15
	v_min_f32_e32 v15, v86, v15
	v_max_f32_e32 v19, v68, v114
	v_min_f32_e32 v114, v68, v114
	v_max_f32_e32 v44, v42, v101
	v_min_f32_e32 v101, v42, v101
	v_max_f32_e32 v23, v65, v46
	v_min_f32_e32 v46, v65, v46
	v_max_f32_e32 v16, v109, v34
	v_min_f32_e32 v34, v109, v34
	v_max_f32_e32 v122, v1, v92
	v_min_f32_e32 v92, v1, v92
	v_max_f32_e32 v45, v50, v52
	v_min_f32_e32 v52, v50, v52
	v_max_f32_e32 v123, v148, v54
	v_min_f32_e32 v54, v148, v54
	v_max_f32_e32 v5, v0, v15
	v_min_f32_e32 v15, v0, v15
	v_max_f32_e32 v150, v19, v23
	v_min_f32_e32 v23, v19, v23
	v_max_f32_e32 v99, v44, v16
	v_min_f32_e32 v16, v44, v16
	v_max_f32_e32 v107, v114, v46
	v_min_f32_e32 v46, v114, v46
	v_max_f32_e32 v11, v101, v34
	v_min_f32_e32 v34, v101, v34
	v_max_f32_e32 v108, v122, v123
	v_min_f32_e32 v123, v122, v123
	v_max_f32_e32 v113, v45, v5
	v_min_f32_e32 v5, v45, v5
	v_max_f32_e32 v110, v92, v54
	v_min_f32_e32 v54, v92, v54
	v_max_f32_e32 v98, v52, v15
	v_min_f32_e32 v15, v52, v15
	v_max_f32_e32 v151, v150, v99
	v_min_f32_e32 v99, v150, v99
	v_max_f32_e32 v252, v23, v16
	v_min_f32_e32 v16, v23, v16
	v_max_f32_e32 v112, v107, v11
	v_min_f32_e32 v11, v107, v11
	v_max_f32_e32 v147, v46, v34
	v_min_f32_e32 v34, v46, v34
	v_max_f32_e32 v253, v108, v113
	v_min_f32_e32 v113, v108, v113
	v_max_f32_e32 v4, v123, v5
	v_min_f32_e32 v5, v123, v5
	v_max_f32_e32 v31, v110, v98
	v_min_f32_e32 v98, v110, v98
	v_max_f32_e32 v105, v54, v15
	v_min_f32_e32 v15, v54, v15
	v_mov_b32_e32 v120, v151
	v_mov_b32_e32 v126, v99
	v_mov_b32_e32 v70, v252
	v_mov_b32_e32 v115, v16
	v_mov_b32_e32 v71, v112
	v_mov_b32_e32 v75, v11
	v_mov_b32_e32 v72, v147
	v_mov_b32_e32 v85, v34
	v_mov_b32_e32 v17, v253
	v_mov_b32_e32 v81, v113
	v_mov_b32_e32 v64, v4
	v_mov_b32_e32 v76, v5
	v_mov_b32_e32 v73, v31
	v_mov_b32_e32 v69, v98
	v_mov_b32_e32 v74, v105
	v_mov_b32_e32 v82, v15
	s_nop 1
	v_permlane32_swap_b32_e32 v151, v120
	v_permlane32_swap_b32_e32 v99, v126
	v_permlane32_swap_b32_e32 v252, v70
	v_permlane32_swap_b32_e32 v16, v115
	v_permlane32_swap_b32_e32 v112, v71
	v_permlane32_swap_b32_e32 v11, v75
	v_permlane32_swap_b32_e32 v147, v72
	v_permlane32_swap_b32_e32 v34, v85
	v_permlane32_swap_b32_e32 v253, v17
	v_permlane32_swap_b32_e32 v113, v81
	v_permlane32_swap_b32_e32 v4, v64
	v_permlane32_swap_b32_e32 v5, v76
	v_permlane32_swap_b32_e32 v31, v73
	v_permlane32_swap_b32_e32 v98, v69
	v_permlane32_swap_b32_e32 v105, v74
	v_permlane32_swap_b32_e32 v15, v82
	s_nop 1
	v_max_f32_e32 v151, v151, v82
	v_max_f32_e32 v99, v99, v74
	v_max_f32_e32 v252, v252, v69
	v_max_f32_e32 v16, v16, v73
	v_max_f32_e32 v112, v112, v76
	v_max_f32_e32 v11, v11, v64
	v_max_f32_e32 v147, v147, v81
	v_max_f32_e32 v34, v34, v17
	v_max_f32_e32 v253, v253, v85
	v_max_f32_e32 v113, v113, v72
	v_max_f32_e32 v4, v4, v75
	v_max_f32_e32 v5, v5, v71
	v_max_f32_e32 v31, v31, v115
	v_max_f32_e32 v98, v98, v70
	v_max_f32_e32 v105, v105, v126
	v_max_f32_e32 v15, v15, v120
	v_max_f32_e32 v78, v151, v253
	v_min_f32_e32 v253, v151, v253
	v_max_f32_e32 v91, v99, v113
	v_min_f32_e32 v113, v99, v113
	v_max_f32_e32 v26, v252, v4
	v_min_f32_e32 v4, v252, v4
	v_max_f32_e32 v3, v16, v5
	v_min_f32_e32 v5, v16, v5
	v_max_f32_e32 v28, v112, v31
	v_min_f32_e32 v31, v112, v31
	v_max_f32_e32 v111, v11, v98
	v_min_f32_e32 v98, v11, v98
	v_max_f32_e32 v119, v147, v105
	v_min_f32_e32 v105, v147, v105
	v_max_f32_e32 v90, v34, v15
	v_min_f32_e32 v15, v34, v15
	v_max_f32_e32 v30, v78, v28
	v_min_f32_e32 v28, v78, v28
	v_max_f32_e32 v87, v91, v111
	v_min_f32_e32 v111, v91, v111
	v_max_f32_e32 v93, v26, v119
	v_min_f32_e32 v119, v26, v119
	v_max_f32_e32 v49, v3, v90
	v_min_f32_e32 v90, v3, v90
	v_max_f32_e32 v7, v253, v31
	v_min_f32_e32 v31, v253, v31
	v_max_f32_e32 v51, v113, v98
	v_min_f32_e32 v98, v113, v98
	v_max_f32_e32 v104, v4, v105
	v_min_f32_e32 v105, v4, v105
	v_max_f32_e32 v37, v5, v15
	v_min_f32_e32 v15, v5, v15
	v_max_f32_e32 v124, v30, v93
	v_min_f32_e32 v93, v30, v93
	v_max_f32_e32 v117, v87, v49
	v_min_f32_e32 v49, v87, v49
	v_max_f32_e32 v25, v28, v119
	v_min_f32_e32 v119, v28, v119
	v_max_f32_e32 v43, v111, v90
	v_min_f32_e32 v90, v111, v90
	v_max_f32_e32 v77, v7, v104
	v_min_f32_e32 v104, v7, v104
	v_max_f32_e32 v24, v51, v37
	v_min_f32_e32 v37, v51, v37
	v_max_f32_e32 v79, v31, v105
	v_min_f32_e32 v105, v31, v105
	v_max_f32_e32 v67, v98, v15
	v_min_f32_e32 v15, v98, v15
	v_max_f32_e32 v125, v124, v117
	v_min_f32_e32 v117, v124, v117
	v_max_f32_e32 v102, v93, v49
	v_min_f32_e32 v49, v93, v49
	v_max_f32_e32 v22, v25, v43
	v_min_f32_e32 v43, v25, v43
	v_max_f32_e32 v96, v119, v90
	v_min_f32_e32 v90, v119, v90
	v_max_f32_e32 v66, v77, v24
	v_min_f32_e32 v24, v77, v24
	v_max_f32_e32 v36, v104, v37
	v_min_f32_e32 v37, v104, v37
	v_max_f32_e32 v63, v79, v67
	v_min_f32_e32 v67, v79, v67
	v_max_f32_e32 v21, v105, v15
	v_min_f32_e32 v15, v105, v15
	s_waitcnt vmcnt(0)
	v_pk_mul_f32 v[160:161], v[160:161], v[176:177]
	v_pk_mul_f32 v[162:163], v[162:163], v[178:179]
	v_pk_mul_f32 v[164:165], v[164:165], v[180:181]
	v_pk_mul_f32 v[166:167], v[166:167], v[182:183]
	v_pk_mul_f32 v[168:169], v[168:169], v[184:185]
	v_pk_mul_f32 v[170:171], v[170:171], v[186:187]
	v_pk_mul_f32 v[172:173], v[172:173], v[188:189]
	v_pk_mul_f32 v[174:175], v[174:175], v[190:191]
	v_max3_f32 v192, |v160|, |v161|, |v162|
	v_max3_f32 v192, |v163|, |v164|, v192
	v_max3_f32 v192, |v165|, |v166|, v192
	v_max3_f32 v192, |v167|, |v168|, v192
	v_max3_f32 v192, |v169|, |v170|, v192
	v_max3_f32 v192, |v171|, |v172|, v192
	v_max3_f32 v192, |v173|, |v174|, v192
	v_max_f32_e64 v192, |v175|, v192
	s_nop 1
	v_mov_b32_dpp v193, v192 quad_perm:[1,0,3,2] row_mask:0xf bank_mask:0xf bound_ctrl:1
	v_max_f32_e32 v192, v192, v193
	s_nop 1
	v_mov_b32_dpp v193, v192 quad_perm:[2,3,0,1] row_mask:0xf bank_mask:0xf bound_ctrl:1
	v_max_f32_e32 v192, v192, v193
	s_nop 1
	v_mov_b32_dpp v193, v192 row_half_mirror row_mask:0xf bank_mask:0xf bound_ctrl:1
	v_max_f32_e32 v192, v192, v193
	s_nop 1
	v_mov_b32_dpp v193, v192 row_mirror row_mask:0xf bank_mask:0xf bound_ctrl:1
	v_max_f32_e32 v192, v192, v193
	v_mov_b32_e32 v193, v192
	s_nop 1
	v_permlane16_swap_b32_e32 v192, v193
	s_nop 1
	v_max_f32_e32 v192, v192, v193
	v_mov_b32_e32 v193, v192
	s_nop 1
	v_permlane32_swap_b32_e32 v192, v193
	s_nop 1
	v_max_f32_e32 v192, v192, v193
	v_max_f32_e32 v192, 0xda24260, v192
	v_mul_f32_e32 v194, 0x3e2aaaab, v192
	global_store_dword v214, v194, s[12:13]
	v_div_scale_f32 v195, s[26:27], v194, v194, 1.0
	v_rcp_f32_e32 v196, v195
	v_div_scale_f32 v204, vcc, 1.0, v194, 1.0
	v_fma_f32 v205, -v195, v196, 1.0
	v_fmac_f32_e32 v196, v205, v196
	v_mul_f32_e32 v205, v204, v196
	v_fma_f32 v206, -v195, v205, v204
	v_fmac_f32_e32 v205, v206, v196
	v_fma_f32 v195, -v195, v205, v204
	s_nop 0
	v_div_fmas_f32 v195, v195, v196, v205
	v_div_fixup_f32 v207, v195, v194, 1.0
	v_mul_f32_e32 v160, v207, v160
	v_mul_f32_e32 v161, v207, v161
	v_mul_f32_e32 v162, v207, v162
	v_mul_f32_e32 v163, v207, v163
	v_mul_f32_e32 v164, v207, v164
	v_mul_f32_e32 v165, v207, v165
	v_mul_f32_e32 v166, v207, v166
	v_mul_f32_e32 v167, v207, v167
	v_mul_f32_e32 v168, v207, v168
	v_mul_f32_e32 v169, v207, v169
	v_mul_f32_e32 v170, v207, v170
	v_mul_f32_e32 v171, v207, v171
	v_mul_f32_e32 v172, v207, v172
	v_mul_f32_e32 v173, v207, v173
	v_mul_f32_e32 v174, v207, v174
	v_mul_f32_e32 v175, v207, v175
	v_mov_b32_e32 v208, 0
	v_mov_b32_e32 v209, 0
	v_mov_b32_e32 v210, 0
	v_mov_b32_e32 v193, 0
	v_cvt_scalef32_pk_fp4_f32 v208, v160, v161, 1.0
	v_cvt_scalef32_pk_fp4_f32 v209, v164, v165, 1.0
	v_cvt_scalef32_pk_fp4_f32 v210, v168, v169, 1.0
	v_cvt_scalef32_pk_fp4_f32 v193, v172, v173, 1.0
	v_cvt_scalef32_pk_fp4_f32 v208, v162, v163, 1.0 op_sel:[0,0,1,0]
	v_cvt_scalef32_pk_fp4_f32 v209, v166, v167, 1.0 op_sel:[0,0,1,0]
	v_cvt_scalef32_pk_fp4_f32 v210, v170, v171, 1.0 op_sel:[0,0,1,0]
	v_cvt_scalef32_pk_fp4_f32 v193, v174, v175, 1.0 op_sel:[0,0,1,0]
	global_store_short v213, v208, s[10:11] nt
	s_add_u32 s14, s10, 0x200000
	s_addc_u32 s15, s11, 0
	global_store_short v213, v209, s[14:15] nt
	s_add_u32 s14, s10, 0x400000
	s_addc_u32 s15, s11, 0
	global_store_short v213, v210, s[14:15] nt
	s_add_u32 s14, s10, 0x600000
	s_addc_u32 s15, s11, 0
	global_store_short v213, v193, s[14:15] nt
	s_add_u32 s10, s10, 0x20000
	s_addc_u32 s11, s11, 0
	s_add_u32 s12, s12, 0x2000
	s_addc_u32 s13, s13, 0
	global_load_dwordx4 v[160:163], v212, s[8:9] offset:0 nt
	global_load_dwordx4 v[164:167], v212, s[8:9] offset:1024 nt
	global_load_dwordx4 v[168:171], v212, s[8:9] offset:2048 nt
	global_load_dwordx4 v[172:175], v212, s[8:9] offset:3072 nt
	s_add_u32 s8, s8, 0x800000
	s_addc_u32 s9, s9, 0
	ds_write_b8 v240, v125 offset:512
	ds_write_b8 v240, v117 offset:513
	ds_write_b8 v240, v102 offset:514
	ds_write_b8 v240, v49 offset:515
	ds_write_b8 v240, v22 offset:516
	ds_write_b8 v240, v43 offset:517
	ds_write_b8 v240, v96 offset:518
	ds_write_b8 v240, v90 offset:519
	ds_write_b8 v240, v66 offset:520
	ds_write_b8 v240, v24 offset:521
	ds_write_b8 v240, v36 offset:522
	ds_write_b8 v240, v37 offset:523
	ds_write_b8 v240, v63 offset:524
	ds_write_b8 v240, v67 offset:525
	ds_write_b8 v240, v21 offset:526
	ds_write_b8 v240, v15 offset:527
	v_cndmask_b32_e64 v0, v128, v125, s[4:5]
	v_cndmask_b32_e64 v17, v125, v128, s[4:5]
	v_cndmask_b32_e64 v1, v129, v117, s[4:5]
	v_cndmask_b32_e64 v18, v117, v129, s[4:5]
	v_cndmask_b32_e64 v2, v130, v102, s[4:5]
	v_cndmask_b32_e64 v19, v102, v130, s[4:5]
	v_cndmask_b32_e64 v3, v131, v49, s[4:5]
	v_cndmask_b32_e64 v20, v49, v131, s[4:5]
	v_cndmask_b32_e64 v4, v132, v22, s[4:5]
	v_cndmask_b32_e64 v23, v22, v132, s[4:5]
	v_cndmask_b32_e64 v5, v133, v43, s[4:5]
	v_cndmask_b32_e64 v25, v43, v133, s[4:5]
	v_cndmask_b32_e64 v6, v134, v96, s[4:5]
	v_cndmask_b32_e64 v26, v96, v134, s[4:5]
	v_cndmask_b32_e64 v7, v135, v90, s[4:5]
	v_cndmask_b32_e64 v27, v90, v135, s[4:5]
	v_cndmask_b32_e64 v8, v136, v66, s[4:5]
	v_cndmask_b32_e64 v28, v66, v136, s[4:5]
	v_cndmask_b32_e64 v9, v137, v24, s[4:5]
	v_cndmask_b32_e64 v29, v24, v137, s[4:5]
	v_cndmask_b32_e64 v10, v138, v36, s[4:5]
	v_cndmask_b32_e64 v30, v36, v138, s[4:5]
	v_cndmask_b32_e64 v11, v139, v37, s[4:5]
	v_cndmask_b32_e64 v31, v37, v139, s[4:5]
	v_cndmask_b32_e64 v12, v140, v63, s[4:5]
	v_cndmask_b32_e64 v32, v63, v140, s[4:5]
	v_cndmask_b32_e64 v13, v141, v67, s[4:5]
	v_cndmask_b32_e64 v33, v67, v141, s[4:5]
	v_cndmask_b32_e64 v14, v142, v21, s[4:5]
	v_cndmask_b32_e64 v34, v21, v142, s[4:5]
	v_cndmask_b32_e64 v16, v143, v15, s[4:5]
	v_cndmask_b32_e64 v35, v15, v143, s[4:5]
	v_and_b32_e32 v0, s6, v0
	v_and_b32_e32 v17, s6, v17
	v_and_b32_e32 v1, s6, v1
	v_and_b32_e32 v18, s6, v18
	v_and_b32_e32 v2, s6, v2
	v_and_b32_e32 v19, s6, v19
	v_and_b32_e32 v3, s6, v3
	v_and_b32_e32 v20, s6, v20
	v_and_b32_e32 v4, s6, v4
	v_and_b32_e32 v23, s6, v23
	v_and_b32_e32 v5, s6, v5
	v_and_b32_e32 v25, s6, v25
	v_and_b32_e32 v6, s6, v6
	v_and_b32_e32 v26, s6, v26
	v_and_b32_e32 v7, s6, v7
	v_and_b32_e32 v27, s6, v27
	v_and_b32_e32 v8, s6, v8
	v_and_b32_e32 v28, s6, v28
	v_and_b32_e32 v9, s6, v9
	v_and_b32_e32 v29, s6, v29
	v_and_b32_e32 v10, s6, v10
	v_and_b32_e32 v30, s6, v30
	v_and_b32_e32 v11, s6, v11
	v_and_b32_e32 v31, s6, v31
	v_and_b32_e32 v12, s6, v12
	v_and_b32_e32 v32, s6, v32
	v_and_b32_e32 v13, s6, v13
	v_and_b32_e32 v33, s6, v33
	v_and_b32_e32 v14, s6, v14
	v_and_b32_e32 v34, s6, v34
	v_and_b32_e32 v16, s6, v16
	v_and_b32_e32 v35, s6, v35
	v_add_f32_e32 v38, v0, v18
	v_and_or_b32 v38, v38, s7, 0
	v_add_f32_e32 v39, v0, v19
	v_and_or_b32 v39, v39, s7, 2
	v_add_f32_e32 v40, v0, v20
	v_and_or_b32 v40, v40, s7, 4
	v_add_f32_e32 v41, v0, v23
	v_and_or_b32 v41, v41, s7, 6
	v_add_f32_e32 v42, v0, v25
	v_and_or_b32 v42, v42, s7, 8
	v_add_f32_e32 v44, v0, v26
	v_and_or_b32 v44, v44, s7, 10
	v_add_f32_e32 v45, v0, v27
	v_and_or_b32 v45, v45, s7, 12
	v_add_f32_e32 v46, v0, v28
	v_and_or_b32 v46, v46, s7, 14
	v_add_f32_e32 v47, v0, v29
	v_and_or_b32 v47, v47, s7, 16
	v_add_f32_e32 v48, v0, v30
	v_and_or_b32 v48, v48, s7, 18
	v_add_f32_e32 v50, v0, v31
	v_and_or_b32 v50, v50, s7, 20
	v_add_f32_e32 v51, v0, v32
	v_and_or_b32 v51, v51, s7, 22
	v_add_f32_e32 v52, v0, v33
	v_and_or_b32 v52, v52, s7, 24
	v_add_f32_e32 v53, v0, v34
	v_and_or_b32 v53, v53, s7, 26
	v_add_f32_e32 v54, v0, v35
	v_and_or_b32 v54, v54, s7, 28
	v_add_f32_e32 v55, v1, v19
	v_and_or_b32 v55, v55, s7, 30
	v_add_f32_e32 v56, v1, v20
	v_and_or_b32 v56, v56, s7, 32
	v_add_f32_e32 v57, v1, v23
	v_and_or_b32 v57, v57, s7, 34
	v_add_f32_e32 v58, v1, v25
	v_and_or_b32 v58, v58, s7, 36
	v_add_f32_e32 v59, v1, v26
	v_and_or_b32 v59, v59, s7, 38
	v_add_f32_e32 v60, v1, v27
	v_and_or_b32 v60, v60, s7, 40
	v_add_f32_e32 v61, v2, v20
	v_and_or_b32 v61, v61, s7, 42
	v_add_f32_e32 v62, v2, v23
	v_and_or_b32 v62, v62, s7, 44
	v_add_f32_e32 v64, v0, v17
	v_and_or_b32 v64, v64, s7, 46
	v_cndmask_b32_e64 v64, v64, v244, s[4:5]
	v_add_f32_e32 v65, v1, v18
	v_and_or_b32 v65, v65, s7, 48
	v_cndmask_b32_e64 v65, v65, v244, s[4:5]
	v_add_f32_e32 v68, v2, v19
	v_and_or_b32 v68, v68, s7, 50
	v_cndmask_b32_e64 v68, v68, v244, s[4:5]
	v_add_f32_e32 v69, v3, v20
	v_and_or_b32 v69, v69, s7, 52
	v_cndmask_b32_e64 v69, v69, v244, s[4:5]
	v_max_f32_e32 v70, v38, v53
	v_min_f32_e32 v53, v38, v53
	v_max_f32_e32 v71, v39, v52
	v_min_f32_e32 v52, v39, v52
	v_max_f32_e32 v72, v40, v55
	v_min_f32_e32 v55, v40, v55
	v_max_f32_e32 v73, v41, v54
	v_min_f32_e32 v54, v41, v54
	v_max_f32_e32 v74, v42, v47
	v_min_f32_e32 v47, v42, v47
	v_max_f32_e32 v75, v44, v45
	v_min_f32_e32 v45, v44, v45
	v_max_f32_e32 v76, v46, v51
	v_min_f32_e32 v51, v46, v51
	v_max_f32_e32 v77, v48, v50
	v_min_f32_e32 v50, v48, v50
	v_max_f32_e32 v78, v70, v75
	v_min_f32_e32 v75, v70, v75
	v_max_f32_e32 v79, v71, v76
	v_min_f32_e32 v76, v71, v76
	v_max_f32_e32 v80, v72, v77
	v_min_f32_e32 v77, v72, v77
	v_max_f32_e32 v81, v73, v74
	v_min_f32_e32 v74, v73, v74
	v_max_f32_e32 v82, v45, v53
	v_min_f32_e32 v53, v45, v53
	v_max_f32_e32 v83, v47, v54
	v_min_f32_e32 v54, v47, v54
	v_max_f32_e32 v84, v50, v55
	v_min_f32_e32 v55, v50, v55
	v_max_f32_e32 v85, v51, v52
	v_min_f32_e32 v52, v51, v52
	v_max_f32_e32 v86, v78, v79
	v_min_f32_e32 v79, v78, v79
	v_max_f32_e32 v87, v80, v81
	v_min_f32_e32 v81, v80, v81
	v_max_f32_e32 v88, v74, v75
	v_min_f32_e32 v75, v74, v75
	v_max_f32_e32 v89, v82, v83
	v_min_f32_e32 v83, v82, v83
	v_max_f32_e32 v91, v76, v77
	v_min_f32_e32 v77, v76, v77
	v_max_f32_e32 v92, v84, v85
	v_min_f32_e32 v85, v84, v85
	v_max_f32_e32 v93, v52, v53
	v_min_f32_e32 v53, v52, v53
	v_max_f32_e32 v94, v54, v55
	v_min_f32_e32 v55, v54, v55
	v_max_f32_e32 v95, v86, v87
	v_min_f32_e32 v87, v86, v87
	v_max_f32_e32 v97, v79, v81
	v_min_f32_e32 v81, v79, v81
	v_max_f32_e32 v98, v88, v92
	v_min_f32_e32 v92, v88, v92
	v_max_f32_e32 v99, v75, v85
	v_min_f32_e32 v85, v75, v85
	v_max_f32_e32 v100, v89, v91
	v_min_f32_e32 v91, v89, v91
	v_max_f32_e32 v101, v83, v77
	v_min_f32_e32 v77, v83, v77
	v_max_f32_e32 v103, v93, v94
	v_min_f32_e32 v94, v93, v94
	v_max_f32_e32 v104, v53, v55
	v_min_f32_e32 v55, v53, v55
	v_max_f32_e32 v105, v97, v87
	v_min_f32_e32 v87, v97, v87
	v_max_f32_e32 v106, v81, v103
	v_min_f32_e32 v103, v81, v103
	v_max_f32_e32 v107, v98, v100
	v_min_f32_e32 v100, v98, v100
	v_max_f32_e32 v108, v99, v91
	v_min_f32_e32 v91, v99, v91
	v_max_f32_e32 v109, v101, v92
	v_min_f32_e32 v92, v101, v92
	v_max_f32_e32 v110, v77, v85
	v_min_f32_e32 v85, v77, v85
	v_max_f32_e32 v111, v104, v94
	v_min_f32_e32 v94, v104, v94
	v_max_f32_e32 v112, v105, v107
	v_min_f32_e32 v107, v105, v107
	v_max_f32_e32 v113, v87, v100
	v_min_f32_e32 v100, v87, v100
	v_max_f32_e32 v114, v108, v109
	v_min_f32_e32 v109, v108, v109
	v_max_f32_e32 v115, v91, v92
	v_min_f32_e32 v92, v91, v92
	v_max_f32_e32 v116, v110, v111
	v_min_f32_e32 v111, v110, v111
	v_max_f32_e32 v118, v85, v94
	v_min_f32_e32 v94, v85, v94
	v_max_f32_e32 v119, v113, v107
	v_min_f32_e32 v107, v113, v107
	v_max_f32_e32 v120, v106, v100
	v_min_f32_e32 v100, v106, v100
	v_max_f32_e32 v121, v116, v103
	v_min_f32_e32 v103, v116, v103
	v_max_f32_e32 v122, v118, v111
	v_min_f32_e32 v111, v118, v111
	v_max_f32_e32 v123, v120, v114
	v_min_f32_e32 v114, v120, v114
	v_max_f32_e32 v124, v100, v109
	v_min_f32_e32 v109, v100, v109
	v_max_f32_e32 v126, v115, v121
	v_min_f32_e32 v121, v115, v121
	v_max_f32_e32 v127, v92, v103
	v_min_f32_e32 v103, v92, v103
	v_max_f32_e32 v144, v123, v107
	v_min_f32_e32 v107, v123, v107
	v_max_f32_e32 v145, v114, v124
	v_min_f32_e32 v124, v114, v124
	v_max_f32_e32 v146, v126, v109
	v_min_f32_e32 v109, v126, v109
	v_max_f32_e32 v147, v121, v127
	v_min_f32_e32 v127, v121, v127
	v_max_f32_e32 v148, v122, v103
	v_min_f32_e32 v103, v122, v103
	v_max_f32_e32 v149, v124, v146
	v_min_f32_e32 v146, v124, v146
	v_max_f32_e32 v150, v109, v147
	v_min_f32_e32 v147, v109, v147
	v_max_f32_e32 v151, v60, v65
	v_min_f32_e32 v65, v60, v65
	v_max_f32_e32 v249, v61, v62
	v_min_f32_e32 v62, v61, v62
	v_max_f32_e32 v250, v68, v69
	v_min_f32_e32 v69, v68, v69
	v_max_f32_e32 v251, v56, v249
	v_min_f32_e32 v249, v56, v249
	v_max_f32_e32 v252, v57, v64
	v_min_f32_e32 v64, v57, v64
	v_max_f32_e32 v253, v58, v250
	v_min_f32_e32 v250, v58, v250
	v_max_f32_e32 v254, v59, v151
	v_min_f32_e32 v151, v59, v151
	v_max_f32_e32 v255, v251, v252
	v_min_f32_e32 v252, v251, v252
	v_max_f32_e32 v128, v253, v254
	v_min_f32_e32 v254, v253, v254
	v_max_f32_e32 v129, v151, v249
	v_min_f32_e32 v249, v151, v249
	v_max_f32_e32 v130, v62, v65
	v_min_f32_e32 v65, v62, v65
	v_max_f32_e32 v131, v64, v250
	v_min_f32_e32 v250, v64, v250
	v_max_f32_e32 v132, v255, v128
	v_min_f32_e32 v128, v255, v128
	v_max_f32_e32 v133, v252, v254
	v_min_f32_e32 v254, v252, v254
	v_max_f32_e32 v134, v129, v69
	v_min_f32_e32 v69, v129, v69
	v_max_f32_e32 v135, v130, v131
	v_min_f32_e32 v131, v130, v131
	v_max_f32_e32 v136, v65, v250
	v_min_f32_e32 v250, v65, v250
	v_max_f32_e32 v137, v133, v128
	v_min_f32_e32 v128, v133, v128
	v_max_f32_e32 v138, v134, v135
	v_min_f32_e32 v135, v134, v135
	v_max_f32_e32 v139, v249, v131
	v_min_f32_e32 v131, v249, v131
	v_max_f32_e32 v140, v136, v69
	v_min_f32_e32 v69, v136, v69
	v_max_f32_e32 v141, v137, v138
	v_min_f32_e32 v138, v137, v138
	v_max_f32_e32 v142, v128, v135
	v_min_f32_e32 v135, v128, v135
	v_max_f32_e32 v143, v139, v140
	v_min_f32_e32 v140, v139, v140
	v_max_f32_e32 v125, v131, v69
	v_min_f32_e32 v69, v131, v69
	v_max_f32_e32 v117, v142, v138
	v_min_f32_e32 v138, v142, v138
	v_max_f32_e32 v102, v254, v135
	v_min_f32_e32 v135, v254, v135
	v_max_f32_e32 v49, v102, v143
	v_min_f32_e32 v143, v102, v143
	v_max_f32_e32 v22, v135, v140
	v_min_f32_e32 v140, v135, v140
	v_max_f32_e32 v43, v125, v250
	v_min_f32_e32 v250, v125, v250
	v_max_f32_e32 v96, v49, v138
	v_min_f32_e32 v138, v49, v138
	v_max_f32_e32 v90, v143, v22
	v_min_f32_e32 v22, v143, v22
	v_max_f32_e32 v66, v43, v140
	v_min_f32_e32 v140, v43, v140
	v_max_f32_e32 v24, v250, v69
	v_min_f32_e32 v69, v250, v69
	v_max_f32_e32 v36, v22, v66
	v_min_f32_e32 v66, v22, v66
	v_max_f32_e32 v37, v140, v24
	v_min_f32_e32 v24, v140, v24
	s_waitcnt vmcnt(0)
	v_pk_mul_f32 v[160:161], v[160:161], v[176:177]
	v_pk_mul_f32 v[162:163], v[162:163], v[178:179]
	v_pk_mul_f32 v[164:165], v[164:165], v[180:181]
	v_pk_mul_f32 v[166:167], v[166:167], v[182:183]
	v_pk_mul_f32 v[168:169], v[168:169], v[184:185]
	v_pk_mul_f32 v[170:171], v[170:171], v[186:187]
	v_pk_mul_f32 v[172:173], v[172:173], v[188:189]
	v_pk_mul_f32 v[174:175], v[174:175], v[190:191]
	v_max3_f32 v192, |v160|, |v161|, |v162|
	v_max3_f32 v192, |v163|, |v164|, v192
	v_max3_f32 v192, |v165|, |v166|, v192
	v_max3_f32 v192, |v167|, |v168|, v192
	v_max3_f32 v192, |v169|, |v170|, v192
	v_max3_f32 v192, |v171|, |v172|, v192
	v_max3_f32 v192, |v173|, |v174|, v192
	v_max_f32_e64 v192, |v175|, v192
	s_nop 1
	v_mov_b32_dpp v193, v192 quad_perm:[1,0,3,2] row_mask:0xf bank_mask:0xf bound_ctrl:1
	v_max_f32_e32 v192, v192, v193
	s_nop 1
	v_mov_b32_dpp v193, v192 quad_perm:[2,3,0,1] row_mask:0xf bank_mask:0xf bound_ctrl:1
	v_max_f32_e32 v192, v192, v193
	s_nop 1
	v_mov_b32_dpp v193, v192 row_half_mirror row_mask:0xf bank_mask:0xf bound_ctrl:1
	v_max_f32_e32 v192, v192, v193
	s_nop 1
	v_mov_b32_dpp v193, v192 row_mirror row_mask:0xf bank_mask:0xf bound_ctrl:1
	v_max_f32_e32 v192, v192, v193
	v_mov_b32_e32 v193, v192
	s_nop 1
	v_permlane16_swap_b32_e32 v192, v193
	s_nop 1
	v_max_f32_e32 v192, v192, v193
	v_mov_b32_e32 v193, v192
	s_nop 1
	v_permlane32_swap_b32_e32 v192, v193
	s_nop 1
	v_max_f32_e32 v192, v192, v193
	v_max_f32_e32 v192, 0xda24260, v192
	v_mul_f32_e32 v194, 0x3e2aaaab, v192
	global_store_dword v214, v194, s[12:13]
	v_div_scale_f32 v195, s[26:27], v194, v194, 1.0
	v_rcp_f32_e32 v196, v195
	v_div_scale_f32 v204, vcc, 1.0, v194, 1.0
	v_fma_f32 v205, -v195, v196, 1.0
	v_fmac_f32_e32 v196, v205, v196
	v_mul_f32_e32 v205, v204, v196
	v_fma_f32 v206, -v195, v205, v204
	v_fmac_f32_e32 v205, v206, v196
	v_fma_f32 v195, -v195, v205, v204
	s_nop 0
	v_div_fmas_f32 v195, v195, v196, v205
	v_div_fixup_f32 v207, v195, v194, 1.0
	v_mul_f32_e32 v160, v207, v160
	v_mul_f32_e32 v161, v207, v161
	v_mul_f32_e32 v162, v207, v162
	v_mul_f32_e32 v163, v207, v163
	v_mul_f32_e32 v164, v207, v164
	v_mul_f32_e32 v165, v207, v165
	v_mul_f32_e32 v166, v207, v166
	v_mul_f32_e32 v167, v207, v167
	v_mul_f32_e32 v168, v207, v168
	v_mul_f32_e32 v169, v207, v169
	v_mul_f32_e32 v170, v207, v170
	v_mul_f32_e32 v171, v207, v171
	v_mul_f32_e32 v172, v207, v172
	v_mul_f32_e32 v173, v207, v173
	v_mul_f32_e32 v174, v207, v174
	v_mul_f32_e32 v175, v207, v175
	v_mov_b32_e32 v208, 0
	v_mov_b32_e32 v209, 0
	v_mov_b32_e32 v210, 0
	v_mov_b32_e32 v193, 0
	v_cvt_scalef32_pk_fp4_f32 v208, v160, v161, 1.0
	v_cvt_scalef32_pk_fp4_f32 v209, v164, v165, 1.0
	v_cvt_scalef32_pk_fp4_f32 v210, v168, v169, 1.0
	v_cvt_scalef32_pk_fp4_f32 v193, v172, v173, 1.0
	v_cvt_scalef32_pk_fp4_f32 v208, v162, v163, 1.0 op_sel:[0,0,1,0]
	v_cvt_scalef32_pk_fp4_f32 v209, v166, v167, 1.0 op_sel:[0,0,1,0]
	v_cvt_scalef32_pk_fp4_f32 v210, v170, v171, 1.0 op_sel:[0,0,1,0]
	v_cvt_scalef32_pk_fp4_f32 v193, v174, v175, 1.0 op_sel:[0,0,1,0]
	global_store_short v213, v208, s[10:11] nt
	s_add_u32 s14, s10, 0x200000
	s_addc_u32 s15, s11, 0
	global_store_short v213, v209, s[14:15] nt
	s_add_u32 s14, s10, 0x400000
	s_addc_u32 s15, s11, 0
	global_store_short v213, v210, s[14:15] nt
	s_add_u32 s14, s10, 0x600000
	s_addc_u32 s15, s11, 0
	global_store_short v213, v193, s[14:15] nt
	s_add_u32 s10, s10, 0x20000
	s_addc_u32 s11, s11, 0
	s_add_u32 s12, s12, 0x2000
	s_addc_u32 s13, s13, 0
	global_load_dwordx4 v[160:163], v212, s[8:9] offset:0 nt
	global_load_dwordx4 v[164:167], v212, s[8:9] offset:1024 nt
	global_load_dwordx4 v[168:171], v212, s[8:9] offset:2048 nt
	global_load_dwordx4 v[172:175], v212, s[8:9] offset:3072 nt
	s_add_u32 s8, s8, 0x800000
	s_addc_u32 s9, s9, 0
	v_max_f32_e32 v145, v145, v69
	v_max_f32_e32 v149, v149, v24
	v_max_f32_e32 v146, v146, v37
	v_max_f32_e32 v150, v150, v66
	v_max_f32_e32 v147, v147, v36
	v_max_f32_e32 v127, v127, v90
	v_max_f32_e32 v148, v148, v138
	v_max_f32_e32 v103, v103, v96
	v_max_f32_e32 v111, v111, v117
	v_max_f32_e32 v94, v94, v141
	v_max_f32_e32 v55, v55, v132
	v_max_f32_e32 v63, v95, v150
	v_min_f32_e32 v150, v95, v150
	v_max_f32_e32 v67, v112, v147
	v_min_f32_e32 v147, v112, v147
	v_max_f32_e32 v21, v119, v127
	v_min_f32_e32 v127, v119, v127
	v_max_f32_e32 v15, v144, v148
	v_min_f32_e32 v148, v144, v148
	v_max_f32_e32 v0, v107, v103
	v_min_f32_e32 v103, v107, v103
	v_max_f32_e32 v1, v145, v111
	v_min_f32_e32 v111, v145, v111
	v_max_f32_e32 v2, v149, v94
	v_min_f32_e32 v94, v149, v94
	v_max_f32_e32 v3, v146, v55
	v_min_f32_e32 v55, v146, v55
	v_max_f32_e32 v4, v63, v0
	v_min_f32_e32 v0, v63, v0
	v_max_f32_e32 v5, v67, v1
	v_min_f32_e32 v1, v67, v1
	v_max_f32_e32 v6, v21, v2
	v_min_f32_e32 v2, v21, v2
	v_max_f32_e32 v7, v15, v3
	v_min_f32_e32 v3, v15, v3
	v_max_f32_e32 v8, v150, v103
	v_min_f32_e32 v103, v150, v103
	v_max_f32_e32 v9, v147, v111
	v_min_f32_e32 v111, v147, v111
	v_max_f32_e32 v10, v127, v94
	v_min_f32_e32 v94, v127, v94
	v_max_f32_e32 v11, v148, v55
	v_min_f32_e32 v55, v148, v55
	v_max_f32_e32 v12, v4, v6
	v_min_f32_e32 v6, v4, v6
	v_max_f32_e32 v13, v5, v7
	v_min_f32_e32 v7, v5, v7
	v_max_f32_e32 v14, v0, v2
	v_min_f32_e32 v2, v0, v2
	v_max_f32_e32 v16, v1, v3
	v_min_f32_e32 v3, v1, v3
	v_max_f32_e32 v17, v8, v10
	v_min_f32_e32 v10, v8, v10
	v_max_f32_e32 v18, v9, v11
	v_min_f32_e32 v11, v9, v11
	v_max_f32_e32 v19, v103, v94
	v_min_f32_e32 v94, v103, v94
	v_max_f32_e32 v20, v111, v55
	v_min_f32_e32 v55, v111, v55
	v_max_f32_e32 v23, v12, v13
	v_min_f32_e32 v13, v12, v13
	v_max_f32_e32 v25, v6, v7
	v_min_f32_e32 v7, v6, v7
	v_max_f32_e32 v26, v14, v16
	v_min_f32_e32 v16, v14, v16
	v_max_f32_e32 v27, v2, v3
	v_min_f32_e32 v3, v2, v3
	v_max_f32_e32 v28, v17, v18
	v_min_f32_e32 v18, v17, v18
	v_max_f32_e32 v29, v10, v11
	v_min_f32_e32 v11, v10, v11
	v_max_f32_e32 v30, v19, v20
	v_min_f32_e32 v20, v19, v20
	v_max_f32_e32 v31, v94, v55
	v_min_f32_e32 v55, v94, v55
	v_or_b32_e32 v23, v23, v245
	v_or_b32_e32 v13, v13, v245
	v_or_b32_e32 v25, v25, v245
	v_or_b32_e32 v7, v7, v245
	v_or_b32_e32 v26, v26, v245
	v_or_b32_e32 v16, v16, v245
	v_or_b32_e32 v27, v27, v245
	v_or_b32_e32 v3, v3, v245
	v_or_b32_e32 v28, v28, v245
	v_or_b32_e32 v18, v18, v245
	v_or_b32_e32 v29, v29, v245
	v_or_b32_e32 v11, v11, v245
	v_or_b32_e32 v30, v30, v245
	v_or_b32_e32 v20, v20, v245
	v_or_b32_e32 v31, v31, v245
	v_or_b32_e32 v55, v55, v245
	v_mov_b32_e32 v32, v23
	v_mov_b32_e32 v33, v13
	v_mov_b32_e32 v34, v25
	v_mov_b32_e32 v35, v7
	v_mov_b32_e32 v38, v26
	v_mov_b32_e32 v39, v16
	v_mov_b32_e32 v40, v27
	v_mov_b32_e32 v41, v3
	v_mov_b32_e32 v42, v28
	v_mov_b32_e32 v44, v18
	v_mov_b32_e32 v46, v29
	v_mov_b32_e32 v48, v11
	v_mov_b32_e32 v70, v30
	v_mov_b32_e32 v71, v20
	v_mov_b32_e32 v72, v31
	v_mov_b32_e32 v73, v55
	s_nop 1
	v_permlane32_swap_b32_e32 v23, v32
	v_permlane32_swap_b32_e32 v13, v33
	v_permlane32_swap_b32_e32 v25, v34
	v_permlane32_swap_b32_e32 v7, v35
	v_permlane32_swap_b32_e32 v26, v38
	v_permlane32_swap_b32_e32 v16, v39
	v_permlane32_swap_b32_e32 v27, v40
	v_permlane32_swap_b32_e32 v3, v41
	v_permlane32_swap_b32_e32 v28, v42
	v_permlane32_swap_b32_e32 v18, v44
	v_permlane32_swap_b32_e32 v29, v46
	v_permlane32_swap_b32_e32 v11, v48
	v_permlane32_swap_b32_e32 v30, v70
	v_permlane32_swap_b32_e32 v20, v71
	v_permlane32_swap_b32_e32 v31, v72
	v_permlane32_swap_b32_e32 v55, v73
	s_nop 1
	v_max_f32_e32 v23, v23, v73
	v_max_f32_e32 v13, v13, v72
	v_max_f32_e32 v25, v25, v71
	v_max_f32_e32 v7, v7, v70
	v_max_f32_e32 v26, v26, v48
	v_max_f32_e32 v16, v16, v46
	v_max_f32_e32 v27, v27, v44
	v_max_f32_e32 v3, v3, v42
	v_max_f32_e32 v28, v28, v41
	v_max_f32_e32 v18, v18, v40
	v_max_f32_e32 v29, v29, v39
	v_max_f32_e32 v11, v11, v38
	v_max_f32_e32 v30, v30, v35
	v_max_f32_e32 v20, v20, v34
	v_max_f32_e32 v31, v31, v33
	v_max_f32_e32 v55, v55, v32
	v_max_f32_e32 v45, v23, v28
	v_min_f32_e32 v28, v23, v28
	v_max_f32_e32 v47, v13, v18
	v_min_f32_e32 v18, v13, v18
	v_max_f32_e32 v50, v25, v29
	v_min_f32_e32 v29, v25, v29
	v_max_f32_e32 v51, v7, v11
	v_min_f32_e32 v11, v7, v11
	v_max_f32_e32 v78, v26, v30
	v_min_f32_e32 v30, v26, v30
	v_max_f32_e32 v80, v16, v20
	v_min_f32_e32 v20, v16, v20
	v_max_f32_e32 v74, v27, v31
	v_min_f32_e32 v31, v27, v31
	v_max_f32_e32 v82, v3, v55
	v_min_f32_e32 v55, v3, v55
	v_max_f32_e32 v76, v45, v78
	v_min_f32_e32 v78, v45, v78
	v_max_f32_e32 v84, v47, v80
	v_min_f32_e32 v80, v47, v80
	v_max_f32_e32 v52, v50, v74
	v_min_f32_e32 v74, v50, v74
	v_max_f32_e32 v54, v51, v82
	v_min_f32_e32 v82, v51, v82
	v_max_f32_e32 v86, v28, v30
	v_min_f32_e32 v30, v28, v30
	v_max_f32_e32 v79, v18, v20
	v_min_f32_e32 v20, v18, v20
	v_max_f32_e32 v88, v29, v31
	v_min_f32_e32 v31, v29, v31
	v_max_f32_e32 v75, v11, v55
	v_min_f32_e32 v55, v11, v55
	v_max_f32_e32 v89, v76, v52
	v_min_f32_e32 v52, v76, v52
	v_max_f32_e32 v83, v84, v54
	v_min_f32_e32 v54, v84, v54
	v_max_f32_e32 v93, v78, v74
	v_min_f32_e32 v74, v78, v74
	v_max_f32_e32 v53, v80, v82
	v_min_f32_e32 v82, v80, v82
	v_max_f32_e32 v97, v86, v88
	v_min_f32_e32 v88, v86, v88
	v_max_f32_e32 v81, v79, v75
	v_min_f32_e32 v75, v79, v75
	v_max_f32_e32 v98, v30, v31
	v_min_f32_e32 v31, v30, v31
	v_max_f32_e32 v99, v20, v55
	v_min_f32_e32 v55, v20, v55
	v_max_f32_e32 v101, v89, v83
	v_min_f32_e32 v83, v89, v83
	v_max_f32_e32 v77, v52, v54
	v_min_f32_e32 v54, v52, v54
	v_max_f32_e32 v104, v93, v53
	v_min_f32_e32 v53, v93, v53
	v_max_f32_e32 v105, v74, v82
	v_min_f32_e32 v82, v74, v82
	v_max_f32_e32 v87, v97, v81
	v_min_f32_e32 v81, v97, v81
	v_max_f32_e32 v108, v88, v75
	v_min_f32_e32 v75, v88, v75
	v_max_f32_e32 v91, v98, v99
	v_min_f32_e32 v99, v98, v99
	v_max_f32_e32 v110, v31, v55
	v_min_f32_e32 v55, v31, v55
	v_and_b32_e32 v85, s7, v101
	v_cndmask_b32_e64 v113, v101, v87, s[4:5]
	v_cndmask_b32_e64 v106, v83, v81, s[4:5]
	v_cndmask_b32_e64 v116, v77, v108, s[4:5]
	v_cndmask_b32_e64 v118, v54, v75, s[4:5]
	v_cndmask_b32_e64 v120, v104, v91, s[4:5]
	v_cndmask_b32_e64 v100, v53, v99, s[4:5]
	v_cndmask_b32_e64 v115, v105, v110, s[4:5]
	v_cndmask_b32_e64 v92, v82, v55, s[4:5]
	v_and_or_b32 v123, v113, 63, v246
	ds_read_u8 v123, v123
	v_and_or_b32 v114, v106, 63, v246
	ds_read_u8 v114, v114
	v_and_or_b32 v126, v116, 63, v246
	ds_read_u8 v126, v126
	v_and_or_b32 v121, v118, 63, v246
	ds_read_u8 v121, v121
	v_and_or_b32 v122, v120, 63, v246
	ds_read_u8 v122, v122
	v_and_or_b32 v124, v100, 63, v246
	ds_read_u8 v124, v124
	v_and_or_b32 v109, v115, 63, v246
	ds_read_u8 v109, v109
	v_and_or_b32 v60, v92, 63, v246
	ds_read_u8 v60, v60
	v_and_b32_e32 v113, s7, v113
	v_sub_f32_e32 v113, v113, v85
	v_mul_f32_e32 v113, 0x3fb8aa3b, v113
	v_exp_f32_e32 v113, v113
	v_and_b32_e32 v106, s7, v106
	v_sub_f32_e32 v106, v106, v85
	v_mul_f32_e32 v106, 0x3fb8aa3b, v106
	v_exp_f32_e32 v106, v106
	v_and_b32_e32 v116, s7, v116
	v_sub_f32_e32 v116, v116, v85
	v_mul_f32_e32 v116, 0x3fb8aa3b, v116
	v_exp_f32_e32 v116, v116
	v_and_b32_e32 v118, s7, v118
	v_sub_f32_e32 v118, v118, v85
	v_mul_f32_e32 v118, 0x3fb8aa3b, v118
	v_exp_f32_e32 v118, v118
	v_and_b32_e32 v120, s7, v120
	v_sub_f32_e32 v120, v120, v85
	v_mul_f32_e32 v120, 0x3fb8aa3b, v120
	v_exp_f32_e32 v120, v120
	v_and_b32_e32 v100, s7, v100
	v_sub_f32_e32 v100, v100, v85
	v_mul_f32_e32 v100, 0x3fb8aa3b, v100
	v_exp_f32_e32 v100, v100
	v_and_b32_e32 v115, s7, v115
	v_sub_f32_e32 v115, v115, v85
	v_mul_f32_e32 v115, 0x3fb8aa3b, v115
	v_exp_f32_e32 v115, v115
	v_and_b32_e32 v92, s7, v92
	v_sub_f32_e32 v92, v92, v85
	v_mul_f32_e32 v92, 0x3fb8aa3b, v92
	v_exp_f32_e32 v92, v92
	s_nop 0
	v_add_f32_e32 v85, v113, v106
	v_add_f32_e32 v85, v85, v116
	v_add_f32_e32 v85, v85, v118
	v_add_f32_e32 v85, v85, v120
	v_add_f32_e32 v85, v85, v100
	v_add_f32_e32 v85, v85, v115
	v_add_f32_e32 v85, v85, v92
	v_mov_b32_e32 v61, v85
	s_nop 1
	v_permlane32_swap_b32_e32 v85, v61
	s_nop 1
	v_add_f32_e32 v85, v85, v61
	s_waitcnt lgkmcnt(0)
	v_bfe_u32 v68, v123, 4, 4
	v_or_b32_e32 v68, v68, v240
	v_and_or_b32 v123, v123, 15, v240
	ds_read_u8 v68, v68
	ds_read_u8 v123, v123 offset:512
	v_bfe_u32 v56, v114, 4, 4
	v_or_b32_e32 v56, v56, v240
	v_and_or_b32 v114, v114, 15, v240
	ds_read_u8 v56, v56
	ds_read_u8 v114, v114 offset:512
	v_bfe_u32 v57, v126, 4, 4
	v_or_b32_e32 v57, v57, v240
	v_and_or_b32 v126, v126, 15, v240
	ds_read_u8 v57, v57
	ds_read_u8 v126, v126 offset:512
	v_bfe_u32 v58, v121, 4, 4
	v_or_b32_e32 v58, v58, v240
	v_and_or_b32 v121, v121, 15, v240
	ds_read_u8 v58, v58
	ds_read_u8 v121, v121 offset:512
	v_bfe_u32 v59, v122, 4, 4
	v_or_b32_e32 v59, v59, v240
	v_and_or_b32 v122, v122, 15, v240
	ds_read_u8 v59, v59
	ds_read_u8 v122, v122 offset:512
	v_bfe_u32 v251, v124, 4, 4
	v_or_b32_e32 v251, v251, v240
	v_and_or_b32 v124, v124, 15, v240
	ds_read_u8 v251, v251
	ds_read_u8 v124, v124 offset:512
	v_bfe_u32 v253, v109, 4, 4
	v_or_b32_e32 v253, v253, v240
	v_and_or_b32 v109, v109, 15, v240
	ds_read_u8 v253, v253
	ds_read_u8 v109, v109 offset:512
	v_bfe_u32 v151, v60, 4, 4
	v_or_b32_e32 v151, v151, v240
	v_and_or_b32 v60, v60, 15, v240
	ds_read_u8 v151, v151
	ds_read_u8 v60, v60 offset:512
	v_div_scale_f32 v134, s[26:27], v85, v85, v113
	v_rcp_f32_e32 v249, v134
	s_nop 0
	v_fma_f32 v136, -v134, v249, 1.0
	v_fmac_f32_e32 v249, v136, v249
	v_div_scale_f32 v136, vcc, v113, v85, v113
	v_mul_f32_e32 v137, v136, v249
	v_fma_f32 v62, -v134, v137, v136
	v_fmac_f32_e32 v137, v62, v249
	v_fma_f32 v136, -v134, v137, v136
	s_nop 0
	v_div_fmas_f32 v136, v136, v249, v137
	v_div_fixup_f32 v62, v136, v85, v113
	v_div_scale_f32 v134, s[26:27], v85, v85, v106
	v_rcp_f32_e32 v249, v134
	s_nop 0
	v_fma_f32 v136, -v134, v249, 1.0
	v_fmac_f32_e32 v249, v136, v249
	v_div_scale_f32 v136, vcc, v106, v85, v106
	v_mul_f32_e32 v137, v136, v249
	v_fma_f32 v64, -v134, v137, v136
	v_fmac_f32_e32 v137, v64, v249
	v_fma_f32 v136, -v134, v137, v136
	s_nop 0
	v_div_fmas_f32 v136, v136, v249, v137
	v_div_fixup_f32 v64, v136, v85, v106
	v_div_scale_f32 v134, s[26:27], v85, v85, v116
	v_rcp_f32_e32 v249, v134
	s_nop 0
	v_fma_f32 v136, -v134, v249, 1.0
	v_fmac_f32_e32 v249, v136, v249
	v_div_scale_f32 v136, vcc, v116, v85, v116
	v_mul_f32_e32 v137, v136, v249
	v_fma_f32 v255, -v134, v137, v136
	v_fmac_f32_e32 v137, v255, v249
	v_fma_f32 v136, -v134, v137, v136
	s_nop 0
	v_div_fmas_f32 v136, v136, v249, v137
	v_div_fixup_f32 v255, v136, v85, v116
	v_div_scale_f32 v134, s[26:27], v85, v85, v118
	v_rcp_f32_e32 v249, v134
	s_nop 0
	v_fma_f32 v136, -v134, v249, 1.0
	v_fmac_f32_e32 v249, v136, v249
	v_div_scale_f32 v136, vcc, v118, v85, v118
	v_mul_f32_e32 v137, v136, v249
	v_fma_f32 v252, -v134, v137, v136
	v_fmac_f32_e32 v137, v252, v249
	v_fma_f32 v136, -v134, v137, v136
	s_nop 0
	v_div_fmas_f32 v136, v136, v249, v137
	v_div_fixup_f32 v252, v136, v85, v118
	v_div_scale_f32 v134, s[26:27], v85, v85, v120
	v_rcp_f32_e32 v249, v134
	s_nop 0
	v_fma_f32 v136, -v134, v249, 1.0
	v_fmac_f32_e32 v249, v136, v249
	v_div_scale_f32 v136, vcc, v120, v85, v120
	v_mul_f32_e32 v137, v136, v249
	v_fma_f32 v129, -v134, v137, v136
	v_fmac_f32_e32 v137, v129, v249
	v_fma_f32 v136, -v134, v137, v136
	s_nop 0
	v_div_fmas_f32 v136, v136, v249, v137
	v_div_fixup_f32 v129, v136, v85, v120
	v_div_scale_f32 v134, s[26:27], v85, v85, v100
	v_rcp_f32_e32 v249, v134
	s_nop 0
	v_fma_f32 v136, -v134, v249, 1.0
	v_fmac_f32_e32 v249, v136, v249
	v_div_scale_f32 v136, vcc, v100, v85, v100
	v_mul_f32_e32 v137, v136, v249
	v_fma_f32 v130, -v134, v137, v136
	v_fmac_f32_e32 v137, v130, v249
	v_fma_f32 v136, -v134, v137, v136
	s_nop 0
	v_div_fmas_f32 v136, v136, v249, v137
	v_div_fixup_f32 v130, v136, v85, v100
	v_div_scale_f32 v134, s[26:27], v85, v85, v115
	v_rcp_f32_e32 v249, v134
	s_nop 0
	v_fma_f32 v136, -v134, v249, 1.0
	v_fmac_f32_e32 v249, v136, v249
	v_div_scale_f32 v136, vcc, v115, v85, v115
	v_mul_f32_e32 v137, v136, v249
	v_fma_f32 v65, -v134, v137, v136
	v_fmac_f32_e32 v137, v65, v249
	v_fma_f32 v136, -v134, v137, v136
	s_nop 0
	v_div_fmas_f32 v136, v136, v249, v137
	v_div_fixup_f32 v65, v136, v85, v115
	v_div_scale_f32 v134, s[26:27], v85, v85, v92
	v_rcp_f32_e32 v249, v134
	s_nop 0
	v_fma_f32 v136, -v134, v249, 1.0
	v_fmac_f32_e32 v249, v136, v249
	v_div_scale_f32 v136, vcc, v92, v85, v92
	v_mul_f32_e32 v137, v136, v249
	v_fma_f32 v133, -v134, v137, v136
	v_fmac_f32_e32 v137, v133, v249
	v_fma_f32 v136, -v134, v137, v136
	s_nop 0
	v_div_fmas_f32 v136, v136, v249, v137
	v_div_fixup_f32 v133, v136, v85, v92
	s_waitcnt lgkmcnt(0)
	v_and_b32_e32 v68, 0x7f, v68
	v_and_b32_e32 v123, 0x7f, v123
	v_lshl_or_b32 v68, v68, 7, v123
	v_xor_b32_e32 v68, 0x3fff, v68
	v_and_b32_e32 v56, 0x7f, v56
	v_and_b32_e32 v114, 0x7f, v114
	v_lshl_or_b32 v56, v56, 7, v114
	v_xor_b32_e32 v56, 0x3fff, v56
	v_and_b32_e32 v57, 0x7f, v57
	v_and_b32_e32 v126, 0x7f, v126
	v_lshl_or_b32 v57, v57, 7, v126
	v_xor_b32_e32 v57, 0x3fff, v57
	v_and_b32_e32 v58, 0x7f, v58
	v_and_b32_e32 v121, 0x7f, v121
	v_lshl_or_b32 v58, v58, 7, v121
	v_xor_b32_e32 v58, 0x3fff, v58
	v_and_b32_e32 v59, 0x7f, v59
	v_and_b32_e32 v122, 0x7f, v122
	v_lshl_or_b32 v59, v59, 7, v122
	v_xor_b32_e32 v59, 0x3fff, v59
	v_and_b32_e32 v251, 0x7f, v251
	v_and_b32_e32 v124, 0x7f, v124
	v_lshl_or_b32 v251, v251, 7, v124
	v_xor_b32_e32 v251, 0x3fff, v251
	v_and_b32_e32 v253, 0x7f, v253
	v_and_b32_e32 v109, 0x7f, v109
	v_lshl_or_b32 v253, v253, 7, v109
	v_xor_b32_e32 v253, 0x3fff, v253
	v_and_b32_e32 v151, 0x7f, v151
	v_and_b32_e32 v60, 0x7f, v60
	v_lshl_or_b32 v151, v151, 7, v60
	v_xor_b32_e32 v151, 0x3fff, v151
	s_waitcnt vmcnt(0)
	v_pk_mul_f32 v[160:161], v[160:161], v[176:177]
	v_pk_mul_f32 v[162:163], v[162:163], v[178:179]
	v_pk_mul_f32 v[164:165], v[164:165], v[180:181]
	v_pk_mul_f32 v[166:167], v[166:167], v[182:183]
	v_pk_mul_f32 v[168:169], v[168:169], v[184:185]
	v_pk_mul_f32 v[170:171], v[170:171], v[186:187]
	v_pk_mul_f32 v[172:173], v[172:173], v[188:189]
	v_pk_mul_f32 v[174:175], v[174:175], v[190:191]
	v_max3_f32 v192, |v160|, |v161|, |v162|
	v_max3_f32 v192, |v163|, |v164|, v192
	v_max3_f32 v192, |v165|, |v166|, v192
	v_max3_f32 v192, |v167|, |v168|, v192
	v_max3_f32 v192, |v169|, |v170|, v192
	v_max3_f32 v192, |v171|, |v172|, v192
	v_max3_f32 v192, |v173|, |v174|, v192
	v_max_f32_e64 v192, |v175|, v192
	s_nop 1
	v_mov_b32_dpp v193, v192 quad_perm:[1,0,3,2] row_mask:0xf bank_mask:0xf bound_ctrl:1
	v_max_f32_e32 v192, v192, v193
	s_nop 1
	v_mov_b32_dpp v193, v192 quad_perm:[2,3,0,1] row_mask:0xf bank_mask:0xf bound_ctrl:1
	v_max_f32_e32 v192, v192, v193
	s_nop 1
	v_mov_b32_dpp v193, v192 row_half_mirror row_mask:0xf bank_mask:0xf bound_ctrl:1
	v_max_f32_e32 v192, v192, v193
	s_nop 1
	v_mov_b32_dpp v193, v192 row_mirror row_mask:0xf bank_mask:0xf bound_ctrl:1
	v_max_f32_e32 v192, v192, v193
	v_mov_b32_e32 v193, v192
	s_nop 1
	v_permlane16_swap_b32_e32 v192, v193
	s_nop 1
	v_max_f32_e32 v192, v192, v193
	v_mov_b32_e32 v193, v192
	s_nop 1
	v_permlane32_swap_b32_e32 v192, v193
	s_nop 1
	v_max_f32_e32 v192, v192, v193
	v_max_f32_e32 v192, 0xda24260, v192
	v_mul_f32_e32 v194, 0x3e2aaaab, v192
	global_store_dword v214, v194, s[12:13]
	v_div_scale_f32 v195, s[26:27], v194, v194, 1.0
	v_rcp_f32_e32 v196, v195
	v_div_scale_f32 v204, vcc, 1.0, v194, 1.0
	v_fma_f32 v205, -v195, v196, 1.0
	v_fmac_f32_e32 v196, v205, v196
	v_mul_f32_e32 v205, v204, v196
	v_fma_f32 v206, -v195, v205, v204
	v_fmac_f32_e32 v205, v206, v196
	v_fma_f32 v195, -v195, v205, v204
	s_nop 0
	v_div_fmas_f32 v195, v195, v196, v205
	v_div_fixup_f32 v207, v195, v194, 1.0
	v_mul_f32_e32 v160, v207, v160
	v_mul_f32_e32 v161, v207, v161
	v_mul_f32_e32 v162, v207, v162
	v_mul_f32_e32 v163, v207, v163
	v_mul_f32_e32 v164, v207, v164
	v_mul_f32_e32 v165, v207, v165
	v_mul_f32_e32 v166, v207, v166
	v_mul_f32_e32 v167, v207, v167
	v_mul_f32_e32 v168, v207, v168
	v_mul_f32_e32 v169, v207, v169
	v_mul_f32_e32 v170, v207, v170
	v_mul_f32_e32 v171, v207, v171
	v_mul_f32_e32 v172, v207, v172
	v_mul_f32_e32 v173, v207, v173
	v_mul_f32_e32 v174, v207, v174
	v_mul_f32_e32 v175, v207, v175
	v_mov_b32_e32 v208, 0
	v_mov_b32_e32 v209, 0
	v_mov_b32_e32 v210, 0
	v_mov_b32_e32 v193, 0
	v_cvt_scalef32_pk_fp4_f32 v208, v160, v161, 1.0
	v_cvt_scalef32_pk_fp4_f32 v209, v164, v165, 1.0
	v_cvt_scalef32_pk_fp4_f32 v210, v168, v169, 1.0
	v_cvt_scalef32_pk_fp4_f32 v193, v172, v173, 1.0
	v_cvt_scalef32_pk_fp4_f32 v208, v162, v163, 1.0 op_sel:[0,0,1,0]
	v_cvt_scalef32_pk_fp4_f32 v209, v166, v167, 1.0 op_sel:[0,0,1,0]
	v_cvt_scalef32_pk_fp4_f32 v210, v170, v171, 1.0 op_sel:[0,0,1,0]
	v_cvt_scalef32_pk_fp4_f32 v193, v174, v175, 1.0 op_sel:[0,0,1,0]
	global_store_short v213, v208, s[10:11] nt
	s_add_u32 s14, s10, 0x200000
	s_addc_u32 s15, s11, 0
	global_store_short v213, v209, s[14:15] nt
	s_add_u32 s14, s10, 0x400000
	s_addc_u32 s15, s11, 0
	global_store_short v213, v210, s[14:15] nt
	s_add_u32 s14, s10, 0x600000
	s_addc_u32 s15, s11, 0
	global_store_short v213, v193, s[14:15] nt
	s_add_u32 s10, s10, 0x20000
	s_addc_u32 s11, s11, 0
	s_add_u32 s12, s12, 0x2000
	s_addc_u32 s13, s13, 0
	s_cmp_eq_u32 s22, 1
	s_cbranch_scc1 .Ltk0_noload7
	global_load_dwordx4 v[160:163], v212, s[8:9] offset:0 nt
	global_load_dwordx4 v[164:167], v212, s[8:9] offset:1024 nt
	global_load_dwordx4 v[168:171], v212, s[8:9] offset:2048 nt
	global_load_dwordx4 v[172:175], v212, s[8:9] offset:3072 nt
	s_add_u32 s8, s8, 0x800000
	s_addc_u32 s9, s9, 0

.LBB0_782:
	s_and_b32 s5, s19, 0xe00
	s_add_i32 s16, s18, s5
	s_pack_ll_b32_b16 s5, s4, s4
	s_or_b32 s5, s5, 0x1c00180
	s_and_b32 s10, s5, 0xfff
	s_mulk_i32 s10, 0xaab
	s_lshr_b32 s10, s10, 20
	s_mulk_i32 s10, 0x180
	s_sub_i32 s10, s5, s10
	s_and_b32 s10, s10, 0xffff
	v_add_u32_e32 v1, s10, v120
	v_lshlrev_b32_e32 v28, 7, v1
	v_lshrrev_b32_e32 v1, 1, v1
	s_lshr_b32 s5, s5, 16
	v_xor_b32_e32 v1, v1, v115
	s_mul_i32 s17, s5, 0xaab
	v_lshlrev_b32_e32 v1, 4, v1
	s_lshr_b32 s17, s17, 20
	v_and_b32_e32 v1, 0x70, v1
	s_mulk_i32 s17, 0x180
	v_add3_u32 v1, 0, v28, v1
	s_sub_i32 s5, s5, s17
	s_waitcnt vmcnt(1)
	ds_write_b128 v1, v[22:25]
	v_or_b32_e32 v1, s10, v110
	s_and_b32 s5, s5, 0xffff
	v_lshlrev_b32_e32 v1, 1, v1
	v_add_u32_e32 v26, s5, v111
	v_add3_u32 v1, v121, v1, s21
	ds_write2_b64 v1, v[14:15], v[16:17] offset1:1
	v_lshrrev_b32_e32 v1, 1, v26
	v_xor_b32_e32 v1, v1, v115
	v_lshlrev_b32_e32 v1, 4, v1
	v_lshlrev_b32_e32 v27, 7, v26
	v_and_b32_e32 v1, 0x70, v1
	v_add3_u32 v1, 0, v27, v1
	s_addk_i32 s4, 0x200
	ds_write_b128 v1, v[18:21]
	v_or_b32_e32 v1, s5, v110
	s_and_b32 s5, s4, 0x1fff
	s_mulk_i32 s5, 0xaab
	s_lshr_b32 s5, s5, 20
	s_mulk_i32 s5, 0x180
	v_lshlrev_b32_e32 v1, 1, v1
	s_sub_i32 s4, s4, s5
	v_add3_u32 v1, v121, v1, s21
	s_and_b32 s4, s4, 0xffff
	ds_write2_b64 v1, v[10:11], v[12:13] offset1:1
	v_add_u32_e32 v1, s4, v108
	v_lshlrev_b32_e32 v10, 7, v1
	v_lshrrev_b32_e32 v1, 1, v1
	v_xor_b32_e32 v1, v1, v115
	v_lshlrev_b32_e32 v1, 4, v1
	v_and_b32_e32 v1, 0x70, v1
	v_add3_u32 v1, 0, v10, v1
	ds_write_b128 v1, v[6:9]
	v_or_b32_e32 v1, s4, v110
	s_lshl_b32 s4, s24, 2
	s_or_b32 s4, s4, s0
	s_lshl_b32 s10, s4, 7
	s_lshl_b32 s4, s4, 2
	v_lshlrev_b32_e32 v1, 1, v1
	v_or_b32_e32 v130, s14, v114
	s_add_u32 s14, s48, s4
	v_add3_u32 v1, v121, v1, s21
	v_mov_b32_e32 v131, s15
	v_lshl_add_u64 v[134:135], v[116:117], 0, s[10:11]
	s_addc_u32 s15, s49, 0
	v_lshl_add_u64 v[136:137], v[118:119], 0, s[10:11]
	s_waitcnt vmcnt(0)
	ds_write2_b64 v1, v[2:3], v[4:5] offset1:1
	s_waitcnt lgkmcnt(0)
	s_barrier
	s_add_i32 s10, s12, s1
	v_lshl_add_u64 v[186:187], v[130:131], 0, s[10:11]
	v_lshlrev_b64 v[186:187], 11, v[186:187]
	v_lshl_add_u64 v[186:187], v[186:187], 1, v[134:135]
	v_mov_b32_e32 v189, 0
	global_load_dwordx4 v[170:173], v[186:187], off
	global_load_dwordx4 v[174:177], v[186:187], off offset:32
	global_load_dwordx4 v[178:181], v[186:187], off offset:64
	global_load_dwordx4 v[182:185], v[186:187], off offset:96
	global_load_dword v188, v189, s[14:15]
	s_waitcnt vmcnt(0)
	v_mul_f32_e32 v188, 0x3fb8aa3b, v188
	v_mbcnt_lo_u32_b32 v249, -1, 0
	v_mbcnt_hi_u32_b32 v249, -1, v249
	v_and_b32_e32 v251, 3, v249
	v_lshrrev_b32_e32 v250, 4, v249
	v_lshlrev_b32_e32 v250, 5, v250
	v_lshl_or_b32 v250, v251, 3, v250
	v_bfe_u32 v252, v249, 3, 1
	v_lshl_or_b32 v250, v252, 2, v250
	v_lshlrev_b32_e32 v251, 2, v251
	v_lshlrev_b32_e32 v249, 4, v249
	v_mov_b32_e32 v252, 0
	v_readlane_b32 s86, v248, 0
	s_lshr_b32 s86, s86, 6
	s_lshl_b32 s94, s2, 3
	s_add_i32 s94, s94, s86
	s_and_b32 s86, s94, 1
	s_lshr_b32 s94, s94, 1
	v_readlane_b32 s74, v248, 16
	v_readlane_b32 s75, v248, 17
	s_lshl_b32 s95, s94, 13
	s_lshl_b32 s80, s86, 12
	s_add_i32 s95, s95, s80
	s_add_i32 s95, s95, 0x8000000
	s_add_u32 s74, s74, s95
	s_addc_u32 s75, s75, 0
	s_lshl_b32 s95, s86, 23
	s_lshl_b32 s80, s94, 7
	s_add_i32 s95, s95, s80
	s_add_i32 s95, s95, 0x14000000
	s_add_u32 s76, s54, s95
	s_addc_u32 s77, s55, 0
	s_lshl_b32 s95, s94, 3
	s_lshl_b32 s80, s86, 2
	s_add_i32 s95, s95, s80
	s_add_i32 s95, s95, 0xe0000
	s_add_u32 s78, s54, s95
	s_addc_u32 s79, s55, 0
	s_branch .LBB0_784

.LBB0_786:
	s_add_i32 s10, s17, s1
	s_sub_i32 s24, 0x80, s10
	s_ashr_i32 s24, s24, 5
	s_cmpk_lt_u32 s10, 0x80
	v_lshl_add_u64 v[2:3], v[130:131], 0, s[10:11]
	s_cselect_b32 s24, s24, 0
	s_sub_i32 s10, 0x1060, s10
	s_ashr_i32 s10, s10, 5
	s_min_i32 s10, s10, 8
	v_lshlrev_b64 v[138:139], 11, v[2:3]
	s_waitcnt vmcnt(26)
	v_mov_b32_e32 v88, v170
	v_mov_b32_e32 v89, v171
	v_mov_b32_e32 v90, v172
	v_mov_b32_e32 v91, v173
	v_mov_b32_e32 v92, v174
	v_mov_b32_e32 v93, v175
	v_mov_b32_e32 v94, v176
	v_mov_b32_e32 v95, v177
	v_mov_b32_e32 v96, v178
	v_mov_b32_e32 v97, v179
	v_mov_b32_e32 v98, v180
	v_mov_b32_e32 v99, v181
	v_mov_b32_e32 v100, v182
	v_mov_b32_e32 v101, v183
	v_mov_b32_e32 v102, v184
	v_mov_b32_e32 v103, v185
	v_lshl_add_u64 v[186:187], v[138:139], 1, v[134:135]
	v_add_co_u32_e32 v186, vcc, 0x40000, v186
	s_nop 1
	v_addc_co_u32_e32 v187, vcc, 0, v187, vcc
	global_load_dwordx4 v[170:173], v[186:187], off
	global_load_dwordx4 v[174:177], v[186:187], off offset:32
	global_load_dwordx4 v[178:181], v[186:187], off offset:64
	global_load_dwordx4 v[182:185], v[186:187], off offset:96
	global_load_dwordx4 v[204:207], v249, s[74:75] offset:0 nt
	global_load_dwordx4 v[208:211], v249, s[74:75] offset:1024 nt
	global_load_dwordx4 v[212:215], v249, s[74:75] offset:2048 nt
	global_load_dwordx4 v[216:219], v249, s[74:75] offset:3072 nt
	s_add_u32 s74, s74, 0x800000
	s_addc_u32 s75, s75, 0
	global_load_dwordx4 v[220:223], v249, s[74:75] offset:0 nt
	global_load_dwordx4 v[224:227], v249, s[74:75] offset:1024 nt
	global_load_dwordx4 v[228:231], v249, s[74:75] offset:2048 nt
	global_load_dwordx4 v[232:235], v249, s[74:75] offset:3072 nt
	s_add_u32 s74, s74, 0x800000
	s_addc_u32 s75, s75, 0
	v_mov_b32_e32 v31, 0
	s_cmp_gt_i32 s24, s10
	v_mov_b32_e32 v30, 0
	v_mov_b32_e32 v29, 0
	v_mov_b32_e32 v28, 0
	v_mov_b32_e32 v27, 0
	v_mov_b32_e32 v26, 0
	v_mov_b32_e32 v25, 0
	v_mov_b32_e32 v24, 0
	v_mov_b32_e32 v23, 0
	v_mov_b32_e32 v22, 0
	v_mov_b32_e32 v21, 0
	v_mov_b32_e32 v20, 0
	v_mov_b32_e32 v19, 0
	v_mov_b32_e32 v18, 0
	v_mov_b32_e32 v17, 0
	v_mov_b32_e32 v16, 0
	v_mov_b32_e32 v47, 0
	v_mov_b32_e32 v46, 0
	v_mov_b32_e32 v45, 0
	v_mov_b32_e32 v44, 0
	v_mov_b32_e32 v43, 0
	v_mov_b32_e32 v42, 0
	v_mov_b32_e32 v41, 0
	v_mov_b32_e32 v40, 0
	v_mov_b32_e32 v39, 0
	v_mov_b32_e32 v38, 0
	v_mov_b32_e32 v37, 0
	v_mov_b32_e32 v36, 0
	v_mov_b32_e32 v35, 0
	v_mov_b32_e32 v34, 0
	v_mov_b32_e32 v33, 0
	v_mov_b32_e32 v32, 0
	v_mov_b32_e32 v148, v141
	s_cbranch_scc1 .LBB0_794
	v_mov_b32_e32 v14, v0
	v_mov_b32_e32 v15, v0
	v_mov_b32_e32 v1, v0
	v_mov_b32_e32 v2, v0
	v_mov_b32_e32 v3, v0
	v_mov_b32_e32 v4, v0
	v_mov_b32_e32 v5, v0
	v_mov_b32_e32 v6, v0
	v_mov_b32_e32 v7, v0
	v_mov_b32_e32 v8, v0
	v_mov_b32_e32 v9, v0
	v_mov_b32_e32 v10, v0
	v_mov_b32_e32 v11, v0
	v_mov_b32_e32 v12, v0
	v_mov_b32_e32 v13, v0
	v_mov_b64_e32 v[30:31], v[14:15]
	s_lshl_b32 s25, s24, 5
	s_mov_b32 s26, s16
	v_mov_b32_e32 v149, v146
	v_mov_b32_e32 v148, v141
	v_mov_b64_e32 v[28:29], v[12:13]
	v_mov_b64_e32 v[26:27], v[10:11]
	v_mov_b64_e32 v[24:25], v[8:9]
	v_mov_b64_e32 v[22:23], v[6:7]
	v_mov_b64_e32 v[20:21], v[4:5]
	v_mov_b64_e32 v[18:19], v[2:3]
	v_mov_b64_e32 v[16:17], v[0:1]
	v_mov_b32_e32 v150, v188
	v_mov_b64_e32 v[46:47], v[14:15]
	v_mov_b64_e32 v[44:45], v[12:13]
	v_mov_b64_e32 v[42:43], v[10:11]
	v_mov_b64_e32 v[40:41], v[8:9]
	v_mov_b64_e32 v[38:39], v[6:7]
	v_mov_b64_e32 v[36:37], v[4:5]
	v_mov_b64_e32 v[34:35], v[2:3]
	v_mov_b64_e32 v[32:33], v[0:1]
.LBB0_788:
	s_add_i32 s27, s25, s26
	s_mul_hi_i32 s28, s27, 0x2aaaaaab
	s_lshr_b32 s29, s28, 31
	s_lshr_b32 s28, s28, 6
	s_add_i32 s28, s28, s29
	s_mulk_i32 s28, 0x180
	s_sub_i32 s27, s27, s28
	v_add_u32_e32 v1, s27, v114
	v_lshl_add_u32 v10, v1, 7, 0
	v_lshrrev_b32_e32 v1, 1, v1
	v_bitop3_b32 v2, v1, v140, 7 bitop3:0x6c
	v_lshl_add_u32 v2, v2, 4, v10
	ds_read_b128 v[2:5], v2
	v_bitop3_b32 v6, v1, v142, 7 bitop3:0x6c
	v_lshl_add_u32 v6, v6, 4, v10
	ds_read_b128 v[6:9], v6
	s_waitcnt lgkmcnt(1)
	v_mfma_f32_32x32x16_bf16 v[48:63], v[2:5], v[88:91], 0
	v_bitop3_b32 v2, v1, v143, 7 bitop3:0x6c
	v_lshl_add_u32 v2, v2, 4, v10
	ds_read_b128 v[2:5], v2
	v_bitop3_b32 v1, v1, v144, 7 bitop3:0x6c
	v_lshl_add_u32 v1, v1, 4, v10
	ds_read_b128 v[160:163], v1
	v_lshl_add_u32 v1, s27, 1, v145
	s_waitcnt lgkmcnt(2)
	v_mfma_f32_32x32x16_bf16 v[48:63], v[6:9], v[92:95], v[48:63]
	v_add_u32_e32 v1, 0xc000, v1
	ds_read2_b64 v[104:107], v1 offset1:2
	ds_read2_b64 v[6:9], v1 offset0:4 offset1:6
	v_add_u32_e32 v1, 0x6000, v1
	s_and_b32 s27, s24, -9
	s_cmp_lg_u32 s27, 0
	s_waitcnt lgkmcnt(3)
	v_mfma_f32_32x32x16_bf16 v[48:63], v[2:5], v[96:99], v[48:63]
	ds_read2_b64 v[10:13], v1 offset0:32 offset1:34
	ds_read2_b64 v[2:5], v1 offset0:36 offset1:38
	s_waitcnt lgkmcnt(4)
	v_mfma_f32_32x32x16_bf16 v[48:63], v[160:163], v[100:103], v[48:63]
	s_cbranch_scc1 .LBB0_790
	v_add_u32_e32 v1, s25, v149
	v_add_co_u32_e32 v14, vcc, 0xfffffeff, v1
	v_add_u32_e32 v14, 0xffffff00, v1
	s_nop 7
	v_cndmask_b32_e32 v48, v48, v147, vcc
	v_cmp_lt_u32_e32 vcc, s22, v14
	v_add_u32_e32 v14, 0xffffff01, v1
	s_nop 0
	v_cndmask_b32_e32 v49, v147, v49, vcc
	v_cmp_lt_u32_e32 vcc, s22, v14
	v_add_u32_e32 v14, 0xffffff02, v1
	s_nop 0
	v_cndmask_b32_e32 v50, v147, v50, vcc
	v_cmp_lt_u32_e32 vcc, s22, v14
	v_add_u32_e32 v14, 0xffffff07, v1
	s_nop 0
	v_cndmask_b32_e32 v51, v147, v51, vcc
	v_cmp_lt_u32_e32 vcc, s22, v14
	v_add_u32_e32 v14, 0xffffff08, v1
	s_nop 0
	v_cndmask_b32_e32 v52, v147, v52, vcc
	v_cmp_lt_u32_e32 vcc, s22, v14
	v_add_u32_e32 v14, 0xffffff09, v1
	s_nop 0
	v_cndmask_b32_e32 v53, v147, v53, vcc
	v_cmp_lt_u32_e32 vcc, s22, v14
	v_add_u32_e32 v14, 0xffffff0a, v1
	s_nop 0
	v_cndmask_b32_e32 v54, v147, v54, vcc
	v_cmp_lt_u32_e32 vcc, s22, v14
	v_add_u32_e32 v14, 0xffffff0f, v1
	s_nop 0
	v_cndmask_b32_e32 v55, v147, v55, vcc
	v_cmp_lt_u32_e32 vcc, s22, v14
	v_add_u32_e32 v14, 0xffffff10, v1
	s_nop 0
	v_cndmask_b32_e32 v56, v147, v56, vcc
	v_cmp_lt_u32_e32 vcc, s22, v14
	v_add_u32_e32 v14, 0xffffff11, v1
	s_nop 0
	v_cndmask_b32_e32 v57, v147, v57, vcc
	v_cmp_lt_u32_e32 vcc, s22, v14
	v_add_u32_e32 v14, 0xffffff12, v1
	s_nop 0
	v_cndmask_b32_e32 v58, v147, v58, vcc
	v_cmp_lt_u32_e32 vcc, s22, v14
	v_add_u32_e32 v14, 0xffffff17, v1
	s_nop 0
	v_cndmask_b32_e32 v59, v147, v59, vcc
	v_cmp_lt_u32_e32 vcc, s22, v14
	v_add_u32_e32 v14, 0xffffff18, v1
	s_nop 0
	v_cndmask_b32_e32 v60, v147, v60, vcc
	v_cmp_lt_u32_e32 vcc, s22, v14
	v_add_u32_e32 v14, 0xffffff19, v1
	v_add_u32_e32 v1, 0xffffff1a, v1
	v_cndmask_b32_e32 v61, v147, v61, vcc
	v_cmp_lt_u32_e32 vcc, s22, v14
	s_nop 1
	v_cndmask_b32_e32 v62, v147, v62, vcc
	v_cmp_lt_u32_e32 vcc, s22, v1
	s_nop 1
	v_cndmask_b32_e32 v63, v147, v63, vcc

.LBB0_794:
	s_mov_b64 s[84:85], vcc
	s_waitcnt vmcnt(0)
	v_max3_f32 v236, |v204|, |v205|, |v206|
	v_max3_f32 v236, |v207|, |v208|, v236
	v_max3_f32 v236, |v209|, |v210|, v236
	v_max3_f32 v236, |v211|, |v212|, v236
	v_max3_f32 v236, |v213|, |v214|, v236
	v_max3_f32 v236, |v215|, |v216|, v236
	v_max3_f32 v236, |v217|, |v218|, v236
	v_max_f32_e64 v236, |v219|, v236
	s_nop 1
	v_mov_b32_dpp v237, v236 quad_perm:[1,0,3,2] row_mask:0xf bank_mask:0xf bound_ctrl:1
	v_max_f32_e32 v236, v236, v237
	s_nop 1
	v_mov_b32_dpp v237, v236 quad_perm:[2,3,0,1] row_mask:0xf bank_mask:0xf bound_ctrl:1
	v_max_f32_e32 v236, v236, v237
	s_nop 1
	v_mov_b32_dpp v237, v236 row_half_mirror row_mask:0xf bank_mask:0xf bound_ctrl:1
	v_max_f32_e32 v236, v236, v237
	s_nop 1
	v_mov_b32_dpp v237, v236 row_mirror row_mask:0xf bank_mask:0xf bound_ctrl:1
	v_max_f32_e32 v236, v236, v237
	v_mov_b32_e32 v237, v236
	s_nop 1
	v_permlane16_swap_b32_e32 v236, v237
	s_nop 1
	v_max_f32_e32 v236, v236, v237
	v_mov_b32_e32 v237, v236
	s_nop 1
	v_permlane32_swap_b32_e32 v236, v237
	s_nop 1
	v_max_f32_e32 v236, v236, v237
	v_max_f32_e32 v236, 0xda24260, v236
	v_mul_f32_e32 v238, 0x3e2aaaab, v236
	global_store_dword v252, v238, s[78:79]
	v_div_scale_f32 v239, s[82:83], v238, v238, 1.0
	v_rcp_f32_e32 v240, v239
	v_div_scale_f32 v241, vcc, 1.0, v238, 1.0
	v_fma_f32 v242, -v239, v240, 1.0
	v_fmac_f32_e32 v240, v242, v240
	v_mul_f32_e32 v242, v241, v240
	v_fma_f32 v243, -v239, v242, v241
	v_fmac_f32_e32 v242, v243, v240
	v_fma_f32 v239, -v239, v242, v241
	s_nop 0
	v_div_fmas_f32 v239, v239, v240, v242
	v_div_fixup_f32 v244, v239, v238, 1.0
	v_mul_f32_e32 v204, v244, v204
	v_mul_f32_e32 v205, v244, v205
	v_mul_f32_e32 v206, v244, v206
	v_mul_f32_e32 v207, v244, v207
	v_mul_f32_e32 v208, v244, v208
	v_mul_f32_e32 v209, v244, v209
	v_mul_f32_e32 v210, v244, v210
	v_mul_f32_e32 v211, v244, v211
	v_mul_f32_e32 v212, v244, v212
	v_mul_f32_e32 v213, v244, v213
	v_mul_f32_e32 v214, v244, v214
	v_mul_f32_e32 v215, v244, v215
	v_mul_f32_e32 v216, v244, v216
	v_mul_f32_e32 v217, v244, v217
	v_mul_f32_e32 v218, v244, v218
	v_mul_f32_e32 v219, v244, v219
	v_mov_b32_e32 v245, 0
	v_mov_b32_e32 v246, 0
	v_mov_b32_e32 v247, 0
	v_mov_b32_e32 v237, 0
	v_cvt_scalef32_pk_fp4_f32 v245, v204, v205, 1.0
	v_cvt_scalef32_pk_fp4_f32 v246, v208, v209, 1.0
	v_cvt_scalef32_pk_fp4_f32 v247, v212, v213, 1.0
	v_cvt_scalef32_pk_fp4_f32 v237, v216, v217, 1.0
	v_cvt_scalef32_pk_fp4_f32 v245, v206, v207, 1.0 op_sel:[0,0,1,0]
	v_cvt_scalef32_pk_fp4_f32 v246, v210, v211, 1.0 op_sel:[0,0,1,0]
	v_cvt_scalef32_pk_fp4_f32 v247, v214, v215, 1.0 op_sel:[0,0,1,0]
	v_cvt_scalef32_pk_fp4_f32 v237, v218, v219, 1.0 op_sel:[0,0,1,0]
	v_mov_b32_dpp v204, v245 quad_perm:[0,0,0,0] row_mask:0xf bank_mask:0xf bound_ctrl:1
	v_mov_b32_dpp v208, v246 quad_perm:[0,0,0,0] row_mask:0xf bank_mask:0xf bound_ctrl:1
	v_mov_b32_dpp v212, v247 quad_perm:[0,0,0,0] row_mask:0xf bank_mask:0xf bound_ctrl:1
	v_mov_b32_dpp v216, v237 quad_perm:[0,0,0,0] row_mask:0xf bank_mask:0xf bound_ctrl:1
	v_mov_b32_dpp v205, v245 quad_perm:[1,1,1,1] row_mask:0xf bank_mask:0xf bound_ctrl:1
	v_mov_b32_dpp v209, v246 quad_perm:[1,1,1,1] row_mask:0xf bank_mask:0xf bound_ctrl:1
	v_mov_b32_dpp v213, v247 quad_perm:[1,1,1,1] row_mask:0xf bank_mask:0xf bound_ctrl:1
	v_mov_b32_dpp v217, v237 quad_perm:[1,1,1,1] row_mask:0xf bank_mask:0xf bound_ctrl:1
	v_mov_b32_dpp v206, v245 quad_perm:[2,2,2,2] row_mask:0xf bank_mask:0xf bound_ctrl:1
	v_mov_b32_dpp v210, v246 quad_perm:[2,2,2,2] row_mask:0xf bank_mask:0xf bound_ctrl:1
	v_mov_b32_dpp v214, v247 quad_perm:[2,2,2,2] row_mask:0xf bank_mask:0xf bound_ctrl:1
	v_mov_b32_dpp v218, v237 quad_perm:[2,2,2,2] row_mask:0xf bank_mask:0xf bound_ctrl:1
	v_mov_b32_dpp v207, v245 quad_perm:[3,3,3,3] row_mask:0xf bank_mask:0xf bound_ctrl:1
	v_mov_b32_dpp v211, v246 quad_perm:[3,3,3,3] row_mask:0xf bank_mask:0xf bound_ctrl:1
	v_mov_b32_dpp v215, v247 quad_perm:[3,3,3,3] row_mask:0xf bank_mask:0xf bound_ctrl:1
	v_mov_b32_dpp v219, v237 quad_perm:[3,3,3,3] row_mask:0xf bank_mask:0xf bound_ctrl:1
	v_bfe_u32 v204, v204, v251, 4
	v_bfe_u32 v208, v208, v251, 4
	v_bfe_u32 v212, v212, v251, 4
	v_bfe_u32 v216, v216, v251, 4
	v_bfe_u32 v205, v205, v251, 4
	v_bfe_u32 v209, v209, v251, 4
	v_bfe_u32 v213, v213, v251, 4
	v_bfe_u32 v217, v217, v251, 4
	v_bfe_u32 v206, v206, v251, 4
	v_bfe_u32 v210, v210, v251, 4
	v_bfe_u32 v214, v214, v251, 4
	v_bfe_u32 v218, v218, v251, 4
	v_bfe_u32 v207, v207, v251, 4
	v_bfe_u32 v211, v211, v251, 4
	v_bfe_u32 v215, v215, v251, 4
	v_bfe_u32 v219, v219, v251, 4
	v_lshl_or_b32 v204, v205, 4, v204
	v_lshl_or_b32 v208, v209, 4, v208
	v_lshl_or_b32 v212, v213, 4, v212
	v_lshl_or_b32 v216, v217, 4, v216
	v_lshl_or_b32 v204, v206, 8, v204
	v_lshl_or_b32 v208, v210, 8, v208
	v_lshl_or_b32 v212, v214, 8, v212
	v_lshl_or_b32 v216, v218, 8, v216
	v_lshl_or_b32 v204, v207, 12, v204
	v_lshl_or_b32 v208, v211, 12, v208
	v_lshl_or_b32 v212, v215, 12, v212
	v_lshl_or_b32 v216, v219, 12, v216
	v_mov_b32_dpp v205, v204 row_shr:4 row_mask:0xf bank_mask:0xf bound_ctrl:1
	v_mov_b32_dpp v209, v208 row_shr:4 row_mask:0xf bank_mask:0xf bound_ctrl:1
	v_mov_b32_dpp v213, v212 row_shr:4 row_mask:0xf bank_mask:0xf bound_ctrl:1
	v_mov_b32_dpp v217, v216 row_shr:4 row_mask:0xf bank_mask:0xf bound_ctrl:1
	v_lshl_or_b32 v204, v204, 16, v205
	v_lshl_or_b32 v208, v208, 16, v209
	v_lshl_or_b32 v212, v212, 16, v213
	v_lshl_or_b32 v216, v216, 16, v217
	s_mov_b32 vcc_lo, 0xf0f0f0f0
	s_mov_b32 vcc_hi, 0xf0f0f0f0
	s_mov_b64 exec, vcc
	global_store_dword v250, v204, s[76:77] nt
	s_add_u32 s80, s76, 0x200000
	s_addc_u32 s81, s77, 0
	global_store_dword v250, v208, s[80:81] nt
	s_add_u32 s80, s76, 0x400000
	s_addc_u32 s81, s77, 0
	global_store_dword v250, v212, s[80:81] nt
	s_add_u32 s80, s76, 0x600000
	s_addc_u32 s81, s77, 0
	global_store_dword v250, v216, s[80:81] nt
	s_mov_b64 exec, -1
	s_add_u32 s76, s76, 0x20000
	s_addc_u32 s77, s77, 0
	s_add_u32 s78, s78, 0x2000
	s_addc_u32 s79, s79, 0
	v_max3_f32 v236, |v220|, |v221|, |v222|
	v_max3_f32 v236, |v223|, |v224|, v236
	v_max3_f32 v236, |v225|, |v226|, v236
	v_max3_f32 v236, |v227|, |v228|, v236
	v_max3_f32 v236, |v229|, |v230|, v236
	v_max3_f32 v236, |v231|, |v232|, v236
	v_max3_f32 v236, |v233|, |v234|, v236
	v_max_f32_e64 v236, |v235|, v236
	s_nop 1
	v_mov_b32_dpp v237, v236 quad_perm:[1,0,3,2] row_mask:0xf bank_mask:0xf bound_ctrl:1
	v_max_f32_e32 v236, v236, v237
	s_nop 1
	v_mov_b32_dpp v237, v236 quad_perm:[2,3,0,1] row_mask:0xf bank_mask:0xf bound_ctrl:1
	v_max_f32_e32 v236, v236, v237
	s_nop 1
	v_mov_b32_dpp v237, v236 row_half_mirror row_mask:0xf bank_mask:0xf bound_ctrl:1
	v_max_f32_e32 v236, v236, v237
	s_nop 1
	v_mov_b32_dpp v237, v236 row_mirror row_mask:0xf bank_mask:0xf bound_ctrl:1
	v_max_f32_e32 v236, v236, v237
	v_mov_b32_e32 v237, v236
	s_nop 1
	v_permlane16_swap_b32_e32 v236, v237
	s_nop 1
	v_max_f32_e32 v236, v236, v237
	v_mov_b32_e32 v237, v236
	s_nop 1
	v_permlane32_swap_b32_e32 v236, v237
	s_nop 1
	v_max_f32_e32 v236, v236, v237
	v_max_f32_e32 v236, 0xda24260, v236
	v_mul_f32_e32 v238, 0x3e2aaaab, v236
	global_store_dword v252, v238, s[78:79]
	v_div_scale_f32 v239, s[82:83], v238, v238, 1.0
	v_rcp_f32_e32 v240, v239
	v_div_scale_f32 v241, vcc, 1.0, v238, 1.0
	v_fma_f32 v242, -v239, v240, 1.0
	v_fmac_f32_e32 v240, v242, v240
	v_mul_f32_e32 v242, v241, v240
	v_fma_f32 v243, -v239, v242, v241
	v_fmac_f32_e32 v242, v243, v240
	v_fma_f32 v239, -v239, v242, v241
	s_nop 0
	v_div_fmas_f32 v239, v239, v240, v242
	v_div_fixup_f32 v244, v239, v238, 1.0
	v_mul_f32_e32 v220, v244, v220
	v_mul_f32_e32 v221, v244, v221
	v_mul_f32_e32 v222, v244, v222
	v_mul_f32_e32 v223, v244, v223
	v_mul_f32_e32 v224, v244, v224
	v_mul_f32_e32 v225, v244, v225
	v_mul_f32_e32 v226, v244, v226
	v_mul_f32_e32 v227, v244, v227
	v_mul_f32_e32 v228, v244, v228
	v_mul_f32_e32 v229, v244, v229
	v_mul_f32_e32 v230, v244, v230
	v_mul_f32_e32 v231, v244, v231
	v_mul_f32_e32 v232, v244, v232
	v_mul_f32_e32 v233, v244, v233
	v_mul_f32_e32 v234, v244, v234
	v_mul_f32_e32 v235, v244, v235
	v_mov_b32_e32 v245, 0
	v_mov_b32_e32 v246, 0
	v_mov_b32_e32 v247, 0
	v_mov_b32_e32 v237, 0
	v_cvt_scalef32_pk_fp4_f32 v245, v220, v221, 1.0
	v_cvt_scalef32_pk_fp4_f32 v246, v224, v225, 1.0
	v_cvt_scalef32_pk_fp4_f32 v247, v228, v229, 1.0
	v_cvt_scalef32_pk_fp4_f32 v237, v232, v233, 1.0
	v_cvt_scalef32_pk_fp4_f32 v245, v222, v223, 1.0 op_sel:[0,0,1,0]
	v_cvt_scalef32_pk_fp4_f32 v246, v226, v227, 1.0 op_sel:[0,0,1,0]
	v_cvt_scalef32_pk_fp4_f32 v247, v230, v231, 1.0 op_sel:[0,0,1,0]
	v_cvt_scalef32_pk_fp4_f32 v237, v234, v235, 1.0 op_sel:[0,0,1,0]
	v_mov_b32_dpp v220, v245 quad_perm:[0,0,0,0] row_mask:0xf bank_mask:0xf bound_ctrl:1
	v_mov_b32_dpp v224, v246 quad_perm:[0,0,0,0] row_mask:0xf bank_mask:0xf bound_ctrl:1
	v_mov_b32_dpp v228, v247 quad_perm:[0,0,0,0] row_mask:0xf bank_mask:0xf bound_ctrl:1
	v_mov_b32_dpp v232, v237 quad_perm:[0,0,0,0] row_mask:0xf bank_mask:0xf bound_ctrl:1
	v_mov_b32_dpp v221, v245 quad_perm:[1,1,1,1] row_mask:0xf bank_mask:0xf bound_ctrl:1
	v_mov_b32_dpp v225, v246 quad_perm:[1,1,1,1] row_mask:0xf bank_mask:0xf bound_ctrl:1
	v_mov_b32_dpp v229, v247 quad_perm:[1,1,1,1] row_mask:0xf bank_mask:0xf bound_ctrl:1
	v_mov_b32_dpp v233, v237 quad_perm:[1,1,1,1] row_mask:0xf bank_mask:0xf bound_ctrl:1
	v_mov_b32_dpp v222, v245 quad_perm:[2,2,2,2] row_mask:0xf bank_mask:0xf bound_ctrl:1
	v_mov_b32_dpp v226, v246 quad_perm:[2,2,2,2] row_mask:0xf bank_mask:0xf bound_ctrl:1
	v_mov_b32_dpp v230, v247 quad_perm:[2,2,2,2] row_mask:0xf bank_mask:0xf bound_ctrl:1
	v_mov_b32_dpp v234, v237 quad_perm:[2,2,2,2] row_mask:0xf bank_mask:0xf bound_ctrl:1
	v_mov_b32_dpp v223, v245 quad_perm:[3,3,3,3] row_mask:0xf bank_mask:0xf bound_ctrl:1
	v_mov_b32_dpp v227, v246 quad_perm:[3,3,3,3] row_mask:0xf bank_mask:0xf bound_ctrl:1
	v_mov_b32_dpp v231, v247 quad_perm:[3,3,3,3] row_mask:0xf bank_mask:0xf bound_ctrl:1
	v_mov_b32_dpp v235, v237 quad_perm:[3,3,3,3] row_mask:0xf bank_mask:0xf bound_ctrl:1
	v_bfe_u32 v220, v220, v251, 4
	v_bfe_u32 v224, v224, v251, 4
	v_bfe_u32 v228, v228, v251, 4
	v_bfe_u32 v232, v232, v251, 4
	v_bfe_u32 v221, v221, v251, 4
	v_bfe_u32 v225, v225, v251, 4
	v_bfe_u32 v229, v229, v251, 4
	v_bfe_u32 v233, v233, v251, 4
	v_bfe_u32 v222, v222, v251, 4
	v_bfe_u32 v226, v226, v251, 4
	v_bfe_u32 v230, v230, v251, 4
	v_bfe_u32 v234, v234, v251, 4
	v_bfe_u32 v223, v223, v251, 4
	v_bfe_u32 v227, v227, v251, 4
	v_bfe_u32 v231, v231, v251, 4
	v_bfe_u32 v235, v235, v251, 4
	v_lshl_or_b32 v220, v221, 4, v220
	v_lshl_or_b32 v224, v225, 4, v224
	v_lshl_or_b32 v228, v229, 4, v228
	v_lshl_or_b32 v232, v233, 4, v232
	v_lshl_or_b32 v220, v222, 8, v220
	v_lshl_or_b32 v224, v226, 8, v224
	v_lshl_or_b32 v228, v230, 8, v228
	v_lshl_or_b32 v232, v234, 8, v232
	v_lshl_or_b32 v220, v223, 12, v220
	v_lshl_or_b32 v224, v227, 12, v224
	v_lshl_or_b32 v228, v231, 12, v228
	v_lshl_or_b32 v232, v235, 12, v232
	v_mov_b32_dpp v221, v220 row_shr:4 row_mask:0xf bank_mask:0xf bound_ctrl:1
	v_mov_b32_dpp v225, v224 row_shr:4 row_mask:0xf bank_mask:0xf bound_ctrl:1
	v_mov_b32_dpp v229, v228 row_shr:4 row_mask:0xf bank_mask:0xf bound_ctrl:1
	v_mov_b32_dpp v233, v232 row_shr:4 row_mask:0xf bank_mask:0xf bound_ctrl:1
	v_lshl_or_b32 v220, v220, 16, v221
	v_lshl_or_b32 v224, v224, 16, v225
	v_lshl_or_b32 v228, v228, 16, v229
	v_lshl_or_b32 v232, v232, 16, v233
	s_mov_b32 vcc_lo, 0xf0f0f0f0
	s_mov_b32 vcc_hi, 0xf0f0f0f0
	s_mov_b64 exec, vcc
	global_store_dword v250, v220, s[76:77] nt
	s_add_u32 s80, s76, 0x200000
	s_addc_u32 s81, s77, 0
	global_store_dword v250, v224, s[80:81] nt
	s_add_u32 s80, s76, 0x400000
	s_addc_u32 s81, s77, 0
	global_store_dword v250, v228, s[80:81] nt
	s_add_u32 s80, s76, 0x600000
	s_addc_u32 s81, s77, 0
	global_store_dword v250, v232, s[80:81] nt
	s_mov_b64 exec, -1
	s_add_u32 s76, s76, 0x20000
	s_addc_u32 s77, s77, 0
	s_add_u32 s78, s78, 0x2000
	s_addc_u32 s79, s79, 0
	s_mov_b64 vcc, s[84:85]
	v_mov_b32_e32 v1, v148
	s_nop 1
	v_permlane32_swap_b32_e32 v148, v1
	v_add_f32_e32 v1, v148, v1
	v_div_scale_f32 v2, s[24:25], v1, v1, 1.0
	v_rcp_f32_e32 v3, v2
	s_nop 0
	v_fma_f32 v4, -v2, v3, 1.0
	v_fmac_f32_e32 v3, v4, v3
	v_div_scale_f32 v4, vcc, 1.0, v1, 1.0
	v_mul_f32_e32 v5, v4, v3
	v_fma_f32 v6, -v2, v5, v4
	v_fmac_f32_e32 v5, v6, v3
	v_fma_f32 v2, -v2, v5, v4
	v_div_fmas_f32 v2, v2, v3, v5
	v_div_fixup_f32 v1, v2, v1, 1.0
	v_mul_f32_e32 v4, v16, v1
	v_mul_f32_e32 v5, v17, v1
	v_cvt_pk_bf16_f32 v4, v4, v5
	v_mul_f32_e32 v5, v18, v1
	v_mul_f32_e32 v6, v19, v1
	v_cvt_pk_bf16_f32 v5, v5, v6
	v_mul_f32_e32 v6, v32, v1
	v_mul_f32_e32 v7, v33, v1
	v_lshl_add_u64 v[2:3], v[138:139], 1, v[136:137]
	v_cvt_pk_bf16_f32 v6, v6, v7
	v_mul_f32_e32 v7, v34, v1
	v_mul_f32_e32 v8, v35, v1
	v_cvt_pk_bf16_f32 v7, v7, v8
	global_store_dwordx2 v[2:3], v[4:5], off
	global_store_dwordx2 v[2:3], v[6:7], off offset:64
	v_mul_f32_e32 v4, v20, v1
	v_mul_f32_e32 v5, v21, v1
	v_cvt_pk_bf16_f32 v4, v4, v5
	v_mul_f32_e32 v5, v22, v1
	v_mul_f32_e32 v6, v23, v1
	v_cvt_pk_bf16_f32 v5, v5, v6
	v_mul_f32_e32 v6, v36, v1
	v_mul_f32_e32 v7, v37, v1
	v_cvt_pk_bf16_f32 v6, v6, v7
	v_mul_f32_e32 v7, v38, v1
	v_mul_f32_e32 v8, v39, v1
	v_cvt_pk_bf16_f32 v7, v7, v8
	global_store_dwordx2 v[2:3], v[4:5], off offset:16
	global_store_dwordx2 v[2:3], v[6:7], off offset:80
	v_mul_f32_e32 v4, v24, v1
	v_mul_f32_e32 v5, v25, v1
	v_cvt_pk_bf16_f32 v4, v4, v5
	v_mul_f32_e32 v5, v26, v1
	v_mul_f32_e32 v6, v27, v1
	v_cvt_pk_bf16_f32 v5, v5, v6
	v_mul_f32_e32 v6, v40, v1
	v_mul_f32_e32 v7, v41, v1
	v_cvt_pk_bf16_f32 v6, v6, v7
	v_mul_f32_e32 v7, v42, v1
	v_mul_f32_e32 v8, v43, v1
	v_cvt_pk_bf16_f32 v7, v7, v8
	global_store_dwordx2 v[2:3], v[4:5], off offset:32
	global_store_dwordx2 v[2:3], v[6:7], off offset:96
	v_mul_f32_e32 v4, v28, v1
	v_mul_f32_e32 v5, v29, v1
	v_cvt_pk_bf16_f32 v4, v4, v5
	v_mul_f32_e32 v5, v30, v1
	v_mul_f32_e32 v6, v31, v1
	v_cvt_pk_bf16_f32 v5, v5, v6
	v_mul_f32_e32 v6, v44, v1
	v_mul_f32_e32 v7, v45, v1
	v_cvt_pk_bf16_f32 v6, v6, v7
	v_mul_f32_e32 v7, v46, v1
	s_and_b64 vcc, exec, s[4:5]
	v_mul_f32_e32 v1, v47, v1
	v_cvt_pk_bf16_f32 v7, v7, v1
	global_store_dwordx2 v[2:3], v[4:5], off offset:48
	global_store_dwordx2 v[2:3], v[6:7], off offset:112
	s_cbranch_vccnz .LBB0_783
	s_addk_i32 s17, 0x240
	s_and_b32 s4, s17, 0xffff
	s_mul_i32 s4, s4, 0xaaab
	s_lshr_b32 s4, s4, 24
	s_mulk_i32 s4, 0x180
	s_sub_i32 s4, s17, s4
	s_and_b32 s4, s4, 0xffff
	v_add_u32_e32 v1, s4, v108
	v_lshlrev_b32_e32 v2, 7, v1
	v_lshrrev_b32_e32 v1, 1, v1
	v_xor_b32_e32 v1, v1, v115
	v_lshlrev_b32_e32 v1, 4, v1
	v_and_b32_e32 v1, 0x70, v1
	v_add3_u32 v1, 0, v2, v1
	s_waitcnt vmcnt(23)
	ds_write_b128 v1, v[80:83]
	v_or_b32_e32 v1, s4, v110
	v_lshlrev_b32_e32 v1, 1, v1
	v_add3_u32 v1, v121, v1, s21
	s_waitcnt vmcnt(22)
	ds_write2_b64 v1, v[84:85], v[86:87] offset1:1
	s_branch .LBB0_783

.LBB0_966:
	s_cmp_lt_i32 s56, 15
	s_cselect_b64 s[0:1], -1, 0
	s_and_b64 s[40:41], s[0:1], s[4:5]
	s_andn2_b64 vcc, exec, s[40:41]
	s_cbranch_vccnz .LBB0_1021
	v_mbcnt_lo_u32_b32 v246, -1, 0
	v_mbcnt_hi_u32_b32 v246, -1, v246
	v_readlane_b32 s21, v248, 0
	s_andn2_b32 s26, s21, 63
	v_add_u32_e32 v242, s26, v246
	s_lshr_b32 s21, s21, 6
	s_mov_b32 s4, 0
	s_mov_b32 s5, -1
	s_mov_b32 s6, 0xffffff80
	s_mov_b32 s7, 0xffffffc0
	v_lshrrev_b32_e32 v245, 5, v246
	v_and_b32_e32 v247, 31, v246
	v_lshlrev_b32_e32 v239, 12, v247
	v_lshl_or_b32 v239, v245, 4, v239
	v_lshlrev_b32_e32 v241, 9, v247
	v_lshl_or_b32 v241, v245, 5, v241
	v_lshlrev_b32_e32 v240, 4, v247
	s_lshl_b32 s26, s21, 11
	s_add_i32 s26, s26, 0x10000
	v_add_u32_e32 v240, s26, v240
	v_and_b32_e32 v215, 15, v246
	v_xor_b32_e32 v215, v215, v245
	v_lshlrev_b32_e32 v215, 4, v215
	v_lshl_or_b32 v215, v247, 8, v215
	v_xor_b32_e32 v232, 32, v215
	v_xor_b32_e32 v233, 64, v215
	v_xor_b32_e32 v234, 0x60, v215
	v_xor_b32_e32 v235, 0x80, v215
	v_xor_b32_e32 v236, 0xa0, v215
	v_xor_b32_e32 v237, 0xc0, v215
	v_xor_b32_e32 v238, 0xe0, v215
	v_lshlrev_b32_e32 v247, 2, v245
	v_xor_b32_e32 v211, 4, v247
	v_lshrrev_b32_e32 v243, 4, v242
	v_xor_b32_e32 v247, v243, v242
	v_lshlrev_b32_e32 v242, 4, v242
	v_and_b32_e32 v247, 15, v247
	v_lshlrev_b32_e32 v247, 4, v247
	v_lshl_or_b32 v243, v243, 8, v247
	v_mov_b32_e32 v244, 0xff800000
	v_mov_b32_e32 v247, 0x14000
	v_mov_b32_e32 v128, 0x20021001
	ds_write_b32 v247, v128 offset:0
	v_mov_b32_e32 v128, 0x40043003
	ds_write_b32 v247, v128 offset:4
	v_mov_b32_e32 v128, 0x60065005
	ds_write_b32 v247, v128 offset:8
	v_mov_b32_e32 v128, 0x80087007
	ds_write_b32 v247, v128 offset:12
	v_mov_b32_e32 v128, 0xa00a9009
	ds_write_b32 v247, v128 offset:16
	v_mov_b32_e32 v128, 0xc00cb00b
	ds_write_b32 v247, v128 offset:20
	v_mov_b32_e32 v128, 0xe00ed00d
	ds_write_b32 v247, v128 offset:24
	v_mov_b32_e32 v128, 0x2112f00f
	ds_write_b32 v247, v128 offset:28
	v_mov_b32_e32 v128, 0x41143113
	ds_write_b32 v247, v128 offset:32
	v_mov_b32_e32 v128, 0x61165115
	ds_write_b32 v247, v128 offset:36
	v_mov_b32_e32 v128, 0x32237117
	ds_write_b32 v247, v128 offset:40
	v_mov_b32_e32 v128, 0x4224
	ds_write_b32 v247, v128 offset:44
	v_mov_b32_e32 v128, 0x22221111
	ds_write_b32 v247, v128 offset:48
	v_mov_b32_e32 v128, 0x3333
	ds_write_b32 v247, v128 offset:52
	v_mov_b32_e32 v128, 0
	ds_write_b32 v247, v128 offset:56
	v_mov_b32_e32 v128, 0
	ds_write_b32 v247, v128 offset:60
	s_and_b32 s25, s2, 7
	s_lshl_b32 s25, s25, 3
	s_bfe_u32 s26, s2, 0x30003
	s_add_i32 s25, s25, s26
	s_lshl_b32 s23, s25, 8
	s_lshl_b32 s26, s21, 5
	s_add_i32 s23, s23, s26
	v_lshlrev_b32_e32 v212, 4, v246
	v_lshlrev_b32_e32 v213, 1, v246
	v_mov_b32_e32 v214, 0
	s_lshl_b32 s14, s2, 3
	s_add_i32 s14, s14, s21
	s_and_b32 s15, s14, 1
	s_lshr_b32 s14, s14, 1
	v_readlane_b32 s8, v248, 12
	v_readlane_b32 s9, v248, 13
	s_lshl_b32 s26, s14, 13
	s_lshl_b32 s25, s15, 12
	s_add_i32 s26, s26, s25
	s_add_i32 s26, s26, 0x8000000
	s_add_u32 s8, s8, s26
	s_addc_u32 s9, s9, 0
	v_readlane_b32 s12, v248, 14
	v_readlane_b32 s13, v248, 15
	s_add_i32 s25, s25, 0x2000
	s_add_u32 s12, s12, s25
	s_addc_u32 s13, s13, 0
	global_load_dwordx4 v[176:179], v212, s[12:13] offset:0
	global_load_dwordx4 v[180:183], v212, s[12:13] offset:1024
	global_load_dwordx4 v[184:187], v212, s[12:13] offset:2048
	global_load_dwordx4 v[188:191], v212, s[12:13] offset:3072
	s_lshl_b32 s26, s15, 23
	s_lshl_b32 s25, s14, 7
	s_add_i32 s26, s26, s25
	s_add_i32 s26, s26, 0x10000000
	s_add_u32 s10, s54, s26
	s_addc_u32 s11, s55, 0
	s_lshl_b32 s26, s14, 3
	s_lshl_b32 s25, s15, 2
	s_add_i32 s26, s26, s25
	s_add_i32 s26, s26, 0xa0000
	s_add_u32 s12, s54, s26
	s_addc_u32 s13, s55, 0
	global_load_dwordx4 v[160:163], v212, s[8:9] offset:0 nt
	global_load_dwordx4 v[164:167], v212, s[8:9] offset:1024 nt
	global_load_dwordx4 v[168:171], v212, s[8:9] offset:2048 nt
	global_load_dwordx4 v[172:175], v212, s[8:9] offset:3072 nt
	s_add_u32 s8, s8, 0x800000
	s_addc_u32 s9, s9, 0
	v_mov_b32_e32 v246, 0x14000
	s_lshr_b32 s24, s2, 6
	s_mov_b32 s22, 0
.Ltk1_unit:
	s_lshl_b32 s26, s24, 9
	s_lshl_b32 s20, s23, 12
	s_add_i32 s26, s26, s20
	s_add_i32 s26, s26, 0x1c000000
	s_add_u32 s16, s54, s26
	s_addc_u32 s17, s55, 0
	s_lshl_b32 s26, s24, 16
	s_add_i32 s26, s26, 0x380000
	s_add_u32 s18, s54, s26
	s_addc_u32 s19, s55, 0
	s_lshl_b32 s20, s23, 9
	s_lshl_b32 s26, s24, 6
	s_add_i32 s20, s20, s26
	s_add_i32 s26, s20, 0x28000000
	s_add_u32 s28, s54, s26
	s_addc_u32 s29, s55, 0
	s_add_i32 s26, s20, 0x28800000
	s_add_u32 s30, s54, s26
	s_addc_u32 s31, s55, 0
	s_barrier
	global_load_dwordx4 v[0:3], v242, s[18:19]
	v_add_u32_e32 v247, 0x2000, v242
	global_load_dwordx4 v[4:7], v247, s[18:19]
	v_add_u32_e32 v247, 0x4000, v242
	global_load_dwordx4 v[8:11], v247, s[18:19]
	v_add_u32_e32 v247, 0x6000, v242
	global_load_dwordx4 v[12:15], v247, s[18:19]
	v_add_u32_e32 v247, 0x8000, v242
	global_load_dwordx4 v[16:19], v247, s[18:19]
	v_add_u32_e32 v247, 0xa000, v242
	global_load_dwordx4 v[20:23], v247, s[18:19]
	v_add_u32_e32 v247, 0xc000, v242
	global_load_dwordx4 v[24:27], v247, s[18:19]
	v_add_u32_e32 v247, 0xe000, v242
	global_load_dwordx4 v[28:31], v247, s[18:19]
	global_load_dwordx4 v[64:67], v239, s[16:17] offset:0
	global_load_dwordx4 v[68:71], v239, s[16:17] offset:32
	global_load_dwordx4 v[72:75], v239, s[16:17] offset:64
	global_load_dwordx4 v[76:79], v239, s[16:17] offset:96
	global_load_dwordx4 v[80:83], v239, s[16:17] offset:128
	global_load_dwordx4 v[84:87], v239, s[16:17] offset:160
	global_load_dwordx4 v[88:91], v239, s[16:17] offset:192
	global_load_dwordx4 v[92:95], v239, s[16:17] offset:224
	s_waitcnt vmcnt(15)
	ds_write_b128 v243, v[0:3] offset:0
	s_waitcnt vmcnt(14)
	ds_write_b128 v243, v[4:7] offset:8192
	s_waitcnt vmcnt(13)
	ds_write_b128 v243, v[8:11] offset:16384
	s_waitcnt vmcnt(12)
	ds_write_b128 v243, v[12:15] offset:24576
	s_waitcnt vmcnt(11)
	ds_write_b128 v243, v[16:19] offset:32768
	s_waitcnt vmcnt(10)
	ds_write_b128 v243, v[20:23] offset:40960
	s_waitcnt vmcnt(9)
	ds_write_b128 v243, v[24:27] offset:49152
	s_waitcnt vmcnt(8)
	ds_write_b128 v243, v[28:31] offset:57344
	s_waitcnt lgkmcnt(0)
	s_barrier
	ds_read_b128 v[96:99], v215 offset:0
	ds_read_b128 v[100:103], v232 offset:0
	ds_read_b128 v[104:107], v233 offset:0
	ds_read_b128 v[108:111], v234 offset:0
	ds_read_b128 v[112:115], v235 offset:0
	ds_read_b128 v[116:119], v236 offset:0
	ds_read_b128 v[120:123], v237 offset:0
	ds_read_b128 v[124:127], v238 offset:0
	s_waitcnt vmcnt(0)
	s_waitcnt lgkmcnt(4)
	v_mfma_f32_32x32x16_bf16 v[0:15], v[96:99], v[64:67], 0
	v_mfma_f32_32x32x16_bf16 v[0:15], v[100:103], v[68:71], v[0:15]
	v_mfma_f32_32x32x16_bf16 v[0:15], v[104:107], v[72:75], v[0:15]
	v_mfma_f32_32x32x16_bf16 v[0:15], v[108:111], v[76:79], v[0:15]
	ds_read_b128 v[96:99], v215 offset:8192
	ds_read_b128 v[100:103], v232 offset:8192
	ds_read_b128 v[104:107], v233 offset:8192
	ds_read_b128 v[108:111], v234 offset:8192
	s_waitcnt lgkmcnt(4)
	v_mfma_f32_32x32x16_bf16 v[0:15], v[112:115], v[80:83], v[0:15]
	v_mfma_f32_32x32x16_bf16 v[0:15], v[116:119], v[84:87], v[0:15]
	v_mfma_f32_32x32x16_bf16 v[0:15], v[120:123], v[88:91], v[0:15]
	v_mfma_f32_32x32x16_bf16 v[0:15], v[124:127], v[92:95], v[0:15]
	ds_read_b128 v[112:115], v235 offset:8192
	ds_read_b128 v[116:119], v236 offset:8192
	ds_read_b128 v[120:123], v237 offset:8192
	ds_read_b128 v[124:127], v238 offset:8192
	s_waitcnt lgkmcnt(4)
	v_mfma_f32_32x32x16_bf16 v[16:31], v[96:99], v[64:67], 0
	v_mfma_f32_32x32x16_bf16 v[16:31], v[100:103], v[68:71], v[16:31]
	v_mfma_f32_32x32x16_bf16 v[16:31], v[104:107], v[72:75], v[16:31]
	v_mfma_f32_32x32x16_bf16 v[16:31], v[108:111], v[76:79], v[16:31]
	ds_read_b128 v[96:99], v215 offset:16384
	ds_read_b128 v[100:103], v232 offset:16384
	ds_read_b128 v[104:107], v233 offset:16384
	ds_read_b128 v[108:111], v234 offset:16384
	s_waitcnt lgkmcnt(4)
	v_mfma_f32_32x32x16_bf16 v[16:31], v[112:115], v[80:83], v[16:31]
	v_mfma_f32_32x32x16_bf16 v[16:31], v[116:119], v[84:87], v[16:31]
	v_mfma_f32_32x32x16_bf16 v[16:31], v[120:123], v[88:91], v[16:31]
	v_mfma_f32_32x32x16_bf16 v[16:31], v[124:127], v[92:95], v[16:31]
	ds_read_b128 v[112:115], v235 offset:16384
	ds_read_b128 v[116:119], v236 offset:16384
	ds_read_b128 v[120:123], v237 offset:16384
	ds_read_b128 v[124:127], v238 offset:16384
	s_waitcnt lgkmcnt(4)
	v_mfma_f32_32x32x16_bf16 v[32:47], v[96:99], v[64:67], 0
	v_mfma_f32_32x32x16_bf16 v[32:47], v[100:103], v[68:71], v[32:47]
	v_mfma_f32_32x32x16_bf16 v[32:47], v[104:107], v[72:75], v[32:47]
	v_mfma_f32_32x32x16_bf16 v[32:47], v[108:111], v[76:79], v[32:47]
	ds_read_b128 v[96:99], v215 offset:24576
	ds_read_b128 v[100:103], v232 offset:24576
	ds_read_b128 v[104:107], v233 offset:24576
	ds_read_b128 v[108:111], v234 offset:24576
	s_waitcnt lgkmcnt(4)
	v_mfma_f32_32x32x16_bf16 v[32:47], v[112:115], v[80:83], v[32:47]
	v_mfma_f32_32x32x16_bf16 v[32:47], v[116:119], v[84:87], v[32:47]
	v_mfma_f32_32x32x16_bf16 v[32:47], v[120:123], v[88:91], v[32:47]
	v_mfma_f32_32x32x16_bf16 v[32:47], v[124:127], v[92:95], v[32:47]
	ds_read_b128 v[112:115], v235 offset:24576
	ds_read_b128 v[116:119], v236 offset:24576
	ds_read_b128 v[120:123], v237 offset:24576
	ds_read_b128 v[124:127], v238 offset:24576
	s_waitcnt lgkmcnt(4)
	v_mfma_f32_32x32x16_bf16 v[48:63], v[96:99], v[64:67], 0
	v_mfma_f32_32x32x16_bf16 v[48:63], v[100:103], v[68:71], v[48:63]
	v_mfma_f32_32x32x16_bf16 v[48:63], v[104:107], v[72:75], v[48:63]
	v_mfma_f32_32x32x16_bf16 v[48:63], v[108:111], v[76:79], v[48:63]
	s_waitcnt lgkmcnt(0)
	v_mfma_f32_32x32x16_bf16 v[48:63], v[112:115], v[80:83], v[48:63]
	v_mfma_f32_32x32x16_bf16 v[48:63], v[116:119], v[84:87], v[48:63]
	v_mfma_f32_32x32x16_bf16 v[48:63], v[120:123], v[88:91], v[48:63]
	v_mfma_f32_32x32x16_bf16 v[48:63], v[124:127], v[92:95], v[48:63]
	global_load_dwordx4 v[64:67], v239, s[16:17] offset:256
	global_load_dwordx4 v[68:71], v239, s[16:17] offset:288
	global_load_dwordx4 v[72:75], v239, s[16:17] offset:320
	global_load_dwordx4 v[76:79], v239, s[16:17] offset:352
	global_load_dwordx4 v[80:83], v239, s[16:17] offset:384
	global_load_dwordx4 v[84:87], v239, s[16:17] offset:416
	global_load_dwordx4 v[88:91], v239, s[16:17] offset:448
	global_load_dwordx4 v[92:95], v239, s[16:17] offset:480
	s_nop 11
	v_and_or_b32 v0, v0, s6, v211
	v_or_b32_e32 v0, 0x7b, v0
	v_and_or_b32 v1, v1, s6, v211
	v_or_b32_e32 v1, 0x7a, v1
	v_and_or_b32 v2, v2, s6, v211
	v_or_b32_e32 v2, 0x79, v2
	v_and_or_b32 v3, v3, s6, v211
	v_or_b32_e32 v3, 0x78, v3
	v_and_or_b32 v4, v4, s6, v211
	v_or_b32_e32 v4, 0x73, v4
	v_and_or_b32 v5, v5, s6, v211
	v_or_b32_e32 v5, 0x72, v5
	v_and_or_b32 v6, v6, s6, v211
	v_or_b32_e32 v6, 0x71, v6
	v_and_or_b32 v7, v7, s6, v211
	v_or_b32_e32 v7, 0x70, v7
	v_and_or_b32 v8, v8, s6, v211
	v_or_b32_e32 v8, 0x6b, v8
	v_and_or_b32 v9, v9, s6, v211
	v_or_b32_e32 v9, 0x6a, v9
	v_and_or_b32 v10, v10, s6, v211
	v_or_b32_e32 v10, 0x69, v10
	v_and_or_b32 v11, v11, s6, v211
	v_or_b32_e32 v11, 0x68, v11
	v_and_or_b32 v12, v12, s6, v211
	v_or_b32_e32 v12, 0x63, v12
	v_and_or_b32 v13, v13, s6, v211
	v_or_b32_e32 v13, 0x62, v13
	v_and_or_b32 v14, v14, s6, v211
	v_or_b32_e32 v14, 0x61, v14
	v_and_or_b32 v15, v15, s6, v211
	v_or_b32_e32 v15, 0x60, v15
	v_and_or_b32 v16, v16, s6, v211
	v_or_b32_e32 v16, 0x5b, v16
	v_and_or_b32 v17, v17, s6, v211
	v_or_b32_e32 v17, 0x5a, v17
	v_and_or_b32 v18, v18, s6, v211
	v_or_b32_e32 v18, 0x59, v18
	v_and_or_b32 v19, v19, s6, v211
	v_or_b32_e32 v19, 0x58, v19
	v_and_or_b32 v20, v20, s6, v211
	v_or_b32_e32 v20, 0x53, v20
	v_and_or_b32 v21, v21, s6, v211
	v_or_b32_e32 v21, 0x52, v21
	v_and_or_b32 v22, v22, s6, v211
	v_or_b32_e32 v22, 0x51, v22
	v_and_or_b32 v23, v23, s6, v211
	v_or_b32_e32 v23, 0x50, v23
	v_and_or_b32 v24, v24, s6, v211
	v_or_b32_e32 v24, 0x4b, v24
	v_and_or_b32 v25, v25, s6, v211
	v_or_b32_e32 v25, 0x4a, v25
	v_and_or_b32 v26, v26, s6, v211
	v_or_b32_e32 v26, 0x49, v26
	v_and_or_b32 v27, v27, s6, v211
	v_or_b32_e32 v27, 0x48, v27
	v_and_or_b32 v28, v28, s6, v211
	v_or_b32_e32 v28, 0x43, v28
	v_and_or_b32 v29, v29, s6, v211
	v_or_b32_e32 v29, 0x42, v29
	v_and_or_b32 v30, v30, s6, v211
	v_or_b32_e32 v30, 0x41, v30
	v_and_or_b32 v31, v31, s6, v211
	v_or_b32_e32 v31, 64, v31
	v_and_or_b32 v32, v32, s6, v211
	v_or_b32_e32 v32, 59, v32
	v_and_or_b32 v33, v33, s6, v211
	v_or_b32_e32 v33, 58, v33
	v_and_or_b32 v34, v34, s6, v211
	v_or_b32_e32 v34, 57, v34
	v_and_or_b32 v35, v35, s6, v211
	v_or_b32_e32 v35, 56, v35
	v_and_or_b32 v36, v36, s6, v211
	v_or_b32_e32 v36, 51, v36
	v_and_or_b32 v37, v37, s6, v211
	v_or_b32_e32 v37, 50, v37
	v_and_or_b32 v38, v38, s6, v211
	v_or_b32_e32 v38, 49, v38
	v_and_or_b32 v39, v39, s6, v211
	v_or_b32_e32 v39, 48, v39
	v_and_or_b32 v40, v40, s6, v211
	v_or_b32_e32 v40, 43, v40
	v_and_or_b32 v41, v41, s6, v211
	v_or_b32_e32 v41, 42, v41
	v_and_or_b32 v42, v42, s6, v211
	v_or_b32_e32 v42, 41, v42
	v_and_or_b32 v43, v43, s6, v211
	v_or_b32_e32 v43, 40, v43
	v_and_or_b32 v44, v44, s6, v211
	v_or_b32_e32 v44, 35, v44
	v_and_or_b32 v45, v45, s6, v211
	v_or_b32_e32 v45, 34, v45
	v_and_or_b32 v46, v46, s6, v211
	v_or_b32_e32 v46, 33, v46
	v_and_or_b32 v47, v47, s6, v211
	v_or_b32_e32 v47, 32, v47
	v_and_or_b32 v48, v48, s6, v211
	v_or_b32_e32 v48, 27, v48
	v_and_or_b32 v49, v49, s6, v211
	v_or_b32_e32 v49, 26, v49
	v_and_or_b32 v50, v50, s6, v211
	v_or_b32_e32 v50, 25, v50
	v_and_or_b32 v51, v51, s6, v211
	v_or_b32_e32 v51, 24, v51
	v_and_or_b32 v52, v52, s6, v211
	v_or_b32_e32 v52, 19, v52
	v_and_or_b32 v53, v53, s6, v211
	v_or_b32_e32 v53, 18, v53
	v_and_or_b32 v54, v54, s6, v211
	v_or_b32_e32 v54, 17, v54
	v_and_or_b32 v55, v55, s6, v211
	v_or_b32_e32 v55, 16, v55
	v_and_or_b32 v56, v56, s6, v211
	v_or_b32_e32 v56, 11, v56
	v_and_or_b32 v57, v57, s6, v211
	v_or_b32_e32 v57, 10, v57
	v_and_or_b32 v58, v58, s6, v211
	v_or_b32_e32 v58, 9, v58
	v_and_or_b32 v59, v59, s6, v211
	v_or_b32_e32 v59, 8, v59
	v_and_or_b32 v60, v60, s6, v211
	v_or_b32_e32 v60, 3, v60
	v_and_or_b32 v61, v61, s6, v211
	v_or_b32_e32 v61, 2, v61
	v_and_or_b32 v62, v62, s6, v211
	v_or_b32_e32 v62, 1, v62
	v_and_or_b32 v63, v63, s6, v211
	v_or_b32_e32 v63, 0, v63
	v_max_f32_e32 v144, v0, v13
	v_min_f32_e32 v13, v0, v13
	v_max_f32_e32 v145, v1, v12
	v_min_f32_e32 v12, v1, v12
	v_max_f32_e32 v146, v2, v15
	v_min_f32_e32 v15, v2, v15
	v_max_f32_e32 v147, v3, v14
	v_min_f32_e32 v14, v3, v14
	v_max_f32_e32 v148, v4, v8
	v_min_f32_e32 v8, v4, v8
	v_max_f32_e32 v149, v5, v6
	v_min_f32_e32 v6, v5, v6
	v_max_f32_e32 v150, v7, v11
	v_min_f32_e32 v11, v7, v11
	v_max_f32_e32 v151, v9, v10
	v_min_f32_e32 v10, v9, v10
	v_max_f32_e32 v249, v144, v149
	v_min_f32_e32 v149, v144, v149
	v_max_f32_e32 v250, v145, v150
	v_min_f32_e32 v150, v145, v150
	v_max_f32_e32 v251, v146, v151
	v_min_f32_e32 v151, v146, v151
	v_max_f32_e32 v252, v147, v148
	v_min_f32_e32 v148, v147, v148
	v_max_f32_e32 v253, v6, v13
	v_min_f32_e32 v13, v6, v13
	v_max_f32_e32 v254, v8, v14
	v_min_f32_e32 v14, v8, v14
	v_max_f32_e32 v255, v10, v15
	v_min_f32_e32 v15, v10, v15
	v_max_f32_e32 v96, v11, v12
	v_min_f32_e32 v12, v11, v12
	v_max_f32_e32 v97, v249, v250
	v_min_f32_e32 v250, v249, v250
	v_max_f32_e32 v98, v251, v252
	v_min_f32_e32 v252, v251, v252
	v_max_f32_e32 v99, v148, v149
	v_min_f32_e32 v149, v148, v149
	v_max_f32_e32 v100, v253, v254
	v_min_f32_e32 v254, v253, v254
	v_max_f32_e32 v101, v150, v151
	v_min_f32_e32 v151, v150, v151
	v_max_f32_e32 v102, v255, v96
	v_min_f32_e32 v96, v255, v96
	v_max_f32_e32 v103, v12, v13
	v_min_f32_e32 v13, v12, v13
	v_max_f32_e32 v104, v14, v15
	v_min_f32_e32 v15, v14, v15
	v_max_f32_e32 v105, v97, v98
	v_min_f32_e32 v98, v97, v98
	v_max_f32_e32 v106, v250, v252
	v_min_f32_e32 v252, v250, v252
	v_max_f32_e32 v107, v99, v102
	v_min_f32_e32 v102, v99, v102
	v_max_f32_e32 v108, v149, v96
	v_min_f32_e32 v96, v149, v96
	v_max_f32_e32 v109, v100, v101
	v_min_f32_e32 v101, v100, v101
	v_max_f32_e32 v110, v254, v151
	v_min_f32_e32 v151, v254, v151
	v_max_f32_e32 v111, v103, v104
	v_min_f32_e32 v104, v103, v104
	v_max_f32_e32 v112, v13, v15
	v_min_f32_e32 v15, v13, v15
	v_max_f32_e32 v113, v106, v98
	v_min_f32_e32 v98, v106, v98
	v_max_f32_e32 v114, v252, v111
	v_min_f32_e32 v111, v252, v111
	v_max_f32_e32 v115, v107, v109
	v_min_f32_e32 v109, v107, v109
	v_max_f32_e32 v116, v108, v101
	v_min_f32_e32 v101, v108, v101
	v_max_f32_e32 v117, v110, v102
	v_min_f32_e32 v102, v110, v102
	v_max_f32_e32 v118, v151, v96
	v_min_f32_e32 v96, v151, v96
	v_max_f32_e32 v119, v112, v104
	v_min_f32_e32 v104, v112, v104
	v_max_f32_e32 v120, v113, v115
	v_min_f32_e32 v115, v113, v115
	v_max_f32_e32 v121, v98, v109
	v_min_f32_e32 v109, v98, v109
	v_max_f32_e32 v122, v116, v117
	v_min_f32_e32 v117, v116, v117
	v_max_f32_e32 v123, v101, v102
	v_min_f32_e32 v102, v101, v102
	v_max_f32_e32 v124, v118, v119
	v_min_f32_e32 v119, v118, v119
	v_max_f32_e32 v125, v96, v104
	v_min_f32_e32 v104, v96, v104
	v_max_f32_e32 v126, v121, v115
	v_min_f32_e32 v115, v121, v115
	v_max_f32_e32 v127, v114, v109
	v_min_f32_e32 v109, v114, v109
	v_max_f32_e32 v0, v124, v111
	v_min_f32_e32 v111, v124, v111
	v_max_f32_e32 v1, v125, v119
	v_min_f32_e32 v119, v125, v119
	v_max_f32_e32 v2, v127, v122
	v_min_f32_e32 v122, v127, v122
	v_max_f32_e32 v3, v109, v117
	v_min_f32_e32 v117, v109, v117
	v_max_f32_e32 v4, v123, v0
	v_min_f32_e32 v0, v123, v0
	v_max_f32_e32 v5, v102, v111
	v_min_f32_e32 v111, v102, v111
	v_max_f32_e32 v7, v2, v115
	v_min_f32_e32 v115, v2, v115
	v_max_f32_e32 v9, v122, v3
	v_min_f32_e32 v3, v122, v3
	v_max_f32_e32 v144, v4, v117
	v_min_f32_e32 v117, v4, v117
	v_max_f32_e32 v145, v0, v5
	v_min_f32_e32 v5, v0, v5
	v_max_f32_e32 v146, v1, v111
	v_min_f32_e32 v111, v1, v111
	v_max_f32_e32 v147, v3, v144
	v_min_f32_e32 v144, v3, v144
	v_max_f32_e32 v6, v117, v145
	v_min_f32_e32 v145, v117, v145
	v_max_f32_e32 v8, v16, v29
	v_min_f32_e32 v29, v16, v29
	v_max_f32_e32 v10, v17, v28
	v_min_f32_e32 v28, v17, v28
	v_max_f32_e32 v11, v18, v31
	v_min_f32_e32 v31, v18, v31
	v_max_f32_e32 v249, v19, v30
	v_min_f32_e32 v30, v19, v30
	v_max_f32_e32 v251, v20, v24
	v_min_f32_e32 v24, v20, v24
	v_max_f32_e32 v148, v21, v22
	v_min_f32_e32 v22, v21, v22
	v_max_f32_e32 v253, v23, v27
	v_min_f32_e32 v27, v23, v27
	v_max_f32_e32 v150, v25, v26
	v_min_f32_e32 v26, v25, v26
	v_max_f32_e32 v255, v8, v148
	v_min_f32_e32 v148, v8, v148
	v_max_f32_e32 v12, v10, v253
	v_min_f32_e32 v253, v10, v253
	v_max_f32_e32 v14, v11, v150
	v_min_f32_e32 v150, v11, v150
	v_max_f32_e32 v97, v249, v251
	v_min_f32_e32 v251, v249, v251
	v_max_f32_e32 v250, v22, v29
	v_min_f32_e32 v29, v22, v29
	v_max_f32_e32 v99, v24, v30
	v_min_f32_e32 v30, v24, v30
	v_max_f32_e32 v149, v26, v31
	v_min_f32_e32 v31, v26, v31
	v_max_f32_e32 v100, v27, v28
	v_min_f32_e32 v28, v27, v28
	v_max_f32_e32 v254, v255, v12
	v_min_f32_e32 v12, v255, v12
	v_max_f32_e32 v103, v14, v97
	v_min_f32_e32 v97, v14, v97
	v_max_f32_e32 v13, v251, v148
	v_min_f32_e32 v148, v251, v148
	v_max_f32_e32 v106, v250, v99
	v_min_f32_e32 v99, v250, v99
	v_max_f32_e32 v252, v253, v150
	v_min_f32_e32 v150, v253, v150
	v_max_f32_e32 v107, v149, v100
	v_min_f32_e32 v100, v149, v100
	v_max_f32_e32 v108, v28, v29
	v_min_f32_e32 v29, v28, v29
	v_max_f32_e32 v110, v30, v31
	v_min_f32_e32 v31, v30, v31
	v_max_f32_e32 v151, v254, v103
	v_min_f32_e32 v103, v254, v103
	v_max_f32_e32 v112, v12, v97
	v_min_f32_e32 v97, v12, v97
	v_max_f32_e32 v113, v13, v107
	v_min_f32_e32 v107, v13, v107
	v_max_f32_e32 v98, v148, v100
	v_min_f32_e32 v100, v148, v100
	v_max_f32_e32 v116, v106, v252
	v_min_f32_e32 v252, v106, v252
	v_max_f32_e32 v101, v99, v150
	v_min_f32_e32 v150, v99, v150
	v_max_f32_e32 v118, v108, v110
	v_min_f32_e32 v110, v108, v110
	v_max_f32_e32 v96, v29, v31
	v_min_f32_e32 v31, v29, v31
	v_max_f32_e32 v121, v112, v103
	v_min_f32_e32 v103, v112, v103
	v_max_f32_e32 v114, v97, v118
	v_min_f32_e32 v118, v97, v118
	v_max_f32_e32 v124, v113, v116
	v_min_f32_e32 v116, v113, v116
	v_max_f32_e32 v125, v98, v252
	v_min_f32_e32 v252, v98, v252
	v_max_f32_e32 v127, v101, v107
	v_min_f32_e32 v107, v101, v107
	v_max_f32_e32 v109, v150, v100
	v_min_f32_e32 v100, v150, v100
	v_max_f32_e32 v123, v96, v110
	v_min_f32_e32 v110, v96, v110
	v_max_f32_e32 v102, v121, v124
	v_min_f32_e32 v124, v121, v124
	v_max_f32_e32 v2, v103, v116
	v_min_f32_e32 v116, v103, v116
	v_max_f32_e32 v122, v125, v127
	v_min_f32_e32 v127, v125, v127
	v_max_f32_e32 v4, v252, v107
	v_min_f32_e32 v107, v252, v107
	v_max_f32_e32 v0, v109, v123
	v_min_f32_e32 v123, v109, v123
	v_max_f32_e32 v1, v100, v110
	v_min_f32_e32 v110, v100, v110
	v_max_f32_e32 v3, v2, v124
	v_min_f32_e32 v124, v2, v124
	v_max_f32_e32 v117, v114, v116
	v_min_f32_e32 v116, v114, v116
	v_max_f32_e32 v16, v0, v118
	v_min_f32_e32 v118, v0, v118
	v_max_f32_e32 v17, v1, v123
	v_min_f32_e32 v123, v1, v123
	v_max_f32_e32 v18, v117, v122
	v_min_f32_e32 v122, v117, v122
	v_max_f32_e32 v19, v116, v127
	v_min_f32_e32 v127, v116, v127
	v_max_f32_e32 v20, v4, v16
	v_min_f32_e32 v16, v4, v16
	v_max_f32_e32 v21, v107, v118
	v_min_f32_e32 v118, v107, v118
	v_max_f32_e32 v23, v18, v124
	v_min_f32_e32 v124, v18, v124
	v_max_f32_e32 v25, v122, v19
	v_min_f32_e32 v19, v122, v19
	v_max_f32_e32 v8, v20, v127
	v_min_f32_e32 v127, v20, v127
	v_max_f32_e32 v10, v16, v21
	v_min_f32_e32 v21, v16, v21
	v_max_f32_e32 v11, v17, v118
	v_min_f32_e32 v118, v17, v118
	v_max_f32_e32 v249, v19, v8
	v_min_f32_e32 v8, v19, v8
	v_max_f32_e32 v22, v127, v10
	v_min_f32_e32 v10, v127, v10
	s_waitcnt vmcnt(24)
	v_pk_mul_f32 v[160:161], v[160:161], v[176:177]
	v_pk_mul_f32 v[162:163], v[162:163], v[178:179]
	v_pk_mul_f32 v[164:165], v[164:165], v[180:181]
	v_pk_mul_f32 v[166:167], v[166:167], v[182:183]
	v_pk_mul_f32 v[168:169], v[168:169], v[184:185]
	v_pk_mul_f32 v[170:171], v[170:171], v[186:187]
	v_pk_mul_f32 v[172:173], v[172:173], v[188:189]
	v_pk_mul_f32 v[174:175], v[174:175], v[190:191]
	v_max3_f32 v192, |v160|, |v161|, |v162|
	v_max3_f32 v192, |v163|, |v164|, v192
	v_max3_f32 v192, |v165|, |v166|, v192
	v_max3_f32 v192, |v167|, |v168|, v192
	v_max3_f32 v192, |v169|, |v170|, v192
	v_max3_f32 v192, |v171|, |v172|, v192
	v_max3_f32 v192, |v173|, |v174|, v192
	v_max_f32_e64 v192, |v175|, v192
	s_nop 1
	v_mov_b32_dpp v193, v192 quad_perm:[1,0,3,2] row_mask:0xf bank_mask:0xf bound_ctrl:1
	v_max_f32_e32 v192, v192, v193
	s_nop 1
	v_mov_b32_dpp v193, v192 quad_perm:[2,3,0,1] row_mask:0xf bank_mask:0xf bound_ctrl:1
	v_max_f32_e32 v192, v192, v193
	s_nop 1
	v_mov_b32_dpp v193, v192 row_half_mirror row_mask:0xf bank_mask:0xf bound_ctrl:1
	v_max_f32_e32 v192, v192, v193
	s_nop 1
	v_mov_b32_dpp v193, v192 row_mirror row_mask:0xf bank_mask:0xf bound_ctrl:1
	v_max_f32_e32 v192, v192, v193
	v_mov_b32_e32 v193, v192
	s_nop 1
	v_permlane16_swap_b32_e32 v192, v193
	s_nop 1
	v_max_f32_e32 v192, v192, v193
	v_mov_b32_e32 v193, v192
	s_nop 1
	v_permlane32_swap_b32_e32 v192, v193
	s_nop 1
	v_max_f32_e32 v192, v192, v193
	v_max_f32_e32 v192, 0xda24260, v192
	v_mul_f32_e32 v194, 0x3e2aaaab, v192
	global_store_dword v214, v194, s[12:13]
	v_div_scale_f32 v195, s[26:27], v194, v194, 1.0
	v_rcp_f32_e32 v196, v195
	v_div_scale_f32 v204, vcc, 1.0, v194, 1.0
	v_fma_f32 v205, -v195, v196, 1.0
	v_fmac_f32_e32 v196, v205, v196
	v_mul_f32_e32 v205, v204, v196
	v_fma_f32 v206, -v195, v205, v204
	v_fmac_f32_e32 v205, v206, v196
	v_fma_f32 v195, -v195, v205, v204
	s_nop 0
	v_div_fmas_f32 v195, v195, v196, v205
	v_div_fixup_f32 v207, v195, v194, 1.0
	v_mul_f32_e32 v160, v207, v160
	v_mul_f32_e32 v161, v207, v161
	v_mul_f32_e32 v162, v207, v162
	v_mul_f32_e32 v163, v207, v163
	v_mul_f32_e32 v164, v207, v164
	v_mul_f32_e32 v165, v207, v165
	v_mul_f32_e32 v166, v207, v166
	v_mul_f32_e32 v167, v207, v167
	v_mul_f32_e32 v168, v207, v168
	v_mul_f32_e32 v169, v207, v169
	v_mul_f32_e32 v170, v207, v170
	v_mul_f32_e32 v171, v207, v171
	v_mul_f32_e32 v172, v207, v172
	v_mul_f32_e32 v173, v207, v173
	v_mul_f32_e32 v174, v207, v174
	v_mul_f32_e32 v175, v207, v175
	v_mov_b32_e32 v208, 0
	v_mov_b32_e32 v209, 0
	v_mov_b32_e32 v210, 0
	v_mov_b32_e32 v193, 0
	v_cvt_scalef32_pk_fp4_f32 v208, v160, v161, 1.0
	v_cvt_scalef32_pk_fp4_f32 v209, v164, v165, 1.0
	v_cvt_scalef32_pk_fp4_f32 v210, v168, v169, 1.0
	v_cvt_scalef32_pk_fp4_f32 v193, v172, v173, 1.0
	v_cvt_scalef32_pk_fp4_f32 v208, v162, v163, 1.0 op_sel:[0,0,1,0]
	v_cvt_scalef32_pk_fp4_f32 v209, v166, v167, 1.0 op_sel:[0,0,1,0]
	v_cvt_scalef32_pk_fp4_f32 v210, v170, v171, 1.0 op_sel:[0,0,1,0]
	v_cvt_scalef32_pk_fp4_f32 v193, v174, v175, 1.0 op_sel:[0,0,1,0]
	global_store_short v213, v208, s[10:11] nt
	s_add_u32 s14, s10, 0x200000
	s_addc_u32 s15, s11, 0
	global_store_short v213, v209, s[14:15] nt
	s_add_u32 s14, s10, 0x400000
	s_addc_u32 s15, s11, 0
	global_store_short v213, v210, s[14:15] nt
	s_add_u32 s14, s10, 0x600000
	s_addc_u32 s15, s11, 0
	global_store_short v213, v193, s[14:15] nt
	s_add_u32 s10, s10, 0x20000
	s_addc_u32 s11, s11, 0
	s_add_u32 s12, s12, 0x2000
	s_addc_u32 s13, s13, 0
	global_load_dwordx4 v[160:163], v212, s[8:9] offset:0 nt
	global_load_dwordx4 v[164:167], v212, s[8:9] offset:1024 nt
	global_load_dwordx4 v[168:171], v212, s[8:9] offset:2048 nt
	global_load_dwordx4 v[172:175], v212, s[8:9] offset:3072 nt
	s_add_u32 s8, s8, 0x800000
	s_addc_u32 s9, s9, 0
	v_max_f32_e32 v24, v32, v45
	v_min_f32_e32 v45, v32, v45
	v_max_f32_e32 v26, v33, v44
	v_min_f32_e32 v44, v33, v44
	v_max_f32_e32 v27, v34, v47
	v_min_f32_e32 v47, v34, v47
	v_max_f32_e32 v255, v35, v46
	v_min_f32_e32 v46, v35, v46
	v_max_f32_e32 v14, v36, v40
	v_min_f32_e32 v40, v36, v40
	v_max_f32_e32 v251, v37, v38
	v_min_f32_e32 v38, v37, v38
	v_max_f32_e32 v250, v39, v43
	v_min_f32_e32 v43, v39, v43
	v_max_f32_e32 v253, v41, v42
	v_min_f32_e32 v42, v41, v42
	v_max_f32_e32 v149, v24, v251
	v_min_f32_e32 v251, v24, v251
	v_max_f32_e32 v28, v26, v250
	v_min_f32_e32 v250, v26, v250
	v_max_f32_e32 v30, v27, v253
	v_min_f32_e32 v253, v27, v253
	v_max_f32_e32 v254, v255, v14
	v_min_f32_e32 v14, v255, v14
	v_max_f32_e32 v12, v38, v45
	v_min_f32_e32 v45, v38, v45
	v_max_f32_e32 v13, v40, v46
	v_min_f32_e32 v46, v40, v46
	v_max_f32_e32 v148, v42, v47
	v_min_f32_e32 v47, v42, v47
	v_max_f32_e32 v106, v43, v44
	v_min_f32_e32 v44, v43, v44
	v_max_f32_e32 v99, v149, v28
	v_min_f32_e32 v28, v149, v28
	v_max_f32_e32 v108, v30, v254
	v_min_f32_e32 v254, v30, v254
	v_max_f32_e32 v29, v14, v251
	v_min_f32_e32 v251, v14, v251
	v_max_f32_e32 v112, v12, v13
	v_min_f32_e32 v13, v12, v13
	v_max_f32_e32 v97, v250, v253
	v_min_f32_e32 v253, v250, v253
	v_max_f32_e32 v113, v148, v106
	v_min_f32_e32 v106, v148, v106
	v_max_f32_e32 v98, v44, v45
	v_min_f32_e32 v45, v44, v45
	v_max_f32_e32 v101, v46, v47
	v_min_f32_e32 v47, v46, v47
	v_max_f32_e32 v150, v99, v108
	v_min_f32_e32 v108, v99, v108
	v_max_f32_e32 v96, v28, v254
	v_min_f32_e32 v254, v28, v254
	v_max_f32_e32 v121, v29, v113
	v_min_f32_e32 v113, v29, v113
	v_max_f32_e32 v103, v251, v106
	v_min_f32_e32 v106, v251, v106
	v_max_f32_e32 v125, v112, v97
	v_min_f32_e32 v97, v112, v97
	v_max_f32_e32 v252, v13, v253
	v_min_f32_e32 v253, v13, v253
	v_max_f32_e32 v109, v98, v101
	v_min_f32_e32 v101, v98, v101
	v_max_f32_e32 v100, v45, v47
	v_min_f32_e32 v47, v45, v47
	v_max_f32_e32 v2, v96, v108
	v_min_f32_e32 v108, v96, v108
	v_max_f32_e32 v114, v254, v109
	v_min_f32_e32 v109, v254, v109
	v_max_f32_e32 v0, v121, v125
	v_min_f32_e32 v125, v121, v125
	v_max_f32_e32 v1, v103, v97
	v_min_f32_e32 v97, v103, v97
	v_max_f32_e32 v117, v252, v113
	v_min_f32_e32 v113, v252, v113
	v_max_f32_e32 v116, v253, v106
	v_min_f32_e32 v106, v253, v106
	v_max_f32_e32 v4, v100, v101
	v_min_f32_e32 v101, v100, v101
	v_max_f32_e32 v107, v2, v0
	v_min_f32_e32 v0, v2, v0
	v_max_f32_e32 v18, v108, v125
	v_min_f32_e32 v125, v108, v125
	v_max_f32_e32 v122, v1, v117
	v_min_f32_e32 v117, v1, v117
	v_max_f32_e32 v20, v97, v113
	v_min_f32_e32 v113, v97, v113
	v_max_f32_e32 v16, v116, v4
	v_min_f32_e32 v4, v116, v4
	v_max_f32_e32 v17, v106, v101
	v_min_f32_e32 v101, v106, v101
	v_max_f32_e32 v19, v18, v0
	v_min_f32_e32 v0, v18, v0
	v_max_f32_e32 v127, v114, v125
	v_min_f32_e32 v125, v114, v125
	v_max_f32_e32 v32, v16, v109
	v_min_f32_e32 v109, v16, v109
	v_max_f32_e32 v33, v17, v4
	v_min_f32_e32 v4, v17, v4
	v_max_f32_e32 v34, v127, v122
	v_min_f32_e32 v122, v127, v122
	v_max_f32_e32 v35, v125, v117
	v_min_f32_e32 v117, v125, v117
	v_max_f32_e32 v36, v20, v32
	v_min_f32_e32 v32, v20, v32
	v_max_f32_e32 v37, v113, v109
	v_min_f32_e32 v109, v113, v109
	v_max_f32_e32 v39, v34, v0
	v_min_f32_e32 v0, v34, v0
	v_max_f32_e32 v41, v122, v35
	v_min_f32_e32 v35, v122, v35
	v_max_f32_e32 v24, v36, v117
	v_min_f32_e32 v117, v36, v117
	v_max_f32_e32 v26, v32, v37
	v_min_f32_e32 v37, v32, v37
	v_max_f32_e32 v27, v33, v109
	v_min_f32_e32 v109, v33, v109
	v_max_f32_e32 v255, v35, v24
	v_min_f32_e32 v24, v35, v24
	v_max_f32_e32 v38, v117, v26
	v_min_f32_e32 v26, v117, v26
	v_max_f32_e32 v40, v48, v61
	v_min_f32_e32 v61, v48, v61
	v_max_f32_e32 v42, v49, v60
	v_min_f32_e32 v60, v49, v60
	v_max_f32_e32 v43, v50, v63
	v_min_f32_e32 v63, v50, v63
	v_max_f32_e32 v149, v51, v62
	v_min_f32_e32 v62, v51, v62
	v_max_f32_e32 v30, v52, v56
	v_min_f32_e32 v56, v52, v56
	v_max_f32_e32 v14, v53, v54
	v_min_f32_e32 v54, v53, v54
	v_max_f32_e32 v12, v55, v59
	v_min_f32_e32 v59, v55, v59
	v_max_f32_e32 v250, v57, v58
	v_min_f32_e32 v58, v57, v58
	v_max_f32_e32 v148, v40, v14
	v_min_f32_e32 v14, v40, v14
	v_max_f32_e32 v44, v42, v12
	v_min_f32_e32 v12, v42, v12
	v_max_f32_e32 v46, v43, v250
	v_min_f32_e32 v250, v43, v250
	v_max_f32_e32 v99, v149, v30
	v_min_f32_e32 v30, v149, v30
	v_max_f32_e32 v28, v54, v61
	v_min_f32_e32 v61, v54, v61
	v_max_f32_e32 v29, v56, v62
	v_min_f32_e32 v62, v56, v62
	v_max_f32_e32 v251, v58, v63
	v_min_f32_e32 v63, v58, v63
	v_max_f32_e32 v112, v59, v60
	v_min_f32_e32 v60, v59, v60
	v_max_f32_e32 v13, v148, v44
	v_min_f32_e32 v44, v148, v44
	v_max_f32_e32 v98, v46, v99
	v_min_f32_e32 v99, v46, v99
	v_max_f32_e32 v45, v30, v14
	v_min_f32_e32 v14, v30, v14
	v_max_f32_e32 v96, v28, v29
	v_min_f32_e32 v29, v28, v29
	v_max_f32_e32 v254, v12, v250
	v_min_f32_e32 v250, v12, v250
	v_max_f32_e32 v121, v251, v112
	v_min_f32_e32 v112, v251, v112
	v_max_f32_e32 v103, v60, v61
	v_min_f32_e32 v61, v60, v61
	v_max_f32_e32 v252, v62, v63
	v_min_f32_e32 v63, v62, v63
	v_max_f32_e32 v253, v13, v98
	v_min_f32_e32 v98, v13, v98
	v_max_f32_e32 v100, v44, v99
	v_min_f32_e32 v99, v44, v99
	v_max_f32_e32 v2, v45, v121
	v_min_f32_e32 v121, v45, v121
	v_max_f32_e32 v108, v14, v112
	v_min_f32_e32 v112, v14, v112
	v_max_f32_e32 v1, v96, v254
	v_min_f32_e32 v254, v96, v254
	v_max_f32_e32 v97, v29, v250
	v_min_f32_e32 v250, v29, v250
	v_max_f32_e32 v116, v103, v252
	v_min_f32_e32 v252, v103, v252
	v_max_f32_e32 v106, v61, v63
	v_min_f32_e32 v63, v61, v63
	v_max_f32_e32 v18, v100, v98
	v_min_f32_e32 v98, v100, v98
	v_max_f32_e32 v114, v99, v116
	v_min_f32_e32 v116, v99, v116
	v_max_f32_e32 v16, v2, v1
	v_min_f32_e32 v1, v2, v1
	v_max_f32_e32 v17, v108, v254
	v_min_f32_e32 v254, v108, v254
	v_max_f32_e32 v127, v97, v121
	v_min_f32_e32 v121, v97, v121
	v_max_f32_e32 v125, v250, v112
	v_min_f32_e32 v112, v250, v112
	v_max_f32_e32 v20, v106, v252
	v_min_f32_e32 v252, v106, v252
	v_max_f32_e32 v113, v18, v16
	v_min_f32_e32 v16, v18, v16
	v_max_f32_e32 v34, v98, v1
	v_min_f32_e32 v1, v98, v1
	v_max_f32_e32 v122, v17, v127
	v_min_f32_e32 v127, v17, v127
	v_max_f32_e32 v36, v254, v121
	v_min_f32_e32 v121, v254, v121
	v_max_f32_e32 v32, v125, v20
	v_min_f32_e32 v20, v125, v20
	v_max_f32_e32 v33, v112, v252
	v_min_f32_e32 v252, v112, v252
	v_max_f32_e32 v35, v34, v16
	v_min_f32_e32 v16, v34, v16
	v_max_f32_e32 v117, v114, v1
	v_min_f32_e32 v1, v114, v1
	v_max_f32_e32 v48, v32, v116
	v_min_f32_e32 v116, v32, v116
	v_max_f32_e32 v49, v33, v20
	v_min_f32_e32 v20, v33, v20
	v_max_f32_e32 v50, v117, v122
	v_min_f32_e32 v122, v117, v122
	v_max_f32_e32 v51, v1, v127
	v_min_f32_e32 v127, v1, v127
	v_max_f32_e32 v52, v36, v48
	v_min_f32_e32 v48, v36, v48
	v_max_f32_e32 v53, v121, v116
	v_min_f32_e32 v116, v121, v116
	v_max_f32_e32 v55, v50, v16
	v_min_f32_e32 v16, v50, v16
	v_max_f32_e32 v57, v122, v51
	v_min_f32_e32 v51, v122, v51
	v_max_f32_e32 v40, v52, v127
	v_min_f32_e32 v127, v52, v127
	v_max_f32_e32 v42, v48, v53
	v_min_f32_e32 v53, v48, v53
	v_max_f32_e32 v43, v49, v116
	v_min_f32_e32 v116, v49, v116
	v_max_f32_e32 v149, v51, v40
	v_min_f32_e32 v40, v51, v40
	v_max_f32_e32 v54, v127, v42
	v_min_f32_e32 v42, v127, v42
	s_waitcnt vmcnt(0)
	v_pk_mul_f32 v[160:161], v[160:161], v[176:177]
	v_pk_mul_f32 v[162:163], v[162:163], v[178:179]
	v_pk_mul_f32 v[164:165], v[164:165], v[180:181]
	v_pk_mul_f32 v[166:167], v[166:167], v[182:183]
	v_pk_mul_f32 v[168:169], v[168:169], v[184:185]
	v_pk_mul_f32 v[170:171], v[170:171], v[186:187]
	v_pk_mul_f32 v[172:173], v[172:173], v[188:189]
	v_pk_mul_f32 v[174:175], v[174:175], v[190:191]
	v_max3_f32 v192, |v160|, |v161|, |v162|
	v_max3_f32 v192, |v163|, |v164|, v192
	v_max3_f32 v192, |v165|, |v166|, v192
	v_max3_f32 v192, |v167|, |v168|, v192
	v_max3_f32 v192, |v169|, |v170|, v192
	v_max3_f32 v192, |v171|, |v172|, v192
	v_max3_f32 v192, |v173|, |v174|, v192
	v_max_f32_e64 v192, |v175|, v192
	s_nop 1
	v_mov_b32_dpp v193, v192 quad_perm:[1,0,3,2] row_mask:0xf bank_mask:0xf bound_ctrl:1
	v_max_f32_e32 v192, v192, v193
	s_nop 1
	v_mov_b32_dpp v193, v192 quad_perm:[2,3,0,1] row_mask:0xf bank_mask:0xf bound_ctrl:1
	v_max_f32_e32 v192, v192, v193
	s_nop 1
	v_mov_b32_dpp v193, v192 row_half_mirror row_mask:0xf bank_mask:0xf bound_ctrl:1
	v_max_f32_e32 v192, v192, v193
	s_nop 1
	v_mov_b32_dpp v193, v192 row_mirror row_mask:0xf bank_mask:0xf bound_ctrl:1
	v_max_f32_e32 v192, v192, v193
	v_mov_b32_e32 v193, v192
	s_nop 1
	v_permlane16_swap_b32_e32 v192, v193
	s_nop 1
	v_max_f32_e32 v192, v192, v193
	v_mov_b32_e32 v193, v192
	s_nop 1
	v_permlane32_swap_b32_e32 v192, v193
	s_nop 1
	v_max_f32_e32 v192, v192, v193
	v_max_f32_e32 v192, 0xda24260, v192
	v_mul_f32_e32 v194, 0x3e2aaaab, v192
	global_store_dword v214, v194, s[12:13]
	v_div_scale_f32 v195, s[26:27], v194, v194, 1.0
	v_rcp_f32_e32 v196, v195
	v_div_scale_f32 v204, vcc, 1.0, v194, 1.0
	v_fma_f32 v205, -v195, v196, 1.0
	v_fmac_f32_e32 v196, v205, v196
	v_mul_f32_e32 v205, v204, v196
	v_fma_f32 v206, -v195, v205, v204
	v_fmac_f32_e32 v205, v206, v196
	v_fma_f32 v195, -v195, v205, v204
	s_nop 0
	v_div_fmas_f32 v195, v195, v196, v205
	v_div_fixup_f32 v207, v195, v194, 1.0
	v_mul_f32_e32 v160, v207, v160
	v_mul_f32_e32 v161, v207, v161
	v_mul_f32_e32 v162, v207, v162
	v_mul_f32_e32 v163, v207, v163
	v_mul_f32_e32 v164, v207, v164
	v_mul_f32_e32 v165, v207, v165
	v_mul_f32_e32 v166, v207, v166
	v_mul_f32_e32 v167, v207, v167
	v_mul_f32_e32 v168, v207, v168
	v_mul_f32_e32 v169, v207, v169
	v_mul_f32_e32 v170, v207, v170
	v_mul_f32_e32 v171, v207, v171
	v_mul_f32_e32 v172, v207, v172
	v_mul_f32_e32 v173, v207, v173
	v_mul_f32_e32 v174, v207, v174
	v_mul_f32_e32 v175, v207, v175
	v_mov_b32_e32 v208, 0
	v_mov_b32_e32 v209, 0
	v_mov_b32_e32 v210, 0
	v_mov_b32_e32 v193, 0
	v_cvt_scalef32_pk_fp4_f32 v208, v160, v161, 1.0
	v_cvt_scalef32_pk_fp4_f32 v209, v164, v165, 1.0
	v_cvt_scalef32_pk_fp4_f32 v210, v168, v169, 1.0
	v_cvt_scalef32_pk_fp4_f32 v193, v172, v173, 1.0
	v_cvt_scalef32_pk_fp4_f32 v208, v162, v163, 1.0 op_sel:[0,0,1,0]
	v_cvt_scalef32_pk_fp4_f32 v209, v166, v167, 1.0 op_sel:[0,0,1,0]
	v_cvt_scalef32_pk_fp4_f32 v210, v170, v171, 1.0 op_sel:[0,0,1,0]
	v_cvt_scalef32_pk_fp4_f32 v193, v174, v175, 1.0 op_sel:[0,0,1,0]
	global_store_short v213, v208, s[10:11] nt
	s_add_u32 s14, s10, 0x200000
	s_addc_u32 s15, s11, 0
	global_store_short v213, v209, s[14:15] nt
	s_add_u32 s14, s10, 0x400000
	s_addc_u32 s15, s11, 0
	global_store_short v213, v210, s[14:15] nt
	s_add_u32 s14, s10, 0x600000
	s_addc_u32 s15, s11, 0
	global_store_short v213, v193, s[14:15] nt
	s_add_u32 s10, s10, 0x20000
	s_addc_u32 s11, s11, 0
	s_add_u32 s12, s12, 0x2000
	s_addc_u32 s13, s13, 0
	global_load_dwordx4 v[160:163], v212, s[8:9] offset:0 nt
	global_load_dwordx4 v[164:167], v212, s[8:9] offset:1024 nt
	global_load_dwordx4 v[168:171], v212, s[8:9] offset:2048 nt
	global_load_dwordx4 v[172:175], v212, s[8:9] offset:3072 nt
	s_add_u32 s8, s8, 0x800000
	s_addc_u32 s9, s9, 0
	v_max_f32_e32 v105, v105, v31
	v_max_f32_e32 v120, v120, v110
	v_max_f32_e32 v126, v126, v123
	v_max_f32_e32 v7, v7, v118
	v_max_f32_e32 v115, v115, v11
	v_max_f32_e32 v9, v9, v21
	v_max_f32_e32 v147, v147, v10
	v_max_f32_e32 v144, v144, v22
	v_max_f32_e32 v6, v6, v8
	v_max_f32_e32 v145, v145, v249
	v_max_f32_e32 v5, v5, v25
	v_max_f32_e32 v146, v146, v124
	v_max_f32_e32 v111, v111, v23
	v_max_f32_e32 v119, v119, v3
	v_max_f32_e32 v104, v104, v102
	v_max_f32_e32 v15, v15, v151
	v_max_f32_e32 v56, v105, v6
	v_min_f32_e32 v6, v105, v6
	v_max_f32_e32 v58, v120, v145
	v_min_f32_e32 v145, v120, v145
	v_max_f32_e32 v59, v126, v5
	v_min_f32_e32 v5, v126, v5
	v_max_f32_e32 v148, v7, v146
	v_min_f32_e32 v146, v7, v146
	v_max_f32_e32 v46, v115, v111
	v_min_f32_e32 v111, v115, v111
	v_max_f32_e32 v30, v9, v119
	v_min_f32_e32 v119, v9, v119
	v_max_f32_e32 v28, v147, v104
	v_min_f32_e32 v104, v147, v104
	v_max_f32_e32 v12, v144, v15
	v_min_f32_e32 v15, v144, v15
	v_max_f32_e32 v251, v56, v46
	v_min_f32_e32 v46, v56, v46
	v_max_f32_e32 v60, v58, v30
	v_min_f32_e32 v30, v58, v30
	v_max_f32_e32 v62, v59, v28
	v_min_f32_e32 v28, v59, v28
	v_max_f32_e32 v13, v148, v12
	v_min_f32_e32 v12, v148, v12
	v_max_f32_e32 v44, v6, v111
	v_min_f32_e32 v111, v6, v111
	v_max_f32_e32 v45, v145, v119
	v_min_f32_e32 v119, v145, v119
	v_max_f32_e32 v14, v5, v104
	v_min_f32_e32 v104, v5, v104
	v_max_f32_e32 v96, v146, v15
	v_min_f32_e32 v15, v146, v15
	v_max_f32_e32 v29, v251, v62
	v_min_f32_e32 v62, v251, v62
	v_max_f32_e32 v103, v60, v13
	v_min_f32_e32 v13, v60, v13
	v_max_f32_e32 v61, v46, v28
	v_min_f32_e32 v28, v46, v28
	v_max_f32_e32 v100, v30, v12
	v_min_f32_e32 v12, v30, v12
	v_max_f32_e32 v99, v44, v14
	v_min_f32_e32 v14, v44, v14
	v_max_f32_e32 v2, v45, v96
	v_min_f32_e32 v96, v45, v96
	v_max_f32_e32 v108, v111, v104
	v_min_f32_e32 v104, v111, v104
	v_max_f32_e32 v97, v119, v15
	v_min_f32_e32 v15, v119, v15
	v_max_f32_e32 v250, v29, v103
	v_min_f32_e32 v103, v29, v103
	v_max_f32_e32 v106, v62, v13
	v_min_f32_e32 v13, v62, v13
	v_max_f32_e32 v18, v61, v100
	v_min_f32_e32 v100, v61, v100
	v_max_f32_e32 v98, v28, v12
	v_min_f32_e32 v12, v28, v12
	v_max_f32_e32 v17, v99, v2
	v_min_f32_e32 v2, v99, v2
	v_max_f32_e32 v254, v14, v96
	v_min_f32_e32 v96, v14, v96
	v_max_f32_e32 v125, v108, v97
	v_min_f32_e32 v97, v108, v97
	v_max_f32_e32 v112, v104, v15
	v_min_f32_e32 v15, v104, v15
	v_max_f32_e32 v150, v150, v63
	v_max_f32_e32 v107, v107, v252
	v_max_f32_e32 v19, v19, v20
	v_max_f32_e32 v39, v39, v116
	v_max_f32_e32 v0, v0, v43
	v_max_f32_e32 v41, v41, v53
	v_max_f32_e32 v255, v255, v42
	v_max_f32_e32 v24, v24, v54
	v_max_f32_e32 v38, v38, v40
	v_max_f32_e32 v26, v26, v149
	v_max_f32_e32 v37, v37, v57
	v_max_f32_e32 v27, v27, v16
	v_max_f32_e32 v109, v109, v55
	v_max_f32_e32 v4, v4, v35
	v_max_f32_e32 v101, v101, v113
	v_max_f32_e32 v47, v47, v253
	v_max_f32_e32 v34, v150, v38
	v_min_f32_e32 v38, v150, v38
	v_max_f32_e32 v114, v107, v26
	v_min_f32_e32 v26, v107, v26
	v_max_f32_e32 v32, v19, v37
	v_min_f32_e32 v37, v19, v37
	v_max_f32_e32 v33, v39, v27
	v_min_f32_e32 v27, v39, v27
	v_max_f32_e32 v117, v0, v109
	v_min_f32_e32 v109, v0, v109
	v_max_f32_e32 v1, v41, v4
	v_min_f32_e32 v4, v41, v4
	v_max_f32_e32 v36, v255, v101
	v_min_f32_e32 v101, v255, v101
	v_max_f32_e32 v121, v24, v47
	v_min_f32_e32 v47, v24, v47
	v_max_f32_e32 v50, v34, v117
	v_min_f32_e32 v117, v34, v117
	v_max_f32_e32 v122, v114, v1
	v_min_f32_e32 v1, v114, v1
	v_max_f32_e32 v52, v32, v36
	v_min_f32_e32 v36, v32, v36
	v_max_f32_e32 v48, v33, v121
	v_min_f32_e32 v121, v33, v121
	v_max_f32_e32 v49, v38, v109
	v_min_f32_e32 v109, v38, v109
	v_max_f32_e32 v51, v26, v4
	v_min_f32_e32 v4, v26, v4
	v_max_f32_e32 v127, v37, v101
	v_min_f32_e32 v101, v37, v101
	v_max_f32_e32 v151, v27, v47
	v_min_f32_e32 v47, v27, v47
	v_max_f32_e32 v102, v50, v52
	v_min_f32_e32 v52, v50, v52
	v_max_f32_e32 v3, v122, v48
	v_min_f32_e32 v48, v122, v48
	v_max_f32_e32 v23, v117, v36
	v_min_f32_e32 v36, v117, v36
	v_max_f32_e32 v124, v1, v121
	v_min_f32_e32 v121, v1, v121
	v_max_f32_e32 v25, v49, v127
	v_min_f32_e32 v127, v49, v127
	v_max_f32_e32 v249, v51, v151
	v_min_f32_e32 v151, v51, v151
	v_max_f32_e32 v8, v109, v101
	v_min_f32_e32 v101, v109, v101
	v_max_f32_e32 v22, v4, v47
	v_min_f32_e32 v47, v4, v47
	v_max_f32_e32 v10, v102, v3
	v_min_f32_e32 v3, v102, v3
	v_max_f32_e32 v21, v52, v48
	v_min_f32_e32 v48, v52, v48
	v_max_f32_e32 v11, v23, v124
	v_min_f32_e32 v124, v23, v124
	v_max_f32_e32 v118, v36, v121
	v_min_f32_e32 v121, v36, v121
	v_max_f32_e32 v123, v25, v249
	v_min_f32_e32 v249, v25, v249
	v_max_f32_e32 v110, v127, v151
	v_min_f32_e32 v151, v127, v151
	v_max_f32_e32 v31, v8, v22
	v_min_f32_e32 v22, v8, v22
	v_max_f32_e32 v105, v101, v47
	v_min_f32_e32 v47, v101, v47
	v_max_f32_e32 v250, v250, v47
	v_max_f32_e32 v103, v103, v105
	v_max_f32_e32 v106, v106, v22
	v_max_f32_e32 v13, v13, v31
	v_max_f32_e32 v18, v18, v151
	v_max_f32_e32 v100, v100, v110
	v_max_f32_e32 v98, v98, v249
	v_max_f32_e32 v12, v12, v123
	v_max_f32_e32 v17, v17, v121
	v_max_f32_e32 v2, v2, v118
	v_max_f32_e32 v254, v254, v124
	v_max_f32_e32 v96, v96, v11
	v_max_f32_e32 v125, v125, v48
	v_max_f32_e32 v97, v97, v21
	v_max_f32_e32 v112, v112, v3
	v_max_f32_e32 v15, v15, v10
	v_max_f32_e32 v120, v250, v17
	v_min_f32_e32 v17, v250, v17
	v_max_f32_e32 v126, v103, v2
	v_min_f32_e32 v2, v103, v2
	v_max_f32_e32 v7, v106, v254
	v_min_f32_e32 v254, v106, v254
	v_max_f32_e32 v115, v13, v96
	v_min_f32_e32 v96, v13, v96
	v_max_f32_e32 v9, v18, v125
	v_min_f32_e32 v125, v18, v125
	v_max_f32_e32 v147, v100, v97
	v_min_f32_e32 v97, v100, v97
	v_max_f32_e32 v144, v98, v112
	v_min_f32_e32 v112, v98, v112
	v_max_f32_e32 v56, v12, v15
	v_min_f32_e32 v15, v12, v15
	v_max_f32_e32 v58, v120, v9
	v_min_f32_e32 v9, v120, v9
	v_max_f32_e32 v59, v126, v147
	v_min_f32_e32 v147, v126, v147
	v_max_f32_e32 v148, v7, v144
	v_min_f32_e32 v144, v7, v144
	v_max_f32_e32 v6, v115, v56
	v_min_f32_e32 v56, v115, v56
	v_max_f32_e32 v145, v17, v125
	v_min_f32_e32 v125, v17, v125
	v_max_f32_e32 v5, v2, v97
	v_min_f32_e32 v97, v2, v97
	v_max_f32_e32 v146, v254, v112
	v_min_f32_e32 v112, v254, v112
	v_max_f32_e32 v251, v96, v15
	v_min_f32_e32 v15, v96, v15
	v_max_f32_e32 v60, v58, v148
	v_min_f32_e32 v148, v58, v148
	v_max_f32_e32 v46, v59, v6
	v_min_f32_e32 v6, v59, v6
	v_max_f32_e32 v30, v9, v144
	v_min_f32_e32 v144, v9, v144
	v_max_f32_e32 v44, v147, v56
	v_min_f32_e32 v56, v147, v56
	v_max_f32_e32 v45, v145, v146
	v_min_f32_e32 v146, v145, v146
	v_max_f32_e32 v111, v5, v251
	v_min_f32_e32 v251, v5, v251
	v_max_f32_e32 v119, v125, v112
	v_min_f32_e32 v112, v125, v112
	v_max_f32_e32 v29, v97, v15
	v_min_f32_e32 v15, v97, v15
	v_max_f32_e32 v62, v60, v46
	v_min_f32_e32 v46, v60, v46
	v_max_f32_e32 v61, v148, v6
	v_min_f32_e32 v6, v148, v6
	v_max_f32_e32 v28, v30, v44
	v_min_f32_e32 v44, v30, v44
	v_max_f32_e32 v99, v144, v56
	v_min_f32_e32 v56, v144, v56
	v_max_f32_e32 v14, v45, v111
	v_min_f32_e32 v111, v45, v111
	v_max_f32_e32 v108, v146, v251
	v_min_f32_e32 v251, v146, v251
	v_max_f32_e32 v104, v119, v29
	v_min_f32_e32 v29, v119, v29
	v_max_f32_e32 v253, v112, v15
	v_min_f32_e32 v15, v112, v15
	v_mov_b32_e32 v113, v62
	v_mov_b32_e32 v35, v46
	v_mov_b32_e32 v55, v61
	v_mov_b32_e32 v16, v6
	v_mov_b32_e32 v57, v28
	v_mov_b32_e32 v149, v44
	v_mov_b32_e32 v40, v99
	v_mov_b32_e32 v54, v56
	v_mov_b32_e32 v42, v14
	v_mov_b32_e32 v53, v111
	v_mov_b32_e32 v43, v108
	v_mov_b32_e32 v116, v251
	v_mov_b32_e32 v20, v104
	v_mov_b32_e32 v252, v29
	v_mov_b32_e32 v63, v253
	v_mov_b32_e32 v150, v15
	s_nop 1
	v_permlane32_swap_b32_e32 v62, v113
	v_permlane32_swap_b32_e32 v46, v35
	v_permlane32_swap_b32_e32 v61, v55
	v_permlane32_swap_b32_e32 v6, v16
	v_permlane32_swap_b32_e32 v28, v57
	v_permlane32_swap_b32_e32 v44, v149
	v_permlane32_swap_b32_e32 v99, v40
	v_permlane32_swap_b32_e32 v56, v54
	v_permlane32_swap_b32_e32 v14, v42
	v_permlane32_swap_b32_e32 v111, v53
	v_permlane32_swap_b32_e32 v108, v43
	v_permlane32_swap_b32_e32 v251, v116
	v_permlane32_swap_b32_e32 v104, v20
	v_permlane32_swap_b32_e32 v29, v252
	v_permlane32_swap_b32_e32 v253, v63
	v_permlane32_swap_b32_e32 v15, v150
	s_nop 1
	v_max_f32_e32 v62, v62, v150
	v_max_f32_e32 v46, v46, v63
	v_max_f32_e32 v61, v61, v252
	v_max_f32_e32 v6, v6, v20
	v_max_f32_e32 v28, v28, v116
	v_max_f32_e32 v44, v44, v43
	v_max_f32_e32 v99, v99, v53
	v_max_f32_e32 v56, v56, v42
	v_max_f32_e32 v14, v14, v54
	v_max_f32_e32 v111, v111, v40
	v_max_f32_e32 v108, v108, v149
	v_max_f32_e32 v251, v251, v57
	v_max_f32_e32 v104, v104, v16
	v_max_f32_e32 v29, v29, v55
	v_max_f32_e32 v253, v253, v35
	v_max_f32_e32 v15, v15, v113
	v_max_f32_e32 v107, v62, v14
	v_min_f32_e32 v14, v62, v14
	v_max_f32_e32 v19, v46, v111
	v_min_f32_e32 v111, v46, v111
	v_max_f32_e32 v39, v61, v108
	v_min_f32_e32 v108, v61, v108
	v_max_f32_e32 v0, v6, v251
	v_min_f32_e32 v251, v6, v251
	v_max_f32_e32 v41, v28, v104
	v_min_f32_e32 v104, v28, v104
	v_max_f32_e32 v255, v44, v29
	v_min_f32_e32 v29, v44, v29
	v_max_f32_e32 v24, v99, v253
	v_min_f32_e32 v253, v99, v253
	v_max_f32_e32 v34, v56, v15
	v_min_f32_e32 v15, v56, v15
	v_max_f32_e32 v114, v107, v41
	v_min_f32_e32 v41, v107, v41
	v_max_f32_e32 v32, v19, v255
	v_min_f32_e32 v255, v19, v255
	v_max_f32_e32 v33, v39, v24
	v_min_f32_e32 v24, v39, v24
	v_max_f32_e32 v38, v0, v34
	v_min_f32_e32 v34, v0, v34
	v_max_f32_e32 v26, v14, v104
	v_min_f32_e32 v104, v14, v104
	v_max_f32_e32 v37, v111, v29
	v_min_f32_e32 v29, v111, v29
	v_max_f32_e32 v27, v108, v253
	v_min_f32_e32 v253, v108, v253
	v_max_f32_e32 v50, v251, v15
	v_min_f32_e32 v15, v251, v15
	v_max_f32_e32 v122, v114, v33
	v_min_f32_e32 v33, v114, v33
	v_max_f32_e32 v117, v32, v38
	v_min_f32_e32 v38, v32, v38
	v_max_f32_e32 v1, v41, v24
	v_min_f32_e32 v24, v41, v24
	v_max_f32_e32 v49, v255, v34
	v_min_f32_e32 v34, v255, v34
	v_max_f32_e32 v51, v26, v27
	v_min_f32_e32 v27, v26, v27
	v_max_f32_e32 v109, v37, v50
	v_min_f32_e32 v50, v37, v50
	v_max_f32_e32 v4, v104, v253
	v_min_f32_e32 v253, v104, v253
	v_max_f32_e32 v102, v29, v15
	v_min_f32_e32 v15, v29, v15
	v_max_f32_e32 v128, v122, v117
	v_min_f32_e32 v129, v122, v117
	v_max_f32_e32 v130, v33, v38
	v_min_f32_e32 v131, v33, v38
	v_max_f32_e32 v132, v1, v49
	v_min_f32_e32 v133, v1, v49
	v_max_f32_e32 v134, v24, v34
	v_min_f32_e32 v135, v24, v34
	v_max_f32_e32 v136, v51, v109
	v_min_f32_e32 v137, v51, v109
	v_max_f32_e32 v138, v27, v50
	v_min_f32_e32 v139, v27, v50
	v_max_f32_e32 v140, v4, v102
	v_min_f32_e32 v141, v4, v102
	v_max_f32_e32 v142, v253, v15
	v_min_f32_e32 v143, v253, v15
	s_waitcnt vmcnt(0)
	v_pk_mul_f32 v[160:161], v[160:161], v[176:177]
	v_pk_mul_f32 v[162:163], v[162:163], v[178:179]
	v_pk_mul_f32 v[164:165], v[164:165], v[180:181]
	v_pk_mul_f32 v[166:167], v[166:167], v[182:183]
	v_pk_mul_f32 v[168:169], v[168:169], v[184:185]
	v_pk_mul_f32 v[170:171], v[170:171], v[186:187]
	v_pk_mul_f32 v[172:173], v[172:173], v[188:189]
	v_pk_mul_f32 v[174:175], v[174:175], v[190:191]
	v_max3_f32 v192, |v160|, |v161|, |v162|
	v_max3_f32 v192, |v163|, |v164|, v192
	v_max3_f32 v192, |v165|, |v166|, v192
	v_max3_f32 v192, |v167|, |v168|, v192
	v_max3_f32 v192, |v169|, |v170|, v192
	v_max3_f32 v192, |v171|, |v172|, v192
	v_max3_f32 v192, |v173|, |v174|, v192
	v_max_f32_e64 v192, |v175|, v192
	s_nop 1
	v_mov_b32_dpp v193, v192 quad_perm:[1,0,3,2] row_mask:0xf bank_mask:0xf bound_ctrl:1
	v_max_f32_e32 v192, v192, v193
	s_nop 1
	v_mov_b32_dpp v193, v192 quad_perm:[2,3,0,1] row_mask:0xf bank_mask:0xf bound_ctrl:1
	v_max_f32_e32 v192, v192, v193
	s_nop 1
	v_mov_b32_dpp v193, v192 row_half_mirror row_mask:0xf bank_mask:0xf bound_ctrl:1
	v_max_f32_e32 v192, v192, v193
	s_nop 1
	v_mov_b32_dpp v193, v192 row_mirror row_mask:0xf bank_mask:0xf bound_ctrl:1
	v_max_f32_e32 v192, v192, v193
	v_mov_b32_e32 v193, v192
	s_nop 1
	v_permlane16_swap_b32_e32 v192, v193
	s_nop 1
	v_max_f32_e32 v192, v192, v193
	v_mov_b32_e32 v193, v192
	s_nop 1
	v_permlane32_swap_b32_e32 v192, v193
	s_nop 1
	v_max_f32_e32 v192, v192, v193
	v_max_f32_e32 v192, 0xda24260, v192
	v_mul_f32_e32 v194, 0x3e2aaaab, v192
	global_store_dword v214, v194, s[12:13]
	v_div_scale_f32 v195, s[26:27], v194, v194, 1.0
	v_rcp_f32_e32 v196, v195
	v_div_scale_f32 v204, vcc, 1.0, v194, 1.0
	v_fma_f32 v205, -v195, v196, 1.0
	v_fmac_f32_e32 v196, v205, v196
	v_mul_f32_e32 v205, v204, v196
	v_fma_f32 v206, -v195, v205, v204
	v_fmac_f32_e32 v205, v206, v196
	v_fma_f32 v195, -v195, v205, v204
	s_nop 0
	v_div_fmas_f32 v195, v195, v196, v205
	v_div_fixup_f32 v207, v195, v194, 1.0
	v_mul_f32_e32 v160, v207, v160
	v_mul_f32_e32 v161, v207, v161
	v_mul_f32_e32 v162, v207, v162
	v_mul_f32_e32 v163, v207, v163
	v_mul_f32_e32 v164, v207, v164
	v_mul_f32_e32 v165, v207, v165
	v_mul_f32_e32 v166, v207, v166
	v_mul_f32_e32 v167, v207, v167
	v_mul_f32_e32 v168, v207, v168
	v_mul_f32_e32 v169, v207, v169
	v_mul_f32_e32 v170, v207, v170
	v_mul_f32_e32 v171, v207, v171
	v_mul_f32_e32 v172, v207, v172
	v_mul_f32_e32 v173, v207, v173
	v_mul_f32_e32 v174, v207, v174
	v_mul_f32_e32 v175, v207, v175
	v_mov_b32_e32 v208, 0
	v_mov_b32_e32 v209, 0
	v_mov_b32_e32 v210, 0
	v_mov_b32_e32 v193, 0
	v_cvt_scalef32_pk_fp4_f32 v208, v160, v161, 1.0
	v_cvt_scalef32_pk_fp4_f32 v209, v164, v165, 1.0
	v_cvt_scalef32_pk_fp4_f32 v210, v168, v169, 1.0
	v_cvt_scalef32_pk_fp4_f32 v193, v172, v173, 1.0
	v_cvt_scalef32_pk_fp4_f32 v208, v162, v163, 1.0 op_sel:[0,0,1,0]
	v_cvt_scalef32_pk_fp4_f32 v209, v166, v167, 1.0 op_sel:[0,0,1,0]
	v_cvt_scalef32_pk_fp4_f32 v210, v170, v171, 1.0 op_sel:[0,0,1,0]
	v_cvt_scalef32_pk_fp4_f32 v193, v174, v175, 1.0 op_sel:[0,0,1,0]
	global_store_short v213, v208, s[10:11] nt
	s_add_u32 s14, s10, 0x200000
	s_addc_u32 s15, s11, 0
	global_store_short v213, v209, s[14:15] nt
	s_add_u32 s14, s10, 0x400000
	s_addc_u32 s15, s11, 0
	global_store_short v213, v210, s[14:15] nt
	s_add_u32 s14, s10, 0x600000
	s_addc_u32 s15, s11, 0
	global_store_short v213, v193, s[14:15] nt
	s_add_u32 s10, s10, 0x20000
	s_addc_u32 s11, s11, 0
	s_add_u32 s12, s12, 0x2000
	s_addc_u32 s13, s13, 0
	global_load_dwordx4 v[160:163], v212, s[8:9] offset:0 nt
	global_load_dwordx4 v[164:167], v212, s[8:9] offset:1024 nt
	global_load_dwordx4 v[168:171], v212, s[8:9] offset:2048 nt
	global_load_dwordx4 v[172:175], v212, s[8:9] offset:3072 nt
	s_add_u32 s8, s8, 0x800000
	s_addc_u32 s9, s9, 0
	ds_write_b8 v240, v128 offset:0
	ds_write_b8 v240, v129 offset:1
	ds_write_b8 v240, v130 offset:2
	ds_write_b8 v240, v131 offset:3
	ds_write_b8 v240, v132 offset:4
	ds_write_b8 v240, v133 offset:5
	ds_write_b8 v240, v134 offset:6
	ds_write_b8 v240, v135 offset:7
	ds_write_b8 v240, v136 offset:8
	ds_write_b8 v240, v137 offset:9
	ds_write_b8 v240, v138 offset:10
	ds_write_b8 v240, v139 offset:11
	ds_write_b8 v240, v140 offset:12
	ds_write_b8 v240, v141 offset:13
	ds_write_b8 v240, v142 offset:14
	ds_write_b8 v240, v143 offset:15
	ds_read_b128 v[96:99], v215 offset:32768
	ds_read_b128 v[100:103], v232 offset:32768
	ds_read_b128 v[104:107], v233 offset:32768
	ds_read_b128 v[108:111], v234 offset:32768
	ds_read_b128 v[112:115], v235 offset:32768
	ds_read_b128 v[116:119], v236 offset:32768
	ds_read_b128 v[120:123], v237 offset:32768
	ds_read_b128 v[124:127], v238 offset:32768
	s_waitcnt vmcnt(27)
	s_waitcnt lgkmcnt(4)
	v_mfma_f32_32x32x16_bf16 v[0:15], v[96:99], v[64:67], 0
	v_mfma_f32_32x32x16_bf16 v[0:15], v[100:103], v[68:71], v[0:15]
	v_mfma_f32_32x32x16_bf16 v[0:15], v[104:107], v[72:75], v[0:15]
	v_mfma_f32_32x32x16_bf16 v[0:15], v[108:111], v[76:79], v[0:15]
	ds_read_b128 v[96:99], v215 offset:40960
	ds_read_b128 v[100:103], v232 offset:40960
	ds_read_b128 v[104:107], v233 offset:40960
	ds_read_b128 v[108:111], v234 offset:40960
	s_waitcnt lgkmcnt(4)
	v_mfma_f32_32x32x16_bf16 v[0:15], v[112:115], v[80:83], v[0:15]
	v_mfma_f32_32x32x16_bf16 v[0:15], v[116:119], v[84:87], v[0:15]
	v_mfma_f32_32x32x16_bf16 v[0:15], v[120:123], v[88:91], v[0:15]
	v_mfma_f32_32x32x16_bf16 v[0:15], v[124:127], v[92:95], v[0:15]
	ds_read_b128 v[112:115], v235 offset:40960
	ds_read_b128 v[116:119], v236 offset:40960
	ds_read_b128 v[120:123], v237 offset:40960
	ds_read_b128 v[124:127], v238 offset:40960
	s_waitcnt lgkmcnt(4)
	v_mfma_f32_32x32x16_bf16 v[16:31], v[96:99], v[64:67], 0
	v_mfma_f32_32x32x16_bf16 v[16:31], v[100:103], v[68:71], v[16:31]
	v_mfma_f32_32x32x16_bf16 v[16:31], v[104:107], v[72:75], v[16:31]
	v_mfma_f32_32x32x16_bf16 v[16:31], v[108:111], v[76:79], v[16:31]
	ds_read_b128 v[96:99], v215 offset:49152
	ds_read_b128 v[100:103], v232 offset:49152
	ds_read_b128 v[104:107], v233 offset:49152
	ds_read_b128 v[108:111], v234 offset:49152
	s_waitcnt lgkmcnt(4)
	v_mfma_f32_32x32x16_bf16 v[16:31], v[112:115], v[80:83], v[16:31]
	v_mfma_f32_32x32x16_bf16 v[16:31], v[116:119], v[84:87], v[16:31]
	v_mfma_f32_32x32x16_bf16 v[16:31], v[120:123], v[88:91], v[16:31]
	v_mfma_f32_32x32x16_bf16 v[16:31], v[124:127], v[92:95], v[16:31]
	ds_read_b128 v[112:115], v235 offset:49152
	ds_read_b128 v[116:119], v236 offset:49152
	ds_read_b128 v[120:123], v237 offset:49152
	ds_read_b128 v[124:127], v238 offset:49152
	s_waitcnt lgkmcnt(4)
	v_mfma_f32_32x32x16_bf16 v[32:47], v[96:99], v[64:67], 0
	v_mfma_f32_32x32x16_bf16 v[32:47], v[100:103], v[68:71], v[32:47]
	v_mfma_f32_32x32x16_bf16 v[32:47], v[104:107], v[72:75], v[32:47]
	v_mfma_f32_32x32x16_bf16 v[32:47], v[108:111], v[76:79], v[32:47]
	ds_read_b128 v[96:99], v215 offset:57344
	ds_read_b128 v[100:103], v232 offset:57344
	ds_read_b128 v[104:107], v233 offset:57344
	ds_read_b128 v[108:111], v234 offset:57344
	s_waitcnt lgkmcnt(4)
	v_mfma_f32_32x32x16_bf16 v[32:47], v[112:115], v[80:83], v[32:47]
	v_mfma_f32_32x32x16_bf16 v[32:47], v[116:119], v[84:87], v[32:47]
	v_mfma_f32_32x32x16_bf16 v[32:47], v[120:123], v[88:91], v[32:47]
	v_mfma_f32_32x32x16_bf16 v[32:47], v[124:127], v[92:95], v[32:47]
	ds_read_b128 v[112:115], v235 offset:57344
	ds_read_b128 v[116:119], v236 offset:57344
	ds_read_b128 v[120:123], v237 offset:57344
	ds_read_b128 v[124:127], v238 offset:57344
	s_waitcnt lgkmcnt(4)
	v_mfma_f32_32x32x16_bf16 v[48:63], v[96:99], v[64:67], 0
	v_mfma_f32_32x32x16_bf16 v[48:63], v[100:103], v[68:71], v[48:63]
	v_mfma_f32_32x32x16_bf16 v[48:63], v[104:107], v[72:75], v[48:63]
	v_mfma_f32_32x32x16_bf16 v[48:63], v[108:111], v[76:79], v[48:63]
	s_waitcnt lgkmcnt(0)
	v_mfma_f32_32x32x16_bf16 v[48:63], v[112:115], v[80:83], v[48:63]
	v_mfma_f32_32x32x16_bf16 v[48:63], v[116:119], v[84:87], v[48:63]
	v_mfma_f32_32x32x16_bf16 v[48:63], v[120:123], v[88:91], v[48:63]
	v_mfma_f32_32x32x16_bf16 v[48:63], v[124:127], v[92:95], v[48:63]
	s_nop 11
	v_and_or_b32 v0, v0, s6, v211
	v_or_b32_e32 v0, 0x7b, v0
	v_and_or_b32 v1, v1, s6, v211
	v_or_b32_e32 v1, 0x7a, v1
	v_and_or_b32 v2, v2, s6, v211
	v_or_b32_e32 v2, 0x79, v2
	v_and_or_b32 v3, v3, s6, v211
	v_or_b32_e32 v3, 0x78, v3
	v_and_or_b32 v4, v4, s6, v211
	v_or_b32_e32 v4, 0x73, v4
	v_and_or_b32 v5, v5, s6, v211
	v_or_b32_e32 v5, 0x72, v5
	v_and_or_b32 v6, v6, s6, v211
	v_or_b32_e32 v6, 0x71, v6
	v_and_or_b32 v7, v7, s6, v211
	v_or_b32_e32 v7, 0x70, v7
	v_and_or_b32 v8, v8, s6, v211
	v_or_b32_e32 v8, 0x6b, v8
	v_and_or_b32 v9, v9, s6, v211
	v_or_b32_e32 v9, 0x6a, v9
	v_and_or_b32 v10, v10, s6, v211
	v_or_b32_e32 v10, 0x69, v10
	v_and_or_b32 v11, v11, s6, v211
	v_or_b32_e32 v11, 0x68, v11
	v_and_or_b32 v12, v12, s6, v211
	v_or_b32_e32 v12, 0x63, v12
	v_and_or_b32 v13, v13, s6, v211
	v_or_b32_e32 v13, 0x62, v13
	v_and_or_b32 v14, v14, s6, v211
	v_or_b32_e32 v14, 0x61, v14
	v_and_or_b32 v15, v15, s6, v211
	v_or_b32_e32 v15, 0x60, v15
	v_and_or_b32 v16, v16, s6, v211
	v_or_b32_e32 v16, 0x5b, v16
	v_and_or_b32 v17, v17, s6, v211
	v_or_b32_e32 v17, 0x5a, v17
	v_and_or_b32 v18, v18, s6, v211
	v_or_b32_e32 v18, 0x59, v18
	v_and_or_b32 v19, v19, s6, v211
	v_or_b32_e32 v19, 0x58, v19
	v_and_or_b32 v20, v20, s6, v211
	v_or_b32_e32 v20, 0x53, v20
	v_and_or_b32 v21, v21, s6, v211
	v_or_b32_e32 v21, 0x52, v21
	v_and_or_b32 v22, v22, s6, v211
	v_or_b32_e32 v22, 0x51, v22
	v_and_or_b32 v23, v23, s6, v211
	v_or_b32_e32 v23, 0x50, v23
	v_and_or_b32 v24, v24, s6, v211
	v_or_b32_e32 v24, 0x4b, v24
	v_and_or_b32 v25, v25, s6, v211
	v_or_b32_e32 v25, 0x4a, v25
	v_and_or_b32 v26, v26, s6, v211
	v_or_b32_e32 v26, 0x49, v26
	v_and_or_b32 v27, v27, s6, v211
	v_or_b32_e32 v27, 0x48, v27
	v_and_or_b32 v28, v28, s6, v211
	v_or_b32_e32 v28, 0x43, v28
	v_and_or_b32 v29, v29, s6, v211
	v_or_b32_e32 v29, 0x42, v29
	v_and_or_b32 v30, v30, s6, v211
	v_or_b32_e32 v30, 0x41, v30
	v_and_or_b32 v31, v31, s6, v211
	v_or_b32_e32 v31, 64, v31
	v_and_or_b32 v32, v32, s6, v211
	v_or_b32_e32 v32, 59, v32
	v_and_or_b32 v33, v33, s6, v211
	v_or_b32_e32 v33, 58, v33
	v_and_or_b32 v34, v34, s6, v211
	v_or_b32_e32 v34, 57, v34
	v_and_or_b32 v35, v35, s6, v211
	v_or_b32_e32 v35, 56, v35
	v_and_or_b32 v36, v36, s6, v211
	v_or_b32_e32 v36, 51, v36
	v_and_or_b32 v37, v37, s6, v211
	v_or_b32_e32 v37, 50, v37
	v_and_or_b32 v38, v38, s6, v211
	v_or_b32_e32 v38, 49, v38
	v_and_or_b32 v39, v39, s6, v211
	v_or_b32_e32 v39, 48, v39
	v_and_or_b32 v40, v40, s6, v211
	v_or_b32_e32 v40, 43, v40
	v_and_or_b32 v41, v41, s6, v211
	v_or_b32_e32 v41, 42, v41
	v_and_or_b32 v42, v42, s6, v211
	v_or_b32_e32 v42, 41, v42
	v_and_or_b32 v43, v43, s6, v211
	v_or_b32_e32 v43, 40, v43
	v_and_or_b32 v44, v44, s6, v211
	v_or_b32_e32 v44, 35, v44
	v_and_or_b32 v45, v45, s6, v211
	v_or_b32_e32 v45, 34, v45
	v_and_or_b32 v46, v46, s6, v211
	v_or_b32_e32 v46, 33, v46
	v_and_or_b32 v47, v47, s6, v211
	v_or_b32_e32 v47, 32, v47
	v_and_or_b32 v48, v48, s6, v211
	v_or_b32_e32 v48, 27, v48
	v_and_or_b32 v49, v49, s6, v211
	v_or_b32_e32 v49, 26, v49
	v_and_or_b32 v50, v50, s6, v211
	v_or_b32_e32 v50, 25, v50
	v_and_or_b32 v51, v51, s6, v211
	v_or_b32_e32 v51, 24, v51
	v_and_or_b32 v52, v52, s6, v211
	v_or_b32_e32 v52, 19, v52
	v_and_or_b32 v53, v53, s6, v211
	v_or_b32_e32 v53, 18, v53
	v_and_or_b32 v54, v54, s6, v211
	v_or_b32_e32 v54, 17, v54
	v_and_or_b32 v55, v55, s6, v211
	v_or_b32_e32 v55, 16, v55
	v_and_or_b32 v56, v56, s6, v211
	v_or_b32_e32 v56, 11, v56
	v_and_or_b32 v57, v57, s6, v211
	v_or_b32_e32 v57, 10, v57
	v_and_or_b32 v58, v58, s6, v211
	v_or_b32_e32 v58, 9, v58
	v_and_or_b32 v59, v59, s6, v211
	v_or_b32_e32 v59, 8, v59
	v_and_or_b32 v60, v60, s6, v211
	v_or_b32_e32 v60, 3, v60
	v_and_or_b32 v61, v61, s6, v211
	v_or_b32_e32 v61, 2, v61
	v_and_or_b32 v62, v62, s6, v211
	v_or_b32_e32 v62, 1, v62
	v_and_or_b32 v63, v63, s6, v211
	v_or_b32_e32 v63, 0, v63
	v_max_f32_e32 v144, v0, v13
	v_min_f32_e32 v13, v0, v13
	v_max_f32_e32 v145, v1, v12
	v_min_f32_e32 v12, v1, v12
	v_max_f32_e32 v146, v2, v15
	v_min_f32_e32 v15, v2, v15
	v_max_f32_e32 v147, v3, v14
	v_min_f32_e32 v14, v3, v14
	v_max_f32_e32 v148, v4, v8
	v_min_f32_e32 v8, v4, v8
	v_max_f32_e32 v149, v5, v6
	v_min_f32_e32 v6, v5, v6
	v_max_f32_e32 v150, v7, v11
	v_min_f32_e32 v11, v7, v11
	v_max_f32_e32 v151, v9, v10
	v_min_f32_e32 v10, v9, v10
	v_max_f32_e32 v249, v144, v149
	v_min_f32_e32 v149, v144, v149
	v_max_f32_e32 v250, v145, v150
	v_min_f32_e32 v150, v145, v150
	v_max_f32_e32 v251, v146, v151
	v_min_f32_e32 v151, v146, v151
	v_max_f32_e32 v252, v147, v148
	v_min_f32_e32 v148, v147, v148
	v_max_f32_e32 v253, v6, v13
	v_min_f32_e32 v13, v6, v13
	v_max_f32_e32 v254, v8, v14
	v_min_f32_e32 v14, v8, v14
	v_max_f32_e32 v255, v10, v15
	v_min_f32_e32 v15, v10, v15
	v_max_f32_e32 v96, v11, v12
	v_min_f32_e32 v12, v11, v12
	v_max_f32_e32 v97, v249, v250
	v_min_f32_e32 v250, v249, v250
	v_max_f32_e32 v98, v251, v252
	v_min_f32_e32 v252, v251, v252
	v_max_f32_e32 v99, v148, v149
	v_min_f32_e32 v149, v148, v149
	v_max_f32_e32 v100, v253, v254
	v_min_f32_e32 v254, v253, v254
	v_max_f32_e32 v101, v150, v151
	v_min_f32_e32 v151, v150, v151
	v_max_f32_e32 v102, v255, v96
	v_min_f32_e32 v96, v255, v96
	v_max_f32_e32 v103, v12, v13
	v_min_f32_e32 v13, v12, v13
	v_max_f32_e32 v104, v14, v15
	v_min_f32_e32 v15, v14, v15
	v_max_f32_e32 v105, v97, v98
	v_min_f32_e32 v98, v97, v98
	v_max_f32_e32 v106, v250, v252
	v_min_f32_e32 v252, v250, v252
	v_max_f32_e32 v107, v99, v102
	v_min_f32_e32 v102, v99, v102
	v_max_f32_e32 v108, v149, v96
	v_min_f32_e32 v96, v149, v96
	v_max_f32_e32 v109, v100, v101
	v_min_f32_e32 v101, v100, v101
	v_max_f32_e32 v110, v254, v151
	v_min_f32_e32 v151, v254, v151
	v_max_f32_e32 v111, v103, v104
	v_min_f32_e32 v104, v103, v104
	v_max_f32_e32 v112, v13, v15
	v_min_f32_e32 v15, v13, v15
	v_max_f32_e32 v113, v106, v98
	v_min_f32_e32 v98, v106, v98
	v_max_f32_e32 v114, v252, v111
	v_min_f32_e32 v111, v252, v111
	v_max_f32_e32 v115, v107, v109
	v_min_f32_e32 v109, v107, v109
	v_max_f32_e32 v116, v108, v101
	v_min_f32_e32 v101, v108, v101
	v_max_f32_e32 v117, v110, v102
	v_min_f32_e32 v102, v110, v102
	v_max_f32_e32 v118, v151, v96
	v_min_f32_e32 v96, v151, v96
	v_max_f32_e32 v119, v112, v104
	v_min_f32_e32 v104, v112, v104
	v_max_f32_e32 v120, v113, v115
	v_min_f32_e32 v115, v113, v115
	v_max_f32_e32 v121, v98, v109
	v_min_f32_e32 v109, v98, v109
	v_max_f32_e32 v122, v116, v117
	v_min_f32_e32 v117, v116, v117
	v_max_f32_e32 v123, v101, v102
	v_min_f32_e32 v102, v101, v102
	v_max_f32_e32 v124, v118, v119
	v_min_f32_e32 v119, v118, v119
	v_max_f32_e32 v125, v96, v104
	v_min_f32_e32 v104, v96, v104
	v_max_f32_e32 v126, v121, v115
	v_min_f32_e32 v115, v121, v115
	v_max_f32_e32 v127, v114, v109
	v_min_f32_e32 v109, v114, v109
	v_max_f32_e32 v64, v124, v111
	v_min_f32_e32 v111, v124, v111
	v_max_f32_e32 v65, v125, v119
	v_min_f32_e32 v119, v125, v119
	v_max_f32_e32 v66, v127, v122
	v_min_f32_e32 v122, v127, v122
	v_max_f32_e32 v67, v109, v117
	v_min_f32_e32 v117, v109, v117
	v_max_f32_e32 v68, v123, v64
	v_min_f32_e32 v64, v123, v64
	v_max_f32_e32 v69, v102, v111
	v_min_f32_e32 v111, v102, v111
	v_max_f32_e32 v70, v66, v115
	v_min_f32_e32 v115, v66, v115
	v_max_f32_e32 v71, v122, v67
	v_min_f32_e32 v67, v122, v67
	v_max_f32_e32 v72, v68, v117
	v_min_f32_e32 v117, v68, v117
	v_max_f32_e32 v73, v64, v69
	v_min_f32_e32 v69, v64, v69
	v_max_f32_e32 v74, v65, v111
	v_min_f32_e32 v111, v65, v111
	v_max_f32_e32 v75, v67, v72
	v_min_f32_e32 v72, v67, v72
	v_max_f32_e32 v76, v117, v73
	v_min_f32_e32 v73, v117, v73
	v_max_f32_e32 v77, v16, v29
	v_min_f32_e32 v29, v16, v29
	v_max_f32_e32 v78, v17, v28
	v_min_f32_e32 v28, v17, v28
	v_max_f32_e32 v79, v18, v31
	v_min_f32_e32 v31, v18, v31
	v_max_f32_e32 v80, v19, v30
	v_min_f32_e32 v30, v19, v30
	v_max_f32_e32 v81, v20, v24
	v_min_f32_e32 v24, v20, v24
	v_max_f32_e32 v82, v21, v22
	v_min_f32_e32 v22, v21, v22
	v_max_f32_e32 v83, v23, v27
	v_min_f32_e32 v27, v23, v27
	v_max_f32_e32 v84, v25, v26
	v_min_f32_e32 v26, v25, v26
	v_max_f32_e32 v85, v77, v82
	v_min_f32_e32 v82, v77, v82
	v_max_f32_e32 v86, v78, v83
	v_min_f32_e32 v83, v78, v83
	v_max_f32_e32 v87, v79, v84
	v_min_f32_e32 v84, v79, v84
	v_max_f32_e32 v88, v80, v81
	v_min_f32_e32 v81, v80, v81
	v_max_f32_e32 v89, v22, v29
	v_min_f32_e32 v29, v22, v29
	v_max_f32_e32 v90, v24, v30
	v_min_f32_e32 v30, v24, v30
	v_max_f32_e32 v91, v26, v31
	v_min_f32_e32 v31, v26, v31
	v_max_f32_e32 v92, v27, v28
	v_min_f32_e32 v28, v27, v28
	v_max_f32_e32 v93, v85, v86
	v_min_f32_e32 v86, v85, v86
	v_max_f32_e32 v94, v87, v88
	v_min_f32_e32 v88, v87, v88
	v_max_f32_e32 v95, v81, v82
	v_min_f32_e32 v82, v81, v82
	v_max_f32_e32 v0, v89, v90
	v_min_f32_e32 v90, v89, v90
	v_max_f32_e32 v1, v83, v84
	v_min_f32_e32 v84, v83, v84
	v_max_f32_e32 v2, v91, v92
	v_min_f32_e32 v92, v91, v92
	v_max_f32_e32 v3, v28, v29
	v_min_f32_e32 v29, v28, v29
	v_max_f32_e32 v4, v30, v31
	v_min_f32_e32 v31, v30, v31
	v_max_f32_e32 v5, v93, v94
	v_min_f32_e32 v94, v93, v94
	v_max_f32_e32 v7, v86, v88
	v_min_f32_e32 v88, v86, v88
	v_max_f32_e32 v9, v95, v2
	v_min_f32_e32 v2, v95, v2
	v_max_f32_e32 v144, v82, v92
	v_min_f32_e32 v92, v82, v92
	v_max_f32_e32 v145, v0, v1
	v_min_f32_e32 v1, v0, v1
	v_max_f32_e32 v146, v90, v84
	v_min_f32_e32 v84, v90, v84
	v_max_f32_e32 v147, v3, v4
	v_min_f32_e32 v4, v3, v4
	v_max_f32_e32 v6, v29, v31
	v_min_f32_e32 v31, v29, v31
	v_max_f32_e32 v8, v7, v94
	v_min_f32_e32 v94, v7, v94
	v_max_f32_e32 v10, v88, v147
	v_min_f32_e32 v147, v88, v147
	v_max_f32_e32 v11, v9, v145
	v_min_f32_e32 v145, v9, v145
	v_max_f32_e32 v249, v144, v1
	v_min_f32_e32 v1, v144, v1
	v_max_f32_e32 v251, v146, v2
	v_min_f32_e32 v2, v146, v2
	v_max_f32_e32 v148, v84, v92
	v_min_f32_e32 v92, v84, v92
	v_max_f32_e32 v253, v6, v4
	v_min_f32_e32 v4, v6, v4
	v_max_f32_e32 v150, v8, v11
	v_min_f32_e32 v11, v8, v11
	v_max_f32_e32 v255, v94, v145
	v_min_f32_e32 v145, v94, v145
	v_max_f32_e32 v12, v249, v251
	v_min_f32_e32 v251, v249, v251
	v_max_f32_e32 v14, v1, v2
	v_min_f32_e32 v2, v1, v2
	v_max_f32_e32 v97, v148, v253
	v_min_f32_e32 v253, v148, v253
	v_max_f32_e32 v250, v92, v4
	v_min_f32_e32 v4, v92, v4
	v_max_f32_e32 v99, v255, v11
	v_min_f32_e32 v11, v255, v11
	v_max_f32_e32 v149, v10, v145
	v_min_f32_e32 v145, v10, v145
	v_max_f32_e32 v100, v97, v147
	v_min_f32_e32 v147, v97, v147
	v_max_f32_e32 v254, v250, v253
	v_min_f32_e32 v253, v250, v253
	v_max_f32_e32 v103, v149, v12
	v_min_f32_e32 v12, v149, v12
	v_max_f32_e32 v13, v145, v251
	v_min_f32_e32 v251, v145, v251
	v_max_f32_e32 v106, v14, v100
	v_min_f32_e32 v100, v14, v100
	v_max_f32_e32 v252, v2, v147
	v_min_f32_e32 v147, v2, v147
	v_max_f32_e32 v107, v103, v11
	v_min_f32_e32 v11, v103, v11
	v_max_f32_e32 v108, v12, v13
	v_min_f32_e32 v13, v12, v13
	v_max_f32_e32 v110, v106, v251
	v_min_f32_e32 v251, v106, v251
	v_max_f32_e32 v151, v100, v252
	v_min_f32_e32 v252, v100, v252
	v_max_f32_e32 v112, v254, v147
	v_min_f32_e32 v147, v254, v147
	v_max_f32_e32 v113, v13, v110
	v_min_f32_e32 v110, v13, v110
	v_max_f32_e32 v98, v251, v151
	v_min_f32_e32 v151, v251, v151
	s_waitcnt vmcnt(0)
	v_pk_mul_f32 v[160:161], v[160:161], v[176:177]
	v_pk_mul_f32 v[162:163], v[162:163], v[178:179]
	v_pk_mul_f32 v[164:165], v[164:165], v[180:181]
	v_pk_mul_f32 v[166:167], v[166:167], v[182:183]
	v_pk_mul_f32 v[168:169], v[168:169], v[184:185]
	v_pk_mul_f32 v[170:171], v[170:171], v[186:187]
	v_pk_mul_f32 v[172:173], v[172:173], v[188:189]
	v_pk_mul_f32 v[174:175], v[174:175], v[190:191]
	v_max3_f32 v192, |v160|, |v161|, |v162|
	v_max3_f32 v192, |v163|, |v164|, v192
	v_max3_f32 v192, |v165|, |v166|, v192
	v_max3_f32 v192, |v167|, |v168|, v192
	v_max3_f32 v192, |v169|, |v170|, v192
	v_max3_f32 v192, |v171|, |v172|, v192
	v_max3_f32 v192, |v173|, |v174|, v192
	v_max_f32_e64 v192, |v175|, v192
	s_nop 1
	v_mov_b32_dpp v193, v192 quad_perm:[1,0,3,2] row_mask:0xf bank_mask:0xf bound_ctrl:1
	v_max_f32_e32 v192, v192, v193
	s_nop 1
	v_mov_b32_dpp v193, v192 quad_perm:[2,3,0,1] row_mask:0xf bank_mask:0xf bound_ctrl:1
	v_max_f32_e32 v192, v192, v193
	s_nop 1
	v_mov_b32_dpp v193, v192 row_half_mirror row_mask:0xf bank_mask:0xf bound_ctrl:1
	v_max_f32_e32 v192, v192, v193
	s_nop 1
	v_mov_b32_dpp v193, v192 row_mirror row_mask:0xf bank_mask:0xf bound_ctrl:1
	v_max_f32_e32 v192, v192, v193
	v_mov_b32_e32 v193, v192
	s_nop 1
	v_permlane16_swap_b32_e32 v192, v193
	s_nop 1
	v_max_f32_e32 v192, v192, v193
	v_mov_b32_e32 v193, v192
	s_nop 1
	v_permlane32_swap_b32_e32 v192, v193
	s_nop 1
	v_max_f32_e32 v192, v192, v193
	v_max_f32_e32 v192, 0xda24260, v192
	v_mul_f32_e32 v194, 0x3e2aaaab, v192
	global_store_dword v214, v194, s[12:13]
	v_div_scale_f32 v195, s[26:27], v194, v194, 1.0
	v_rcp_f32_e32 v196, v195
	v_div_scale_f32 v204, vcc, 1.0, v194, 1.0
	v_fma_f32 v205, -v195, v196, 1.0
	v_fmac_f32_e32 v196, v205, v196
	v_mul_f32_e32 v205, v204, v196
	v_fma_f32 v206, -v195, v205, v204
	v_fmac_f32_e32 v205, v206, v196
	v_fma_f32 v195, -v195, v205, v204
	s_nop 0
	v_div_fmas_f32 v195, v195, v196, v205
	v_div_fixup_f32 v207, v195, v194, 1.0
	v_mul_f32_e32 v160, v207, v160
	v_mul_f32_e32 v161, v207, v161
	v_mul_f32_e32 v162, v207, v162
	v_mul_f32_e32 v163, v207, v163
	v_mul_f32_e32 v164, v207, v164
	v_mul_f32_e32 v165, v207, v165
	v_mul_f32_e32 v166, v207, v166
	v_mul_f32_e32 v167, v207, v167
	v_mul_f32_e32 v168, v207, v168
	v_mul_f32_e32 v169, v207, v169
	v_mul_f32_e32 v170, v207, v170
	v_mul_f32_e32 v171, v207, v171
	v_mul_f32_e32 v172, v207, v172
	v_mul_f32_e32 v173, v207, v173
	v_mul_f32_e32 v174, v207, v174
	v_mul_f32_e32 v175, v207, v175
	v_mov_b32_e32 v208, 0
	v_mov_b32_e32 v209, 0
	v_mov_b32_e32 v210, 0
	v_mov_b32_e32 v193, 0
	v_cvt_scalef32_pk_fp4_f32 v208, v160, v161, 1.0
	v_cvt_scalef32_pk_fp4_f32 v209, v164, v165, 1.0
	v_cvt_scalef32_pk_fp4_f32 v210, v168, v169, 1.0
	v_cvt_scalef32_pk_fp4_f32 v193, v172, v173, 1.0
	v_cvt_scalef32_pk_fp4_f32 v208, v162, v163, 1.0 op_sel:[0,0,1,0]
	v_cvt_scalef32_pk_fp4_f32 v209, v166, v167, 1.0 op_sel:[0,0,1,0]
	v_cvt_scalef32_pk_fp4_f32 v210, v170, v171, 1.0 op_sel:[0,0,1,0]
	v_cvt_scalef32_pk_fp4_f32 v193, v174, v175, 1.0 op_sel:[0,0,1,0]
	global_store_short v213, v208, s[10:11] nt
	s_add_u32 s14, s10, 0x200000
	s_addc_u32 s15, s11, 0
	global_store_short v213, v209, s[14:15] nt
	s_add_u32 s14, s10, 0x400000
	s_addc_u32 s15, s11, 0
	global_store_short v213, v210, s[14:15] nt
	s_add_u32 s14, s10, 0x600000
	s_addc_u32 s15, s11, 0
	global_store_short v213, v193, s[14:15] nt
	s_add_u32 s10, s10, 0x20000
	s_addc_u32 s11, s11, 0
	s_add_u32 s12, s12, 0x2000
	s_addc_u32 s13, s13, 0
	global_load_dwordx4 v[160:163], v212, s[8:9] offset:0 nt
	global_load_dwordx4 v[164:167], v212, s[8:9] offset:1024 nt
	global_load_dwordx4 v[168:171], v212, s[8:9] offset:2048 nt
	global_load_dwordx4 v[172:175], v212, s[8:9] offset:3072 nt
	s_add_u32 s8, s8, 0x800000
	s_addc_u32 s9, s9, 0
	v_max_f32_e32 v116, v32, v45
	v_min_f32_e32 v45, v32, v45
	v_max_f32_e32 v101, v33, v44
	v_min_f32_e32 v44, v33, v44
	v_max_f32_e32 v118, v34, v47
	v_min_f32_e32 v47, v34, v47
	v_max_f32_e32 v96, v35, v46
	v_min_f32_e32 v46, v35, v46
	v_max_f32_e32 v121, v36, v40
	v_min_f32_e32 v40, v36, v40
	v_max_f32_e32 v114, v37, v38
	v_min_f32_e32 v38, v37, v38
	v_max_f32_e32 v124, v39, v43
	v_min_f32_e32 v43, v39, v43
	v_max_f32_e32 v125, v41, v42
	v_min_f32_e32 v42, v41, v42
	v_max_f32_e32 v127, v116, v114
	v_min_f32_e32 v114, v116, v114
	v_max_f32_e32 v109, v101, v124
	v_min_f32_e32 v124, v101, v124
	v_max_f32_e32 v123, v118, v125
	v_min_f32_e32 v125, v118, v125
	v_max_f32_e32 v102, v96, v121
	v_min_f32_e32 v121, v96, v121
	v_max_f32_e32 v66, v38, v45
	v_min_f32_e32 v45, v38, v45
	v_max_f32_e32 v122, v40, v46
	v_min_f32_e32 v46, v40, v46
	v_max_f32_e32 v68, v42, v47
	v_min_f32_e32 v47, v42, v47
	v_max_f32_e32 v64, v43, v44
	v_min_f32_e32 v44, v43, v44
	v_max_f32_e32 v65, v127, v109
	v_min_f32_e32 v109, v127, v109
	v_max_f32_e32 v67, v123, v102
	v_min_f32_e32 v102, v123, v102
	v_max_f32_e32 v117, v121, v114
	v_min_f32_e32 v114, v121, v114
	v_max_f32_e32 v16, v66, v122
	v_min_f32_e32 v122, v66, v122
	v_max_f32_e32 v17, v124, v125
	v_min_f32_e32 v125, v124, v125
	v_max_f32_e32 v18, v68, v64
	v_min_f32_e32 v64, v68, v64
	v_max_f32_e32 v19, v44, v45
	v_min_f32_e32 v45, v44, v45
	v_max_f32_e32 v20, v46, v47
	v_min_f32_e32 v47, v46, v47
	v_max_f32_e32 v21, v65, v67
	v_min_f32_e32 v67, v65, v67
	v_max_f32_e32 v23, v109, v102
	v_min_f32_e32 v102, v109, v102
	v_max_f32_e32 v25, v117, v18
	v_min_f32_e32 v18, v117, v18
	v_max_f32_e32 v77, v114, v64
	v_min_f32_e32 v64, v114, v64
	v_max_f32_e32 v78, v16, v17
	v_min_f32_e32 v17, v16, v17
	v_max_f32_e32 v79, v122, v125
	v_min_f32_e32 v125, v122, v125
	v_max_f32_e32 v80, v19, v20
	v_min_f32_e32 v20, v19, v20
	v_max_f32_e32 v22, v45, v47
	v_min_f32_e32 v47, v45, v47
	v_max_f32_e32 v24, v23, v67
	v_min_f32_e32 v67, v23, v67
	v_max_f32_e32 v26, v102, v80
	v_min_f32_e32 v80, v102, v80
	v_max_f32_e32 v27, v25, v78
	v_min_f32_e32 v78, v25, v78
	v_max_f32_e32 v85, v77, v17
	v_min_f32_e32 v17, v77, v17
	v_max_f32_e32 v87, v79, v18
	v_min_f32_e32 v18, v79, v18
	v_max_f32_e32 v81, v125, v64
	v_min_f32_e32 v64, v125, v64
	v_max_f32_e32 v89, v22, v20
	v_min_f32_e32 v20, v22, v20
	v_max_f32_e32 v83, v24, v27
	v_min_f32_e32 v27, v24, v27
	v_max_f32_e32 v91, v67, v78
	v_min_f32_e32 v78, v67, v78
	v_max_f32_e32 v28, v85, v87
	v_min_f32_e32 v87, v85, v87
	v_max_f32_e32 v30, v17, v18
	v_min_f32_e32 v18, v17, v18
	v_max_f32_e32 v93, v81, v89
	v_min_f32_e32 v89, v81, v89
	v_max_f32_e32 v86, v64, v20
	v_min_f32_e32 v20, v64, v20
	v_max_f32_e32 v95, v91, v27
	v_min_f32_e32 v27, v91, v27
	v_max_f32_e32 v82, v26, v78
	v_min_f32_e32 v78, v26, v78
	v_max_f32_e32 v0, v93, v80
	v_min_f32_e32 v80, v93, v80
	v_max_f32_e32 v90, v86, v89
	v_min_f32_e32 v89, v86, v89
	v_max_f32_e32 v3, v82, v28
	v_min_f32_e32 v28, v82, v28
	v_max_f32_e32 v29, v78, v87
	v_min_f32_e32 v87, v78, v87
	v_max_f32_e32 v7, v30, v0
	v_min_f32_e32 v0, v30, v0
	v_max_f32_e32 v88, v18, v80
	v_min_f32_e32 v80, v18, v80
	v_max_f32_e32 v9, v3, v27
	v_min_f32_e32 v27, v3, v27
	v_max_f32_e32 v144, v28, v29
	v_min_f32_e32 v29, v28, v29
	v_max_f32_e32 v146, v7, v87
	v_min_f32_e32 v87, v7, v87
	v_max_f32_e32 v84, v0, v88
	v_min_f32_e32 v88, v0, v88
	v_max_f32_e32 v6, v90, v80
	v_min_f32_e32 v80, v90, v80
	v_max_f32_e32 v8, v29, v146
	v_min_f32_e32 v146, v29, v146
	v_max_f32_e32 v94, v87, v84
	v_min_f32_e32 v84, v87, v84
	v_max_f32_e32 v249, v48, v61
	v_min_f32_e32 v61, v48, v61
	v_max_f32_e32 v1, v49, v60
	v_min_f32_e32 v60, v49, v60
	v_max_f32_e32 v148, v50, v63
	v_min_f32_e32 v63, v50, v63
	v_max_f32_e32 v92, v51, v62
	v_min_f32_e32 v62, v51, v62
	v_max_f32_e32 v255, v52, v56
	v_min_f32_e32 v56, v52, v56
	v_max_f32_e32 v10, v53, v54
	v_min_f32_e32 v54, v53, v54
	v_max_f32_e32 v97, v55, v59
	v_min_f32_e32 v59, v55, v59
	v_max_f32_e32 v250, v57, v58
	v_min_f32_e32 v58, v57, v58
	v_max_f32_e32 v149, v249, v10
	v_min_f32_e32 v10, v249, v10
	v_max_f32_e32 v145, v1, v97
	v_min_f32_e32 v97, v1, v97
	v_max_f32_e32 v14, v148, v250
	v_min_f32_e32 v250, v148, v250
	v_max_f32_e32 v2, v92, v255
	v_min_f32_e32 v255, v92, v255
	v_max_f32_e32 v103, v54, v61
	v_min_f32_e32 v61, v54, v61
	v_max_f32_e32 v12, v56, v62
	v_min_f32_e32 v62, v56, v62
	v_max_f32_e32 v106, v58, v63
	v_min_f32_e32 v63, v58, v63
	v_max_f32_e32 v100, v59, v60
	v_min_f32_e32 v60, v59, v60
	v_max_f32_e32 v254, v149, v145
	v_min_f32_e32 v145, v149, v145
	v_max_f32_e32 v13, v14, v2
	v_min_f32_e32 v2, v14, v2
	v_max_f32_e32 v251, v255, v10
	v_min_f32_e32 v10, v255, v10
	v_max_f32_e32 v32, v103, v12
	v_min_f32_e32 v12, v103, v12
	v_max_f32_e32 v33, v97, v250
	v_min_f32_e32 v250, v97, v250
	v_max_f32_e32 v34, v106, v100
	v_min_f32_e32 v100, v106, v100
	v_max_f32_e32 v35, v60, v61
	v_min_f32_e32 v61, v60, v61
	v_max_f32_e32 v36, v62, v63
	v_min_f32_e32 v63, v62, v63
	v_max_f32_e32 v37, v254, v13
	v_min_f32_e32 v13, v254, v13
	v_max_f32_e32 v39, v145, v2
	v_min_f32_e32 v2, v145, v2
	v_max_f32_e32 v41, v251, v34
	v_min_f32_e32 v34, v251, v34
	v_max_f32_e32 v116, v10, v100
	v_min_f32_e32 v100, v10, v100
	v_max_f32_e32 v101, v32, v33
	v_min_f32_e32 v33, v32, v33
	v_max_f32_e32 v118, v12, v250
	v_min_f32_e32 v250, v12, v250
	v_max_f32_e32 v96, v35, v36
	v_min_f32_e32 v36, v35, v36
	v_max_f32_e32 v38, v61, v63
	v_min_f32_e32 v63, v61, v63
	v_max_f32_e32 v40, v39, v13
	v_min_f32_e32 v13, v39, v13
	v_max_f32_e32 v42, v2, v96
	v_min_f32_e32 v96, v2, v96
	v_max_f32_e32 v43, v41, v101
	v_min_f32_e32 v101, v41, v101
	v_max_f32_e32 v127, v116, v33
	v_min_f32_e32 v33, v116, v33
	v_max_f32_e32 v123, v118, v34
	v_min_f32_e32 v34, v118, v34
	v_max_f32_e32 v121, v250, v100
	v_min_f32_e32 v100, v250, v100
	v_max_f32_e32 v66, v38, v36
	v_min_f32_e32 v36, v38, v36
	v_max_f32_e32 v124, v40, v43
	v_min_f32_e32 v43, v40, v43
	v_max_f32_e32 v68, v13, v101
	v_min_f32_e32 v101, v13, v101
	v_max_f32_e32 v44, v127, v123
	v_min_f32_e32 v123, v127, v123
	v_max_f32_e32 v46, v33, v34
	v_min_f32_e32 v34, v33, v34
	v_max_f32_e32 v65, v121, v66
	v_min_f32_e32 v66, v121, v66
	v_max_f32_e32 v109, v100, v36
	v_min_f32_e32 v36, v100, v36
	v_max_f32_e32 v117, v68, v43
	v_min_f32_e32 v43, v68, v43
	v_max_f32_e32 v114, v42, v101
	v_min_f32_e32 v101, v42, v101
	v_max_f32_e32 v16, v65, v96
	v_min_f32_e32 v96, v65, v96
	v_max_f32_e32 v122, v109, v66
	v_min_f32_e32 v66, v109, v66
	v_max_f32_e32 v19, v114, v44
	v_min_f32_e32 v44, v114, v44
	v_max_f32_e32 v45, v101, v123
	v_min_f32_e32 v123, v101, v123
	v_max_f32_e32 v23, v46, v16
	v_min_f32_e32 v16, v46, v16
	v_max_f32_e32 v102, v34, v96
	v_min_f32_e32 v96, v34, v96
	v_max_f32_e32 v25, v19, v43
	v_min_f32_e32 v43, v19, v43
	v_max_f32_e32 v77, v44, v45
	v_min_f32_e32 v45, v44, v45
	v_max_f32_e32 v79, v23, v123
	v_min_f32_e32 v123, v23, v123
	v_max_f32_e32 v125, v16, v102
	v_min_f32_e32 v102, v16, v102
	v_max_f32_e32 v22, v122, v96
	v_min_f32_e32 v96, v122, v96
	v_max_f32_e32 v24, v45, v79
	v_min_f32_e32 v79, v45, v79
	v_max_f32_e32 v67, v123, v125
	v_min_f32_e32 v125, v123, v125
	s_waitcnt vmcnt(0)
	v_pk_mul_f32 v[160:161], v[160:161], v[176:177]
	v_pk_mul_f32 v[162:163], v[162:163], v[178:179]
	v_pk_mul_f32 v[164:165], v[164:165], v[180:181]
	v_pk_mul_f32 v[166:167], v[166:167], v[182:183]
	v_pk_mul_f32 v[168:169], v[168:169], v[184:185]
	v_pk_mul_f32 v[170:171], v[170:171], v[186:187]
	v_pk_mul_f32 v[172:173], v[172:173], v[188:189]
	v_pk_mul_f32 v[174:175], v[174:175], v[190:191]
	v_max3_f32 v192, |v160|, |v161|, |v162|
	v_max3_f32 v192, |v163|, |v164|, v192
	v_max3_f32 v192, |v165|, |v166|, v192
	v_max3_f32 v192, |v167|, |v168|, v192
	v_max3_f32 v192, |v169|, |v170|, v192
	v_max3_f32 v192, |v171|, |v172|, v192
	v_max3_f32 v192, |v173|, |v174|, v192
	v_max_f32_e64 v192, |v175|, v192
	s_nop 1
	v_mov_b32_dpp v193, v192 quad_perm:[1,0,3,2] row_mask:0xf bank_mask:0xf bound_ctrl:1
	v_max_f32_e32 v192, v192, v193
	s_nop 1
	v_mov_b32_dpp v193, v192 quad_perm:[2,3,0,1] row_mask:0xf bank_mask:0xf bound_ctrl:1
	v_max_f32_e32 v192, v192, v193
	s_nop 1
	v_mov_b32_dpp v193, v192 row_half_mirror row_mask:0xf bank_mask:0xf bound_ctrl:1
	v_max_f32_e32 v192, v192, v193
	s_nop 1
	v_mov_b32_dpp v193, v192 row_mirror row_mask:0xf bank_mask:0xf bound_ctrl:1
	v_max_f32_e32 v192, v192, v193
	v_mov_b32_e32 v193, v192
	s_nop 1
	v_permlane16_swap_b32_e32 v192, v193
	s_nop 1
	v_max_f32_e32 v192, v192, v193
	v_mov_b32_e32 v193, v192
	s_nop 1
	v_permlane32_swap_b32_e32 v192, v193
	s_nop 1
	v_max_f32_e32 v192, v192, v193
	v_max_f32_e32 v192, 0xda24260, v192
	v_mul_f32_e32 v194, 0x3e2aaaab, v192
	global_store_dword v214, v194, s[12:13]
	v_div_scale_f32 v195, s[26:27], v194, v194, 1.0
	v_rcp_f32_e32 v196, v195
	v_div_scale_f32 v204, vcc, 1.0, v194, 1.0
	v_fma_f32 v205, -v195, v196, 1.0
	v_fmac_f32_e32 v196, v205, v196
	v_mul_f32_e32 v205, v204, v196
	v_fma_f32 v206, -v195, v205, v204
	v_fmac_f32_e32 v205, v206, v196
	v_fma_f32 v195, -v195, v205, v204
	s_nop 0
	v_div_fmas_f32 v195, v195, v196, v205
	v_div_fixup_f32 v207, v195, v194, 1.0
	v_mul_f32_e32 v160, v207, v160
	v_mul_f32_e32 v161, v207, v161
	v_mul_f32_e32 v162, v207, v162
	v_mul_f32_e32 v163, v207, v163
	v_mul_f32_e32 v164, v207, v164
	v_mul_f32_e32 v165, v207, v165
	v_mul_f32_e32 v166, v207, v166
	v_mul_f32_e32 v167, v207, v167
	v_mul_f32_e32 v168, v207, v168
	v_mul_f32_e32 v169, v207, v169
	v_mul_f32_e32 v170, v207, v170
	v_mul_f32_e32 v171, v207, v171
	v_mul_f32_e32 v172, v207, v172
	v_mul_f32_e32 v173, v207, v173
	v_mul_f32_e32 v174, v207, v174
	v_mul_f32_e32 v175, v207, v175
	v_mov_b32_e32 v208, 0
	v_mov_b32_e32 v209, 0
	v_mov_b32_e32 v210, 0
	v_mov_b32_e32 v193, 0
	v_cvt_scalef32_pk_fp4_f32 v208, v160, v161, 1.0
	v_cvt_scalef32_pk_fp4_f32 v209, v164, v165, 1.0
	v_cvt_scalef32_pk_fp4_f32 v210, v168, v169, 1.0
	v_cvt_scalef32_pk_fp4_f32 v193, v172, v173, 1.0
	v_cvt_scalef32_pk_fp4_f32 v208, v162, v163, 1.0 op_sel:[0,0,1,0]
	v_cvt_scalef32_pk_fp4_f32 v209, v166, v167, 1.0 op_sel:[0,0,1,0]
	v_cvt_scalef32_pk_fp4_f32 v210, v170, v171, 1.0 op_sel:[0,0,1,0]
	v_cvt_scalef32_pk_fp4_f32 v193, v174, v175, 1.0 op_sel:[0,0,1,0]
	global_store_short v213, v208, s[10:11] nt
	s_add_u32 s14, s10, 0x200000
	s_addc_u32 s15, s11, 0
	global_store_short v213, v209, s[14:15] nt
	s_add_u32 s14, s10, 0x400000
	s_addc_u32 s15, s11, 0
	global_store_short v213, v210, s[14:15] nt
	s_add_u32 s14, s10, 0x600000
	s_addc_u32 s15, s11, 0
	global_store_short v213, v193, s[14:15] nt
	s_add_u32 s10, s10, 0x20000
	s_addc_u32 s11, s11, 0
	s_add_u32 s12, s12, 0x2000
	s_addc_u32 s13, s13, 0
	global_load_dwordx4 v[160:163], v212, s[8:9] offset:0 nt
	global_load_dwordx4 v[164:167], v212, s[8:9] offset:1024 nt
	global_load_dwordx4 v[168:171], v212, s[8:9] offset:2048 nt
	global_load_dwordx4 v[172:175], v212, s[8:9] offset:3072 nt
	s_add_u32 s8, s8, 0x800000
	s_addc_u32 s9, s9, 0
	v_max_f32_e32 v105, v105, v31
	v_max_f32_e32 v120, v120, v4
	v_max_f32_e32 v126, v126, v253
	v_max_f32_e32 v70, v70, v147
	v_max_f32_e32 v115, v115, v112
	v_max_f32_e32 v71, v71, v252
	v_max_f32_e32 v75, v75, v151
	v_max_f32_e32 v72, v72, v98
	v_max_f32_e32 v76, v76, v110
	v_max_f32_e32 v73, v73, v113
	v_max_f32_e32 v69, v69, v108
	v_max_f32_e32 v74, v74, v11
	v_max_f32_e32 v111, v111, v107
	v_max_f32_e32 v119, v119, v99
	v_max_f32_e32 v104, v104, v150
	v_max_f32_e32 v15, v15, v5
	v_max_f32_e32 v85, v105, v76
	v_min_f32_e32 v76, v105, v76
	v_max_f32_e32 v17, v120, v73
	v_min_f32_e32 v73, v120, v73
	v_max_f32_e32 v81, v126, v69
	v_min_f32_e32 v69, v126, v69
	v_max_f32_e32 v64, v70, v74
	v_min_f32_e32 v74, v70, v74
	v_max_f32_e32 v91, v115, v111
	v_min_f32_e32 v111, v115, v111
	v_max_f32_e32 v26, v71, v119
	v_min_f32_e32 v119, v71, v119
	v_max_f32_e32 v93, v75, v104
	v_min_f32_e32 v104, v75, v104
	v_max_f32_e32 v86, v72, v15
	v_min_f32_e32 v15, v72, v15
	v_max_f32_e32 v82, v85, v91
	v_min_f32_e32 v91, v85, v91
	v_max_f32_e32 v78, v17, v26
	v_min_f32_e32 v26, v17, v26
	v_max_f32_e32 v30, v81, v93
	v_min_f32_e32 v93, v81, v93
	v_max_f32_e32 v18, v64, v86
	v_min_f32_e32 v86, v64, v86
	v_max_f32_e32 v3, v76, v111
	v_min_f32_e32 v111, v76, v111
	v_max_f32_e32 v28, v73, v119
	v_min_f32_e32 v119, v73, v119
	v_max_f32_e32 v7, v69, v104
	v_min_f32_e32 v104, v69, v104
	v_max_f32_e32 v0, v74, v15
	v_min_f32_e32 v15, v74, v15
	v_max_f32_e32 v90, v82, v30
	v_min_f32_e32 v30, v82, v30
	v_max_f32_e32 v29, v78, v18
	v_min_f32_e32 v18, v78, v18
	v_max_f32_e32 v87, v91, v93
	v_min_f32_e32 v93, v91, v93
	v_max_f32_e32 v48, v26, v86
	v_min_f32_e32 v86, v26, v86
	v_max_f32_e32 v49, v3, v7
	v_min_f32_e32 v7, v3, v7
	v_max_f32_e32 v50, v28, v0
	v_min_f32_e32 v0, v28, v0
	v_max_f32_e32 v51, v111, v104
	v_min_f32_e32 v104, v111, v104
	v_max_f32_e32 v52, v119, v15
	v_min_f32_e32 v15, v119, v15
	v_max_f32_e32 v53, v90, v29
	v_min_f32_e32 v29, v90, v29
	v_max_f32_e32 v55, v30, v18
	v_min_f32_e32 v18, v30, v18
	v_max_f32_e32 v57, v87, v48
	v_min_f32_e32 v48, v87, v48
	v_max_f32_e32 v249, v93, v86
	v_min_f32_e32 v86, v93, v86
	v_max_f32_e32 v1, v49, v50
	v_min_f32_e32 v50, v49, v50
	v_max_f32_e32 v148, v7, v0
	v_min_f32_e32 v0, v7, v0
	v_max_f32_e32 v92, v51, v52
	v_min_f32_e32 v52, v51, v52
	v_max_f32_e32 v54, v104, v15
	v_min_f32_e32 v15, v104, v15
	v_max_f32_e32 v21, v21, v63
	v_max_f32_e32 v83, v83, v36
	v_max_f32_e32 v95, v95, v66
	v_max_f32_e32 v9, v9, v96
	v_max_f32_e32 v27, v27, v22
	v_max_f32_e32 v144, v144, v102
	v_max_f32_e32 v8, v8, v125
	v_max_f32_e32 v146, v146, v67
	v_max_f32_e32 v94, v94, v79
	v_max_f32_e32 v84, v84, v24
	v_max_f32_e32 v88, v88, v77
	v_max_f32_e32 v6, v6, v43
	v_max_f32_e32 v80, v80, v25
	v_max_f32_e32 v89, v89, v117
	v_max_f32_e32 v20, v20, v124
	v_max_f32_e32 v47, v47, v37
	v_max_f32_e32 v56, v21, v94
	v_min_f32_e32 v94, v21, v94
	v_max_f32_e32 v58, v83, v84
	v_min_f32_e32 v84, v83, v84
	v_max_f32_e32 v59, v95, v88
	v_min_f32_e32 v88, v95, v88
	v_max_f32_e32 v149, v9, v6
	v_min_f32_e32 v6, v9, v6
	v_max_f32_e32 v14, v27, v80
	v_min_f32_e32 v80, v27, v80
	v_max_f32_e32 v255, v144, v89
	v_min_f32_e32 v89, v144, v89
	v_max_f32_e32 v103, v8, v20
	v_min_f32_e32 v20, v8, v20
	v_max_f32_e32 v97, v146, v47
	v_min_f32_e32 v47, v146, v47
	v_max_f32_e32 v106, v56, v14
	v_min_f32_e32 v14, v56, v14
	v_max_f32_e32 v60, v58, v255
	v_min_f32_e32 v255, v58, v255
	v_max_f32_e32 v62, v59, v103
	v_min_f32_e32 v103, v59, v103
	v_max_f32_e32 v254, v149, v97
	v_min_f32_e32 v97, v149, v97
	v_max_f32_e32 v145, v94, v80
	v_min_f32_e32 v80, v94, v80
	v_max_f32_e32 v251, v84, v89
	v_min_f32_e32 v89, v84, v89
	v_max_f32_e32 v10, v88, v20
	v_min_f32_e32 v20, v88, v20
	v_max_f32_e32 v32, v6, v47
	v_min_f32_e32 v47, v6, v47
	v_max_f32_e32 v12, v106, v62
	v_min_f32_e32 v62, v106, v62
	v_max_f32_e32 v35, v60, v254
	v_min_f32_e32 v254, v60, v254
	v_max_f32_e32 v61, v14, v103
	v_min_f32_e32 v103, v14, v103
	v_max_f32_e32 v39, v255, v97
	v_min_f32_e32 v97, v255, v97
	v_max_f32_e32 v2, v145, v10
	v_min_f32_e32 v10, v145, v10
	v_max_f32_e32 v41, v251, v32
	v_min_f32_e32 v32, v251, v32
	v_max_f32_e32 v116, v80, v20
	v_min_f32_e32 v20, v80, v20
	v_max_f32_e32 v118, v89, v47
	v_min_f32_e32 v47, v89, v47
	v_max_f32_e32 v250, v12, v35
	v_min_f32_e32 v35, v12, v35
	v_max_f32_e32 v38, v62, v254
	v_min_f32_e32 v254, v62, v254
	v_max_f32_e32 v40, v61, v39
	v_min_f32_e32 v39, v61, v39
	v_max_f32_e32 v13, v103, v97
	v_min_f32_e32 v97, v103, v97
	v_max_f32_e32 v127, v2, v41
	v_min_f32_e32 v41, v2, v41
	v_max_f32_e32 v33, v10, v32
	v_min_f32_e32 v32, v10, v32
	v_max_f32_e32 v121, v116, v118
	v_min_f32_e32 v118, v116, v118
	v_max_f32_e32 v100, v20, v47
	v_min_f32_e32 v47, v20, v47
	v_max_f32_e32 v53, v53, v47
	v_max_f32_e32 v29, v29, v100
	v_max_f32_e32 v55, v55, v118
	v_max_f32_e32 v18, v18, v121
	v_max_f32_e32 v57, v57, v32
	v_max_f32_e32 v48, v48, v33
	v_max_f32_e32 v249, v249, v41
	v_max_f32_e32 v86, v86, v127
	v_max_f32_e32 v1, v1, v97
	v_max_f32_e32 v50, v50, v13
	v_max_f32_e32 v148, v148, v39
	v_max_f32_e32 v0, v0, v40
	v_max_f32_e32 v92, v92, v254
	v_max_f32_e32 v52, v52, v38
	v_max_f32_e32 v54, v54, v35
	v_max_f32_e32 v15, v15, v250
	v_max_f32_e32 v68, v53, v1
	v_min_f32_e32 v1, v53, v1
	v_max_f32_e32 v42, v29, v50
	v_min_f32_e32 v50, v29, v50
	v_max_f32_e32 v65, v55, v148
	v_min_f32_e32 v148, v55, v148
	v_max_f32_e32 v109, v18, v0
	v_min_f32_e32 v0, v18, v0
	v_max_f32_e32 v114, v57, v92
	v_min_f32_e32 v92, v57, v92
	v_max_f32_e32 v101, v48, v52
	v_min_f32_e32 v52, v48, v52
	v_max_f32_e32 v46, v249, v54
	v_min_f32_e32 v54, v249, v54
	v_max_f32_e32 v34, v86, v15
	v_min_f32_e32 v15, v86, v15
	v_max_f32_e32 v19, v68, v114
	v_min_f32_e32 v114, v68, v114
	v_max_f32_e32 v44, v42, v101
	v_min_f32_e32 v101, v42, v101
	v_max_f32_e32 v23, v65, v46
	v_min_f32_e32 v46, v65, v46
	v_max_f32_e32 v16, v109, v34
	v_min_f32_e32 v34, v109, v34
	v_max_f32_e32 v122, v1, v92
	v_min_f32_e32 v92, v1, v92
	v_max_f32_e32 v45, v50, v52
	v_min_f32_e32 v52, v50, v52
	v_max_f32_e32 v123, v148, v54
	v_min_f32_e32 v54, v148, v54
	v_max_f32_e32 v5, v0, v15
	v_min_f32_e32 v15, v0, v15
	v_max_f32_e32 v150, v19, v23
	v_min_f32_e32 v23, v19, v23
	v_max_f32_e32 v99, v44, v16
	v_min_f32_e32 v16, v44, v16
	v_max_f32_e32 v107, v114, v46
	v_min_f32_e32 v46, v114, v46
	v_max_f32_e32 v11, v101, v34
	v_min_f32_e32 v34, v101, v34
	v_max_f32_e32 v108, v122, v123
	v_min_f32_e32 v123, v122, v123
	v_max_f32_e32 v113, v45, v5
	v_min_f32_e32 v5, v45, v5
	v_max_f32_e32 v110, v92, v54
	v_min_f32_e32 v54, v92, v54
	v_max_f32_e32 v98, v52, v15
	v_min_f32_e32 v15, v52, v15
	v_max_f32_e32 v151, v150, v99
	v_min_f32_e32 v99, v150, v99
	v_max_f32_e32 v252, v23, v16
	v_min_f32_e32 v16, v23, v16
	v_max_f32_e32 v112, v107, v11
	v_min_f32_e32 v11, v107, v11
	v_max_f32_e32 v147, v46, v34
	v_min_f32_e32 v34, v46, v34
	v_max_f32_e32 v253, v108, v113
	v_min_f32_e32 v113, v108, v113
	v_max_f32_e32 v4, v123, v5
	v_min_f32_e32 v5, v123, v5
	v_max_f32_e32 v31, v110, v98
	v_min_f32_e32 v98, v110, v98
	v_max_f32_e32 v105, v54, v15
	v_min_f32_e32 v15, v54, v15
	v_mov_b32_e32 v120, v151
	v_mov_b32_e32 v126, v99
	v_mov_b32_e32 v70, v252
	v_mov_b32_e32 v115, v16
	v_mov_b32_e32 v71, v112
	v_mov_b32_e32 v75, v11
	v_mov_b32_e32 v72, v147
	v_mov_b32_e32 v85, v34
	v_mov_b32_e32 v17, v253
	v_mov_b32_e32 v81, v113
	v_mov_b32_e32 v64, v4
	v_mov_b32_e32 v76, v5
	v_mov_b32_e32 v73, v31
	v_mov_b32_e32 v69, v98
	v_mov_b32_e32 v74, v105
	v_mov_b32_e32 v82, v15
	s_nop 1
	v_permlane32_swap_b32_e32 v151, v120
	v_permlane32_swap_b32_e32 v99, v126
	v_permlane32_swap_b32_e32 v252, v70
	v_permlane32_swap_b32_e32 v16, v115
	v_permlane32_swap_b32_e32 v112, v71
	v_permlane32_swap_b32_e32 v11, v75
	v_permlane32_swap_b32_e32 v147, v72
	v_permlane32_swap_b32_e32 v34, v85
	v_permlane32_swap_b32_e32 v253, v17
	v_permlane32_swap_b32_e32 v113, v81
	v_permlane32_swap_b32_e32 v4, v64
	v_permlane32_swap_b32_e32 v5, v76
	v_permlane32_swap_b32_e32 v31, v73
	v_permlane32_swap_b32_e32 v98, v69
	v_permlane32_swap_b32_e32 v105, v74
	v_permlane32_swap_b32_e32 v15, v82
	s_nop 1
	v_max_f32_e32 v151, v151, v82
	v_max_f32_e32 v99, v99, v74
	v_max_f32_e32 v252, v252, v69
	v_max_f32_e32 v16, v16, v73
	v_max_f32_e32 v112, v112, v76
	v_max_f32_e32 v11, v11, v64
	v_max_f32_e32 v147, v147, v81
	v_max_f32_e32 v34, v34, v17
	v_max_f32_e32 v253, v253, v85
	v_max_f32_e32 v113, v113, v72
	v_max_f32_e32 v4, v4, v75
	v_max_f32_e32 v5, v5, v71
	v_max_f32_e32 v31, v31, v115
	v_max_f32_e32 v98, v98, v70
	v_max_f32_e32 v105, v105, v126
	v_max_f32_e32 v15, v15, v120
	v_max_f32_e32 v78, v151, v253
	v_min_f32_e32 v253, v151, v253
	v_max_f32_e32 v91, v99, v113
	v_min_f32_e32 v113, v99, v113
	v_max_f32_e32 v26, v252, v4
	v_min_f32_e32 v4, v252, v4
	v_max_f32_e32 v3, v16, v5
	v_min_f32_e32 v5, v16, v5
	v_max_f32_e32 v28, v112, v31
	v_min_f32_e32 v31, v112, v31
	v_max_f32_e32 v111, v11, v98
	v_min_f32_e32 v98, v11, v98
	v_max_f32_e32 v119, v147, v105
	v_min_f32_e32 v105, v147, v105
	v_max_f32_e32 v90, v34, v15
	v_min_f32_e32 v15, v34, v15
	v_max_f32_e32 v30, v78, v28
	v_min_f32_e32 v28, v78, v28
	v_max_f32_e32 v87, v91, v111
	v_min_f32_e32 v111, v91, v111
	v_max_f32_e32 v93, v26, v119
	v_min_f32_e32 v119, v26, v119
	v_max_f32_e32 v49, v3, v90
	v_min_f32_e32 v90, v3, v90
	v_max_f32_e32 v7, v253, v31
	v_min_f32_e32 v31, v253, v31
	v_max_f32_e32 v51, v113, v98
	v_min_f32_e32 v98, v113, v98
	v_max_f32_e32 v104, v4, v105
	v_min_f32_e32 v105, v4, v105
	v_max_f32_e32 v37, v5, v15
	v_min_f32_e32 v15, v5, v15
	v_max_f32_e32 v124, v30, v93
	v_min_f32_e32 v93, v30, v93
	v_max_f32_e32 v117, v87, v49
	v_min_f32_e32 v49, v87, v49
	v_max_f32_e32 v25, v28, v119
	v_min_f32_e32 v119, v28, v119
	v_max_f32_e32 v43, v111, v90
	v_min_f32_e32 v90, v111, v90
	v_max_f32_e32 v77, v7, v104
	v_min_f32_e32 v104, v7, v104
	v_max_f32_e32 v24, v51, v37
	v_min_f32_e32 v37, v51, v37
	v_max_f32_e32 v79, v31, v105
	v_min_f32_e32 v105, v31, v105
	v_max_f32_e32 v67, v98, v15
	v_min_f32_e32 v15, v98, v15
	v_max_f32_e32 v125, v124, v117
	v_min_f32_e32 v117, v124, v117
	v_max_f32_e32 v102, v93, v49
	v_min_f32_e32 v49, v93, v49
	v_max_f32_e32 v22, v25, v43
	v_min_f32_e32 v43, v25, v43
	v_max_f32_e32 v96, v119, v90
	v_min_f32_e32 v90, v119, v90
	v_max_f32_e32 v66, v77, v24
	v_min_f32_e32 v24, v77, v24
	v_max_f32_e32 v36, v104, v37
	v_min_f32_e32 v37, v104, v37
	v_max_f32_e32 v63, v79, v67
	v_min_f32_e32 v67, v79, v67
	v_max_f32_e32 v21, v105, v15
	v_min_f32_e32 v15, v105, v15
	s_waitcnt vmcnt(0)
	v_pk_mul_f32 v[160:161], v[160:161], v[176:177]
	v_pk_mul_f32 v[162:163], v[162:163], v[178:179]
	v_pk_mul_f32 v[164:165], v[164:165], v[180:181]
	v_pk_mul_f32 v[166:167], v[166:167], v[182:183]
	v_pk_mul_f32 v[168:169], v[168:169], v[184:185]
	v_pk_mul_f32 v[170:171], v[170:171], v[186:187]
	v_pk_mul_f32 v[172:173], v[172:173], v[188:189]
	v_pk_mul_f32 v[174:175], v[174:175], v[190:191]
	v_max3_f32 v192, |v160|, |v161|, |v162|
	v_max3_f32 v192, |v163|, |v164|, v192
	v_max3_f32 v192, |v165|, |v166|, v192
	v_max3_f32 v192, |v167|, |v168|, v192
	v_max3_f32 v192, |v169|, |v170|, v192
	v_max3_f32 v192, |v171|, |v172|, v192
	v_max3_f32 v192, |v173|, |v174|, v192
	v_max_f32_e64 v192, |v175|, v192
	s_nop 1
	v_mov_b32_dpp v193, v192 quad_perm:[1,0,3,2] row_mask:0xf bank_mask:0xf bound_ctrl:1
	v_max_f32_e32 v192, v192, v193
	s_nop 1
	v_mov_b32_dpp v193, v192 quad_perm:[2,3,0,1] row_mask:0xf bank_mask:0xf bound_ctrl:1
	v_max_f32_e32 v192, v192, v193
	s_nop 1
	v_mov_b32_dpp v193, v192 row_half_mirror row_mask:0xf bank_mask:0xf bound_ctrl:1
	v_max_f32_e32 v192, v192, v193
	s_nop 1
	v_mov_b32_dpp v193, v192 row_mirror row_mask:0xf bank_mask:0xf bound_ctrl:1
	v_max_f32_e32 v192, v192, v193
	v_mov_b32_e32 v193, v192
	s_nop 1
	v_permlane16_swap_b32_e32 v192, v193
	s_nop 1
	v_max_f32_e32 v192, v192, v193
	v_mov_b32_e32 v193, v192
	s_nop 1
	v_permlane32_swap_b32_e32 v192, v193
	s_nop 1
	v_max_f32_e32 v192, v192, v193
	v_max_f32_e32 v192, 0xda24260, v192
	v_mul_f32_e32 v194, 0x3e2aaaab, v192
	global_store_dword v214, v194, s[12:13]
	v_div_scale_f32 v195, s[26:27], v194, v194, 1.0
	v_rcp_f32_e32 v196, v195
	v_div_scale_f32 v204, vcc, 1.0, v194, 1.0
	v_fma_f32 v205, -v195, v196, 1.0
	v_fmac_f32_e32 v196, v205, v196
	v_mul_f32_e32 v205, v204, v196
	v_fma_f32 v206, -v195, v205, v204
	v_fmac_f32_e32 v205, v206, v196
	v_fma_f32 v195, -v195, v205, v204
	s_nop 0
	v_div_fmas_f32 v195, v195, v196, v205
	v_div_fixup_f32 v207, v195, v194, 1.0
	v_mul_f32_e32 v160, v207, v160
	v_mul_f32_e32 v161, v207, v161
	v_mul_f32_e32 v162, v207, v162
	v_mul_f32_e32 v163, v207, v163
	v_mul_f32_e32 v164, v207, v164
	v_mul_f32_e32 v165, v207, v165
	v_mul_f32_e32 v166, v207, v166
	v_mul_f32_e32 v167, v207, v167
	v_mul_f32_e32 v168, v207, v168
	v_mul_f32_e32 v169, v207, v169
	v_mul_f32_e32 v170, v207, v170
	v_mul_f32_e32 v171, v207, v171
	v_mul_f32_e32 v172, v207, v172
	v_mul_f32_e32 v173, v207, v173
	v_mul_f32_e32 v174, v207, v174
	v_mul_f32_e32 v175, v207, v175
	v_mov_b32_e32 v208, 0
	v_mov_b32_e32 v209, 0
	v_mov_b32_e32 v210, 0
	v_mov_b32_e32 v193, 0
	v_cvt_scalef32_pk_fp4_f32 v208, v160, v161, 1.0
	v_cvt_scalef32_pk_fp4_f32 v209, v164, v165, 1.0
	v_cvt_scalef32_pk_fp4_f32 v210, v168, v169, 1.0
	v_cvt_scalef32_pk_fp4_f32 v193, v172, v173, 1.0
	v_cvt_scalef32_pk_fp4_f32 v208, v162, v163, 1.0 op_sel:[0,0,1,0]
	v_cvt_scalef32_pk_fp4_f32 v209, v166, v167, 1.0 op_sel:[0,0,1,0]
	v_cvt_scalef32_pk_fp4_f32 v210, v170, v171, 1.0 op_sel:[0,0,1,0]
	v_cvt_scalef32_pk_fp4_f32 v193, v174, v175, 1.0 op_sel:[0,0,1,0]
	global_store_short v213, v208, s[10:11] nt
	s_add_u32 s14, s10, 0x200000
	s_addc_u32 s15, s11, 0
	global_store_short v213, v209, s[14:15] nt
	s_add_u32 s14, s10, 0x400000
	s_addc_u32 s15, s11, 0
	global_store_short v213, v210, s[14:15] nt
	s_add_u32 s14, s10, 0x600000
	s_addc_u32 s15, s11, 0
	global_store_short v213, v193, s[14:15] nt
	s_add_u32 s10, s10, 0x20000
	s_addc_u32 s11, s11, 0
	s_add_u32 s12, s12, 0x2000
	s_addc_u32 s13, s13, 0
	global_load_dwordx4 v[160:163], v212, s[8:9] offset:0 nt
	global_load_dwordx4 v[164:167], v212, s[8:9] offset:1024 nt
	global_load_dwordx4 v[168:171], v212, s[8:9] offset:2048 nt
	global_load_dwordx4 v[172:175], v212, s[8:9] offset:3072 nt
	s_add_u32 s8, s8, 0x800000
	s_addc_u32 s9, s9, 0
	ds_write_b8 v240, v125 offset:512
	ds_write_b8 v240, v117 offset:513
	ds_write_b8 v240, v102 offset:514
	ds_write_b8 v240, v49 offset:515
	ds_write_b8 v240, v22 offset:516
	ds_write_b8 v240, v43 offset:517
	ds_write_b8 v240, v96 offset:518
	ds_write_b8 v240, v90 offset:519
	ds_write_b8 v240, v66 offset:520
	ds_write_b8 v240, v24 offset:521
	ds_write_b8 v240, v36 offset:522
	ds_write_b8 v240, v37 offset:523
	ds_write_b8 v240, v63 offset:524
	ds_write_b8 v240, v67 offset:525
	ds_write_b8 v240, v21 offset:526
	ds_write_b8 v240, v15 offset:527
	v_cndmask_b32_e64 v0, v128, v125, s[4:5]
	v_cndmask_b32_e64 v17, v125, v128, s[4:5]
	v_cndmask_b32_e64 v1, v129, v117, s[4:5]
	v_cndmask_b32_e64 v18, v117, v129, s[4:5]
	v_cndmask_b32_e64 v2, v130, v102, s[4:5]
	v_cndmask_b32_e64 v19, v102, v130, s[4:5]
	v_cndmask_b32_e64 v3, v131, v49, s[4:5]
	v_cndmask_b32_e64 v20, v49, v131, s[4:5]
	v_cndmask_b32_e64 v4, v132, v22, s[4:5]
	v_cndmask_b32_e64 v23, v22, v132, s[4:5]
	v_cndmask_b32_e64 v5, v133, v43, s[4:5]
	v_cndmask_b32_e64 v25, v43, v133, s[4:5]
	v_cndmask_b32_e64 v6, v134, v96, s[4:5]
	v_cndmask_b32_e64 v26, v96, v134, s[4:5]
	v_cndmask_b32_e64 v7, v135, v90, s[4:5]
	v_cndmask_b32_e64 v27, v90, v135, s[4:5]
	v_cndmask_b32_e64 v8, v136, v66, s[4:5]
	v_cndmask_b32_e64 v28, v66, v136, s[4:5]
	v_cndmask_b32_e64 v9, v137, v24, s[4:5]
	v_cndmask_b32_e64 v29, v24, v137, s[4:5]
	v_cndmask_b32_e64 v10, v138, v36, s[4:5]
	v_cndmask_b32_e64 v30, v36, v138, s[4:5]
	v_cndmask_b32_e64 v11, v139, v37, s[4:5]
	v_cndmask_b32_e64 v31, v37, v139, s[4:5]
	v_cndmask_b32_e64 v12, v140, v63, s[4:5]
	v_cndmask_b32_e64 v32, v63, v140, s[4:5]
	v_cndmask_b32_e64 v13, v141, v67, s[4:5]
	v_cndmask_b32_e64 v33, v67, v141, s[4:5]
	v_cndmask_b32_e64 v14, v142, v21, s[4:5]
	v_cndmask_b32_e64 v34, v21, v142, s[4:5]
	v_cndmask_b32_e64 v16, v143, v15, s[4:5]
	v_cndmask_b32_e64 v35, v15, v143, s[4:5]
	v_and_b32_e32 v0, s6, v0
	v_and_b32_e32 v17, s6, v17
	v_and_b32_e32 v1, s6, v1
	v_and_b32_e32 v18, s6, v18
	v_and_b32_e32 v2, s6, v2
	v_and_b32_e32 v19, s6, v19
	v_and_b32_e32 v3, s6, v3
	v_and_b32_e32 v20, s6, v20
	v_and_b32_e32 v4, s6, v4
	v_and_b32_e32 v23, s6, v23
	v_and_b32_e32 v5, s6, v5
	v_and_b32_e32 v25, s6, v25
	v_and_b32_e32 v6, s6, v6
	v_and_b32_e32 v26, s6, v26
	v_and_b32_e32 v7, s6, v7
	v_and_b32_e32 v27, s6, v27
	v_and_b32_e32 v8, s6, v8
	v_and_b32_e32 v28, s6, v28
	v_and_b32_e32 v9, s6, v9
	v_and_b32_e32 v29, s6, v29
	v_and_b32_e32 v10, s6, v10
	v_and_b32_e32 v30, s6, v30
	v_and_b32_e32 v11, s6, v11
	v_and_b32_e32 v31, s6, v31
	v_and_b32_e32 v12, s6, v12
	v_and_b32_e32 v32, s6, v32
	v_and_b32_e32 v13, s6, v13
	v_and_b32_e32 v33, s6, v33
	v_and_b32_e32 v14, s6, v14
	v_and_b32_e32 v34, s6, v34
	v_and_b32_e32 v16, s6, v16
	v_and_b32_e32 v35, s6, v35
	v_add_f32_e32 v38, v0, v18
	v_and_or_b32 v38, v38, s7, 0
	v_add_f32_e32 v39, v0, v19
	v_and_or_b32 v39, v39, s7, 2
	v_add_f32_e32 v40, v0, v20
	v_and_or_b32 v40, v40, s7, 4
	v_add_f32_e32 v41, v0, v23
	v_and_or_b32 v41, v41, s7, 6
	v_add_f32_e32 v42, v0, v25
	v_and_or_b32 v42, v42, s7, 8
	v_add_f32_e32 v44, v0, v26
	v_and_or_b32 v44, v44, s7, 10
	v_add_f32_e32 v45, v0, v27
	v_and_or_b32 v45, v45, s7, 12
	v_add_f32_e32 v46, v0, v28
	v_and_or_b32 v46, v46, s7, 14
	v_add_f32_e32 v47, v0, v29
	v_and_or_b32 v47, v47, s7, 16
	v_add_f32_e32 v48, v0, v30
	v_and_or_b32 v48, v48, s7, 18
	v_add_f32_e32 v50, v0, v31
	v_and_or_b32 v50, v50, s7, 20
	v_add_f32_e32 v51, v0, v32
	v_and_or_b32 v51, v51, s7, 22
	v_add_f32_e32 v52, v0, v33
	v_and_or_b32 v52, v52, s7, 24
	v_add_f32_e32 v53, v0, v34
	v_and_or_b32 v53, v53, s7, 26
	v_add_f32_e32 v54, v0, v35
	v_and_or_b32 v54, v54, s7, 28
	v_add_f32_e32 v55, v1, v19
	v_and_or_b32 v55, v55, s7, 30
	v_add_f32_e32 v56, v1, v20
	v_and_or_b32 v56, v56, s7, 32
	v_add_f32_e32 v57, v1, v23
	v_and_or_b32 v57, v57, s7, 34
	v_add_f32_e32 v58, v1, v25
	v_and_or_b32 v58, v58, s7, 36
	v_add_f32_e32 v59, v1, v26
	v_and_or_b32 v59, v59, s7, 38
	v_add_f32_e32 v60, v1, v27
	v_and_or_b32 v60, v60, s7, 40
	v_add_f32_e32 v61, v2, v20
	v_and_or_b32 v61, v61, s7, 42
	v_add_f32_e32 v62, v2, v23
	v_and_or_b32 v62, v62, s7, 44
	v_add_f32_e32 v64, v0, v17
	v_and_or_b32 v64, v64, s7, 46
	v_cndmask_b32_e64 v64, v64, v244, s[4:5]
	v_add_f32_e32 v65, v1, v18
	v_and_or_b32 v65, v65, s7, 48
	v_cndmask_b32_e64 v65, v65, v244, s[4:5]
	v_add_f32_e32 v68, v2, v19
	v_and_or_b32 v68, v68, s7, 50
	v_cndmask_b32_e64 v68, v68, v244, s[4:5]
	v_add_f32_e32 v69, v3, v20
	v_and_or_b32 v69, v69, s7, 52
	v_cndmask_b32_e64 v69, v69, v244, s[4:5]
	v_max_f32_e32 v70, v38, v53
	v_min_f32_e32 v53, v38, v53
	v_max_f32_e32 v71, v39, v52
	v_min_f32_e32 v52, v39, v52
	v_max_f32_e32 v72, v40, v55
	v_min_f32_e32 v55, v40, v55
	v_max_f32_e32 v73, v41, v54
	v_min_f32_e32 v54, v41, v54
	v_max_f32_e32 v74, v42, v47
	v_min_f32_e32 v47, v42, v47
	v_max_f32_e32 v75, v44, v45
	v_min_f32_e32 v45, v44, v45
	v_max_f32_e32 v76, v46, v51
	v_min_f32_e32 v51, v46, v51
	v_max_f32_e32 v77, v48, v50
	v_min_f32_e32 v50, v48, v50
	v_max_f32_e32 v78, v70, v75
	v_min_f32_e32 v75, v70, v75
	v_max_f32_e32 v79, v71, v76
	v_min_f32_e32 v76, v71, v76
	v_max_f32_e32 v80, v72, v77
	v_min_f32_e32 v77, v72, v77
	v_max_f32_e32 v81, v73, v74
	v_min_f32_e32 v74, v73, v74
	v_max_f32_e32 v82, v45, v53
	v_min_f32_e32 v53, v45, v53
	v_max_f32_e32 v83, v47, v54
	v_min_f32_e32 v54, v47, v54
	v_max_f32_e32 v84, v50, v55
	v_min_f32_e32 v55, v50, v55
	v_max_f32_e32 v85, v51, v52
	v_min_f32_e32 v52, v51, v52
	v_max_f32_e32 v86, v78, v79
	v_min_f32_e32 v79, v78, v79
	v_max_f32_e32 v87, v80, v81
	v_min_f32_e32 v81, v80, v81
	v_max_f32_e32 v88, v74, v75
	v_min_f32_e32 v75, v74, v75
	v_max_f32_e32 v89, v82, v83
	v_min_f32_e32 v83, v82, v83
	v_max_f32_e32 v91, v76, v77
	v_min_f32_e32 v77, v76, v77
	v_max_f32_e32 v92, v84, v85
	v_min_f32_e32 v85, v84, v85
	v_max_f32_e32 v93, v52, v53
	v_min_f32_e32 v53, v52, v53
	v_max_f32_e32 v94, v54, v55
	v_min_f32_e32 v55, v54, v55
	v_max_f32_e32 v95, v86, v87
	v_min_f32_e32 v87, v86, v87
	v_max_f32_e32 v97, v79, v81
	v_min_f32_e32 v81, v79, v81
	v_max_f32_e32 v98, v88, v92
	v_min_f32_e32 v92, v88, v92
	v_max_f32_e32 v99, v75, v85
	v_min_f32_e32 v85, v75, v85
	v_max_f32_e32 v100, v89, v91
	v_min_f32_e32 v91, v89, v91
	v_max_f32_e32 v101, v83, v77
	v_min_f32_e32 v77, v83, v77
	v_max_f32_e32 v103, v93, v94
	v_min_f32_e32 v94, v93, v94
	v_max_f32_e32 v104, v53, v55
	v_min_f32_e32 v55, v53, v55
	v_max_f32_e32 v105, v97, v87
	v_min_f32_e32 v87, v97, v87
	v_max_f32_e32 v106, v81, v103
	v_min_f32_e32 v103, v81, v103
	v_max_f32_e32 v107, v98, v100
	v_min_f32_e32 v100, v98, v100
	v_max_f32_e32 v108, v99, v91
	v_min_f32_e32 v91, v99, v91
	v_max_f32_e32 v109, v101, v92
	v_min_f32_e32 v92, v101, v92
	v_max_f32_e32 v110, v77, v85
	v_min_f32_e32 v85, v77, v85
	v_max_f32_e32 v111, v104, v94
	v_min_f32_e32 v94, v104, v94
	v_max_f32_e32 v112, v105, v107
	v_min_f32_e32 v107, v105, v107
	v_max_f32_e32 v113, v87, v100
	v_min_f32_e32 v100, v87, v100
	v_max_f32_e32 v114, v108, v109
	v_min_f32_e32 v109, v108, v109
	v_max_f32_e32 v115, v91, v92
	v_min_f32_e32 v92, v91, v92
	v_max_f32_e32 v116, v110, v111
	v_min_f32_e32 v111, v110, v111
	v_max_f32_e32 v118, v85, v94
	v_min_f32_e32 v94, v85, v94
	v_max_f32_e32 v119, v113, v107
	v_min_f32_e32 v107, v113, v107
	v_max_f32_e32 v120, v106, v100
	v_min_f32_e32 v100, v106, v100
	v_max_f32_e32 v121, v116, v103
	v_min_f32_e32 v103, v116, v103
	v_max_f32_e32 v122, v118, v111
	v_min_f32_e32 v111, v118, v111
	v_max_f32_e32 v123, v120, v114
	v_min_f32_e32 v114, v120, v114
	v_max_f32_e32 v124, v100, v109
	v_min_f32_e32 v109, v100, v109
	v_max_f32_e32 v126, v115, v121
	v_min_f32_e32 v121, v115, v121
	v_max_f32_e32 v127, v92, v103
	v_min_f32_e32 v103, v92, v103
	v_max_f32_e32 v144, v123, v107
	v_min_f32_e32 v107, v123, v107
	v_max_f32_e32 v145, v114, v124
	v_min_f32_e32 v124, v114, v124
	v_max_f32_e32 v146, v126, v109
	v_min_f32_e32 v109, v126, v109
	v_max_f32_e32 v147, v121, v127
	v_min_f32_e32 v127, v121, v127
	v_max_f32_e32 v148, v122, v103
	v_min_f32_e32 v103, v122, v103
	v_max_f32_e32 v149, v124, v146
	v_min_f32_e32 v146, v124, v146
	v_max_f32_e32 v150, v109, v147
	v_min_f32_e32 v147, v109, v147
	v_max_f32_e32 v151, v60, v65
	v_min_f32_e32 v65, v60, v65
	v_max_f32_e32 v249, v61, v62
	v_min_f32_e32 v62, v61, v62
	v_max_f32_e32 v250, v68, v69
	v_min_f32_e32 v69, v68, v69
	v_max_f32_e32 v251, v56, v249
	v_min_f32_e32 v249, v56, v249
	v_max_f32_e32 v252, v57, v64
	v_min_f32_e32 v64, v57, v64
	v_max_f32_e32 v253, v58, v250
	v_min_f32_e32 v250, v58, v250
	v_max_f32_e32 v254, v59, v151
	v_min_f32_e32 v151, v59, v151
	v_max_f32_e32 v255, v251, v252
	v_min_f32_e32 v252, v251, v252
	v_max_f32_e32 v128, v253, v254
	v_min_f32_e32 v254, v253, v254
	v_max_f32_e32 v129, v151, v249
	v_min_f32_e32 v249, v151, v249
	v_max_f32_e32 v130, v62, v65
	v_min_f32_e32 v65, v62, v65
	v_max_f32_e32 v131, v64, v250
	v_min_f32_e32 v250, v64, v250
	v_max_f32_e32 v132, v255, v128
	v_min_f32_e32 v128, v255, v128
	v_max_f32_e32 v133, v252, v254
	v_min_f32_e32 v254, v252, v254
	v_max_f32_e32 v134, v129, v69
	v_min_f32_e32 v69, v129, v69
	v_max_f32_e32 v135, v130, v131
	v_min_f32_e32 v131, v130, v131
	v_max_f32_e32 v136, v65, v250
	v_min_f32_e32 v250, v65, v250
	v_max_f32_e32 v137, v133, v128
	v_min_f32_e32 v128, v133, v128
	v_max_f32_e32 v138, v134, v135
	v_min_f32_e32 v135, v134, v135
	v_max_f32_e32 v139, v249, v131
	v_min_f32_e32 v131, v249, v131
	v_max_f32_e32 v140, v136, v69
	v_min_f32_e32 v69, v136, v69
	v_max_f32_e32 v141, v137, v138
	v_min_f32_e32 v138, v137, v138
	v_max_f32_e32 v142, v128, v135
	v_min_f32_e32 v135, v128, v135
	v_max_f32_e32 v143, v139, v140
	v_min_f32_e32 v140, v139, v140
	v_max_f32_e32 v125, v131, v69
	v_min_f32_e32 v69, v131, v69
	v_max_f32_e32 v117, v142, v138
	v_min_f32_e32 v138, v142, v138
	v_max_f32_e32 v102, v254, v135
	v_min_f32_e32 v135, v254, v135
	v_max_f32_e32 v49, v102, v143
	v_min_f32_e32 v143, v102, v143
	v_max_f32_e32 v22, v135, v140
	v_min_f32_e32 v140, v135, v140
	v_max_f32_e32 v43, v125, v250
	v_min_f32_e32 v250, v125, v250
	v_max_f32_e32 v96, v49, v138
	v_min_f32_e32 v138, v49, v138
	v_max_f32_e32 v90, v143, v22
	v_min_f32_e32 v22, v143, v22
	v_max_f32_e32 v66, v43, v140
	v_min_f32_e32 v140, v43, v140
	v_max_f32_e32 v24, v250, v69
	v_min_f32_e32 v69, v250, v69
	v_max_f32_e32 v36, v22, v66
	v_min_f32_e32 v66, v22, v66
	v_max_f32_e32 v37, v140, v24
	v_min_f32_e32 v24, v140, v24
	s_waitcnt vmcnt(0)
	v_pk_mul_f32 v[160:161], v[160:161], v[176:177]
	v_pk_mul_f32 v[162:163], v[162:163], v[178:179]
	v_pk_mul_f32 v[164:165], v[164:165], v[180:181]
	v_pk_mul_f32 v[166:167], v[166:167], v[182:183]
	v_pk_mul_f32 v[168:169], v[168:169], v[184:185]
	v_pk_mul_f32 v[170:171], v[170:171], v[186:187]
	v_pk_mul_f32 v[172:173], v[172:173], v[188:189]
	v_pk_mul_f32 v[174:175], v[174:175], v[190:191]
	v_max3_f32 v192, |v160|, |v161|, |v162|
	v_max3_f32 v192, |v163|, |v164|, v192
	v_max3_f32 v192, |v165|, |v166|, v192
	v_max3_f32 v192, |v167|, |v168|, v192
	v_max3_f32 v192, |v169|, |v170|, v192
	v_max3_f32 v192, |v171|, |v172|, v192
	v_max3_f32 v192, |v173|, |v174|, v192
	v_max_f32_e64 v192, |v175|, v192
	s_nop 1
	v_mov_b32_dpp v193, v192 quad_perm:[1,0,3,2] row_mask:0xf bank_mask:0xf bound_ctrl:1
	v_max_f32_e32 v192, v192, v193
	s_nop 1
	v_mov_b32_dpp v193, v192 quad_perm:[2,3,0,1] row_mask:0xf bank_mask:0xf bound_ctrl:1
	v_max_f32_e32 v192, v192, v193
	s_nop 1
	v_mov_b32_dpp v193, v192 row_half_mirror row_mask:0xf bank_mask:0xf bound_ctrl:1
	v_max_f32_e32 v192, v192, v193
	s_nop 1
	v_mov_b32_dpp v193, v192 row_mirror row_mask:0xf bank_mask:0xf bound_ctrl:1
	v_max_f32_e32 v192, v192, v193
	v_mov_b32_e32 v193, v192
	s_nop 1
	v_permlane16_swap_b32_e32 v192, v193
	s_nop 1
	v_max_f32_e32 v192, v192, v193
	v_mov_b32_e32 v193, v192
	s_nop 1
	v_permlane32_swap_b32_e32 v192, v193
	s_nop 1
	v_max_f32_e32 v192, v192, v193
	v_max_f32_e32 v192, 0xda24260, v192
	v_mul_f32_e32 v194, 0x3e2aaaab, v192
	global_store_dword v214, v194, s[12:13]
	v_div_scale_f32 v195, s[26:27], v194, v194, 1.0
	v_rcp_f32_e32 v196, v195
	v_div_scale_f32 v204, vcc, 1.0, v194, 1.0
	v_fma_f32 v205, -v195, v196, 1.0
	v_fmac_f32_e32 v196, v205, v196
	v_mul_f32_e32 v205, v204, v196
	v_fma_f32 v206, -v195, v205, v204
	v_fmac_f32_e32 v205, v206, v196
	v_fma_f32 v195, -v195, v205, v204
	s_nop 0
	v_div_fmas_f32 v195, v195, v196, v205
	v_div_fixup_f32 v207, v195, v194, 1.0
	v_mul_f32_e32 v160, v207, v160
	v_mul_f32_e32 v161, v207, v161
	v_mul_f32_e32 v162, v207, v162
	v_mul_f32_e32 v163, v207, v163
	v_mul_f32_e32 v164, v207, v164
	v_mul_f32_e32 v165, v207, v165
	v_mul_f32_e32 v166, v207, v166
	v_mul_f32_e32 v167, v207, v167
	v_mul_f32_e32 v168, v207, v168
	v_mul_f32_e32 v169, v207, v169
	v_mul_f32_e32 v170, v207, v170
	v_mul_f32_e32 v171, v207, v171
	v_mul_f32_e32 v172, v207, v172
	v_mul_f32_e32 v173, v207, v173
	v_mul_f32_e32 v174, v207, v174
	v_mul_f32_e32 v175, v207, v175
	v_mov_b32_e32 v208, 0
	v_mov_b32_e32 v209, 0
	v_mov_b32_e32 v210, 0
	v_mov_b32_e32 v193, 0
	v_cvt_scalef32_pk_fp4_f32 v208, v160, v161, 1.0
	v_cvt_scalef32_pk_fp4_f32 v209, v164, v165, 1.0
	v_cvt_scalef32_pk_fp4_f32 v210, v168, v169, 1.0
	v_cvt_scalef32_pk_fp4_f32 v193, v172, v173, 1.0
	v_cvt_scalef32_pk_fp4_f32 v208, v162, v163, 1.0 op_sel:[0,0,1,0]
	v_cvt_scalef32_pk_fp4_f32 v209, v166, v167, 1.0 op_sel:[0,0,1,0]
	v_cvt_scalef32_pk_fp4_f32 v210, v170, v171, 1.0 op_sel:[0,0,1,0]
	v_cvt_scalef32_pk_fp4_f32 v193, v174, v175, 1.0 op_sel:[0,0,1,0]
	global_store_short v213, v208, s[10:11] nt
	s_add_u32 s14, s10, 0x200000
	s_addc_u32 s15, s11, 0
	global_store_short v213, v209, s[14:15] nt
	s_add_u32 s14, s10, 0x400000
	s_addc_u32 s15, s11, 0
	global_store_short v213, v210, s[14:15] nt
	s_add_u32 s14, s10, 0x600000
	s_addc_u32 s15, s11, 0
	global_store_short v213, v193, s[14:15] nt
	s_add_u32 s10, s10, 0x20000
	s_addc_u32 s11, s11, 0
	s_add_u32 s12, s12, 0x2000
	s_addc_u32 s13, s13, 0
	global_load_dwordx4 v[160:163], v212, s[8:9] offset:0 nt
	global_load_dwordx4 v[164:167], v212, s[8:9] offset:1024 nt
	global_load_dwordx4 v[168:171], v212, s[8:9] offset:2048 nt
	global_load_dwordx4 v[172:175], v212, s[8:9] offset:3072 nt
	s_add_u32 s8, s8, 0x800000
	s_addc_u32 s9, s9, 0
	v_max_f32_e32 v145, v145, v69
	v_max_f32_e32 v149, v149, v24
	v_max_f32_e32 v146, v146, v37
	v_max_f32_e32 v150, v150, v66
	v_max_f32_e32 v147, v147, v36
	v_max_f32_e32 v127, v127, v90
	v_max_f32_e32 v148, v148, v138
	v_max_f32_e32 v103, v103, v96
	v_max_f32_e32 v111, v111, v117
	v_max_f32_e32 v94, v94, v141
	v_max_f32_e32 v55, v55, v132
	v_max_f32_e32 v63, v95, v150
	v_min_f32_e32 v150, v95, v150
	v_max_f32_e32 v67, v112, v147
	v_min_f32_e32 v147, v112, v147
	v_max_f32_e32 v21, v119, v127
	v_min_f32_e32 v127, v119, v127
	v_max_f32_e32 v15, v144, v148
	v_min_f32_e32 v148, v144, v148
	v_max_f32_e32 v0, v107, v103
	v_min_f32_e32 v103, v107, v103
	v_max_f32_e32 v1, v145, v111
	v_min_f32_e32 v111, v145, v111
	v_max_f32_e32 v2, v149, v94
	v_min_f32_e32 v94, v149, v94
	v_max_f32_e32 v3, v146, v55
	v_min_f32_e32 v55, v146, v55
	v_max_f32_e32 v4, v63, v0
	v_min_f32_e32 v0, v63, v0
	v_max_f32_e32 v5, v67, v1
	v_min_f32_e32 v1, v67, v1
	v_max_f32_e32 v6, v21, v2
	v_min_f32_e32 v2, v21, v2
	v_max_f32_e32 v7, v15, v3
	v_min_f32_e32 v3, v15, v3
	v_max_f32_e32 v8, v150, v103
	v_min_f32_e32 v103, v150, v103
	v_max_f32_e32 v9, v147, v111
	v_min_f32_e32 v111, v147, v111
	v_max_f32_e32 v10, v127, v94
	v_min_f32_e32 v94, v127, v94
	v_max_f32_e32 v11, v148, v55
	v_min_f32_e32 v55, v148, v55
	v_max_f32_e32 v12, v4, v6
	v_min_f32_e32 v6, v4, v6
	v_max_f32_e32 v13, v5, v7
	v_min_f32_e32 v7, v5, v7
	v_max_f32_e32 v14, v0, v2
	v_min_f32_e32 v2, v0, v2
	v_max_f32_e32 v16, v1, v3
	v_min_f32_e32 v3, v1, v3
	v_max_f32_e32 v17, v8, v10
	v_min_f32_e32 v10, v8, v10
	v_max_f32_e32 v18, v9, v11
	v_min_f32_e32 v11, v9, v11
	v_max_f32_e32 v19, v103, v94
	v_min_f32_e32 v94, v103, v94
	v_max_f32_e32 v20, v111, v55
	v_min_f32_e32 v55, v111, v55
	v_max_f32_e32 v23, v12, v13
	v_min_f32_e32 v13, v12, v13
	v_max_f32_e32 v25, v6, v7
	v_min_f32_e32 v7, v6, v7
	v_max_f32_e32 v26, v14, v16
	v_min_f32_e32 v16, v14, v16
	v_max_f32_e32 v27, v2, v3
	v_min_f32_e32 v3, v2, v3
	v_max_f32_e32 v28, v17, v18
	v_min_f32_e32 v18, v17, v18
	v_max_f32_e32 v29, v10, v11
	v_min_f32_e32 v11, v10, v11
	v_max_f32_e32 v30, v19, v20
	v_min_f32_e32 v20, v19, v20
	v_max_f32_e32 v31, v94, v55
	v_min_f32_e32 v55, v94, v55
	v_or_b32_e32 v23, v23, v245
	v_or_b32_e32 v13, v13, v245
	v_or_b32_e32 v25, v25, v245
	v_or_b32_e32 v7, v7, v245
	v_or_b32_e32 v26, v26, v245
	v_or_b32_e32 v16, v16, v245
	v_or_b32_e32 v27, v27, v245
	v_or_b32_e32 v3, v3, v245
	v_or_b32_e32 v28, v28, v245
	v_or_b32_e32 v18, v18, v245
	v_or_b32_e32 v29, v29, v245
	v_or_b32_e32 v11, v11, v245
	v_or_b32_e32 v30, v30, v245
	v_or_b32_e32 v20, v20, v245
	v_or_b32_e32 v31, v31, v245
	v_or_b32_e32 v55, v55, v245
	v_mov_b32_e32 v32, v23
	v_mov_b32_e32 v33, v13
	v_mov_b32_e32 v34, v25
	v_mov_b32_e32 v35, v7
	v_mov_b32_e32 v38, v26
	v_mov_b32_e32 v39, v16
	v_mov_b32_e32 v40, v27
	v_mov_b32_e32 v41, v3
	v_mov_b32_e32 v42, v28
	v_mov_b32_e32 v44, v18
	v_mov_b32_e32 v46, v29
	v_mov_b32_e32 v48, v11
	v_mov_b32_e32 v70, v30
	v_mov_b32_e32 v71, v20
	v_mov_b32_e32 v72, v31
	v_mov_b32_e32 v73, v55
	s_nop 1
	v_permlane32_swap_b32_e32 v23, v32
	v_permlane32_swap_b32_e32 v13, v33
	v_permlane32_swap_b32_e32 v25, v34
	v_permlane32_swap_b32_e32 v7, v35
	v_permlane32_swap_b32_e32 v26, v38
	v_permlane32_swap_b32_e32 v16, v39
	v_permlane32_swap_b32_e32 v27, v40
	v_permlane32_swap_b32_e32 v3, v41
	v_permlane32_swap_b32_e32 v28, v42
	v_permlane32_swap_b32_e32 v18, v44
	v_permlane32_swap_b32_e32 v29, v46
	v_permlane32_swap_b32_e32 v11, v48
	v_permlane32_swap_b32_e32 v30, v70
	v_permlane32_swap_b32_e32 v20, v71
	v_permlane32_swap_b32_e32 v31, v72
	v_permlane32_swap_b32_e32 v55, v73
	s_nop 1
	v_max_f32_e32 v23, v23, v73
	v_max_f32_e32 v13, v13, v72
	v_max_f32_e32 v25, v25, v71
	v_max_f32_e32 v7, v7, v70
	v_max_f32_e32 v26, v26, v48
	v_max_f32_e32 v16, v16, v46
	v_max_f32_e32 v27, v27, v44
	v_max_f32_e32 v3, v3, v42
	v_max_f32_e32 v28, v28, v41
	v_max_f32_e32 v18, v18, v40
	v_max_f32_e32 v29, v29, v39
	v_max_f32_e32 v11, v11, v38
	v_max_f32_e32 v30, v30, v35
	v_max_f32_e32 v20, v20, v34
	v_max_f32_e32 v31, v31, v33
	v_max_f32_e32 v55, v55, v32
	v_max_f32_e32 v45, v23, v28
	v_min_f32_e32 v28, v23, v28
	v_max_f32_e32 v47, v13, v18
	v_min_f32_e32 v18, v13, v18
	v_max_f32_e32 v50, v25, v29
	v_min_f32_e32 v29, v25, v29
	v_max_f32_e32 v51, v7, v11
	v_min_f32_e32 v11, v7, v11
	v_max_f32_e32 v78, v26, v30
	v_min_f32_e32 v30, v26, v30
	v_max_f32_e32 v80, v16, v20
	v_min_f32_e32 v20, v16, v20
	v_max_f32_e32 v74, v27, v31
	v_min_f32_e32 v31, v27, v31
	v_max_f32_e32 v82, v3, v55
	v_min_f32_e32 v55, v3, v55
	v_max_f32_e32 v76, v45, v78
	v_min_f32_e32 v78, v45, v78
	v_max_f32_e32 v84, v47, v80
	v_min_f32_e32 v80, v47, v80
	v_max_f32_e32 v52, v50, v74
	v_min_f32_e32 v74, v50, v74
	v_max_f32_e32 v54, v51, v82
	v_min_f32_e32 v82, v51, v82
	v_max_f32_e32 v86, v28, v30
	v_min_f32_e32 v30, v28, v30
	v_max_f32_e32 v79, v18, v20
	v_min_f32_e32 v20, v18, v20
	v_max_f32_e32 v88, v29, v31
	v_min_f32_e32 v31, v29, v31
	v_max_f32_e32 v75, v11, v55
	v_min_f32_e32 v55, v11, v55
	v_max_f32_e32 v89, v76, v52
	v_min_f32_e32 v52, v76, v52
	v_max_f32_e32 v83, v84, v54
	v_min_f32_e32 v54, v84, v54
	v_max_f32_e32 v93, v78, v74
	v_min_f32_e32 v74, v78, v74
	v_max_f32_e32 v53, v80, v82
	v_min_f32_e32 v82, v80, v82
	v_max_f32_e32 v97, v86, v88
	v_min_f32_e32 v88, v86, v88
	v_max_f32_e32 v81, v79, v75
	v_min_f32_e32 v75, v79, v75
	v_max_f32_e32 v98, v30, v31
	v_min_f32_e32 v31, v30, v31
	v_max_f32_e32 v99, v20, v55
	v_min_f32_e32 v55, v20, v55
	v_max_f32_e32 v101, v89, v83
	v_min_f32_e32 v83, v89, v83
	v_max_f32_e32 v77, v52, v54
	v_min_f32_e32 v54, v52, v54
	v_max_f32_e32 v104, v93, v53
	v_min_f32_e32 v53, v93, v53
	v_max_f32_e32 v105, v74, v82
	v_min_f32_e32 v82, v74, v82
	v_max_f32_e32 v87, v97, v81
	v_min_f32_e32 v81, v97, v81
	v_max_f32_e32 v108, v88, v75
	v_min_f32_e32 v75, v88, v75
	v_max_f32_e32 v91, v98, v99
	v_min_f32_e32 v99, v98, v99
	v_max_f32_e32 v110, v31, v55
	v_min_f32_e32 v55, v31, v55
	v_and_b32_e32 v85, s7, v101
	v_cndmask_b32_e64 v113, v101, v87, s[4:5]
	v_cndmask_b32_e64 v106, v83, v81, s[4:5]
	v_cndmask_b32_e64 v116, v77, v108, s[4:5]
	v_cndmask_b32_e64 v118, v54, v75, s[4:5]
	v_cndmask_b32_e64 v120, v104, v91, s[4:5]
	v_cndmask_b32_e64 v100, v53, v99, s[4:5]
	v_cndmask_b32_e64 v115, v105, v110, s[4:5]
	v_cndmask_b32_e64 v92, v82, v55, s[4:5]
	v_and_or_b32 v123, v113, 63, v246
	ds_read_u8 v123, v123
	v_and_or_b32 v114, v106, 63, v246
	ds_read_u8 v114, v114
	v_and_or_b32 v126, v116, 63, v246
	ds_read_u8 v126, v126
	v_and_or_b32 v121, v118, 63, v246
	ds_read_u8 v121, v121
	v_and_or_b32 v122, v120, 63, v246
	ds_read_u8 v122, v122
	v_and_or_b32 v124, v100, 63, v246
	ds_read_u8 v124, v124
	v_and_or_b32 v109, v115, 63, v246
	ds_read_u8 v109, v109
	v_and_or_b32 v60, v92, 63, v246
	ds_read_u8 v60, v60
	v_and_b32_e32 v113, s7, v113
	v_sub_f32_e32 v113, v113, v85
	v_mul_f32_e32 v113, 0x3fb8aa3b, v113
	v_exp_f32_e32 v113, v113
	v_and_b32_e32 v106, s7, v106
	v_sub_f32_e32 v106, v106, v85
	v_mul_f32_e32 v106, 0x3fb8aa3b, v106
	v_exp_f32_e32 v106, v106
	v_and_b32_e32 v116, s7, v116
	v_sub_f32_e32 v116, v116, v85
	v_mul_f32_e32 v116, 0x3fb8aa3b, v116
	v_exp_f32_e32 v116, v116
	v_and_b32_e32 v118, s7, v118
	v_sub_f32_e32 v118, v118, v85
	v_mul_f32_e32 v118, 0x3fb8aa3b, v118
	v_exp_f32_e32 v118, v118
	v_and_b32_e32 v120, s7, v120
	v_sub_f32_e32 v120, v120, v85
	v_mul_f32_e32 v120, 0x3fb8aa3b, v120
	v_exp_f32_e32 v120, v120
	v_and_b32_e32 v100, s7, v100
	v_sub_f32_e32 v100, v100, v85
	v_mul_f32_e32 v100, 0x3fb8aa3b, v100
	v_exp_f32_e32 v100, v100
	v_and_b32_e32 v115, s7, v115
	v_sub_f32_e32 v115, v115, v85
	v_mul_f32_e32 v115, 0x3fb8aa3b, v115
	v_exp_f32_e32 v115, v115
	v_and_b32_e32 v92, s7, v92
	v_sub_f32_e32 v92, v92, v85
	v_mul_f32_e32 v92, 0x3fb8aa3b, v92
	v_exp_f32_e32 v92, v92
	s_nop 0
	v_add_f32_e32 v85, v113, v106
	v_add_f32_e32 v85, v85, v116
	v_add_f32_e32 v85, v85, v118
	v_add_f32_e32 v85, v85, v120
	v_add_f32_e32 v85, v85, v100
	v_add_f32_e32 v85, v85, v115
	v_add_f32_e32 v85, v85, v92
	v_mov_b32_e32 v61, v85
	s_nop 1
	v_permlane32_swap_b32_e32 v85, v61
	s_nop 1
	v_add_f32_e32 v85, v85, v61
	s_waitcnt lgkmcnt(0)
	v_bfe_u32 v68, v123, 4, 4
	v_or_b32_e32 v68, v68, v240
	v_and_or_b32 v123, v123, 15, v240
	ds_read_u8 v68, v68
	ds_read_u8 v123, v123 offset:512
	v_bfe_u32 v56, v114, 4, 4
	v_or_b32_e32 v56, v56, v240
	v_and_or_b32 v114, v114, 15, v240
	ds_read_u8 v56, v56
	ds_read_u8 v114, v114 offset:512
	v_bfe_u32 v57, v126, 4, 4
	v_or_b32_e32 v57, v57, v240
	v_and_or_b32 v126, v126, 15, v240
	ds_read_u8 v57, v57
	ds_read_u8 v126, v126 offset:512
	v_bfe_u32 v58, v121, 4, 4
	v_or_b32_e32 v58, v58, v240
	v_and_or_b32 v121, v121, 15, v240
	ds_read_u8 v58, v58
	ds_read_u8 v121, v121 offset:512
	v_bfe_u32 v59, v122, 4, 4
	v_or_b32_e32 v59, v59, v240
	v_and_or_b32 v122, v122, 15, v240
	ds_read_u8 v59, v59
	ds_read_u8 v122, v122 offset:512
	v_bfe_u32 v251, v124, 4, 4
	v_or_b32_e32 v251, v251, v240
	v_and_or_b32 v124, v124, 15, v240
	ds_read_u8 v251, v251
	ds_read_u8 v124, v124 offset:512
	v_bfe_u32 v253, v109, 4, 4
	v_or_b32_e32 v253, v253, v240
	v_and_or_b32 v109, v109, 15, v240
	ds_read_u8 v253, v253
	ds_read_u8 v109, v109 offset:512
	v_bfe_u32 v151, v60, 4, 4
	v_or_b32_e32 v151, v151, v240
	v_and_or_b32 v60, v60, 15, v240
	ds_read_u8 v151, v151
	ds_read_u8 v60, v60 offset:512
	v_div_scale_f32 v134, s[26:27], v85, v85, v113
	v_rcp_f32_e32 v249, v134
	s_nop 0
	v_fma_f32 v136, -v134, v249, 1.0
	v_fmac_f32_e32 v249, v136, v249
	v_div_scale_f32 v136, vcc, v113, v85, v113
	v_mul_f32_e32 v137, v136, v249
	v_fma_f32 v62, -v134, v137, v136
	v_fmac_f32_e32 v137, v62, v249
	v_fma_f32 v136, -v134, v137, v136
	s_nop 0
	v_div_fmas_f32 v136, v136, v249, v137
	v_div_fixup_f32 v62, v136, v85, v113
	v_div_scale_f32 v134, s[26:27], v85, v85, v106
	v_rcp_f32_e32 v249, v134
	s_nop 0
	v_fma_f32 v136, -v134, v249, 1.0
	v_fmac_f32_e32 v249, v136, v249
	v_div_scale_f32 v136, vcc, v106, v85, v106
	v_mul_f32_e32 v137, v136, v249
	v_fma_f32 v64, -v134, v137, v136
	v_fmac_f32_e32 v137, v64, v249
	v_fma_f32 v136, -v134, v137, v136
	s_nop 0
	v_div_fmas_f32 v136, v136, v249, v137
	v_div_fixup_f32 v64, v136, v85, v106
	v_div_scale_f32 v134, s[26:27], v85, v85, v116
	v_rcp_f32_e32 v249, v134
	s_nop 0
	v_fma_f32 v136, -v134, v249, 1.0
	v_fmac_f32_e32 v249, v136, v249
	v_div_scale_f32 v136, vcc, v116, v85, v116
	v_mul_f32_e32 v137, v136, v249
	v_fma_f32 v255, -v134, v137, v136
	v_fmac_f32_e32 v137, v255, v249
	v_fma_f32 v136, -v134, v137, v136
	s_nop 0
	v_div_fmas_f32 v136, v136, v249, v137
	v_div_fixup_f32 v255, v136, v85, v116
	v_div_scale_f32 v134, s[26:27], v85, v85, v118
	v_rcp_f32_e32 v249, v134
	s_nop 0
	v_fma_f32 v136, -v134, v249, 1.0
	v_fmac_f32_e32 v249, v136, v249
	v_div_scale_f32 v136, vcc, v118, v85, v118
	v_mul_f32_e32 v137, v136, v249
	v_fma_f32 v252, -v134, v137, v136
	v_fmac_f32_e32 v137, v252, v249
	v_fma_f32 v136, -v134, v137, v136
	s_nop 0
	v_div_fmas_f32 v136, v136, v249, v137
	v_div_fixup_f32 v252, v136, v85, v118
	v_div_scale_f32 v134, s[26:27], v85, v85, v120
	v_rcp_f32_e32 v249, v134
	s_nop 0
	v_fma_f32 v136, -v134, v249, 1.0
	v_fmac_f32_e32 v249, v136, v249
	v_div_scale_f32 v136, vcc, v120, v85, v120
	v_mul_f32_e32 v137, v136, v249
	v_fma_f32 v129, -v134, v137, v136
	v_fmac_f32_e32 v137, v129, v249
	v_fma_f32 v136, -v134, v137, v136
	s_nop 0
	v_div_fmas_f32 v136, v136, v249, v137
	v_div_fixup_f32 v129, v136, v85, v120
	v_div_scale_f32 v134, s[26:27], v85, v85, v100
	v_rcp_f32_e32 v249, v134
	s_nop 0
	v_fma_f32 v136, -v134, v249, 1.0
	v_fmac_f32_e32 v249, v136, v249
	v_div_scale_f32 v136, vcc, v100, v85, v100
	v_mul_f32_e32 v137, v136, v249
	v_fma_f32 v130, -v134, v137, v136
	v_fmac_f32_e32 v137, v130, v249
	v_fma_f32 v136, -v134, v137, v136
	s_nop 0
	v_div_fmas_f32 v136, v136, v249, v137
	v_div_fixup_f32 v130, v136, v85, v100
	v_div_scale_f32 v134, s[26:27], v85, v85, v115
	v_rcp_f32_e32 v249, v134
	s_nop 0
	v_fma_f32 v136, -v134, v249, 1.0
	v_fmac_f32_e32 v249, v136, v249
	v_div_scale_f32 v136, vcc, v115, v85, v115
	v_mul_f32_e32 v137, v136, v249
	v_fma_f32 v65, -v134, v137, v136
	v_fmac_f32_e32 v137, v65, v249
	v_fma_f32 v136, -v134, v137, v136
	s_nop 0
	v_div_fmas_f32 v136, v136, v249, v137
	v_div_fixup_f32 v65, v136, v85, v115
	v_div_scale_f32 v134, s[26:27], v85, v85, v92
	v_rcp_f32_e32 v249, v134
	s_nop 0
	v_fma_f32 v136, -v134, v249, 1.0
	v_fmac_f32_e32 v249, v136, v249
	v_div_scale_f32 v136, vcc, v92, v85, v92
	v_mul_f32_e32 v137, v136, v249
	v_fma_f32 v133, -v134, v137, v136
	v_fmac_f32_e32 v137, v133, v249
	v_fma_f32 v136, -v134, v137, v136
	s_nop 0
	v_div_fmas_f32 v136, v136, v249, v137
	v_div_fixup_f32 v133, v136, v85, v92
	s_waitcnt lgkmcnt(0)
	v_and_b32_e32 v68, 0x7f, v68
	v_and_b32_e32 v123, 0x7f, v123
	v_lshl_or_b32 v68, v68, 7, v123
	v_xor_b32_e32 v68, 0x3fff, v68
	v_and_b32_e32 v56, 0x7f, v56
	v_and_b32_e32 v114, 0x7f, v114
	v_lshl_or_b32 v56, v56, 7, v114
	v_xor_b32_e32 v56, 0x3fff, v56
	v_and_b32_e32 v57, 0x7f, v57
	v_and_b32_e32 v126, 0x7f, v126
	v_lshl_or_b32 v57, v57, 7, v126
	v_xor_b32_e32 v57, 0x3fff, v57
	v_and_b32_e32 v58, 0x7f, v58
	v_and_b32_e32 v121, 0x7f, v121
	v_lshl_or_b32 v58, v58, 7, v121
	v_xor_b32_e32 v58, 0x3fff, v58
	v_and_b32_e32 v59, 0x7f, v59
	v_and_b32_e32 v122, 0x7f, v122
	v_lshl_or_b32 v59, v59, 7, v122
	v_xor_b32_e32 v59, 0x3fff, v59
	v_and_b32_e32 v251, 0x7f, v251
	v_and_b32_e32 v124, 0x7f, v124
	v_lshl_or_b32 v251, v251, 7, v124
	v_xor_b32_e32 v251, 0x3fff, v251
	v_and_b32_e32 v253, 0x7f, v253
	v_and_b32_e32 v109, 0x7f, v109
	v_lshl_or_b32 v253, v253, 7, v109
	v_xor_b32_e32 v253, 0x3fff, v253
	v_and_b32_e32 v151, 0x7f, v151
	v_and_b32_e32 v60, 0x7f, v60
	v_lshl_or_b32 v151, v151, 7, v60
	v_xor_b32_e32 v151, 0x3fff, v151
	s_waitcnt vmcnt(0)
	v_pk_mul_f32 v[160:161], v[160:161], v[176:177]
	v_pk_mul_f32 v[162:163], v[162:163], v[178:179]
	v_pk_mul_f32 v[164:165], v[164:165], v[180:181]
	v_pk_mul_f32 v[166:167], v[166:167], v[182:183]
	v_pk_mul_f32 v[168:169], v[168:169], v[184:185]
	v_pk_mul_f32 v[170:171], v[170:171], v[186:187]
	v_pk_mul_f32 v[172:173], v[172:173], v[188:189]
	v_pk_mul_f32 v[174:175], v[174:175], v[190:191]
	v_max3_f32 v192, |v160|, |v161|, |v162|
	v_max3_f32 v192, |v163|, |v164|, v192
	v_max3_f32 v192, |v165|, |v166|, v192
	v_max3_f32 v192, |v167|, |v168|, v192
	v_max3_f32 v192, |v169|, |v170|, v192
	v_max3_f32 v192, |v171|, |v172|, v192
	v_max3_f32 v192, |v173|, |v174|, v192
	v_max_f32_e64 v192, |v175|, v192
	s_nop 1
	v_mov_b32_dpp v193, v192 quad_perm:[1,0,3,2] row_mask:0xf bank_mask:0xf bound_ctrl:1
	v_max_f32_e32 v192, v192, v193
	s_nop 1
	v_mov_b32_dpp v193, v192 quad_perm:[2,3,0,1] row_mask:0xf bank_mask:0xf bound_ctrl:1
	v_max_f32_e32 v192, v192, v193
	s_nop 1
	v_mov_b32_dpp v193, v192 row_half_mirror row_mask:0xf bank_mask:0xf bound_ctrl:1
	v_max_f32_e32 v192, v192, v193
	s_nop 1
	v_mov_b32_dpp v193, v192 row_mirror row_mask:0xf bank_mask:0xf bound_ctrl:1
	v_max_f32_e32 v192, v192, v193
	v_mov_b32_e32 v193, v192
	s_nop 1
	v_permlane16_swap_b32_e32 v192, v193
	s_nop 1
	v_max_f32_e32 v192, v192, v193
	v_mov_b32_e32 v193, v192
	s_nop 1
	v_permlane32_swap_b32_e32 v192, v193
	s_nop 1
	v_max_f32_e32 v192, v192, v193
	v_max_f32_e32 v192, 0xda24260, v192
	v_mul_f32_e32 v194, 0x3e2aaaab, v192
	global_store_dword v214, v194, s[12:13]
	v_div_scale_f32 v195, s[26:27], v194, v194, 1.0
	v_rcp_f32_e32 v196, v195
	v_div_scale_f32 v204, vcc, 1.0, v194, 1.0
	v_fma_f32 v205, -v195, v196, 1.0
	v_fmac_f32_e32 v196, v205, v196
	v_mul_f32_e32 v205, v204, v196
	v_fma_f32 v206, -v195, v205, v204
	v_fmac_f32_e32 v205, v206, v196
	v_fma_f32 v195, -v195, v205, v204
	s_nop 0
	v_div_fmas_f32 v195, v195, v196, v205
	v_div_fixup_f32 v207, v195, v194, 1.0
	v_mul_f32_e32 v160, v207, v160
	v_mul_f32_e32 v161, v207, v161
	v_mul_f32_e32 v162, v207, v162
	v_mul_f32_e32 v163, v207, v163
	v_mul_f32_e32 v164, v207, v164
	v_mul_f32_e32 v165, v207, v165
	v_mul_f32_e32 v166, v207, v166
	v_mul_f32_e32 v167, v207, v167
	v_mul_f32_e32 v168, v207, v168
	v_mul_f32_e32 v169, v207, v169
	v_mul_f32_e32 v170, v207, v170
	v_mul_f32_e32 v171, v207, v171
	v_mul_f32_e32 v172, v207, v172
	v_mul_f32_e32 v173, v207, v173
	v_mul_f32_e32 v174, v207, v174
	v_mul_f32_e32 v175, v207, v175
	v_mov_b32_e32 v208, 0
	v_mov_b32_e32 v209, 0
	v_mov_b32_e32 v210, 0
	v_mov_b32_e32 v193, 0
	v_cvt_scalef32_pk_fp4_f32 v208, v160, v161, 1.0
	v_cvt_scalef32_pk_fp4_f32 v209, v164, v165, 1.0
	v_cvt_scalef32_pk_fp4_f32 v210, v168, v169, 1.0
	v_cvt_scalef32_pk_fp4_f32 v193, v172, v173, 1.0
	v_cvt_scalef32_pk_fp4_f32 v208, v162, v163, 1.0 op_sel:[0,0,1,0]
	v_cvt_scalef32_pk_fp4_f32 v209, v166, v167, 1.0 op_sel:[0,0,1,0]
	v_cvt_scalef32_pk_fp4_f32 v210, v170, v171, 1.0 op_sel:[0,0,1,0]
	v_cvt_scalef32_pk_fp4_f32 v193, v174, v175, 1.0 op_sel:[0,0,1,0]
	global_store_short v213, v208, s[10:11] nt
	s_add_u32 s14, s10, 0x200000
	s_addc_u32 s15, s11, 0
	global_store_short v213, v209, s[14:15] nt
	s_add_u32 s14, s10, 0x400000
	s_addc_u32 s15, s11, 0
	global_store_short v213, v210, s[14:15] nt
	s_add_u32 s14, s10, 0x600000
	s_addc_u32 s15, s11, 0
	global_store_short v213, v193, s[14:15] nt
	s_add_u32 s10, s10, 0x20000
	s_addc_u32 s11, s11, 0
	s_add_u32 s12, s12, 0x2000
	s_addc_u32 s13, s13, 0
	s_cmp_eq_u32 s22, 1
	s_cbranch_scc1 .Ltk1_noload7
	global_load_dwordx4 v[160:163], v212, s[8:9] offset:0 nt
	global_load_dwordx4 v[164:167], v212, s[8:9] offset:1024 nt
	global_load_dwordx4 v[168:171], v212, s[8:9] offset:2048 nt
	global_load_dwordx4 v[172:175], v212, s[8:9] offset:3072 nt
	s_add_u32 s8, s8, 0x800000
	s_addc_u32 s9, s9, 0
